# all flat loads/stores converted to global (all pointers are global memory): LDS lgkmcnt waits no longer drain outstanding memory ops (GEMM epilogue to next K-loop, transposes, rmsnorm, post_token)
# speedup vs baseline: 1.0011x; 1.0011x over previous
; #define LAS __attribute__((address_space(3)))
; DI unsigned pk2(float lo, float hi) { f32x2 v = {lo, hi}; bf16x2_t b = __builtin_convertvector(v, bf16x2_t); return __builtin_bit_cast(unsigned, b); }
; template <bool INMAP>
; DI void transpose_item(const float* W, int K, int N, int nblk, bf16_t* WT, int row_off, LAS float* scr, int item, int lane) {
;     ...
;     for (int i = 0; i < 16; ++i) { const int kk = 4 * i + kr;
;         f32x4 v = {0.f, 0.f, 0.f, 0.f};
;         if (ns >= 0) v = __builtin_nontemporal_load((const f32x4*)(W + (size_t)(k0 + kk) * N + ns));
;         LAS float* d = scr + kk * 65 + 4 * q; d[0] = v.x; d[1] = v.y; d[2] = v.z; d[3] = v.w; }
;     asm volatile("s_waitcnt lgkmcnt(0)" ::: "memory");
;     const int c = lane & 7;
; #pragma unroll
;     for (int j = 0; j < 8; ++j) { const int n = (lane >> 3) + 8 * j; const LAS float* s = scr + (8 * c) * 65 + n;
;         u32x4 o; o.x = pk2(s[0 * 65], s[1 * 65]); o.y = pk2(s[2 * 65], s[3 * 65]); o.z = pk2(s[4 * 65], s[5 * 65]); o.w = pk2(s[6 * 65], s[7 * 65]);
;         *(u32x4*)(WT + (size_t)(row_off + n0 + n) * K + k0 + 8 * c) = o; }
;     asm volatile("s_waitcnt lgkmcnt(0)" ::: "memory");
.LBB0_23:
	s_or_b64 exec, exec, s[2:3]
	v_add_u32_e32 v24, 0x1040, v68
	ds_write2_b32 v24, v4, v5 offset1:1
	v_add_u32_e32 v4, 0x1048, v68
	ds_write2_b32 v4, v6, v7 offset1:1
	v_add_u32_e32 v4, 0x1450, v68
	ds_write2_b32 v4, v0, v1 offset1:1
	v_add_u32_e32 v0, 0x1458, v68
	ds_write2_b32 v0, v2, v3 offset1:1
	s_waitcnt lgkmcnt(0)
	ds_read_b32 v0, v28
	ds_read_b32 v1, v28 offset:260
	ds_read_b32 v2, v28 offset:520
	ds_read_b32 v3, v28 offset:780
	ds_read_b32 v6, v28 offset:1040
	ds_read_b32 v7, v28 offset:1300
	ds_read_b32 v24, v28 offset:1560
	ds_read_b32 v25, v28 offset:1820
	s_waitcnt lgkmcnt(0)
	v_cvt_pk_bf16_f32 v0, v0, v1
	v_cvt_pk_bf16_f32 v1, v2, v3
	v_cvt_pk_bf16_f32 v2, v6, v7
	v_add_u32_e32 v6, s17, v27
	s_ashr_i32 s7, s6, 31
	v_ashrrev_i32_e32 v7, 31, v6
	v_lshl_add_u64 v[4:5], s[6:7], 1, v[10:11]
	v_cvt_pk_bf16_f32 v3, v24, v25
	v_lshlrev_b64 v[24:25], 12, v[6:7]
	v_lshl_add_u64 v[24:25], v[4:5], 0, v[24:25]
	global_store_dwordx4 v[24:25], v[0:3], off
	ds_read_b32 v0, v28 offset:32
	ds_read_b32 v1, v28 offset:292
	ds_read_b32 v2, v28 offset:552
	ds_read_b32 v3, v28 offset:812
	ds_read_b32 v7, v28 offset:1072
	ds_read_b32 v24, v28 offset:1332
	ds_read_b32 v25, v28 offset:1592
	ds_read_b32 v68, v28 offset:1852
	s_waitcnt lgkmcnt(0)
	v_cvt_pk_bf16_f32 v0, v0, v1
	v_cvt_pk_bf16_f32 v1, v2, v3
	v_cvt_pk_bf16_f32 v2, v7, v24
	v_add_u32_e32 v24, 8, v6
	v_cvt_pk_bf16_f32 v3, v25, v68
	v_ashrrev_i32_e32 v25, 31, v24
	v_lshlrev_b64 v[24:25], 12, v[24:25]
	v_lshl_add_u64 v[24:25], v[4:5], 0, v[24:25]
	global_store_dwordx4 v[24:25], v[0:3], off
	ds_read_b32 v0, v28 offset:64
	ds_read_b32 v1, v28 offset:324
	ds_read_b32 v2, v28 offset:584
	ds_read_b32 v3, v28 offset:844
	ds_read_b32 v7, v28 offset:1104
	ds_read_b32 v24, v28 offset:1364
	ds_read_b32 v25, v28 offset:1624
	ds_read_b32 v68, v28 offset:1884
	s_waitcnt lgkmcnt(0)
	v_cvt_pk_bf16_f32 v0, v0, v1
	v_cvt_pk_bf16_f32 v1, v2, v3
	v_cvt_pk_bf16_f32 v2, v7, v24
	v_add_u32_e32 v24, 16, v6
	v_cvt_pk_bf16_f32 v3, v25, v68
	v_ashrrev_i32_e32 v25, 31, v24
	v_lshlrev_b64 v[24:25], 12, v[24:25]
	v_lshl_add_u64 v[24:25], v[4:5], 0, v[24:25]
	global_store_dwordx4 v[24:25], v[0:3], off
	ds_read_b32 v0, v28 offset:96
	ds_read_b32 v1, v28 offset:356
	ds_read_b32 v2, v28 offset:616
	ds_read_b32 v3, v28 offset:876
	ds_read_b32 v7, v28 offset:1136
	ds_read_b32 v24, v28 offset:1396
	ds_read_b32 v25, v28 offset:1656
	ds_read_b32 v68, v28 offset:1916
	s_waitcnt lgkmcnt(0)
	v_cvt_pk_bf16_f32 v0, v0, v1
	v_cvt_pk_bf16_f32 v1, v2, v3
	v_cvt_pk_bf16_f32 v2, v7, v24
	v_add_u32_e32 v24, 24, v6
	v_cvt_pk_bf16_f32 v3, v25, v68
	v_ashrrev_i32_e32 v25, 31, v24
	v_lshlrev_b64 v[24:25], 12, v[24:25]
	v_lshl_add_u64 v[24:25], v[4:5], 0, v[24:25]
	global_store_dwordx4 v[24:25], v[0:3], off
	ds_read_b32 v0, v28 offset:128
	ds_read_b32 v1, v28 offset:388
	ds_read_b32 v2, v28 offset:648
	ds_read_b32 v3, v28 offset:908
	ds_read_b32 v7, v28 offset:1168
	ds_read_b32 v24, v28 offset:1428
	ds_read_b32 v25, v28 offset:1688
	ds_read_b32 v68, v28 offset:1948
	s_waitcnt lgkmcnt(0)
	v_cvt_pk_bf16_f32 v0, v0, v1
	v_cvt_pk_bf16_f32 v1, v2, v3
	v_cvt_pk_bf16_f32 v2, v7, v24
	v_add_u32_e32 v24, 32, v6
	v_cvt_pk_bf16_f32 v3, v25, v68
	v_ashrrev_i32_e32 v25, 31, v24
	v_lshlrev_b64 v[24:25], 12, v[24:25]
	v_lshl_add_u64 v[24:25], v[4:5], 0, v[24:25]
	global_store_dwordx4 v[24:25], v[0:3], off
	ds_read_b32 v0, v28 offset:160
	ds_read_b32 v1, v28 offset:420
	ds_read_b32 v2, v28 offset:680
	ds_read_b32 v3, v28 offset:940
	ds_read_b32 v7, v28 offset:1200
	ds_read_b32 v24, v28 offset:1460
	ds_read_b32 v25, v28 offset:1720
	ds_read_b32 v68, v28 offset:1980
	s_waitcnt lgkmcnt(0)
	v_cvt_pk_bf16_f32 v0, v0, v1
	v_cvt_pk_bf16_f32 v1, v2, v3
	v_cvt_pk_bf16_f32 v2, v7, v24
	v_add_u32_e32 v24, 40, v6
	v_cvt_pk_bf16_f32 v3, v25, v68
	v_ashrrev_i32_e32 v25, 31, v24
	v_lshlrev_b64 v[24:25], 12, v[24:25]
	v_lshl_add_u64 v[24:25], v[4:5], 0, v[24:25]
	global_store_dwordx4 v[24:25], v[0:3], off
	ds_read_b32 v0, v28 offset:192
	ds_read_b32 v1, v28 offset:452
	ds_read_b32 v2, v28 offset:712
	ds_read_b32 v3, v28 offset:972
	ds_read_b32 v7, v28 offset:1232
	ds_read_b32 v24, v28 offset:1492
	ds_read_b32 v25, v28 offset:1752
	ds_read_b32 v68, v28 offset:2012
	s_waitcnt lgkmcnt(0)
	v_cvt_pk_bf16_f32 v0, v0, v1
	v_cvt_pk_bf16_f32 v1, v2, v3
	v_cvt_pk_bf16_f32 v2, v7, v24
	v_add_u32_e32 v24, 48, v6
	v_cvt_pk_bf16_f32 v3, v25, v68
	v_ashrrev_i32_e32 v25, 31, v24
	v_lshlrev_b64 v[24:25], 12, v[24:25]
	v_lshl_add_u64 v[24:25], v[4:5], 0, v[24:25]
	global_store_dwordx4 v[24:25], v[0:3], off
	ds_read_b32 v0, v28 offset:224
	ds_read_b32 v1, v28 offset:484
	ds_read_b32 v2, v28 offset:744
	ds_read_b32 v3, v28 offset:1004
	ds_read_b32 v7, v28 offset:1264
	ds_read_b32 v24, v28 offset:1524
	ds_read_b32 v25, v28 offset:1784
	ds_read_b32 v68, v28 offset:2044
	v_add_u32_e32 v6, 56, v6
	s_waitcnt lgkmcnt(0)
	v_cvt_pk_bf16_f32 v0, v0, v1
	v_cvt_pk_bf16_f32 v1, v2, v3
	v_cvt_pk_bf16_f32 v2, v7, v24
	v_ashrrev_i32_e32 v7, 31, v6
	v_lshlrev_b64 v[6:7], 12, v[6:7]
	v_cvt_pk_bf16_f32 v3, v25, v68
	v_lshl_add_u64 v[4:5], v[4:5], 0, v[6:7]
	global_store_dwordx4 v[4:5], v[0:3], off
	s_waitcnt lgkmcnt(0)

; DI unsigned pk2(float lo, float hi) { f32x2 v = {lo, hi}; bf16x2_t b = __builtin_convertvector(v, bf16x2_t); return __builtin_bit_cast(unsigned, b); }
; DI void rms_row_to_bf16(const float* xrow, const float* g, bf16_t* orow, int lane) {
;     const f32x4* xr = (const f32x4*)xrow + lane; const f32x4* gr = (const f32x4*)g + lane;
;     f32x4 v[8]; float s = 0.f;
; #pragma unroll
;     for (int j = 0; j < 8; ++j) { v[j] = xr[64 * j]; s += (v[j].x * v[j].x + v[j].y * v[j].y) + (v[j].z * v[j].z + v[j].w * v[j].w); }
;     const float rs = rsqrtf(wave_sum(s) * (1.f / D_) + EPS_);
;     u32x2* o8 = (u32x2*)orow + lane;
; #pragma unroll
;     for (int j = 0; j < 8; ++j) { const f32x4 gg = gr[64 * j]; u32x2 w; w.x = pk2(v[j].x * rs * gg.x, v[j].y * rs * gg.y); w.y = pk2(v[j].z * rs * gg.z, v[j].w * rs * gg.w); o8[64 * j] = w; }
; }
.LBB0_73:
	v_add_co_u32_e32 v0, vcc, 0xfffff000, v36
	s_add_i32 s1, s1, s96
	s_nop 0
	v_addc_co_u32_e32 v1, vcc, -1, v37, vcc
	global_load_dwordx4 v[12:15], v[0:1], off offset:-3072
	global_load_dwordx4 v[8:11], v[0:1], off offset:-2048
	s_cmpk_lt_i32 s1, 0x4000
	s_waitcnt vmcnt(0)
	v_mov_b32_e32 v4, v13
	v_mov_b32_e32 v5, v9
	v_mov_b32_e32 v2, v12
	v_mov_b32_e32 v3, v8
	v_pk_mul_f32 v[4:5], v[4:5], v[4:5]
	v_mov_b32_e32 v6, v15
	v_mov_b32_e32 v7, v11
	v_pk_fma_f32 v[2:3], v[2:3], v[2:3], v[4:5]
	v_mov_b32_e32 v4, v14
	v_mov_b32_e32 v5, v10
	v_pk_mul_f32 v[6:7], v[6:7], v[6:7]
	s_nop 0
	v_pk_fma_f32 v[4:5], v[4:5], v[4:5], v[6:7]
	s_nop 0
	v_pk_add_f32 v[20:21], v[2:3], v[4:5]
	global_load_dwordx4 v[4:7], v[0:1], off offset:-1024
	v_pk_add_f32 v[20:21], v[20:21], v[20:21] op_sel:[0,1] op_sel_hi:[1,0]
	s_waitcnt vmcnt(0)
	v_pk_mul_f32 v[0:1], v[6:7], v[6:7]
	v_pk_mul_f32 v[2:3], v[4:5], v[4:5]
	s_nop 0
	v_pk_mov_b32 v[16:17], v[2:3], v[0:1] op_sel:[1,0]
	v_mov_b32_e32 v3, v1
	v_pk_add_f32 v[22:23], v[16:17], v[2:3]
	global_load_dwordx4 v[0:3], v[36:37], off offset:-4096
	global_load_dwordx4 v[16:19], v[36:37], off offset:-3072
	v_pk_add_f32 v[22:23], v[22:23], v[22:23] op_sel:[0,1] op_sel_hi:[1,0]
	s_waitcnt vmcnt(0)
	v_mul_f32_e32 v24, v16, v16
	v_mul_f32_e32 v25, v17, v17
	v_mov_b32_e32 v21, v24
	v_mov_b32_e32 v23, v25
	v_pk_add_f32 v[20:21], v[20:21], v[22:23]
	v_mul_f32_e32 v22, v1, v1
	v_mul_f32_e32 v24, v3, v3
	v_mul_f32_e32 v26, v18, v18
	v_mul_f32_e32 v27, v19, v19
	v_pk_fma_f32 v[22:23], v[0:1], v[0:1], v[22:23] op_sel_hi:[1,1,0]
	v_pk_fma_f32 v[24:25], v[2:3], v[2:3], v[24:25] op_sel_hi:[1,1,0]
	v_mov_b32_e32 v23, v26
	v_mov_b32_e32 v25, v27
	v_pk_add_f32 v[22:23], v[22:23], v[24:25]
	s_nop 0
	v_pk_add_f32 v[32:33], v[20:21], v[22:23]
	global_load_dwordx4 v[20:23], v[36:37], off offset:-2048
	v_pk_add_f32 v[32:33], v[32:33], v[32:33] op_sel:[0,1] op_sel_hi:[1,0]
	s_waitcnt vmcnt(0)
	v_pk_mul_f32 v[24:25], v[22:23], v[22:23]
	v_pk_mul_f32 v[26:27], v[20:21], v[20:21]
	s_nop 0
	v_pk_mov_b32 v[28:29], v[26:27], v[24:25] op_sel:[1,0]
	v_mov_b32_e32 v27, v25
	v_pk_add_f32 v[34:35], v[28:29], v[26:27]
	global_load_dwordx4 v[24:27], v[36:37], off offset:-1024
	global_load_dwordx4 v[28:31], v[36:37], off
	v_pk_add_f32 v[34:35], v[34:35], v[34:35] op_sel:[0,1] op_sel_hi:[1,0]
	v_lshl_add_u64 v[36:37], v[36:37], 0, s[80:81]
	s_waitcnt vmcnt(0)
	v_mul_f32_e32 v40, v28, v28
	v_mul_f32_e32 v47, v29, v29
	v_mov_b32_e32 v33, v40
	v_mov_b32_e32 v35, v47
	v_pk_add_f32 v[32:33], v[32:33], v[34:35]
	v_mul_f32_e32 v34, v25, v25
	v_mul_f32_e32 v48, v30, v30
	v_pk_fma_f32 v[34:35], v[24:25], v[24:25], v[34:35] op_sel_hi:[1,1,0]
	v_mul_f32_e32 v40, v27, v27
	v_mul_f32_e32 v50, v31, v31
	v_mov_b32_e32 v35, v48
	v_pk_fma_f32 v[48:49], v[26:27], v[26:27], v[40:41] op_sel_hi:[1,1,0]
	s_nop 0
	v_mov_b32_e32 v49, v50
	v_pk_add_f32 v[34:35], v[34:35], v[48:49]
	s_nop 0
	v_pk_add_f32 v[32:33], v[32:33], v[34:35]
	s_nop 0
	v_add_f32_e32 v32, v32, v33
	ds_bpermute_b32 v33, v41, v32
	s_waitcnt lgkmcnt(0)
	v_add_f32_e32 v32, v32, v33
	ds_bpermute_b32 v33, v42, v32
	s_waitcnt lgkmcnt(0)
	v_add_f32_e32 v32, v32, v33
	ds_bpermute_b32 v33, v43, v32
	s_waitcnt lgkmcnt(0)
	v_add_f32_e32 v32, v32, v33
	ds_bpermute_b32 v33, v44, v32
	s_waitcnt lgkmcnt(0)
	v_add_f32_e32 v32, v32, v33
	ds_bpermute_b32 v33, v45, v32
	s_waitcnt lgkmcnt(0)
	v_add_f32_e32 v32, v32, v33
	ds_bpermute_b32 v33, v46, v32
	s_waitcnt lgkmcnt(0)
	v_add_f32_e32 v32, v32, v33
	v_fmamk_f32 v32, v32, 0x3a000000, v187
	v_cmp_gt_f32_e32 vcc, s97, v32
	v_mul_f32_e32 v33, 0x4b800000, v32
	s_nop 0
	v_cndmask_b32_e32 v32, v32, v33, vcc
	v_rsq_f32_e32 v32, v32
	s_nop 0
	v_mul_f32_e32 v33, 0x45800000, v32
	v_cndmask_b32_e32 v40, v32, v33, vcc
	global_load_dwordx4 v[32:35], v[134:135], off
	v_pk_mul_f32 v[12:13], v[12:13], v[40:41] op_sel_hi:[1,0]
	v_pk_mul_f32 v[14:15], v[14:15], v[40:41] op_sel_hi:[1,0]
	v_pk_mul_f32 v[8:9], v[8:9], v[40:41] op_sel_hi:[1,0]
	v_pk_mul_f32 v[10:11], v[10:11], v[40:41] op_sel_hi:[1,0]
	v_pk_mul_f32 v[4:5], v[4:5], v[40:41] op_sel_hi:[1,0]
	v_pk_mul_f32 v[6:7], v[6:7], v[40:41] op_sel_hi:[1,0]
	v_pk_mul_f32 v[0:1], v[0:1], v[40:41] op_sel_hi:[1,0]
	v_pk_mul_f32 v[2:3], v[2:3], v[40:41] op_sel_hi:[1,0]
	s_waitcnt vmcnt(0)
	v_pk_mul_f32 v[12:13], v[32:33], v[12:13]
	v_pk_mul_f32 v[14:15], v[34:35], v[14:15]
	v_cvt_pk_bf16_f32 v12, v12, v13
	v_cvt_pk_bf16_f32 v13, v14, v15
	global_store_dwordx2 v[38:39], v[12:13], off
	global_load_dwordx4 v[12:15], v[134:135], off offset:1024
	s_waitcnt vmcnt(0)
	v_pk_mul_f32 v[8:9], v[12:13], v[8:9]
	v_pk_mul_f32 v[10:11], v[14:15], v[10:11]
	v_cvt_pk_bf16_f32 v8, v8, v9
	v_cvt_pk_bf16_f32 v9, v10, v11
	global_store_dwordx2 v[38:39], v[8:9], off offset:512
	global_load_dwordx4 v[8:11], v[134:135], off offset:2048
	s_waitcnt vmcnt(0)
	v_pk_mul_f32 v[4:5], v[8:9], v[4:5]
	v_pk_mul_f32 v[6:7], v[10:11], v[6:7]
	v_cvt_pk_bf16_f32 v4, v4, v5
	v_cvt_pk_bf16_f32 v5, v6, v7
	global_store_dwordx2 v[38:39], v[4:5], off offset:1024
	global_load_dwordx4 v[4:7], v[134:135], off offset:3072
	s_waitcnt vmcnt(0)
	v_pk_mul_f32 v[0:1], v[4:5], v[0:1]
	v_pk_mul_f32 v[2:3], v[6:7], v[2:3]
	v_cvt_pk_bf16_f32 v0, v0, v1
	v_cvt_pk_bf16_f32 v1, v2, v3
	global_store_dwordx2 v[38:39], v[0:1], off offset:1536
	global_load_dwordx4 v[0:3], v[136:137], off
	v_pk_mul_f32 v[4:5], v[16:17], v[40:41] op_sel_hi:[1,0]
	s_waitcnt vmcnt(0)
	v_pk_mul_f32 v[0:1], v[0:1], v[4:5]
	v_pk_mul_f32 v[4:5], v[18:19], v[40:41] op_sel_hi:[1,0]
	v_cvt_pk_bf16_f32 v0, v0, v1
	v_pk_mul_f32 v[2:3], v[2:3], v[4:5]
	v_pk_mul_f32 v[4:5], v[20:21], v[40:41] op_sel_hi:[1,0]
	v_cvt_pk_bf16_f32 v1, v2, v3
	global_store_dwordx2 v[38:39], v[0:1], off offset:2048
	global_load_dwordx4 v[0:3], v[138:139], off
	s_waitcnt vmcnt(0)
	v_pk_mul_f32 v[0:1], v[4:5], v[0:1]
	v_pk_mul_f32 v[4:5], v[22:23], v[40:41] op_sel_hi:[1,0]
	v_cvt_pk_bf16_f32 v0, v0, v1
	v_pk_mul_f32 v[2:3], v[4:5], v[2:3]
	v_pk_mul_f32 v[4:5], v[24:25], v[40:41] op_sel_hi:[1,0]
	v_cvt_pk_bf16_f32 v1, v2, v3
	global_store_dwordx2 v[38:39], v[0:1], off offset:2560
	global_load_dwordx4 v[0:3], v[140:141], off
	s_waitcnt vmcnt(0)
	v_pk_mul_f32 v[0:1], v[4:5], v[0:1]
	v_pk_mul_f32 v[4:5], v[26:27], v[40:41] op_sel_hi:[1,0]
	v_cvt_pk_bf16_f32 v0, v0, v1
	v_pk_mul_f32 v[2:3], v[4:5], v[2:3]
	v_pk_mul_f32 v[4:5], v[28:29], v[40:41] op_sel_hi:[1,0]
	v_cvt_pk_bf16_f32 v1, v2, v3
	global_store_dwordx2 v[38:39], v[0:1], off offset:3072
	global_load_dwordx4 v[0:3], v[142:143], off
	s_waitcnt vmcnt(0)
	v_pk_mul_f32 v[0:1], v[4:5], v[0:1]
	v_pk_mul_f32 v[4:5], v[30:31], v[40:41] op_sel_hi:[1,0]
	v_cvt_pk_bf16_f32 v0, v0, v1
	v_pk_mul_f32 v[2:3], v[4:5], v[2:3]
	s_nop 0
	v_cvt_pk_bf16_f32 v1, v2, v3
	global_store_dwordx2 v[38:39], v[0:1], off offset:3584
	v_lshl_add_u64 v[38:39], v[38:39], 0, s[84:85]
	s_cbranch_scc1 .LBB0_73
	s_mov_b64 s[2:3], 0
; DI float wave_sum(float v) {
; #pragma unroll
;     for (int o = 1; o < 64; o <<= 1) v += __shfl_xor(v, o);
;     return v;
; }
; DI void rms_rows4_to_bf16(const float* xb, size_t xstride, const float* g, bf16_t* ob, size_t ostride, int lane) {
;     f32x4 v[4][8]; float ss[4];
; #pragma unroll
;     for (int r = 0; r < 4; ++r)
; #pragma unroll
;         for (int j = 0; j < 8; ++j) v[r][j] = ((const f32x4*)(xb + r * xstride))[lane + 64 * j];
; #pragma unroll
;     for (int r = 0; r < 4; ++r) { float s = 0.f;
; #pragma unroll
;         for (int j = 0; j < 8; ++j) s += (v[r][j].x * v[r][j].x + v[r][j].y * v[r][j].y) + (v[r][j].z * v[r][j].z + v[r][j].w * v[r][j].w);
;         ss[r] = rsqrtf(wave_sum(s) * (1.f / D_) + EPS_); }
.LBB0_75:
	s_and_b64 vcc, exec, s[2:3]
	s_cbranch_vccz .LBB0_70
	s_ashr_i32 s1, s0, 31
	s_lshl_b64 s[2:3], s[0:1], 13
	s_add_u32 s2, s5, s2
	s_addc_u32 s3, s4, s3
	global_load_dwordx4 v[124:127], v133, s[2:3]
	global_load_dwordx4 v[104:107], v133, s[2:3] offset:1024
	global_load_dwordx4 v[80:83], v133, s[2:3] offset:2048
	global_load_dwordx4 v[64:67], v133, s[2:3] offset:3072
	global_load_dwordx4 v[56:59], v151, s[2:3]
	global_load_dwordx4 v[40:43], v153, s[2:3]
	global_load_dwordx4 v[24:27], v155, s[2:3]
	global_load_dwordx4 v[8:11], v157, s[2:3]
	s_lshl_b64 s[6:7], s[20:21], 2
	s_add_u32 s2, s2, s6
	s_addc_u32 s3, s3, s7
	global_load_dwordx4 v[120:123], v133, s[2:3]
	global_load_dwordx4 v[108:111], v133, s[2:3] offset:1024
	global_load_dwordx4 v[92:95], v133, s[2:3] offset:2048
	global_load_dwordx4 v[68:71], v133, s[2:3] offset:3072
	global_load_dwordx4 v[60:63], v151, s[2:3]
	global_load_dwordx4 v[44:47], v153, s[2:3]
	global_load_dwordx4 v[28:31], v155, s[2:3]
	global_load_dwordx4 v[12:15], v157, s[2:3]
	v_and_b32_e32 v128, 64, v189
	v_add_u32_e32 v128, 64, v128
	v_xor_b32_e32 v129, 1, v189
	v_cmp_lt_i32_e32 vcc, v129, v128
	s_add_u32 s2, s2, s80
	s_addc_u32 s3, s3, s81
	v_cndmask_b32_e32 v129, v189, v129, vcc
	v_lshlrev_b32_e32 v130, 2, v129
	v_xor_b32_e32 v129, 2, v189
	v_cmp_lt_i32_e32 vcc, v129, v128
	global_load_dwordx4 v[116:119], v133, s[2:3]
	global_load_dwordx4 v[100:103], v133, s[2:3] offset:1024
	global_load_dwordx4 v[84:87], v133, s[2:3] offset:2048
	global_load_dwordx4 v[72:75], v133, s[2:3] offset:3072
	global_load_dwordx4 v[52:55], v151, s[2:3]
	global_load_dwordx4 v[36:39], v153, s[2:3]
	global_load_dwordx4 v[20:23], v155, s[2:3]
	global_load_dwordx4 v[4:7], v157, s[2:3]
	v_cndmask_b32_e32 v129, v189, v129, vcc
	v_lshlrev_b32_e32 v131, 2, v129
	v_xor_b32_e32 v129, 4, v189
	v_cmp_lt_i32_e32 vcc, v129, v128
	s_add_u32 s2, s2, s80
	s_addc_u32 s3, s3, s81
	v_cndmask_b32_e32 v129, v189, v129, vcc
	v_lshlrev_b32_e32 v154, 2, v129
	v_xor_b32_e32 v129, 8, v189
	v_cmp_lt_i32_e32 vcc, v129, v128
	global_load_dwordx4 v[112:115], v133, s[2:3]
	global_load_dwordx4 v[96:99], v133, s[2:3] offset:1024
	global_load_dwordx4 v[88:91], v133, s[2:3] offset:2048
	global_load_dwordx4 v[76:79], v133, s[2:3] offset:3072
	global_load_dwordx4 v[48:51], v151, s[2:3]
	global_load_dwordx4 v[32:35], v153, s[2:3]
	global_load_dwordx4 v[16:19], v155, s[2:3]
	global_load_dwordx4 v[0:3], v157, s[2:3]
	v_cndmask_b32_e32 v129, v189, v129, vcc
	v_lshlrev_b32_e32 v156, 2, v129
	v_xor_b32_e32 v129, 16, v189
	v_cmp_lt_i32_e32 vcc, v129, v128
	s_lshl_b64 s[2:3], s[0:1], 12
	s_waitcnt vmcnt(0)
	v_mov_b32_e32 v170, v125
	v_cndmask_b32_e32 v129, v189, v129, vcc
	v_lshlrev_b32_e32 v158, 2, v129
	v_xor_b32_e32 v129, 32, v189
	v_cmp_lt_i32_e32 vcc, v129, v128
	v_mov_b32_e32 v171, v105
	v_pk_mul_f32 v[170:171], v[170:171], v[170:171]
	v_cndmask_b32_e32 v128, v189, v129, vcc
	v_lshlrev_b32_e32 v159, 2, v128
	v_mov_b32_e32 v128, v124
	v_mov_b32_e32 v129, v104
	v_mov_b32_e32 v172, v127
	v_mov_b32_e32 v173, v107
	v_pk_fma_f32 v[128:129], v[128:129], v[128:129], v[170:171]
	v_mov_b32_e32 v170, v126
	v_mov_b32_e32 v171, v106
	v_pk_mul_f32 v[172:173], v[172:173], v[172:173]
	v_mul_f32_e32 v150, v56, v56
	v_pk_fma_f32 v[170:171], v[170:171], v[170:171], v[172:173]
	v_pk_mul_f32 v[172:173], v[80:81], v[80:81]
	v_pk_add_f32 v[128:129], v[128:129], v[170:171]
	v_pk_mul_f32 v[170:171], v[82:83], v[82:83]
	v_mul_f32_e32 v152, v57, v57
	v_pk_mov_b32 v[174:175], v[172:173], v[170:171] op_sel:[1,0]
	v_mov_b32_e32 v173, v171
	v_pk_add_f32 v[170:171], v[174:175], v[172:173]
	v_pk_add_f32 v[128:129], v[128:129], v[128:129] op_sel:[0,1] op_sel_hi:[1,0]
	v_pk_add_f32 v[170:171], v[170:171], v[170:171] op_sel:[0,1] op_sel_hi:[1,0]
	v_mov_b32_e32 v129, v150
	v_mov_b32_e32 v171, v152
	v_mul_f32_e32 v150, v65, v65
	v_pk_add_f32 v[128:129], v[128:129], v[170:171]
	v_pk_fma_f32 v[170:171], v[64:65], v[64:65], v[150:151] op_sel_hi:[1,1,0]
	v_mul_f32_e32 v150, v67, v67
	v_mul_f32_e32 v166, v58, v58
	v_mul_f32_e32 v167, v59, v59
	v_pk_fma_f32 v[172:173], v[66:67], v[66:67], v[150:151] op_sel_hi:[1,1,0]
	v_mov_b32_e32 v171, v166
	v_mov_b32_e32 v173, v167
	v_pk_add_f32 v[170:171], v[170:171], v[172:173]
	v_pk_mul_f32 v[172:173], v[40:41], v[40:41]
	v_pk_add_f32 v[128:129], v[128:129], v[170:171]
	v_pk_mul_f32 v[170:171], v[42:43], v[42:43]
	v_mul_f32_e32 v150, v8, v8
	v_pk_mov_b32 v[174:175], v[172:173], v[170:171] op_sel:[1,0]
	v_mov_b32_e32 v173, v171
	v_pk_add_f32 v[170:171], v[174:175], v[172:173]
	v_mul_f32_e32 v152, v9, v9
	v_pk_add_f32 v[128:129], v[128:129], v[128:129] op_sel:[0,1] op_sel_hi:[1,0]
	v_pk_add_f32 v[170:171], v[170:171], v[170:171] op_sel:[0,1] op_sel_hi:[1,0]
	v_mov_b32_e32 v129, v150
	v_mov_b32_e32 v171, v152
	v_mul_f32_e32 v150, v25, v25
	v_pk_add_f32 v[128:129], v[128:129], v[170:171]
	v_pk_fma_f32 v[170:171], v[24:25], v[24:25], v[150:151] op_sel_hi:[1,1,0]
	v_mul_f32_e32 v150, v27, v27
	v_mul_f32_e32 v166, v10, v10
	v_mul_f32_e32 v167, v11, v11
	v_pk_fma_f32 v[172:173], v[26:27], v[26:27], v[150:151] op_sel_hi:[1,1,0]
	v_mov_b32_e32 v171, v166
	v_mov_b32_e32 v173, v167
	v_pk_add_f32 v[170:171], v[170:171], v[172:173]
	v_mov_b32_e32 v172, v121
	v_mov_b32_e32 v173, v109
	v_pk_add_f32 v[128:129], v[128:129], v[170:171]
	v_mov_b32_e32 v170, v120
	v_mov_b32_e32 v171, v108
	v_pk_mul_f32 v[172:173], v[172:173], v[172:173]
	v_mov_b32_e32 v174, v123
	v_mov_b32_e32 v175, v111
	v_pk_fma_f32 v[170:171], v[170:171], v[170:171], v[172:173]
	v_mov_b32_e32 v172, v122
	v_mov_b32_e32 v173, v110
	v_pk_mul_f32 v[174:175], v[174:175], v[174:175]
	v_mul_f32_e32 v150, v60, v60
; DI float wave_sum(float v) {
; #pragma unroll
;     for (int o = 1; o < 64; o <<= 1) v += __shfl_xor(v, o);
;     return v;
; }
; DI void rms_rows4_to_bf16(const float* xb, size_t xstride, const float* g, bf16_t* ob, size_t ostride, int lane) {
;     ...
;     for (int r = 0; r < 4; ++r) { float s = 0.f;
; #pragma unroll
;         for (int j = 0; j < 8; ++j) s += (v[r][j].x * v[r][j].x + v[r][j].y * v[r][j].y) + (v[r][j].z * v[r][j].z + v[r][j].w * v[r][j].w);
;         ss[r] = rsqrtf(wave_sum(s) * (1.f / D_) + EPS_); }
	v_pk_fma_f32 v[172:173], v[172:173], v[172:173], v[174:175]
	v_pk_mul_f32 v[174:175], v[92:93], v[92:93]
	v_pk_add_f32 v[170:171], v[170:171], v[172:173]
	v_pk_mul_f32 v[172:173], v[94:95], v[94:95]
	v_mul_f32_e32 v152, v61, v61
	v_pk_mov_b32 v[176:177], v[174:175], v[172:173] op_sel:[1,0]
	v_mov_b32_e32 v175, v173
	v_pk_add_f32 v[172:173], v[176:177], v[174:175]
	v_pk_add_f32 v[170:171], v[170:171], v[170:171] op_sel:[0,1] op_sel_hi:[1,0]
	v_pk_add_f32 v[172:173], v[172:173], v[172:173] op_sel:[0,1] op_sel_hi:[1,0]
	v_mov_b32_e32 v171, v150
	v_mov_b32_e32 v173, v152
	v_mul_f32_e32 v150, v69, v69
	v_pk_add_f32 v[170:171], v[170:171], v[172:173]
	v_pk_fma_f32 v[172:173], v[68:69], v[68:69], v[150:151] op_sel_hi:[1,1,0]
	v_mul_f32_e32 v150, v71, v71
	v_mul_f32_e32 v166, v62, v62
	v_mul_f32_e32 v167, v63, v63
	v_pk_fma_f32 v[174:175], v[70:71], v[70:71], v[150:151] op_sel_hi:[1,1,0]
	v_mov_b32_e32 v173, v166
	v_mov_b32_e32 v175, v167
	v_pk_add_f32 v[172:173], v[172:173], v[174:175]
	v_pk_mul_f32 v[174:175], v[44:45], v[44:45]
	v_pk_add_f32 v[170:171], v[170:171], v[172:173]
	v_pk_mul_f32 v[172:173], v[46:47], v[46:47]
	v_mul_f32_e32 v150, v12, v12
	v_pk_mov_b32 v[176:177], v[174:175], v[172:173] op_sel:[1,0]
	v_mov_b32_e32 v175, v173
	v_pk_add_f32 v[172:173], v[176:177], v[174:175]
	v_mul_f32_e32 v152, v13, v13
	v_pk_add_f32 v[170:171], v[170:171], v[170:171] op_sel:[0,1] op_sel_hi:[1,0]
	v_pk_add_f32 v[172:173], v[172:173], v[172:173] op_sel:[0,1] op_sel_hi:[1,0]
	v_mov_b32_e32 v171, v150
	v_mov_b32_e32 v173, v152
	v_mul_f32_e32 v150, v29, v29
	v_pk_add_f32 v[170:171], v[170:171], v[172:173]
	v_pk_fma_f32 v[172:173], v[28:29], v[28:29], v[150:151] op_sel_hi:[1,1,0]
	v_mul_f32_e32 v150, v31, v31
	v_mul_f32_e32 v166, v14, v14
	v_mul_f32_e32 v167, v15, v15
	v_pk_fma_f32 v[174:175], v[30:31], v[30:31], v[150:151] op_sel_hi:[1,1,0]
	v_mov_b32_e32 v173, v166
	v_mov_b32_e32 v175, v167
	v_pk_add_f32 v[172:173], v[172:173], v[174:175]
	v_mov_b32_e32 v174, v119
	v_pk_add_f32 v[170:171], v[170:171], v[172:173]
	v_mov_b32_e32 v173, v128
	v_mov_b32_e32 v172, v170
	v_mov_b32_e32 v128, v171
	v_pk_add_f32 v[128:129], v[172:173], v[128:129]
	ds_bpermute_b32 v171, v130, v129
	ds_bpermute_b32 v170, v130, v128
	v_mov_b32_e32 v172, v117
	v_mov_b32_e32 v173, v101
	v_pk_mul_f32 v[172:173], v[172:173], v[172:173]
	v_mov_b32_e32 v175, v103
	s_waitcnt lgkmcnt(0)
	v_pk_add_f32 v[128:129], v[128:129], v[170:171]
	ds_bpermute_b32 v171, v131, v129
	ds_bpermute_b32 v170, v131, v128
	v_pk_mul_f32 v[174:175], v[174:175], v[174:175]
	v_mul_f32_e32 v167, v53, v53
	v_mul_f32_e32 v168, v54, v54
	v_mul_f32_e32 v169, v55, v55
	s_waitcnt lgkmcnt(0)
	v_pk_add_f32 v[128:129], v[128:129], v[170:171]
	ds_bpermute_b32 v171, v154, v129
	ds_bpermute_b32 v170, v154, v128
	s_waitcnt lgkmcnt(0)
	v_pk_add_f32 v[128:129], v[128:129], v[170:171]
	ds_bpermute_b32 v171, v156, v129
	ds_bpermute_b32 v170, v156, v128
	s_waitcnt lgkmcnt(0)
	v_pk_add_f32 v[128:129], v[128:129], v[170:171]
	ds_bpermute_b32 v171, v158, v129
	ds_bpermute_b32 v170, v158, v128
	s_waitcnt lgkmcnt(0)
	v_pk_add_f32 v[128:129], v[128:129], v[170:171]
	ds_bpermute_b32 v171, v159, v129
	ds_bpermute_b32 v170, v159, v128
	s_waitcnt lgkmcnt(0)
	v_pk_add_f32 v[170:171], v[128:129], v[170:171]
	v_mov_b64_e32 v[128:129], s[34:35]
	v_pk_fma_f32 v[170:171], v[170:171], s[16:17], v[128:129] op_sel_hi:[1,0,0]
	s_nop 0
	v_mul_f32_e32 v150, 0x4b800000, v171
	v_cmp_gt_f32_e64 s[36:37], s97, v171
	v_cmp_gt_f32_e32 vcc, s97, v170
	s_nop 0
	v_cndmask_b32_e64 v150, v171, v150, s[36:37]
	v_rsq_f32_e32 v150, v150
	v_mov_b32_e32 v171, v100
	v_mul_f32_e32 v152, 0x45800000, v150
	v_cndmask_b32_e64 v152, v150, v152, s[36:37]
	v_mul_f32_e32 v150, 0x4b800000, v170
	v_cndmask_b32_e32 v150, v170, v150, vcc
	v_mov_b32_e32 v170, v116
	v_rsq_f32_e32 v150, v150
	v_pk_fma_f32 v[170:171], v[170:171], v[170:171], v[172:173]
	v_mov_b32_e32 v172, v118
	v_mov_b32_e32 v173, v102
	v_pk_fma_f32 v[172:173], v[172:173], v[172:173], v[174:175]
	v_pk_mul_f32 v[174:175], v[84:85], v[84:85]
	v_pk_add_f32 v[170:171], v[170:171], v[172:173]
	v_pk_mul_f32 v[172:173], v[86:87], v[86:87]
	v_mul_f32_e32 v166, 0x45800000, v150
	v_pk_mov_b32 v[176:177], v[174:175], v[172:173] op_sel:[1,0]
	v_mov_b32_e32 v175, v173
	v_pk_add_f32 v[172:173], v[176:177], v[174:175]
	v_cndmask_b32_e32 v150, v150, v166, vcc
	v_mul_f32_e32 v166, v52, v52
	v_pk_add_f32 v[170:171], v[170:171], v[170:171] op_sel:[0,1] op_sel_hi:[1,0]
	v_pk_add_f32 v[172:173], v[172:173], v[172:173] op_sel:[0,1] op_sel_hi:[1,0]
	v_mov_b32_e32 v171, v166
	v_mov_b32_e32 v173, v167
	v_pk_add_f32 v[170:171], v[170:171], v[172:173]
	v_mul_f32_e32 v172, v73, v73
	v_mul_f32_e32 v174, v75, v75
	v_pk_fma_f32 v[172:173], v[72:73], v[72:73], v[172:173] op_sel_hi:[1,1,0]
	v_pk_fma_f32 v[174:175], v[74:75], v[74:75], v[174:175] op_sel_hi:[1,1,0]
	v_mov_b32_e32 v173, v168
	v_mov_b32_e32 v175, v169
	v_pk_add_f32 v[172:173], v[172:173], v[174:175]
	v_pk_mul_f32 v[174:175], v[36:37], v[36:37]
	v_pk_add_f32 v[170:171], v[170:171], v[172:173]
	v_pk_mul_f32 v[172:173], v[38:39], v[38:39]
	v_mul_f32_e32 v166, v4, v4
	v_pk_mov_b32 v[176:177], v[174:175], v[172:173] op_sel:[1,0]
	v_mov_b32_e32 v175, v173
	v_pk_add_f32 v[172:173], v[176:177], v[174:175]
	v_mul_f32_e32 v167, v5, v5
	v_pk_add_f32 v[170:171], v[170:171], v[170:171] op_sel:[0,1] op_sel_hi:[1,0]
	v_pk_add_f32 v[172:173], v[172:173], v[172:173] op_sel:[0,1] op_sel_hi:[1,0]
	v_mov_b32_e32 v171, v166
	v_mov_b32_e32 v173, v167
	v_pk_add_f32 v[170:171], v[170:171], v[172:173]
	v_mul_f32_e32 v172, v21, v21
	v_mul_f32_e32 v174, v23, v23
	v_mul_f32_e32 v168, v6, v6
	v_mul_f32_e32 v169, v7, v7
; DI unsigned pk2(float lo, float hi) { f32x2 v = {lo, hi}; bf16x2_t b = __builtin_convertvector(v, bf16x2_t); return __builtin_bit_cast(unsigned, b); }
; DI void rms_rows4_to_bf16(const float* xb, size_t xstride, const float* g, bf16_t* ob, size_t ostride, int lane) {
;     ...
;     for (int r = 0; r < 4; ++r) { float s = 0.f;
; #pragma unroll
;         for (int j = 0; j < 8; ++j) s += (v[r][j].x * v[r][j].x + v[r][j].y * v[r][j].y) + (v[r][j].z * v[r][j].z + v[r][j].w * v[r][j].w);
;         ss[r] = rsqrtf(wave_sum(s) * (1.f / D_) + EPS_); }
;     const f32x4* gr = (const f32x4*)g + lane;
; #pragma unroll
;     for (int j = 0; j < 8; ++j) { const f32x4 gg = gr[64 * j];
; #pragma unroll
;         for (int r = 0; r < 4; ++r) { u32x2 w; w.x = pk2(v[r][j].x * ss[r] * gg.x, v[r][j].y * ss[r] * gg.y); w.y = pk2(v[r][j].z * ss[r] * gg.z, v[r][j].w * ss[r] * gg.w);
	v_pk_fma_f32 v[172:173], v[20:21], v[20:21], v[172:173] op_sel_hi:[1,1,0]
	v_pk_fma_f32 v[174:175], v[22:23], v[22:23], v[174:175] op_sel_hi:[1,1,0]
	v_mov_b32_e32 v173, v168
	v_mov_b32_e32 v175, v169
	v_pk_add_f32 v[172:173], v[172:173], v[174:175]
	v_mov_b32_e32 v174, v113
	v_mov_b32_e32 v175, v97
	v_pk_add_f32 v[170:171], v[170:171], v[172:173]
	v_mov_b32_e32 v172, v112
	v_mov_b32_e32 v173, v96
	v_pk_mul_f32 v[174:175], v[174:175], v[174:175]
	v_mov_b32_e32 v176, v115
	v_mov_b32_e32 v177, v99
	v_pk_fma_f32 v[172:173], v[172:173], v[172:173], v[174:175]
	v_mov_b32_e32 v174, v114
	v_mov_b32_e32 v175, v98
	v_pk_mul_f32 v[176:177], v[176:177], v[176:177]
	v_mul_f32_e32 v166, v48, v48
	v_pk_fma_f32 v[174:175], v[174:175], v[174:175], v[176:177]
	v_pk_mul_f32 v[176:177], v[88:89], v[88:89]
	v_pk_add_f32 v[172:173], v[172:173], v[174:175]
	v_pk_mul_f32 v[174:175], v[90:91], v[90:91]
	v_mul_f32_e32 v167, v49, v49
	v_pk_mov_b32 v[178:179], v[176:177], v[174:175] op_sel:[1,0]
	v_mov_b32_e32 v177, v175
	v_pk_add_f32 v[174:175], v[178:179], v[176:177]
	v_pk_add_f32 v[172:173], v[172:173], v[172:173] op_sel:[0,1] op_sel_hi:[1,0]
	v_pk_add_f32 v[174:175], v[174:175], v[174:175] op_sel:[0,1] op_sel_hi:[1,0]
	v_mov_b32_e32 v173, v166
	v_mov_b32_e32 v175, v167
	v_pk_add_f32 v[172:173], v[172:173], v[174:175]
	v_mul_f32_e32 v174, v77, v77
	v_mul_f32_e32 v176, v79, v79
	v_mul_f32_e32 v168, v50, v50
	v_mul_f32_e32 v169, v51, v51
	v_pk_fma_f32 v[174:175], v[76:77], v[76:77], v[174:175] op_sel_hi:[1,1,0]
	v_pk_fma_f32 v[176:177], v[78:79], v[78:79], v[176:177] op_sel_hi:[1,1,0]
	v_mov_b32_e32 v175, v168
	v_mov_b32_e32 v177, v169
	v_pk_add_f32 v[174:175], v[174:175], v[176:177]
	v_pk_mul_f32 v[176:177], v[32:33], v[32:33]
	v_pk_add_f32 v[172:173], v[172:173], v[174:175]
	v_pk_mul_f32 v[174:175], v[34:35], v[34:35]
	v_mul_f32_e32 v166, v0, v0
	v_pk_mov_b32 v[178:179], v[176:177], v[174:175] op_sel:[1,0]
	v_mov_b32_e32 v177, v175
	v_pk_add_f32 v[174:175], v[178:179], v[176:177]
	v_mul_f32_e32 v167, v1, v1
	v_pk_add_f32 v[172:173], v[172:173], v[172:173] op_sel:[0,1] op_sel_hi:[1,0]
	v_pk_add_f32 v[174:175], v[174:175], v[174:175] op_sel:[0,1] op_sel_hi:[1,0]
	v_mov_b32_e32 v173, v166
	v_mov_b32_e32 v175, v167
	v_pk_add_f32 v[172:173], v[172:173], v[174:175]
	v_mul_f32_e32 v174, v17, v17
	v_mul_f32_e32 v176, v19, v19
	v_mul_f32_e32 v168, v2, v2
	v_mul_f32_e32 v169, v3, v3
	v_pk_fma_f32 v[174:175], v[16:17], v[16:17], v[174:175] op_sel_hi:[1,1,0]
	v_pk_fma_f32 v[176:177], v[18:19], v[18:19], v[176:177] op_sel_hi:[1,1,0]
	v_mov_b32_e32 v175, v168
	v_mov_b32_e32 v177, v169
	v_pk_add_f32 v[174:175], v[174:175], v[176:177]
	v_pk_mul_f32 v[120:121], v[120:121], v[150:151] op_sel_hi:[1,0]
	v_pk_add_f32 v[172:173], v[172:173], v[174:175]
	v_mov_b32_e32 v175, v170
	v_mov_b32_e32 v174, v172
	v_mov_b32_e32 v170, v173
	v_pk_add_f32 v[170:171], v[174:175], v[170:171]
	ds_bpermute_b32 v173, v130, v171
	ds_bpermute_b32 v172, v130, v170
	v_pk_mul_f32 v[122:123], v[122:123], v[150:151] op_sel_hi:[1,0]
	v_pk_mul_f32 v[124:125], v[124:125], v[152:153] op_sel_hi:[1,0]
	v_pk_mul_f32 v[126:127], v[126:127], v[152:153] op_sel_hi:[1,0]
	v_pk_mul_f32 v[104:105], v[104:105], v[152:153] op_sel_hi:[1,0]
	s_waitcnt lgkmcnt(0)
	v_pk_add_f32 v[170:171], v[170:171], v[172:173]
	ds_bpermute_b32 v173, v131, v171
	ds_bpermute_b32 v172, v131, v170
	v_pk_mul_f32 v[106:107], v[106:107], v[152:153] op_sel_hi:[1,0]
	v_pk_mul_f32 v[80:81], v[80:81], v[152:153] op_sel_hi:[1,0]
	v_pk_mul_f32 v[82:83], v[82:83], v[152:153] op_sel_hi:[1,0]
	v_pk_mul_f32 v[64:65], v[64:65], v[152:153] op_sel_hi:[1,0]
	s_waitcnt lgkmcnt(0)
	v_pk_add_f32 v[130:131], v[170:171], v[172:173]
	ds_bpermute_b32 v171, v154, v131
	ds_bpermute_b32 v170, v154, v130
	v_pk_mul_f32 v[66:67], v[66:67], v[152:153] op_sel_hi:[1,0]
	v_pk_mul_f32 v[56:57], v[56:57], v[152:153] op_sel_hi:[1,0]
	v_pk_mul_f32 v[58:59], v[58:59], v[152:153] op_sel_hi:[1,0]
	v_pk_mul_f32 v[40:41], v[40:41], v[152:153] op_sel_hi:[1,0]
	s_waitcnt lgkmcnt(0)
	v_pk_add_f32 v[130:131], v[130:131], v[170:171]
	ds_bpermute_b32 v171, v156, v131
	ds_bpermute_b32 v170, v156, v130
	v_pk_mul_f32 v[42:43], v[42:43], v[152:153] op_sel_hi:[1,0]
	v_pk_mul_f32 v[24:25], v[24:25], v[152:153] op_sel_hi:[1,0]
	v_pk_mul_f32 v[26:27], v[26:27], v[152:153] op_sel_hi:[1,0]
	v_pk_mul_f32 v[8:9], v[8:9], v[152:153] op_sel_hi:[1,0]
	s_waitcnt lgkmcnt(0)
	v_pk_add_f32 v[130:131], v[130:131], v[170:171]
	ds_bpermute_b32 v171, v158, v131
	ds_bpermute_b32 v170, v158, v130
	v_pk_mul_f32 v[10:11], v[10:11], v[152:153] op_sel_hi:[1,0]
	s_waitcnt lgkmcnt(0)
	v_pk_add_f32 v[130:131], v[130:131], v[170:171]
	ds_bpermute_b32 v171, v159, v131
	ds_bpermute_b32 v170, v159, v130
	v_lshl_add_u64 v[158:159], v[144:145], 0, s[2:3]
	v_readlane_b32 s2, v254, 22
	v_readlane_b32 s3, v254, 23
	s_waitcnt lgkmcnt(0)
; DI unsigned pk2(float lo, float hi) { f32x2 v = {lo, hi}; bf16x2_t b = __builtin_convertvector(v, bf16x2_t); return __builtin_bit_cast(unsigned, b); }
; DI void rms_rows4_to_bf16(const float* xb, size_t xstride, const float* g, bf16_t* ob, size_t ostride, int lane) {
;     ...
;         ss[r] = rsqrtf(wave_sum(s) * (1.f / D_) + EPS_); }
;     const f32x4* gr = (const f32x4*)g + lane;
; #pragma unroll
;     for (int j = 0; j < 8; ++j) { const f32x4 gg = gr[64 * j];
; #pragma unroll
;         for (int r = 0; r < 4; ++r) { u32x2 w; w.x = pk2(v[r][j].x * ss[r] * gg.x, v[r][j].y * ss[r] * gg.y); w.y = pk2(v[r][j].z * ss[r] * gg.z, v[r][j].w * ss[r] * gg.w);
;             ((u32x2*)(ob + r * ostride))[lane + 64 * j] = w; } }
	v_pk_add_f32 v[130:131], v[130:131], v[170:171]
	s_nop 0
	v_pk_fma_f32 v[128:129], v[130:131], s[16:17], v[128:129] op_sel_hi:[1,0,0]
	s_nop 0
	v_mul_f32_e32 v130, 0x4b800000, v129
	v_cmp_gt_f32_e64 s[36:37], s97, v129
	v_cmp_gt_f32_e32 vcc, s97, v128
	s_nop 0
	v_cndmask_b32_e64 v129, v129, v130, s[36:37]
	v_rsq_f32_e32 v129, v129
	s_nop 0
	v_mul_f32_e32 v130, 0x45800000, v129
	v_cndmask_b32_e64 v156, v129, v130, s[36:37]
	v_mul_f32_e32 v129, 0x4b800000, v128
	v_cndmask_b32_e32 v128, v128, v129, vcc
	v_rsq_f32_e32 v128, v128
	v_pk_mul_f32 v[116:117], v[116:117], v[156:157] op_sel_hi:[1,0]
	v_pk_mul_f32 v[118:119], v[118:119], v[156:157] op_sel_hi:[1,0]
	v_pk_mul_f32 v[100:101], v[100:101], v[156:157] op_sel_hi:[1,0]
	v_mul_f32_e32 v129, 0x45800000, v128
	v_cndmask_b32_e32 v154, v128, v129, vcc
	global_load_dwordx4 v[128:131], v[134:135], off
	v_pk_mul_f32 v[112:113], v[112:113], v[154:155] op_sel_hi:[1,0]
	v_pk_mul_f32 v[114:115], v[114:115], v[154:155] op_sel_hi:[1,0]
	v_pk_mul_f32 v[102:103], v[102:103], v[156:157] op_sel_hi:[1,0]
	v_pk_mul_f32 v[96:97], v[96:97], v[154:155] op_sel_hi:[1,0]
	v_pk_mul_f32 v[98:99], v[98:99], v[154:155] op_sel_hi:[1,0]
	v_pk_mul_f32 v[52:53], v[52:53], v[156:157] op_sel_hi:[1,0]
	v_pk_mul_f32 v[54:55], v[54:55], v[156:157] op_sel_hi:[1,0]
	v_pk_mul_f32 v[48:49], v[48:49], v[154:155] op_sel_hi:[1,0]
	v_pk_mul_f32 v[50:51], v[50:51], v[154:155] op_sel_hi:[1,0]
	v_pk_mul_f32 v[36:37], v[36:37], v[156:157] op_sel_hi:[1,0]
	v_pk_mul_f32 v[38:39], v[38:39], v[156:157] op_sel_hi:[1,0]
	v_pk_mul_f32 v[32:33], v[32:33], v[154:155] op_sel_hi:[1,0]
	v_pk_mul_f32 v[34:35], v[34:35], v[154:155] op_sel_hi:[1,0]
	v_pk_mul_f32 v[20:21], v[20:21], v[156:157] op_sel_hi:[1,0]
	v_pk_mul_f32 v[22:23], v[22:23], v[156:157] op_sel_hi:[1,0]
	v_pk_mul_f32 v[16:17], v[16:17], v[154:155] op_sel_hi:[1,0]
	v_pk_mul_f32 v[18:19], v[18:19], v[154:155] op_sel_hi:[1,0]
	v_pk_mul_f32 v[4:5], v[4:5], v[156:157] op_sel_hi:[1,0]
	v_pk_mul_f32 v[6:7], v[6:7], v[156:157] op_sel_hi:[1,0]
	v_pk_mul_f32 v[0:1], v[0:1], v[154:155] op_sel_hi:[1,0]
	v_pk_mul_f32 v[2:3], v[2:3], v[154:155] op_sel_hi:[1,0]
	s_waitcnt vmcnt(0)
	v_pk_mul_f32 v[120:121], v[120:121], v[128:129]
	v_pk_mul_f32 v[122:123], v[122:123], v[130:131]
	v_pk_mul_f32 v[124:125], v[124:125], v[128:129]
	v_pk_mul_f32 v[126:127], v[126:127], v[130:131]
	v_cvt_pk_bf16_f32 v120, v120, v121
	v_cvt_pk_bf16_f32 v121, v122, v123
	v_lshl_add_u64 v[122:123], s[20:21], 1, v[158:159]
	v_pk_mul_f32 v[116:117], v[128:129], v[116:117]
	v_pk_mul_f32 v[118:119], v[130:131], v[118:119]
	v_cvt_pk_bf16_f32 v124, v124, v125
	v_cvt_pk_bf16_f32 v125, v126, v127
	v_cvt_pk_bf16_f32 v116, v116, v117
	v_cvt_pk_bf16_f32 v117, v118, v119
	v_lshl_add_u64 v[118:119], v[122:123], 0, s[84:85]
	v_pk_mul_f32 v[112:113], v[128:129], v[112:113]
	v_pk_mul_f32 v[114:115], v[130:131], v[114:115]
	global_store_dwordx2 v[158:159], v[124:125], off
	global_store_dwordx2 v[122:123], v[120:121], off
	global_store_dwordx2 v[118:119], v[116:117], off
	v_cvt_pk_bf16_f32 v112, v112, v113
	v_cvt_pk_bf16_f32 v113, v114, v115
	v_lshl_add_u64 v[116:117], v[118:119], 0, s[84:85]
	global_store_dwordx2 v[116:117], v[112:113], off
	global_load_dwordx4 v[112:115], v[134:135], off offset:1024
	s_waitcnt vmcnt(0)
	v_pk_mul_f32 v[104:105], v[104:105], v[112:113]
	v_pk_mul_f32 v[106:107], v[106:107], v[114:115]
	v_cvt_pk_bf16_f32 v104, v104, v105
	v_cvt_pk_bf16_f32 v105, v106, v107
	global_store_dwordx2 v[158:159], v[104:105], off offset:512
	v_pk_mul_f32 v[104:105], v[108:109], v[150:151] op_sel_hi:[1,0]
	v_pk_mul_f32 v[106:107], v[110:111], v[150:151] op_sel_hi:[1,0]
	v_pk_mul_f32 v[104:105], v[104:105], v[112:113]
	v_pk_mul_f32 v[106:107], v[106:107], v[114:115]
	v_cvt_pk_bf16_f32 v104, v104, v105
	v_cvt_pk_bf16_f32 v105, v106, v107
	v_lshl_add_u64 v[106:107], v[116:117], 0, s[2:3]
	v_pk_mul_f32 v[100:101], v[100:101], v[112:113]
	v_pk_mul_f32 v[102:103], v[102:103], v[114:115]
	v_cvt_pk_bf16_f32 v100, v100, v101
	v_cvt_pk_bf16_f32 v101, v102, v103
	v_lshl_add_u64 v[102:103], v[106:107], 0, s[84:85]
	v_pk_mul_f32 v[96:97], v[112:113], v[96:97]
	v_pk_mul_f32 v[98:99], v[114:115], v[98:99]
	global_store_dwordx2 v[106:107], v[104:105], off offset:512
	global_store_dwordx2 v[102:103], v[100:101], off offset:512
	v_cvt_pk_bf16_f32 v96, v96, v97
	v_cvt_pk_bf16_f32 v97, v98, v99
	v_lshl_add_u64 v[100:101], v[102:103], 0, s[84:85]
	global_store_dwordx2 v[100:101], v[96:97], off offset:512
	global_load_dwordx4 v[96:99], v[134:135], off offset:2048
	s_waitcnt vmcnt(0)
	v_pk_mul_f32 v[80:81], v[80:81], v[96:97]
	v_pk_mul_f32 v[82:83], v[82:83], v[98:99]
	v_cvt_pk_bf16_f32 v80, v80, v81
	v_cvt_pk_bf16_f32 v81, v82, v83
	global_store_dwordx2 v[158:159], v[80:81], off offset:1024
	v_pk_mul_f32 v[80:81], v[92:93], v[150:151] op_sel_hi:[1,0]
	v_pk_mul_f32 v[82:83], v[94:95], v[150:151] op_sel_hi:[1,0]
	v_pk_mul_f32 v[80:81], v[80:81], v[96:97]
	v_pk_mul_f32 v[82:83], v[82:83], v[98:99]
	v_cvt_pk_bf16_f32 v80, v80, v81
	v_cvt_pk_bf16_f32 v81, v82, v83
	v_lshl_add_u64 v[82:83], v[100:101], 0, s[2:3]
	global_store_dwordx2 v[82:83], v[80:81], off offset:1024
	v_pk_mul_f32 v[80:81], v[84:85], v[156:157] op_sel_hi:[1,0]
	v_pk_mul_f32 v[84:85], v[86:87], v[156:157] op_sel_hi:[1,0]
	v_pk_mul_f32 v[80:81], v[80:81], v[96:97]
	v_pk_mul_f32 v[84:85], v[84:85], v[98:99]
	v_cvt_pk_bf16_f32 v80, v80, v81
	v_cvt_pk_bf16_f32 v81, v84, v85
	v_lshl_add_u64 v[82:83], v[82:83], 0, s[84:85]
	global_store_dwordx2 v[82:83], v[80:81], off offset:1024
	v_pk_mul_f32 v[80:81], v[88:89], v[154:155] op_sel_hi:[1,0]
	v_pk_mul_f32 v[84:85], v[90:91], v[154:155] op_sel_hi:[1,0]
	v_pk_mul_f32 v[80:81], v[80:81], v[96:97]
	v_pk_mul_f32 v[84:85], v[84:85], v[98:99]
	v_cvt_pk_bf16_f32 v80, v80, v81
	v_cvt_pk_bf16_f32 v81, v84, v85
	v_lshl_add_u64 v[84:85], v[82:83], 0, s[84:85]
	global_store_dwordx2 v[84:85], v[80:81], off offset:1024
	global_load_dwordx4 v[80:83], v[134:135], off offset:3072
	s_waitcnt vmcnt(0)
; DI unsigned pk2(float lo, float hi) { f32x2 v = {lo, hi}; bf16x2_t b = __builtin_convertvector(v, bf16x2_t); return __builtin_bit_cast(unsigned, b); }
; DI void rms_rows4_to_bf16(const float* xb, size_t xstride, const float* g, bf16_t* ob, size_t ostride, int lane) {
;     ...
;     const f32x4* gr = (const f32x4*)g + lane;
; #pragma unroll
;     for (int j = 0; j < 8; ++j) { const f32x4 gg = gr[64 * j];
; #pragma unroll
;         for (int r = 0; r < 4; ++r) { u32x2 w; w.x = pk2(v[r][j].x * ss[r] * gg.x, v[r][j].y * ss[r] * gg.y); w.y = pk2(v[r][j].z * ss[r] * gg.z, v[r][j].w * ss[r] * gg.w);
;             ((u32x2*)(ob + r * ostride))[lane + 64 * j] = w; } }
	v_pk_mul_f32 v[64:65], v[64:65], v[80:81]
	v_pk_mul_f32 v[66:67], v[66:67], v[82:83]
	v_cvt_pk_bf16_f32 v64, v64, v65
	v_cvt_pk_bf16_f32 v65, v66, v67
	global_store_dwordx2 v[158:159], v[64:65], off offset:1536
	v_pk_mul_f32 v[64:65], v[68:69], v[150:151] op_sel_hi:[1,0]
	v_pk_mul_f32 v[66:67], v[70:71], v[150:151] op_sel_hi:[1,0]
	v_pk_mul_f32 v[64:65], v[64:65], v[80:81]
	v_pk_mul_f32 v[66:67], v[66:67], v[82:83]
	v_cvt_pk_bf16_f32 v64, v64, v65
	v_cvt_pk_bf16_f32 v65, v66, v67
	v_lshl_add_u64 v[66:67], v[84:85], 0, s[2:3]
	global_store_dwordx2 v[66:67], v[64:65], off offset:1536
	v_pk_mul_f32 v[64:65], v[72:73], v[156:157] op_sel_hi:[1,0]
	v_pk_mul_f32 v[68:69], v[74:75], v[156:157] op_sel_hi:[1,0]
	v_pk_mul_f32 v[64:65], v[64:65], v[80:81]
	v_pk_mul_f32 v[68:69], v[68:69], v[82:83]
	v_cvt_pk_bf16_f32 v64, v64, v65
	v_cvt_pk_bf16_f32 v65, v68, v69
	v_lshl_add_u64 v[66:67], v[66:67], 0, s[84:85]
	global_store_dwordx2 v[66:67], v[64:65], off offset:1536
	v_pk_mul_f32 v[64:65], v[76:77], v[154:155] op_sel_hi:[1,0]
	v_pk_mul_f32 v[68:69], v[78:79], v[154:155] op_sel_hi:[1,0]
	v_pk_mul_f32 v[64:65], v[64:65], v[80:81]
	v_pk_mul_f32 v[68:69], v[68:69], v[82:83]
	v_cvt_pk_bf16_f32 v64, v64, v65
	v_cvt_pk_bf16_f32 v65, v68, v69
	v_lshl_add_u64 v[68:69], v[66:67], 0, s[84:85]
	global_store_dwordx2 v[68:69], v[64:65], off offset:1536
	global_load_dwordx4 v[64:67], v[136:137], off
	s_waitcnt vmcnt(0)
	v_pk_mul_f32 v[56:57], v[56:57], v[64:65]
	v_pk_mul_f32 v[58:59], v[58:59], v[66:67]
	v_cvt_pk_bf16_f32 v56, v56, v57
	v_cvt_pk_bf16_f32 v57, v58, v59
	global_store_dwordx2 v[158:159], v[56:57], off offset:2048
	v_pk_mul_f32 v[56:57], v[60:61], v[150:151] op_sel_hi:[1,0]
	v_pk_mul_f32 v[58:59], v[62:63], v[150:151] op_sel_hi:[1,0]
	v_pk_mul_f32 v[56:57], v[56:57], v[64:65]
	v_pk_mul_f32 v[58:59], v[58:59], v[66:67]
	v_cvt_pk_bf16_f32 v56, v56, v57
	v_cvt_pk_bf16_f32 v57, v58, v59
	v_lshl_add_u64 v[58:59], v[68:69], 0, s[2:3]
	v_pk_mul_f32 v[52:53], v[52:53], v[64:65]
	v_pk_mul_f32 v[54:55], v[54:55], v[66:67]
	v_cvt_pk_bf16_f32 v52, v52, v53
	v_cvt_pk_bf16_f32 v53, v54, v55
	v_lshl_add_u64 v[54:55], v[58:59], 0, s[84:85]
	v_pk_mul_f32 v[48:49], v[48:49], v[64:65]
	v_pk_mul_f32 v[50:51], v[50:51], v[66:67]
	global_store_dwordx2 v[58:59], v[56:57], off offset:2048
	global_store_dwordx2 v[54:55], v[52:53], off offset:2048
	v_cvt_pk_bf16_f32 v48, v48, v49
	v_cvt_pk_bf16_f32 v49, v50, v51
	v_lshl_add_u64 v[52:53], v[54:55], 0, s[84:85]
	global_store_dwordx2 v[52:53], v[48:49], off offset:2048
	global_load_dwordx4 v[48:51], v[138:139], off
	s_waitcnt vmcnt(0)
	v_pk_mul_f32 v[40:41], v[40:41], v[48:49]
	v_pk_mul_f32 v[42:43], v[42:43], v[50:51]
	v_cvt_pk_bf16_f32 v40, v40, v41
	v_cvt_pk_bf16_f32 v41, v42, v43
	global_store_dwordx2 v[158:159], v[40:41], off offset:2560
	v_pk_mul_f32 v[40:41], v[44:45], v[150:151] op_sel_hi:[1,0]
	v_pk_mul_f32 v[42:43], v[46:47], v[150:151] op_sel_hi:[1,0]
	v_pk_mul_f32 v[40:41], v[40:41], v[48:49]
	v_pk_mul_f32 v[42:43], v[42:43], v[50:51]
	v_cvt_pk_bf16_f32 v40, v40, v41
	v_cvt_pk_bf16_f32 v41, v42, v43
	v_lshl_add_u64 v[42:43], v[52:53], 0, s[2:3]
	v_pk_mul_f32 v[36:37], v[36:37], v[48:49]
	v_pk_mul_f32 v[38:39], v[38:39], v[50:51]
	v_cvt_pk_bf16_f32 v36, v36, v37
	v_cvt_pk_bf16_f32 v37, v38, v39
	v_lshl_add_u64 v[38:39], v[42:43], 0, s[84:85]
	v_pk_mul_f32 v[32:33], v[32:33], v[48:49]
	v_pk_mul_f32 v[34:35], v[34:35], v[50:51]
	global_store_dwordx2 v[42:43], v[40:41], off offset:2560
	global_store_dwordx2 v[38:39], v[36:37], off offset:2560
	v_cvt_pk_bf16_f32 v32, v32, v33
	v_cvt_pk_bf16_f32 v33, v34, v35
	v_lshl_add_u64 v[36:37], v[38:39], 0, s[84:85]
	global_store_dwordx2 v[36:37], v[32:33], off offset:2560
	global_load_dwordx4 v[32:35], v[140:141], off
	s_waitcnt vmcnt(0)
	v_pk_mul_f32 v[24:25], v[24:25], v[32:33]
	v_pk_mul_f32 v[26:27], v[26:27], v[34:35]
	v_cvt_pk_bf16_f32 v24, v24, v25
	v_cvt_pk_bf16_f32 v25, v26, v27
	global_store_dwordx2 v[158:159], v[24:25], off offset:3072
	v_pk_mul_f32 v[24:25], v[28:29], v[150:151] op_sel_hi:[1,0]
	v_pk_mul_f32 v[26:27], v[30:31], v[150:151] op_sel_hi:[1,0]
	v_pk_mul_f32 v[24:25], v[24:25], v[32:33]
	v_pk_mul_f32 v[26:27], v[26:27], v[34:35]
	v_cvt_pk_bf16_f32 v24, v24, v25
	v_cvt_pk_bf16_f32 v25, v26, v27
	v_lshl_add_u64 v[26:27], v[36:37], 0, s[2:3]
	v_pk_mul_f32 v[20:21], v[20:21], v[32:33]
	v_pk_mul_f32 v[22:23], v[22:23], v[34:35]
	v_cvt_pk_bf16_f32 v20, v20, v21
	v_cvt_pk_bf16_f32 v21, v22, v23
	v_lshl_add_u64 v[22:23], v[26:27], 0, s[84:85]
	v_pk_mul_f32 v[16:17], v[16:17], v[32:33]
	v_pk_mul_f32 v[18:19], v[18:19], v[34:35]
	global_store_dwordx2 v[26:27], v[24:25], off offset:3072
	global_store_dwordx2 v[22:23], v[20:21], off offset:3072
	v_cvt_pk_bf16_f32 v16, v16, v17
	v_cvt_pk_bf16_f32 v17, v18, v19
	v_lshl_add_u64 v[20:21], v[22:23], 0, s[84:85]
	global_store_dwordx2 v[20:21], v[16:17], off offset:3072
	global_load_dwordx4 v[16:19], v[142:143], off
	s_waitcnt vmcnt(0)
	v_pk_mul_f32 v[8:9], v[8:9], v[16:17]
	v_pk_mul_f32 v[10:11], v[10:11], v[18:19]
	v_cvt_pk_bf16_f32 v8, v8, v9
	v_cvt_pk_bf16_f32 v9, v10, v11
	global_store_dwordx2 v[158:159], v[8:9], off offset:3584
	v_pk_mul_f32 v[8:9], v[12:13], v[150:151] op_sel_hi:[1,0]
	v_pk_mul_f32 v[10:11], v[14:15], v[150:151] op_sel_hi:[1,0]
	v_pk_mul_f32 v[8:9], v[8:9], v[16:17]
	v_pk_mul_f32 v[10:11], v[10:11], v[18:19]
	v_cvt_pk_bf16_f32 v8, v8, v9
	v_cvt_pk_bf16_f32 v9, v10, v11
	v_lshl_add_u64 v[10:11], v[20:21], 0, s[2:3]
	v_pk_mul_f32 v[4:5], v[4:5], v[16:17]
	v_pk_mul_f32 v[6:7], v[6:7], v[18:19]
	v_cvt_pk_bf16_f32 v4, v4, v5
	v_cvt_pk_bf16_f32 v5, v6, v7
	v_lshl_add_u64 v[6:7], v[10:11], 0, s[84:85]
	v_pk_mul_f32 v[0:1], v[0:1], v[16:17]
	v_pk_mul_f32 v[2:3], v[2:3], v[18:19]
	v_cvt_pk_bf16_f32 v0, v0, v1
	v_cvt_pk_bf16_f32 v1, v2, v3
	v_lshl_add_u64 v[2:3], v[6:7], 0, s[84:85]
	global_store_dwordx2 v[10:11], v[8:9], off offset:3584
	global_store_dwordx2 v[6:7], v[4:5], off offset:3584
	global_store_dwordx2 v[2:3], v[0:1], off offset:3584
	s_branch .LBB0_70

; DI unsigned pk2(float lo, float hi) { f32x2 v = {lo, hi}; bf16x2_t b = __builtin_convertvector(v, bf16x2_t); return __builtin_bit_cast(unsigned, b); }
; DI void rms_row_to_bf16(const float* xrow, const float* g, bf16_t* orow, int lane) {
;     const f32x4* xr = (const f32x4*)xrow + lane; const f32x4* gr = (const f32x4*)g + lane;
;     f32x4 v[8]; float s = 0.f;
; #pragma unroll
;     for (int j = 0; j < 8; ++j) { v[j] = xr[64 * j]; s += (v[j].x * v[j].x + v[j].y * v[j].y) + (v[j].z * v[j].z + v[j].w * v[j].w); }
;     const float rs = rsqrtf(wave_sum(s) * (1.f / D_) + EPS_);
;     u32x2* o8 = (u32x2*)orow + lane;
; #pragma unroll
;     for (int j = 0; j < 8; ++j) { const f32x4 gg = gr[64 * j]; u32x2 w; w.x = pk2(v[j].x * rs * gg.x, v[j].y * rs * gg.y); w.y = pk2(v[j].z * rs * gg.z, v[j].w * rs * gg.w); o8[64 * j] = w; }
; }
; __global__ void __launch_bounds__(512, 2) fwd_megakernel(Args args) {
;     ...
;             for (int m = T_ + gw; m < A_ROWS; m += NGW) rms_row_to_bf16(mem + (size_t)(m - T_) * D_, mem_norm_g, A + (size_t)m * D_, lane);
.LBB0_79:
	v_add_co_u32_e32 v0, vcc, 0xfffff000, v48
	s_add_i32 s0, s0, s96
	s_nop 0
	v_addc_co_u32_e32 v1, vcc, -1, v49, vcc
	global_load_dwordx4 v[12:15], v[0:1], off offset:-3072
	global_load_dwordx4 v[8:11], v[0:1], off offset:-2048
	s_cmpk_gt_i32 s0, 0x43ff
	s_waitcnt vmcnt(0)
	v_mov_b32_e32 v4, v13
	v_mov_b32_e32 v5, v9
	v_mov_b32_e32 v2, v12
	v_mov_b32_e32 v3, v8
	v_pk_mul_f32 v[4:5], v[4:5], v[4:5]
	v_mov_b32_e32 v6, v15
	v_mov_b32_e32 v7, v11
	v_pk_fma_f32 v[2:3], v[2:3], v[2:3], v[4:5]
	v_mov_b32_e32 v4, v14
	v_mov_b32_e32 v5, v10
	v_pk_mul_f32 v[6:7], v[6:7], v[6:7]
	s_nop 0
	v_pk_fma_f32 v[4:5], v[4:5], v[4:5], v[6:7]
	s_nop 0
	v_pk_add_f32 v[20:21], v[2:3], v[4:5]
	global_load_dwordx4 v[4:7], v[0:1], off offset:-1024
	v_pk_add_f32 v[20:21], v[20:21], v[20:21] op_sel:[0,1] op_sel_hi:[1,0]
	s_waitcnt vmcnt(0)
	v_pk_mul_f32 v[0:1], v[6:7], v[6:7]
	v_pk_mul_f32 v[2:3], v[4:5], v[4:5]
	s_nop 0
	v_pk_mov_b32 v[16:17], v[2:3], v[0:1] op_sel:[1,0]
	v_mov_b32_e32 v3, v1
	v_pk_add_f32 v[22:23], v[16:17], v[2:3]
	global_load_dwordx4 v[0:3], v[48:49], off offset:-4096
	global_load_dwordx4 v[16:19], v[48:49], off offset:-3072
	v_pk_add_f32 v[22:23], v[22:23], v[22:23] op_sel:[0,1] op_sel_hi:[1,0]
	s_waitcnt vmcnt(0)
	v_mul_f32_e32 v24, v16, v16
	v_mul_f32_e32 v25, v17, v17
	v_mov_b32_e32 v21, v24
	v_mov_b32_e32 v23, v25
	v_pk_add_f32 v[20:21], v[20:21], v[22:23]
	v_mul_f32_e32 v22, v1, v1
	v_mul_f32_e32 v24, v3, v3
	v_mul_f32_e32 v26, v18, v18
	v_mul_f32_e32 v27, v19, v19
	v_pk_fma_f32 v[22:23], v[0:1], v[0:1], v[22:23] op_sel_hi:[1,1,0]
	v_pk_fma_f32 v[24:25], v[2:3], v[2:3], v[24:25] op_sel_hi:[1,1,0]
	v_mov_b32_e32 v23, v26
	v_mov_b32_e32 v25, v27
	v_pk_add_f32 v[22:23], v[22:23], v[24:25]
	s_nop 0
	v_pk_add_f32 v[32:33], v[20:21], v[22:23]
	global_load_dwordx4 v[20:23], v[48:49], off offset:-2048
	v_pk_add_f32 v[32:33], v[32:33], v[32:33] op_sel:[0,1] op_sel_hi:[1,0]
	s_waitcnt vmcnt(0)
	v_pk_mul_f32 v[24:25], v[22:23], v[22:23]
	v_pk_mul_f32 v[26:27], v[20:21], v[20:21]
	s_nop 0
	v_pk_mov_b32 v[28:29], v[26:27], v[24:25] op_sel:[1,0]
	v_mov_b32_e32 v27, v25
	v_pk_add_f32 v[34:35], v[28:29], v[26:27]
	global_load_dwordx4 v[24:27], v[48:49], off offset:-1024
	global_load_dwordx4 v[28:31], v[48:49], off
	v_pk_add_f32 v[34:35], v[34:35], v[34:35] op_sel:[0,1] op_sel_hi:[1,0]
	v_lshl_add_u64 v[48:49], v[48:49], 0, s[80:81]
	s_waitcnt vmcnt(0)
	v_mul_f32_e32 v50, v28, v28
	v_mul_f32_e32 v57, v29, v29
	v_mov_b32_e32 v33, v50
	v_mov_b32_e32 v35, v57
	v_pk_add_f32 v[32:33], v[32:33], v[34:35]
	v_mul_f32_e32 v34, v25, v25
	v_mul_f32_e32 v58, v30, v30
	v_pk_fma_f32 v[34:35], v[24:25], v[24:25], v[34:35] op_sel_hi:[1,1,0]
	v_mul_f32_e32 v50, v27, v27
	v_mul_f32_e32 v60, v31, v31
	v_mov_b32_e32 v35, v58
	v_pk_fma_f32 v[58:59], v[26:27], v[26:27], v[50:51] op_sel_hi:[1,1,0]
	s_nop 0
	v_mov_b32_e32 v59, v60
	v_pk_add_f32 v[34:35], v[34:35], v[58:59]
	s_nop 0
	v_pk_add_f32 v[32:33], v[32:33], v[34:35]
	s_nop 0
	v_add_f32_e32 v32, v32, v33
	ds_bpermute_b32 v33, v51, v32
	s_waitcnt lgkmcnt(0)
	v_add_f32_e32 v32, v32, v33
	ds_bpermute_b32 v33, v52, v32
	s_waitcnt lgkmcnt(0)
	v_add_f32_e32 v32, v32, v33
	ds_bpermute_b32 v33, v53, v32
	s_waitcnt lgkmcnt(0)
	v_add_f32_e32 v32, v32, v33
	ds_bpermute_b32 v33, v54, v32
	s_waitcnt lgkmcnt(0)
	v_add_f32_e32 v32, v32, v33
	ds_bpermute_b32 v33, v55, v32
	s_waitcnt lgkmcnt(0)
	v_add_f32_e32 v32, v32, v33
	ds_bpermute_b32 v33, v56, v32
	s_waitcnt lgkmcnt(0)
	v_add_f32_e32 v32, v32, v33
	v_fmamk_f32 v32, v32, 0x3a000000, v187
	v_cmp_gt_f32_e32 vcc, s97, v32
	v_mul_f32_e32 v33, 0x4b800000, v32
	s_nop 0
	v_cndmask_b32_e32 v32, v32, v33, vcc
	v_rsq_f32_e32 v32, v32
	s_nop 0
	v_mul_f32_e32 v33, 0x45800000, v32
	v_cndmask_b32_e32 v50, v32, v33, vcc
	global_load_dwordx4 v[32:35], v[36:37], off
	v_pk_mul_f32 v[12:13], v[12:13], v[50:51] op_sel_hi:[1,0]
	v_pk_mul_f32 v[14:15], v[14:15], v[50:51] op_sel_hi:[1,0]
	v_pk_mul_f32 v[8:9], v[8:9], v[50:51] op_sel_hi:[1,0]
	v_pk_mul_f32 v[10:11], v[10:11], v[50:51] op_sel_hi:[1,0]
	v_pk_mul_f32 v[4:5], v[4:5], v[50:51] op_sel_hi:[1,0]
	v_pk_mul_f32 v[6:7], v[6:7], v[50:51] op_sel_hi:[1,0]
	v_pk_mul_f32 v[0:1], v[0:1], v[50:51] op_sel_hi:[1,0]
	v_pk_mul_f32 v[2:3], v[2:3], v[50:51] op_sel_hi:[1,0]
	s_waitcnt vmcnt(0)
	v_pk_mul_f32 v[12:13], v[32:33], v[12:13]
	v_pk_mul_f32 v[14:15], v[34:35], v[14:15]
	v_cvt_pk_bf16_f32 v12, v12, v13
	v_cvt_pk_bf16_f32 v13, v14, v15
	global_store_dwordx2 v[46:47], v[12:13], off
	global_load_dwordx4 v[12:15], v[36:37], off offset:1024
	s_waitcnt vmcnt(0)
	v_pk_mul_f32 v[8:9], v[12:13], v[8:9]
	v_pk_mul_f32 v[10:11], v[14:15], v[10:11]
	v_cvt_pk_bf16_f32 v8, v8, v9
	v_cvt_pk_bf16_f32 v9, v10, v11
	global_store_dwordx2 v[46:47], v[8:9], off offset:512
	global_load_dwordx4 v[8:11], v[36:37], off offset:2048
	s_waitcnt vmcnt(0)
	v_pk_mul_f32 v[4:5], v[8:9], v[4:5]
	v_pk_mul_f32 v[6:7], v[10:11], v[6:7]
	v_cvt_pk_bf16_f32 v4, v4, v5
	v_cvt_pk_bf16_f32 v5, v6, v7
	global_store_dwordx2 v[46:47], v[4:5], off offset:1024
	global_load_dwordx4 v[4:7], v[36:37], off offset:3072
	s_waitcnt vmcnt(0)
	v_pk_mul_f32 v[0:1], v[4:5], v[0:1]
	v_pk_mul_f32 v[2:3], v[6:7], v[2:3]
	v_cvt_pk_bf16_f32 v0, v0, v1
	v_cvt_pk_bf16_f32 v1, v2, v3
	global_store_dwordx2 v[46:47], v[0:1], off offset:1536
	global_load_dwordx4 v[0:3], v[38:39], off
	v_pk_mul_f32 v[4:5], v[16:17], v[50:51] op_sel_hi:[1,0]
	s_waitcnt vmcnt(0)
	v_pk_mul_f32 v[0:1], v[0:1], v[4:5]
	v_pk_mul_f32 v[4:5], v[18:19], v[50:51] op_sel_hi:[1,0]
	v_cvt_pk_bf16_f32 v0, v0, v1
	v_pk_mul_f32 v[2:3], v[2:3], v[4:5]
	v_pk_mul_f32 v[4:5], v[20:21], v[50:51] op_sel_hi:[1,0]
	v_cvt_pk_bf16_f32 v1, v2, v3
	global_store_dwordx2 v[46:47], v[0:1], off offset:2048
	global_load_dwordx4 v[0:3], v[40:41], off
	s_waitcnt vmcnt(0)
	v_pk_mul_f32 v[0:1], v[4:5], v[0:1]
	v_pk_mul_f32 v[4:5], v[22:23], v[50:51] op_sel_hi:[1,0]
	v_cvt_pk_bf16_f32 v0, v0, v1
	v_pk_mul_f32 v[2:3], v[4:5], v[2:3]
	v_pk_mul_f32 v[4:5], v[24:25], v[50:51] op_sel_hi:[1,0]
	v_cvt_pk_bf16_f32 v1, v2, v3
	global_store_dwordx2 v[46:47], v[0:1], off offset:2560
	global_load_dwordx4 v[0:3], v[42:43], off
	s_waitcnt vmcnt(0)
	v_pk_mul_f32 v[0:1], v[4:5], v[0:1]
	v_pk_mul_f32 v[4:5], v[26:27], v[50:51] op_sel_hi:[1,0]
	v_cvt_pk_bf16_f32 v0, v0, v1
	v_pk_mul_f32 v[2:3], v[4:5], v[2:3]
	v_pk_mul_f32 v[4:5], v[28:29], v[50:51] op_sel_hi:[1,0]
	v_cvt_pk_bf16_f32 v1, v2, v3
	global_store_dwordx2 v[46:47], v[0:1], off offset:3072
	global_load_dwordx4 v[0:3], v[44:45], off
	s_waitcnt vmcnt(0)
	v_pk_mul_f32 v[0:1], v[4:5], v[0:1]
	v_pk_mul_f32 v[4:5], v[30:31], v[50:51] op_sel_hi:[1,0]
	v_cvt_pk_bf16_f32 v0, v0, v1
	v_pk_mul_f32 v[2:3], v[4:5], v[2:3]
	s_nop 0
	v_cvt_pk_bf16_f32 v1, v2, v3
	global_store_dwordx2 v[46:47], v[0:1], off offset:3584
	v_lshl_add_u64 v[46:47], v[46:47], 0, s[84:85]
	s_cbranch_scc0 .LBB0_79

; DI unsigned pk2(float lo, float hi) { f32x2 v = {lo, hi}; bf16x2_t b = __builtin_convertvector(v, bf16x2_t); return __builtin_bit_cast(unsigned, b); }
; DI unsigned pack_gate4(float a, float b, float c, float d) {
;     unsigned w = 0u;
;     w = __builtin_amdgcn_cvt_pk_u8_f32(fmaxf(a * 255.f, 1.f), 0, w); w = __builtin_amdgcn_cvt_pk_u8_f32(fmaxf(b * 255.f, 1.f), 1, w);
;     w = __builtin_amdgcn_cvt_pk_u8_f32(fmaxf(c * 255.f, 1.f), 2, w); w = __builtin_amdgcn_cvt_pk_u8_f32(fmaxf(d * 255.f, 1.f), 3, w);
;     return w;
; }
;     DI void operator()(const AccT& acc, const Unit& u, int wr, int wc, int fr, int fq) const {
;         const int row0 = u.pm * BM + wr * 64 + fr;
;         bf16_t* base; int ldc, colt; bool gate = false;
;         if (u.pn >= 41) { base = MKV - (size_t)T_ * 1024; ldc = 1024; colt = (u.pn - 41) * BM; }
;         else if (u.pn >= 17) { base = G; ldc = NGATE; colt = (u.pn - 17) * BM; gate = true; }
;         else { base = P; ldc = NPROJ; colt = u.pn * BM; }
;         const int col0 = colt + wc * 32 + 8 * fq;
;         f32x4 bv[2][2];
; #pragma unroll
;         for (int bj = 0; bj < 2; ++bj)
; #pragma unroll
;             for (int n = 0; n < 2; ++n) bv[bj][n] = gate ? *(const f32x4*)(gate_b + col0 + bj * HALF + 4 * n) : (f32x4){0.f, 0.f, 0.f, 0.f};
; #pragma unroll
;         for (int ai = 0; ai < 2; ++ai)
; #pragma unroll
;             for (int m = 0; m < 4; ++m) { bf16_t* rowp = base + (size_t)(row0 + ai * HALF + m * 16) * ldc + col0;
; #pragma unroll
;                 for (int bj = 0; bj < 2; ++bj) { f32x4 v0 = acc[ai][bj][m][0] + bv[bj][0], v1 = acc[ai][bj][m][1] + bv[bj][1];
;                     if (gate) {
; #pragma unroll
;                         for (int j = 0; j < 4; ++j) { v0[j] = sigmoidf_(v0[j]); v1[j] = sigmoidf_(v1[j]); } }
;                     if (gate) {
;                         u32x2 q; q.x = pack_gate4(v0[0], v0[1], v0[2], v0[3]); q.y = pack_gate4(v1[0], v1[1], v1[2], v1[3]);
;                         *(u32x2*)((unsigned char*)G + (size_t)(row0 + ai * HALF + m * 16) * NGATE + col0 + bj * HALF) = q;
;                     } else {
;                         u32x4 w; w.x = pk2(v0[0], v0[1]); w.y = pk2(v0[2], v0[3]); w.z = pk2(v1[0], v1[1]); w.w = pk2(v1[2], v1[3]);
;                         *(u32x4*)(rowp + bj * HALF) = w; } } }
.LBB0_160:
	v_lshl_add_u32 v176, s52, 8, v172
	v_ashrrev_i32_e32 v138, 31, v176
	v_mul_lo_u32 v177, s30, v138
	v_mul_lo_u32 v140, s31, v176
	v_mad_u64_u32 v[138:139], s[2:3], s30, v176, 0
	v_lshl_add_u64 v[136:137], v[154:155], 1, s[34:35]
	v_add3_u32 v139, v139, v177, v140
	v_lshl_add_u64 v[140:141], v[138:139], 1, v[136:137]
	s_mov_b64 s[2:3], -1
	s_and_b64 vcc, exec, s[38:39]
	s_cbranch_vccz .LBB0_162
	v_cvt_pk_bf16_f32 v178, v170, v171
	v_cvt_pk_bf16_f32 v179, v156, v157
	v_cvt_pk_bf16_f32 v180, v158, v159
	v_cvt_pk_bf16_f32 v181, v142, v143
	global_store_dwordx4 v[140:141], v[178:181], off
	s_mov_b64 s[2:3], 0
.LBB0_162:
	v_mad_i64_i32 v[138:139], s[22:23], v176, s20, 0
	v_lshl_add_u64 v[138:139], s[4:5], 0, v[138:139]
	s_andn2_b64 vcc, exec, s[2:3]
	v_lshl_add_u64 v[138:139], v[138:139], 0, v[154:155]
	s_cbranch_vccnz .LBB0_164
	v_mul_f32_e32 v166, 0x437f0000, v170
	v_max_f32_e32 v166, 1.0, v166
	v_mul_f32_e32 v167, 0x437f0000, v171
	v_cvt_pk_u8_f32 v166, v166, 0, 0
	v_max_f32_e32 v167, 1.0, v167
	v_mul_f32_e32 v156, 0x437f0000, v156
	v_cvt_pk_u8_f32 v166, v167, 1, v166
	v_max_f32_e32 v156, 1.0, v156
	v_mul_f32_e32 v157, 0x437f0000, v157
	v_cvt_pk_u8_f32 v156, v156, 2, v166
	v_max_f32_e32 v157, 1.0, v157
	v_cvt_pk_u8_f32 v156, v157, 3, v156
	v_mul_f32_e32 v157, 0x437f0000, v158
	v_max_f32_e32 v157, 1.0, v157
	v_mul_f32_e32 v158, 0x437f0000, v159
	v_cvt_pk_u8_f32 v157, v157, 0, 0
	v_max_f32_e32 v158, 1.0, v158
	v_mul_f32_e32 v142, 0x437f0000, v142
	v_cvt_pk_u8_f32 v157, v158, 1, v157
	v_max_f32_e32 v142, 1.0, v142
	v_mul_f32_e32 v143, 0x437f0000, v143
	v_cvt_pk_u8_f32 v142, v142, 2, v157
	v_max_f32_e32 v143, 1.0, v143
	v_cvt_pk_u8_f32 v157, v143, 3, v142
	global_store_dwordx2 v[138:139], v[156:157], off

; DI unsigned pk2(float lo, float hi) { f32x2 v = {lo, hi}; bf16x2_t b = __builtin_convertvector(v, bf16x2_t); return __builtin_bit_cast(unsigned, b); }
; DI float sigmoidf_(float x) { return __builtin_amdgcn_rcpf(1.0f + __builtin_amdgcn_exp2f(x * -1.4426950408889634f)); }
;     DI void operator()(const AccT& acc, const Unit& u, int wr, int wc, int fr, int fq) const {
;     ...
;                 for (int bj = 0; bj < 2; ++bj) { f32x4 v0 = acc[ai][bj][m][0] + bv[bj][0], v1 = acc[ai][bj][m][1] + bv[bj][1];
;                     if (gate) {
; #pragma unroll
;                         for (int j = 0; j < 4; ++j) { v0[j] = sigmoidf_(v0[j]); v1[j] = sigmoidf_(v1[j]); } }
;                     if (gate) {
;                         u32x2 q; q.x = pack_gate4(v0[0], v0[1], v0[2], v0[3]); q.y = pack_gate4(v1[0], v1[1], v1[2], v1[3]);
;                         *(u32x2*)((unsigned char*)G + (size_t)(row0 + ai * HALF + m * 16) * NGATE + col0 + bj * HALF) = q;
;                     } else {
;                         u32x4 w; w.x = pk2(v0[0], v0[1]); w.y = pk2(v0[2], v0[3]); w.z = pk2(v1[0], v1[1]); w.w = pk2(v1[2], v1[3]);
;                         *(u32x4*)(rowp + bj * HALF) = w; } } }
.LBB0_167:
	v_cvt_pk_bf16_f32 v156, v132, v133
	v_cvt_pk_bf16_f32 v157, v134, v135
	v_cvt_pk_bf16_f32 v158, v128, v129
	v_cvt_pk_bf16_f32 v159, v130, v131
	global_store_dwordx4 v[140:141], v[156:159], off offset:256
	s_cbranch_execz .LBB0_171
	s_branch .LBB0_172

; DI unsigned pack_gate4(float a, float b, float c, float d) {
;     unsigned w = 0u;
;     w = __builtin_amdgcn_cvt_pk_u8_f32(fmaxf(a * 255.f, 1.f), 0, w); w = __builtin_amdgcn_cvt_pk_u8_f32(fmaxf(b * 255.f, 1.f), 1, w);
;     w = __builtin_amdgcn_cvt_pk_u8_f32(fmaxf(c * 255.f, 1.f), 2, w); w = __builtin_amdgcn_cvt_pk_u8_f32(fmaxf(d * 255.f, 1.f), 3, w);
;     return w;
; }
;     DI void operator()(const AccT& acc, const Unit& u, int wr, int wc, int fr, int fq) const {
;     ...
;                     if (gate) {
;                         u32x2 q; q.x = pack_gate4(v0[0], v0[1], v0[2], v0[3]); q.y = pack_gate4(v1[0], v1[1], v1[2], v1[3]);
;                         *(u32x2*)((unsigned char*)G + (size_t)(row0 + ai * HALF + m * 16) * NGATE + col0 + bj * HALF) = q;
.LBB0_171:
	v_mul_f32_e32 v132, 0x437f0000, v132
	v_mul_f32_e32 v128, 0x437f0000, v128
	v_max_f32_e32 v132, 1.0, v132
	v_mul_f32_e32 v133, 0x437f0000, v133
	v_max_f32_e32 v128, 1.0, v128
	v_mul_f32_e32 v129, 0x437f0000, v129
	v_cvt_pk_u8_f32 v132, v132, 0, 0
	v_max_f32_e32 v133, 1.0, v133
	v_cvt_pk_u8_f32 v128, v128, 0, 0
	v_max_f32_e32 v129, 1.0, v129
	v_cvt_pk_u8_f32 v132, v133, 1, v132
	v_mul_f32_e32 v133, 0x437f0000, v134
	v_cvt_pk_u8_f32 v128, v129, 1, v128
	v_mul_f32_e32 v129, 0x437f0000, v130
	v_max_f32_e32 v133, 1.0, v133
	v_max_f32_e32 v129, 1.0, v129
	v_cvt_pk_u8_f32 v132, v133, 2, v132
	v_mul_f32_e32 v133, 0x437f0000, v135
	v_cvt_pk_u8_f32 v128, v129, 2, v128
	v_mul_f32_e32 v129, 0x437f0000, v131
	v_max_f32_e32 v133, 1.0, v133
	v_max_f32_e32 v129, 1.0, v129
	v_cvt_pk_u8_f32 v132, v133, 3, v132
	v_cvt_pk_u8_f32 v133, v129, 3, v128
	global_store_dwordx2 v[138:139], v[132:133], off offset:128

; DI unsigned pk2(float lo, float hi) { f32x2 v = {lo, hi}; bf16x2_t b = __builtin_convertvector(v, bf16x2_t); return __builtin_bit_cast(unsigned, b); }
; DI float sigmoidf_(float x) { return __builtin_amdgcn_rcpf(1.0f + __builtin_amdgcn_exp2f(x * -1.4426950408889634f)); }
;     DI void operator()(const AccT& acc, const Unit& u, int wr, int wc, int fr, int fq) const {
;     ...
;             for (int m = 0; m < 4; ++m) { bf16_t* rowp = base + (size_t)(row0 + ai * HALF + m * 16) * ldc + col0;
; #pragma unroll
;                 for (int bj = 0; bj < 2; ++bj) { f32x4 v0 = acc[ai][bj][m][0] + bv[bj][0], v1 = acc[ai][bj][m][1] + bv[bj][1];
;                     if (gate) {
; #pragma unroll
;                         for (int j = 0; j < 4; ++j) { v0[j] = sigmoidf_(v0[j]); v1[j] = sigmoidf_(v1[j]); } }
;                     if (gate) {
;                         u32x2 q; q.x = pack_gate4(v0[0], v0[1], v0[2], v0[3]); q.y = pack_gate4(v1[0], v1[1], v1[2], v1[3]);
;                         *(u32x2*)((unsigned char*)G + (size_t)(row0 + ai * HALF + m * 16) * NGATE + col0 + bj * HALF) = q;
;                     } else {
;                         u32x4 w; w.x = pk2(v0[0], v0[1]); w.y = pk2(v0[2], v0[3]); w.z = pk2(v1[0], v1[1]); w.w = pk2(v1[2], v1[3]);
;                         *(u32x4*)(rowp + bj * HALF) = w; } } }
.LBB0_176:
	v_or_b32_e32 v120, 16, v176
	v_mul_lo_u32 v121, s31, v120
	v_mad_u64_u32 v[122:123], s[2:3], s30, v120, 0
	v_add3_u32 v123, v123, v177, v121
	v_lshl_add_u64 v[122:123], v[122:123], 1, v[136:137]
	s_and_b64 vcc, exec, s[36:37]
	s_mov_b64 s[2:3], -1
	s_cbranch_vccnz .LBB0_178
	v_cvt_pk_bf16_f32 v132, v130, v131
	v_cvt_pk_bf16_f32 v133, v126, v127
	v_cvt_pk_bf16_f32 v134, v128, v129
	v_cvt_pk_bf16_f32 v135, v124, v125
	s_mov_b64 s[2:3], 0
	global_store_dwordx4 v[122:123], v[132:135], off
.LBB0_178:
	v_mad_i64_i32 v[120:121], s[22:23], v120, s20, 0
	v_lshl_add_u64 v[120:121], s[4:5], 0, v[120:121]
	s_andn2_b64 vcc, exec, s[2:3]
	v_lshl_add_u64 v[120:121], v[120:121], 0, v[154:155]
	s_cbranch_vccnz .LBB0_180
	v_mul_f32_e32 v130, 0x437f0000, v130
	v_max_f32_e32 v130, 1.0, v130
	v_mul_f32_e32 v131, 0x437f0000, v131
	v_cvt_pk_u8_f32 v130, v130, 0, 0
	v_max_f32_e32 v131, 1.0, v131
	v_mul_f32_e32 v126, 0x437f0000, v126
	v_cvt_pk_u8_f32 v130, v131, 1, v130
	v_max_f32_e32 v126, 1.0, v126
	v_mul_f32_e32 v127, 0x437f0000, v127
	v_cvt_pk_u8_f32 v126, v126, 2, v130
	v_max_f32_e32 v127, 1.0, v127
	v_cvt_pk_u8_f32 v126, v127, 3, v126
	v_mul_f32_e32 v127, 0x437f0000, v128
	v_max_f32_e32 v127, 1.0, v127
	v_mul_f32_e32 v128, 0x437f0000, v129
	v_cvt_pk_u8_f32 v127, v127, 0, 0
	v_max_f32_e32 v128, 1.0, v128
	v_mul_f32_e32 v124, 0x437f0000, v124
	v_cvt_pk_u8_f32 v127, v128, 1, v127
	v_max_f32_e32 v124, 1.0, v124
	v_mul_f32_e32 v125, 0x437f0000, v125
	v_cvt_pk_u8_f32 v124, v124, 2, v127
	v_max_f32_e32 v125, 1.0, v125
	v_cvt_pk_u8_f32 v127, v125, 3, v124
	global_store_dwordx2 v[120:121], v[126:127], off

; DI unsigned pk2(float lo, float hi) { f32x2 v = {lo, hi}; bf16x2_t b = __builtin_convertvector(v, bf16x2_t); return __builtin_bit_cast(unsigned, b); }
; DI float sigmoidf_(float x) { return __builtin_amdgcn_rcpf(1.0f + __builtin_amdgcn_exp2f(x * -1.4426950408889634f)); }
;     DI void operator()(const AccT& acc, const Unit& u, int wr, int wc, int fr, int fq) const {
;     ...
;                 for (int bj = 0; bj < 2; ++bj) { f32x4 v0 = acc[ai][bj][m][0] + bv[bj][0], v1 = acc[ai][bj][m][1] + bv[bj][1];
;                     if (gate) {
; #pragma unroll
;                         for (int j = 0; j < 4; ++j) { v0[j] = sigmoidf_(v0[j]); v1[j] = sigmoidf_(v1[j]); } }
;                     if (gate) {
;                         u32x2 q; q.x = pack_gate4(v0[0], v0[1], v0[2], v0[3]); q.y = pack_gate4(v1[0], v1[1], v1[2], v1[3]);
;                         *(u32x2*)((unsigned char*)G + (size_t)(row0 + ai * HALF + m * 16) * NGATE + col0 + bj * HALF) = q;
;                     } else {
;                         u32x4 w; w.x = pk2(v0[0], v0[1]); w.y = pk2(v0[2], v0[3]); w.z = pk2(v1[0], v1[1]); w.w = pk2(v1[2], v1[3]);
;                         *(u32x4*)(rowp + bj * HALF) = w; } } }
.LBB0_183:
	v_cvt_pk_bf16_f32 v124, v116, v117
	v_cvt_pk_bf16_f32 v125, v118, v119
	v_cvt_pk_bf16_f32 v126, v112, v113
	v_cvt_pk_bf16_f32 v127, v114, v115
	global_store_dwordx4 v[122:123], v[124:127], off offset:256
	s_cbranch_execz .LBB0_187
	s_branch .LBB0_188

; DI unsigned pack_gate4(float a, float b, float c, float d) {
;     unsigned w = 0u;
;     w = __builtin_amdgcn_cvt_pk_u8_f32(fmaxf(a * 255.f, 1.f), 0, w); w = __builtin_amdgcn_cvt_pk_u8_f32(fmaxf(b * 255.f, 1.f), 1, w);
;     w = __builtin_amdgcn_cvt_pk_u8_f32(fmaxf(c * 255.f, 1.f), 2, w); w = __builtin_amdgcn_cvt_pk_u8_f32(fmaxf(d * 255.f, 1.f), 3, w);
;     return w;
; }
;     DI void operator()(const AccT& acc, const Unit& u, int wr, int wc, int fr, int fq) const {
;     ...
;                     if (gate) {
;                         u32x2 q; q.x = pack_gate4(v0[0], v0[1], v0[2], v0[3]); q.y = pack_gate4(v1[0], v1[1], v1[2], v1[3]);
;                         *(u32x2*)((unsigned char*)G + (size_t)(row0 + ai * HALF + m * 16) * NGATE + col0 + bj * HALF) = q;
.LBB0_187:
	v_mul_f32_e32 v116, 0x437f0000, v116
	v_mul_f32_e32 v112, 0x437f0000, v112
	v_max_f32_e32 v116, 1.0, v116
	v_mul_f32_e32 v117, 0x437f0000, v117
	v_max_f32_e32 v112, 1.0, v112
	v_mul_f32_e32 v113, 0x437f0000, v113
	v_cvt_pk_u8_f32 v116, v116, 0, 0
	v_max_f32_e32 v117, 1.0, v117
	v_cvt_pk_u8_f32 v112, v112, 0, 0
	v_max_f32_e32 v113, 1.0, v113
	v_cvt_pk_u8_f32 v116, v117, 1, v116
	v_mul_f32_e32 v117, 0x437f0000, v118
	v_cvt_pk_u8_f32 v112, v113, 1, v112
	v_mul_f32_e32 v113, 0x437f0000, v114
	v_max_f32_e32 v117, 1.0, v117
	v_max_f32_e32 v113, 1.0, v113
	v_cvt_pk_u8_f32 v116, v117, 2, v116
	v_mul_f32_e32 v117, 0x437f0000, v119
	v_cvt_pk_u8_f32 v112, v113, 2, v112
	v_mul_f32_e32 v113, 0x437f0000, v115
	v_max_f32_e32 v117, 1.0, v117
	v_max_f32_e32 v113, 1.0, v113
	v_cvt_pk_u8_f32 v116, v117, 3, v116
	v_cvt_pk_u8_f32 v117, v113, 3, v112
	global_store_dwordx2 v[120:121], v[116:117], off offset:128

; DI unsigned pk2(float lo, float hi) { f32x2 v = {lo, hi}; bf16x2_t b = __builtin_convertvector(v, bf16x2_t); return __builtin_bit_cast(unsigned, b); }
; DI float sigmoidf_(float x) { return __builtin_amdgcn_rcpf(1.0f + __builtin_amdgcn_exp2f(x * -1.4426950408889634f)); }
;     DI void operator()(const AccT& acc, const Unit& u, int wr, int wc, int fr, int fq) const {
;     ...
;             for (int m = 0; m < 4; ++m) { bf16_t* rowp = base + (size_t)(row0 + ai * HALF + m * 16) * ldc + col0;
; #pragma unroll
;                 for (int bj = 0; bj < 2; ++bj) { f32x4 v0 = acc[ai][bj][m][0] + bv[bj][0], v1 = acc[ai][bj][m][1] + bv[bj][1];
;                     if (gate) {
; #pragma unroll
;                         for (int j = 0; j < 4; ++j) { v0[j] = sigmoidf_(v0[j]); v1[j] = sigmoidf_(v1[j]); } }
;                     if (gate) {
;                         u32x2 q; q.x = pack_gate4(v0[0], v0[1], v0[2], v0[3]); q.y = pack_gate4(v1[0], v1[1], v1[2], v1[3]);
;                         *(u32x2*)((unsigned char*)G + (size_t)(row0 + ai * HALF + m * 16) * NGATE + col0 + bj * HALF) = q;
;                     } else {
;                         u32x4 w; w.x = pk2(v0[0], v0[1]); w.y = pk2(v0[2], v0[3]); w.z = pk2(v1[0], v1[1]); w.w = pk2(v1[2], v1[3]);
;                         *(u32x4*)(rowp + bj * HALF) = w; } } }
.LBB0_192:
	v_or_b32_e32 v104, 32, v176
	v_mul_lo_u32 v105, s31, v104
	v_mad_u64_u32 v[106:107], s[2:3], s30, v104, 0
	v_add3_u32 v107, v107, v177, v105
	v_lshl_add_u64 v[106:107], v[106:107], 1, v[136:137]
	s_and_b64 vcc, exec, s[36:37]
	s_mov_b64 s[2:3], -1
	s_cbranch_vccnz .LBB0_194
	v_cvt_pk_bf16_f32 v116, v114, v115
	v_cvt_pk_bf16_f32 v117, v110, v111
	v_cvt_pk_bf16_f32 v118, v112, v113
	v_cvt_pk_bf16_f32 v119, v108, v109
	s_mov_b64 s[2:3], 0
	global_store_dwordx4 v[106:107], v[116:119], off
.LBB0_194:
	v_mad_i64_i32 v[104:105], s[22:23], v104, s20, 0
	v_lshl_add_u64 v[104:105], s[4:5], 0, v[104:105]
	s_andn2_b64 vcc, exec, s[2:3]
	v_lshl_add_u64 v[104:105], v[104:105], 0, v[154:155]
	s_cbranch_vccnz .LBB0_196
	v_mul_f32_e32 v114, 0x437f0000, v114
	v_max_f32_e32 v114, 1.0, v114
	v_mul_f32_e32 v115, 0x437f0000, v115
	v_cvt_pk_u8_f32 v114, v114, 0, 0
	v_max_f32_e32 v115, 1.0, v115
	v_mul_f32_e32 v110, 0x437f0000, v110
	v_cvt_pk_u8_f32 v114, v115, 1, v114
	v_max_f32_e32 v110, 1.0, v110
	v_mul_f32_e32 v111, 0x437f0000, v111
	v_cvt_pk_u8_f32 v110, v110, 2, v114
	v_max_f32_e32 v111, 1.0, v111
	v_cvt_pk_u8_f32 v110, v111, 3, v110
	v_mul_f32_e32 v111, 0x437f0000, v112
	v_max_f32_e32 v111, 1.0, v111
	v_mul_f32_e32 v112, 0x437f0000, v113
	v_cvt_pk_u8_f32 v111, v111, 0, 0
	v_max_f32_e32 v112, 1.0, v112
	v_mul_f32_e32 v108, 0x437f0000, v108
	v_cvt_pk_u8_f32 v111, v112, 1, v111
	v_max_f32_e32 v108, 1.0, v108
	v_mul_f32_e32 v109, 0x437f0000, v109
	v_cvt_pk_u8_f32 v108, v108, 2, v111
	v_max_f32_e32 v109, 1.0, v109
	v_cvt_pk_u8_f32 v111, v109, 3, v108
	global_store_dwordx2 v[104:105], v[110:111], off

; DI unsigned pk2(float lo, float hi) { f32x2 v = {lo, hi}; bf16x2_t b = __builtin_convertvector(v, bf16x2_t); return __builtin_bit_cast(unsigned, b); }
; DI float sigmoidf_(float x) { return __builtin_amdgcn_rcpf(1.0f + __builtin_amdgcn_exp2f(x * -1.4426950408889634f)); }
;     DI void operator()(const AccT& acc, const Unit& u, int wr, int wc, int fr, int fq) const {
;     ...
;                 for (int bj = 0; bj < 2; ++bj) { f32x4 v0 = acc[ai][bj][m][0] + bv[bj][0], v1 = acc[ai][bj][m][1] + bv[bj][1];
;                     if (gate) {
; #pragma unroll
;                         for (int j = 0; j < 4; ++j) { v0[j] = sigmoidf_(v0[j]); v1[j] = sigmoidf_(v1[j]); } }
;                     if (gate) {
;                         u32x2 q; q.x = pack_gate4(v0[0], v0[1], v0[2], v0[3]); q.y = pack_gate4(v1[0], v1[1], v1[2], v1[3]);
;                         *(u32x2*)((unsigned char*)G + (size_t)(row0 + ai * HALF + m * 16) * NGATE + col0 + bj * HALF) = q;
;                     } else {
;                         u32x4 w; w.x = pk2(v0[0], v0[1]); w.y = pk2(v0[2], v0[3]); w.z = pk2(v1[0], v1[1]); w.w = pk2(v1[2], v1[3]);
;                         *(u32x4*)(rowp + bj * HALF) = w; } } }
.LBB0_199:
	v_cvt_pk_bf16_f32 v108, v100, v101
	v_cvt_pk_bf16_f32 v109, v102, v103
	v_cvt_pk_bf16_f32 v110, v96, v97
	v_cvt_pk_bf16_f32 v111, v98, v99
	global_store_dwordx4 v[106:107], v[108:111], off offset:256
	s_cbranch_execz .LBB0_203
	s_branch .LBB0_204

; DI unsigned pack_gate4(float a, float b, float c, float d) {
;     unsigned w = 0u;
;     w = __builtin_amdgcn_cvt_pk_u8_f32(fmaxf(a * 255.f, 1.f), 0, w); w = __builtin_amdgcn_cvt_pk_u8_f32(fmaxf(b * 255.f, 1.f), 1, w);
;     w = __builtin_amdgcn_cvt_pk_u8_f32(fmaxf(c * 255.f, 1.f), 2, w); w = __builtin_amdgcn_cvt_pk_u8_f32(fmaxf(d * 255.f, 1.f), 3, w);
;     return w;
; }
;     DI void operator()(const AccT& acc, const Unit& u, int wr, int wc, int fr, int fq) const {
;     ...
;                     if (gate) {
;                         u32x2 q; q.x = pack_gate4(v0[0], v0[1], v0[2], v0[3]); q.y = pack_gate4(v1[0], v1[1], v1[2], v1[3]);
;                         *(u32x2*)((unsigned char*)G + (size_t)(row0 + ai * HALF + m * 16) * NGATE + col0 + bj * HALF) = q;
.LBB0_203:
	v_mul_f32_e32 v100, 0x437f0000, v100
	v_mul_f32_e32 v96, 0x437f0000, v96
	v_max_f32_e32 v100, 1.0, v100
	v_mul_f32_e32 v101, 0x437f0000, v101
	v_max_f32_e32 v96, 1.0, v96
	v_mul_f32_e32 v97, 0x437f0000, v97
	v_cvt_pk_u8_f32 v100, v100, 0, 0
	v_max_f32_e32 v101, 1.0, v101
	v_cvt_pk_u8_f32 v96, v96, 0, 0
	v_max_f32_e32 v97, 1.0, v97
	v_cvt_pk_u8_f32 v100, v101, 1, v100
	v_mul_f32_e32 v101, 0x437f0000, v102
	v_cvt_pk_u8_f32 v96, v97, 1, v96
	v_mul_f32_e32 v97, 0x437f0000, v98
	v_max_f32_e32 v101, 1.0, v101
	v_max_f32_e32 v97, 1.0, v97
	v_cvt_pk_u8_f32 v100, v101, 2, v100
	v_mul_f32_e32 v101, 0x437f0000, v103
	v_cvt_pk_u8_f32 v96, v97, 2, v96
	v_mul_f32_e32 v97, 0x437f0000, v99
	v_max_f32_e32 v101, 1.0, v101
	v_max_f32_e32 v97, 1.0, v97
	v_cvt_pk_u8_f32 v100, v101, 3, v100
	v_cvt_pk_u8_f32 v101, v97, 3, v96
	global_store_dwordx2 v[104:105], v[100:101], off offset:128

; DI unsigned pk2(float lo, float hi) { f32x2 v = {lo, hi}; bf16x2_t b = __builtin_convertvector(v, bf16x2_t); return __builtin_bit_cast(unsigned, b); }
; DI float sigmoidf_(float x) { return __builtin_amdgcn_rcpf(1.0f + __builtin_amdgcn_exp2f(x * -1.4426950408889634f)); }
;     DI void operator()(const AccT& acc, const Unit& u, int wr, int wc, int fr, int fq) const {
;     ...
;             for (int m = 0; m < 4; ++m) { bf16_t* rowp = base + (size_t)(row0 + ai * HALF + m * 16) * ldc + col0;
; #pragma unroll
;                 for (int bj = 0; bj < 2; ++bj) { f32x4 v0 = acc[ai][bj][m][0] + bv[bj][0], v1 = acc[ai][bj][m][1] + bv[bj][1];
;                     if (gate) {
; #pragma unroll
;                         for (int j = 0; j < 4; ++j) { v0[j] = sigmoidf_(v0[j]); v1[j] = sigmoidf_(v1[j]); } }
;                     if (gate) {
;                         u32x2 q; q.x = pack_gate4(v0[0], v0[1], v0[2], v0[3]); q.y = pack_gate4(v1[0], v1[1], v1[2], v1[3]);
;                         *(u32x2*)((unsigned char*)G + (size_t)(row0 + ai * HALF + m * 16) * NGATE + col0 + bj * HALF) = q;
;                     } else {
;                         u32x4 w; w.x = pk2(v0[0], v0[1]); w.y = pk2(v0[2], v0[3]); w.z = pk2(v1[0], v1[1]); w.w = pk2(v1[2], v1[3]);
;                         *(u32x4*)(rowp + bj * HALF) = w; } } }
.LBB0_208:
	v_or_b32_e32 v88, 48, v176
	v_mul_lo_u32 v89, s31, v88
	v_mad_u64_u32 v[90:91], s[2:3], s30, v88, 0
	v_add3_u32 v91, v91, v177, v89
	v_lshl_add_u64 v[90:91], v[90:91], 1, v[136:137]
	s_and_b64 vcc, exec, s[36:37]
	s_mov_b64 s[2:3], -1
	s_cbranch_vccnz .LBB0_210
	v_cvt_pk_bf16_f32 v100, v98, v99
	v_cvt_pk_bf16_f32 v101, v94, v95
	v_cvt_pk_bf16_f32 v102, v96, v97
	v_cvt_pk_bf16_f32 v103, v92, v93
	s_mov_b64 s[2:3], 0
	global_store_dwordx4 v[90:91], v[100:103], off
.LBB0_210:
	v_mad_i64_i32 v[88:89], s[22:23], v88, s20, 0
	v_lshl_add_u64 v[88:89], s[4:5], 0, v[88:89]
	s_andn2_b64 vcc, exec, s[2:3]
	v_lshl_add_u64 v[88:89], v[88:89], 0, v[154:155]
	s_cbranch_vccnz .LBB0_212
	v_mul_f32_e32 v98, 0x437f0000, v98
	v_max_f32_e32 v98, 1.0, v98
	v_mul_f32_e32 v99, 0x437f0000, v99
	v_cvt_pk_u8_f32 v98, v98, 0, 0
	v_max_f32_e32 v99, 1.0, v99
	v_mul_f32_e32 v94, 0x437f0000, v94
	v_cvt_pk_u8_f32 v98, v99, 1, v98
	v_max_f32_e32 v94, 1.0, v94
	v_mul_f32_e32 v95, 0x437f0000, v95
	v_cvt_pk_u8_f32 v94, v94, 2, v98
	v_max_f32_e32 v95, 1.0, v95
	v_cvt_pk_u8_f32 v94, v95, 3, v94
	v_mul_f32_e32 v95, 0x437f0000, v96
	v_max_f32_e32 v95, 1.0, v95
	v_mul_f32_e32 v96, 0x437f0000, v97
	v_cvt_pk_u8_f32 v95, v95, 0, 0
	v_max_f32_e32 v96, 1.0, v96
	v_mul_f32_e32 v92, 0x437f0000, v92
	v_cvt_pk_u8_f32 v95, v96, 1, v95
	v_max_f32_e32 v92, 1.0, v92
	v_mul_f32_e32 v93, 0x437f0000, v93
	v_cvt_pk_u8_f32 v92, v92, 2, v95
	v_max_f32_e32 v93, 1.0, v93
	v_cvt_pk_u8_f32 v95, v93, 3, v92
	global_store_dwordx2 v[88:89], v[94:95], off

; DI unsigned pk2(float lo, float hi) { f32x2 v = {lo, hi}; bf16x2_t b = __builtin_convertvector(v, bf16x2_t); return __builtin_bit_cast(unsigned, b); }
; DI float sigmoidf_(float x) { return __builtin_amdgcn_rcpf(1.0f + __builtin_amdgcn_exp2f(x * -1.4426950408889634f)); }
;     DI void operator()(const AccT& acc, const Unit& u, int wr, int wc, int fr, int fq) const {
;     ...
;                 for (int bj = 0; bj < 2; ++bj) { f32x4 v0 = acc[ai][bj][m][0] + bv[bj][0], v1 = acc[ai][bj][m][1] + bv[bj][1];
;                     if (gate) {
; #pragma unroll
;                         for (int j = 0; j < 4; ++j) { v0[j] = sigmoidf_(v0[j]); v1[j] = sigmoidf_(v1[j]); } }
;                     if (gate) {
;                         u32x2 q; q.x = pack_gate4(v0[0], v0[1], v0[2], v0[3]); q.y = pack_gate4(v1[0], v1[1], v1[2], v1[3]);
;                         *(u32x2*)((unsigned char*)G + (size_t)(row0 + ai * HALF + m * 16) * NGATE + col0 + bj * HALF) = q;
;                     } else {
;                         u32x4 w; w.x = pk2(v0[0], v0[1]); w.y = pk2(v0[2], v0[3]); w.z = pk2(v1[0], v1[1]); w.w = pk2(v1[2], v1[3]);
;                         *(u32x4*)(rowp + bj * HALF) = w; } } }
.LBB0_215:
	v_cvt_pk_bf16_f32 v92, v84, v85
	v_cvt_pk_bf16_f32 v93, v86, v87
	v_cvt_pk_bf16_f32 v94, v80, v81
	v_cvt_pk_bf16_f32 v95, v82, v83
	global_store_dwordx4 v[90:91], v[92:95], off offset:256
	s_cbranch_execz .LBB0_219
	s_branch .LBB0_220

; DI unsigned pack_gate4(float a, float b, float c, float d) {
;     unsigned w = 0u;
;     w = __builtin_amdgcn_cvt_pk_u8_f32(fmaxf(a * 255.f, 1.f), 0, w); w = __builtin_amdgcn_cvt_pk_u8_f32(fmaxf(b * 255.f, 1.f), 1, w);
;     w = __builtin_amdgcn_cvt_pk_u8_f32(fmaxf(c * 255.f, 1.f), 2, w); w = __builtin_amdgcn_cvt_pk_u8_f32(fmaxf(d * 255.f, 1.f), 3, w);
;     return w;
; }
;     DI void operator()(const AccT& acc, const Unit& u, int wr, int wc, int fr, int fq) const {
;     ...
;                     if (gate) {
;                         u32x2 q; q.x = pack_gate4(v0[0], v0[1], v0[2], v0[3]); q.y = pack_gate4(v1[0], v1[1], v1[2], v1[3]);
;                         *(u32x2*)((unsigned char*)G + (size_t)(row0 + ai * HALF + m * 16) * NGATE + col0 + bj * HALF) = q;
.LBB0_219:
	v_mul_f32_e32 v84, 0x437f0000, v84
	v_mul_f32_e32 v80, 0x437f0000, v80
	v_max_f32_e32 v84, 1.0, v84
	v_mul_f32_e32 v85, 0x437f0000, v85
	v_max_f32_e32 v80, 1.0, v80
	v_mul_f32_e32 v81, 0x437f0000, v81
	v_cvt_pk_u8_f32 v84, v84, 0, 0
	v_max_f32_e32 v85, 1.0, v85
	v_cvt_pk_u8_f32 v80, v80, 0, 0
	v_max_f32_e32 v81, 1.0, v81
	v_cvt_pk_u8_f32 v84, v85, 1, v84
	v_mul_f32_e32 v85, 0x437f0000, v86
	v_cvt_pk_u8_f32 v80, v81, 1, v80
	v_mul_f32_e32 v81, 0x437f0000, v82
	v_max_f32_e32 v85, 1.0, v85
	v_max_f32_e32 v81, 1.0, v81
	v_cvt_pk_u8_f32 v84, v85, 2, v84
	v_mul_f32_e32 v85, 0x437f0000, v87
	v_cvt_pk_u8_f32 v80, v81, 2, v80
	v_mul_f32_e32 v81, 0x437f0000, v83
	v_max_f32_e32 v85, 1.0, v85
	v_max_f32_e32 v81, 1.0, v81
	v_cvt_pk_u8_f32 v84, v85, 3, v84
	v_cvt_pk_u8_f32 v85, v81, 3, v80
	global_store_dwordx2 v[88:89], v[84:85], off offset:128

; DI unsigned pk2(float lo, float hi) { f32x2 v = {lo, hi}; bf16x2_t b = __builtin_convertvector(v, bf16x2_t); return __builtin_bit_cast(unsigned, b); }
; DI float sigmoidf_(float x) { return __builtin_amdgcn_rcpf(1.0f + __builtin_amdgcn_exp2f(x * -1.4426950408889634f)); }
;     DI void operator()(const AccT& acc, const Unit& u, int wr, int wc, int fr, int fq) const {
;     ...
;             for (int m = 0; m < 4; ++m) { bf16_t* rowp = base + (size_t)(row0 + ai * HALF + m * 16) * ldc + col0;
; #pragma unroll
;                 for (int bj = 0; bj < 2; ++bj) { f32x4 v0 = acc[ai][bj][m][0] + bv[bj][0], v1 = acc[ai][bj][m][1] + bv[bj][1];
;                     if (gate) {
; #pragma unroll
;                         for (int j = 0; j < 4; ++j) { v0[j] = sigmoidf_(v0[j]); v1[j] = sigmoidf_(v1[j]); } }
;                     if (gate) {
;                         u32x2 q; q.x = pack_gate4(v0[0], v0[1], v0[2], v0[3]); q.y = pack_gate4(v1[0], v1[1], v1[2], v1[3]);
;                         *(u32x2*)((unsigned char*)G + (size_t)(row0 + ai * HALF + m * 16) * NGATE + col0 + bj * HALF) = q;
;                     } else {
;                         u32x4 w; w.x = pk2(v0[0], v0[1]); w.y = pk2(v0[2], v0[3]); w.z = pk2(v1[0], v1[1]); w.w = pk2(v1[2], v1[3]);
;                         *(u32x4*)(rowp + bj * HALF) = w; } } }
.LBB0_224:
	v_add_u32_e32 v72, 0x80, v176
	v_ashrrev_i32_e32 v73, 31, v72
	v_mul_lo_u32 v73, s30, v73
	v_mul_lo_u32 v84, s31, v72
	v_mad_u64_u32 v[74:75], s[2:3], s30, v72, 0
	v_add3_u32 v75, v75, v73, v84
	v_lshl_add_u64 v[74:75], v[74:75], 1, v[136:137]
	s_and_b64 vcc, exec, s[36:37]
	s_mov_b64 s[2:3], -1
	s_cbranch_vccnz .LBB0_226
	v_cvt_pk_bf16_f32 v84, v82, v83
	v_cvt_pk_bf16_f32 v85, v78, v79
	v_cvt_pk_bf16_f32 v86, v80, v81
	v_cvt_pk_bf16_f32 v87, v76, v77
	s_mov_b64 s[2:3], 0
	global_store_dwordx4 v[74:75], v[84:87], off
.LBB0_226:
	v_mad_i64_i32 v[72:73], s[22:23], v72, s20, 0
	v_lshl_add_u64 v[72:73], s[4:5], 0, v[72:73]
	s_andn2_b64 vcc, exec, s[2:3]
	v_lshl_add_u64 v[72:73], v[72:73], 0, v[154:155]
	s_cbranch_vccnz .LBB0_228
	v_mul_f32_e32 v82, 0x437f0000, v82
	v_max_f32_e32 v82, 1.0, v82
	v_mul_f32_e32 v83, 0x437f0000, v83
	v_cvt_pk_u8_f32 v82, v82, 0, 0
	v_max_f32_e32 v83, 1.0, v83
	v_mul_f32_e32 v78, 0x437f0000, v78
	v_cvt_pk_u8_f32 v82, v83, 1, v82
	v_max_f32_e32 v78, 1.0, v78
	v_mul_f32_e32 v79, 0x437f0000, v79
	v_cvt_pk_u8_f32 v78, v78, 2, v82
	v_max_f32_e32 v79, 1.0, v79
	v_cvt_pk_u8_f32 v78, v79, 3, v78
	v_mul_f32_e32 v79, 0x437f0000, v80
	v_max_f32_e32 v79, 1.0, v79
	v_mul_f32_e32 v80, 0x437f0000, v81
	v_cvt_pk_u8_f32 v79, v79, 0, 0
	v_max_f32_e32 v80, 1.0, v80
	v_mul_f32_e32 v76, 0x437f0000, v76
	v_cvt_pk_u8_f32 v79, v80, 1, v79
	v_max_f32_e32 v76, 1.0, v76
	v_mul_f32_e32 v77, 0x437f0000, v77
	v_cvt_pk_u8_f32 v76, v76, 2, v79
	v_max_f32_e32 v77, 1.0, v77
	v_cvt_pk_u8_f32 v79, v77, 3, v76
	global_store_dwordx2 v[72:73], v[78:79], off

; DI unsigned pk2(float lo, float hi) { f32x2 v = {lo, hi}; bf16x2_t b = __builtin_convertvector(v, bf16x2_t); return __builtin_bit_cast(unsigned, b); }
; DI float sigmoidf_(float x) { return __builtin_amdgcn_rcpf(1.0f + __builtin_amdgcn_exp2f(x * -1.4426950408889634f)); }
;     DI void operator()(const AccT& acc, const Unit& u, int wr, int wc, int fr, int fq) const {
;     ...
;                 for (int bj = 0; bj < 2; ++bj) { f32x4 v0 = acc[ai][bj][m][0] + bv[bj][0], v1 = acc[ai][bj][m][1] + bv[bj][1];
;                     if (gate) {
; #pragma unroll
;                         for (int j = 0; j < 4; ++j) { v0[j] = sigmoidf_(v0[j]); v1[j] = sigmoidf_(v1[j]); } }
;                     if (gate) {
;                         u32x2 q; q.x = pack_gate4(v0[0], v0[1], v0[2], v0[3]); q.y = pack_gate4(v1[0], v1[1], v1[2], v1[3]);
;                         *(u32x2*)((unsigned char*)G + (size_t)(row0 + ai * HALF + m * 16) * NGATE + col0 + bj * HALF) = q;
;                     } else {
;                         u32x4 w; w.x = pk2(v0[0], v0[1]); w.y = pk2(v0[2], v0[3]); w.z = pk2(v1[0], v1[1]); w.w = pk2(v1[2], v1[3]);
;                         *(u32x4*)(rowp + bj * HALF) = w; } } }
.LBB0_231:
	v_cvt_pk_bf16_f32 v76, v68, v69
	v_cvt_pk_bf16_f32 v77, v70, v71
	v_cvt_pk_bf16_f32 v78, v64, v65
	v_cvt_pk_bf16_f32 v79, v66, v67
	global_store_dwordx4 v[74:75], v[76:79], off offset:256
	s_cbranch_execz .LBB0_235
	s_branch .LBB0_236

; DI unsigned pack_gate4(float a, float b, float c, float d) {
;     unsigned w = 0u;
;     w = __builtin_amdgcn_cvt_pk_u8_f32(fmaxf(a * 255.f, 1.f), 0, w); w = __builtin_amdgcn_cvt_pk_u8_f32(fmaxf(b * 255.f, 1.f), 1, w);
;     w = __builtin_amdgcn_cvt_pk_u8_f32(fmaxf(c * 255.f, 1.f), 2, w); w = __builtin_amdgcn_cvt_pk_u8_f32(fmaxf(d * 255.f, 1.f), 3, w);
;     return w;
; }
;     DI void operator()(const AccT& acc, const Unit& u, int wr, int wc, int fr, int fq) const {
;     ...
;                     if (gate) {
;                         u32x2 q; q.x = pack_gate4(v0[0], v0[1], v0[2], v0[3]); q.y = pack_gate4(v1[0], v1[1], v1[2], v1[3]);
;                         *(u32x2*)((unsigned char*)G + (size_t)(row0 + ai * HALF + m * 16) * NGATE + col0 + bj * HALF) = q;
.LBB0_235:
	v_mul_f32_e32 v68, 0x437f0000, v68
	v_mul_f32_e32 v64, 0x437f0000, v64
	v_max_f32_e32 v68, 1.0, v68
	v_mul_f32_e32 v69, 0x437f0000, v69
	v_max_f32_e32 v64, 1.0, v64
	v_mul_f32_e32 v65, 0x437f0000, v65
	v_cvt_pk_u8_f32 v68, v68, 0, 0
	v_max_f32_e32 v69, 1.0, v69
	v_cvt_pk_u8_f32 v64, v64, 0, 0
	v_max_f32_e32 v65, 1.0, v65
	v_cvt_pk_u8_f32 v68, v69, 1, v68
	v_mul_f32_e32 v69, 0x437f0000, v70
	v_cvt_pk_u8_f32 v64, v65, 1, v64
	v_mul_f32_e32 v65, 0x437f0000, v66
	v_max_f32_e32 v69, 1.0, v69
	v_max_f32_e32 v65, 1.0, v65
	v_cvt_pk_u8_f32 v68, v69, 2, v68
	v_mul_f32_e32 v69, 0x437f0000, v71
	v_cvt_pk_u8_f32 v64, v65, 2, v64
	v_mul_f32_e32 v65, 0x437f0000, v67
	v_max_f32_e32 v69, 1.0, v69
	v_max_f32_e32 v65, 1.0, v65
	v_cvt_pk_u8_f32 v68, v69, 3, v68
	v_cvt_pk_u8_f32 v69, v65, 3, v64
	global_store_dwordx2 v[72:73], v[68:69], off offset:128

; DI unsigned pk2(float lo, float hi) { f32x2 v = {lo, hi}; bf16x2_t b = __builtin_convertvector(v, bf16x2_t); return __builtin_bit_cast(unsigned, b); }
; DI float sigmoidf_(float x) { return __builtin_amdgcn_rcpf(1.0f + __builtin_amdgcn_exp2f(x * -1.4426950408889634f)); }
;     DI void operator()(const AccT& acc, const Unit& u, int wr, int wc, int fr, int fq) const {
;     ...
;             for (int m = 0; m < 4; ++m) { bf16_t* rowp = base + (size_t)(row0 + ai * HALF + m * 16) * ldc + col0;
; #pragma unroll
;                 for (int bj = 0; bj < 2; ++bj) { f32x4 v0 = acc[ai][bj][m][0] + bv[bj][0], v1 = acc[ai][bj][m][1] + bv[bj][1];
;                     if (gate) {
; #pragma unroll
;                         for (int j = 0; j < 4; ++j) { v0[j] = sigmoidf_(v0[j]); v1[j] = sigmoidf_(v1[j]); } }
;                     if (gate) {
;                         u32x2 q; q.x = pack_gate4(v0[0], v0[1], v0[2], v0[3]); q.y = pack_gate4(v1[0], v1[1], v1[2], v1[3]);
;                         *(u32x2*)((unsigned char*)G + (size_t)(row0 + ai * HALF + m * 16) * NGATE + col0 + bj * HALF) = q;
;                     } else {
;                         u32x4 w; w.x = pk2(v0[0], v0[1]); w.y = pk2(v0[2], v0[3]); w.z = pk2(v1[0], v1[1]); w.w = pk2(v1[2], v1[3]);
;                         *(u32x4*)(rowp + bj * HALF) = w; } } }
.LBB0_240:
	v_add_u32_e32 v48, 0x90, v176
	v_ashrrev_i32_e32 v49, 31, v48
	v_mul_lo_u32 v49, s30, v49
	v_mul_lo_u32 v68, s31, v48
	v_mad_u64_u32 v[50:51], s[2:3], s30, v48, 0
	v_add3_u32 v51, v51, v49, v68
	v_lshl_add_u64 v[50:51], v[50:51], 1, v[136:137]
	s_and_b64 vcc, exec, s[36:37]
	s_mov_b64 s[2:3], -1
	s_cbranch_vccnz .LBB0_242
	v_cvt_pk_bf16_f32 v68, v66, v67
	v_cvt_pk_bf16_f32 v69, v54, v55
	v_cvt_pk_bf16_f32 v70, v64, v65
	v_cvt_pk_bf16_f32 v71, v52, v53
	s_mov_b64 s[2:3], 0
	global_store_dwordx4 v[50:51], v[68:71], off
.LBB0_242:
	v_mad_i64_i32 v[48:49], s[22:23], v48, s20, 0
	v_lshl_add_u64 v[48:49], s[4:5], 0, v[48:49]
	s_andn2_b64 vcc, exec, s[2:3]
	v_lshl_add_u64 v[48:49], v[48:49], 0, v[154:155]
	s_cbranch_vccnz .LBB0_244
	v_mul_f32_e32 v66, 0x437f0000, v66
	v_max_f32_e32 v66, 1.0, v66
	v_mul_f32_e32 v67, 0x437f0000, v67
	v_cvt_pk_u8_f32 v66, v66, 0, 0
	v_max_f32_e32 v67, 1.0, v67
	v_mul_f32_e32 v54, 0x437f0000, v54
	v_cvt_pk_u8_f32 v66, v67, 1, v66
	v_max_f32_e32 v54, 1.0, v54
	v_mul_f32_e32 v55, 0x437f0000, v55
	v_cvt_pk_u8_f32 v54, v54, 2, v66
	v_max_f32_e32 v55, 1.0, v55
	v_cvt_pk_u8_f32 v54, v55, 3, v54
	v_mul_f32_e32 v55, 0x437f0000, v64
	v_max_f32_e32 v55, 1.0, v55
	v_mul_f32_e32 v64, 0x437f0000, v65
	v_cvt_pk_u8_f32 v55, v55, 0, 0
	v_max_f32_e32 v64, 1.0, v64
	v_mul_f32_e32 v52, 0x437f0000, v52
	v_cvt_pk_u8_f32 v55, v64, 1, v55
	v_max_f32_e32 v52, 1.0, v52
	v_mul_f32_e32 v53, 0x437f0000, v53
	v_cvt_pk_u8_f32 v52, v52, 2, v55
	v_max_f32_e32 v53, 1.0, v53
	v_cvt_pk_u8_f32 v55, v53, 3, v52
	global_store_dwordx2 v[48:49], v[54:55], off

; DI unsigned pk2(float lo, float hi) { f32x2 v = {lo, hi}; bf16x2_t b = __builtin_convertvector(v, bf16x2_t); return __builtin_bit_cast(unsigned, b); }
; DI float sigmoidf_(float x) { return __builtin_amdgcn_rcpf(1.0f + __builtin_amdgcn_exp2f(x * -1.4426950408889634f)); }
;     DI void operator()(const AccT& acc, const Unit& u, int wr, int wc, int fr, int fq) const {
;     ...
;                 for (int bj = 0; bj < 2; ++bj) { f32x4 v0 = acc[ai][bj][m][0] + bv[bj][0], v1 = acc[ai][bj][m][1] + bv[bj][1];
;                     if (gate) {
; #pragma unroll
;                         for (int j = 0; j < 4; ++j) { v0[j] = sigmoidf_(v0[j]); v1[j] = sigmoidf_(v1[j]); } }
;                     if (gate) {
;                         u32x2 q; q.x = pack_gate4(v0[0], v0[1], v0[2], v0[3]); q.y = pack_gate4(v1[0], v1[1], v1[2], v1[3]);
;                         *(u32x2*)((unsigned char*)G + (size_t)(row0 + ai * HALF + m * 16) * NGATE + col0 + bj * HALF) = q;
;                     } else {
;                         u32x4 w; w.x = pk2(v0[0], v0[1]); w.y = pk2(v0[2], v0[3]); w.z = pk2(v1[0], v1[1]); w.w = pk2(v1[2], v1[3]);
;                         *(u32x4*)(rowp + bj * HALF) = w; } } }
.LBB0_247:
	v_cvt_pk_bf16_f32 v52, v36, v37
	v_cvt_pk_bf16_f32 v53, v38, v39
	v_cvt_pk_bf16_f32 v54, v32, v33
	v_cvt_pk_bf16_f32 v55, v34, v35
	global_store_dwordx4 v[50:51], v[52:55], off offset:256
	s_cbranch_execz .LBB0_251
	s_branch .LBB0_252

; DI unsigned pack_gate4(float a, float b, float c, float d) {
;     unsigned w = 0u;
;     w = __builtin_amdgcn_cvt_pk_u8_f32(fmaxf(a * 255.f, 1.f), 0, w); w = __builtin_amdgcn_cvt_pk_u8_f32(fmaxf(b * 255.f, 1.f), 1, w);
;     w = __builtin_amdgcn_cvt_pk_u8_f32(fmaxf(c * 255.f, 1.f), 2, w); w = __builtin_amdgcn_cvt_pk_u8_f32(fmaxf(d * 255.f, 1.f), 3, w);
;     return w;
; }
;     DI void operator()(const AccT& acc, const Unit& u, int wr, int wc, int fr, int fq) const {
;     ...
;                     if (gate) {
;                         u32x2 q; q.x = pack_gate4(v0[0], v0[1], v0[2], v0[3]); q.y = pack_gate4(v1[0], v1[1], v1[2], v1[3]);
;                         *(u32x2*)((unsigned char*)G + (size_t)(row0 + ai * HALF + m * 16) * NGATE + col0 + bj * HALF) = q;
.LBB0_251:
	v_mul_f32_e32 v36, 0x437f0000, v36
	v_mul_f32_e32 v32, 0x437f0000, v32
	v_max_f32_e32 v36, 1.0, v36
	v_mul_f32_e32 v37, 0x437f0000, v37
	v_max_f32_e32 v32, 1.0, v32
	v_mul_f32_e32 v33, 0x437f0000, v33
	v_cvt_pk_u8_f32 v36, v36, 0, 0
	v_max_f32_e32 v37, 1.0, v37
	v_cvt_pk_u8_f32 v32, v32, 0, 0
	v_max_f32_e32 v33, 1.0, v33
	v_cvt_pk_u8_f32 v36, v37, 1, v36
	v_mul_f32_e32 v37, 0x437f0000, v38
	v_cvt_pk_u8_f32 v32, v33, 1, v32
	v_mul_f32_e32 v33, 0x437f0000, v34
	v_max_f32_e32 v37, 1.0, v37
	v_max_f32_e32 v33, 1.0, v33
	v_cvt_pk_u8_f32 v36, v37, 2, v36
	v_mul_f32_e32 v37, 0x437f0000, v39
	v_cvt_pk_u8_f32 v32, v33, 2, v32
	v_mul_f32_e32 v33, 0x437f0000, v35
	v_max_f32_e32 v37, 1.0, v37
	v_max_f32_e32 v33, 1.0, v33
	v_cvt_pk_u8_f32 v36, v37, 3, v36
	v_cvt_pk_u8_f32 v37, v33, 3, v32
	global_store_dwordx2 v[48:49], v[36:37], off offset:128

; DI unsigned pk2(float lo, float hi) { f32x2 v = {lo, hi}; bf16x2_t b = __builtin_convertvector(v, bf16x2_t); return __builtin_bit_cast(unsigned, b); }
; DI float sigmoidf_(float x) { return __builtin_amdgcn_rcpf(1.0f + __builtin_amdgcn_exp2f(x * -1.4426950408889634f)); }
;     DI void operator()(const AccT& acc, const Unit& u, int wr, int wc, int fr, int fq) const {
;     ...
;             for (int m = 0; m < 4; ++m) { bf16_t* rowp = base + (size_t)(row0 + ai * HALF + m * 16) * ldc + col0;
; #pragma unroll
;                 for (int bj = 0; bj < 2; ++bj) { f32x4 v0 = acc[ai][bj][m][0] + bv[bj][0], v1 = acc[ai][bj][m][1] + bv[bj][1];
;                     if (gate) {
; #pragma unroll
;                         for (int j = 0; j < 4; ++j) { v0[j] = sigmoidf_(v0[j]); v1[j] = sigmoidf_(v1[j]); } }
;                     if (gate) {
;                         u32x2 q; q.x = pack_gate4(v0[0], v0[1], v0[2], v0[3]); q.y = pack_gate4(v1[0], v1[1], v1[2], v1[3]);
;                         *(u32x2*)((unsigned char*)G + (size_t)(row0 + ai * HALF + m * 16) * NGATE + col0 + bj * HALF) = q;
;                     } else {
;                         u32x4 w; w.x = pk2(v0[0], v0[1]); w.y = pk2(v0[2], v0[3]); w.z = pk2(v1[0], v1[1]); w.w = pk2(v1[2], v1[3]);
;                         *(u32x4*)(rowp + bj * HALF) = w; } } }
.LBB0_256:
	v_add_u32_e32 v24, 0xa0, v176
	v_ashrrev_i32_e32 v25, 31, v24
	v_mul_lo_u32 v25, s30, v25
	v_mul_lo_u32 v36, s31, v24
	v_mad_u64_u32 v[26:27], s[2:3], s30, v24, 0
	v_add3_u32 v27, v27, v25, v36
	v_lshl_add_u64 v[26:27], v[26:27], 1, v[136:137]
	s_and_b64 vcc, exec, s[36:37]
	s_mov_b64 s[2:3], -1
	s_cbranch_vccnz .LBB0_258
	v_cvt_pk_bf16_f32 v36, v34, v35
	v_cvt_pk_bf16_f32 v37, v30, v31
	v_cvt_pk_bf16_f32 v38, v32, v33
	v_cvt_pk_bf16_f32 v39, v28, v29
	s_mov_b64 s[2:3], 0
	global_store_dwordx4 v[26:27], v[36:39], off
.LBB0_258:
	v_mad_i64_i32 v[24:25], s[22:23], v24, s20, 0
	v_lshl_add_u64 v[24:25], s[4:5], 0, v[24:25]
	s_andn2_b64 vcc, exec, s[2:3]
	v_lshl_add_u64 v[24:25], v[24:25], 0, v[154:155]
	s_cbranch_vccnz .LBB0_260
	v_mul_f32_e32 v34, 0x437f0000, v34
	v_max_f32_e32 v34, 1.0, v34
	v_mul_f32_e32 v35, 0x437f0000, v35
	v_cvt_pk_u8_f32 v34, v34, 0, 0
	v_max_f32_e32 v35, 1.0, v35
	v_mul_f32_e32 v30, 0x437f0000, v30
	v_cvt_pk_u8_f32 v34, v35, 1, v34
	v_max_f32_e32 v30, 1.0, v30
	v_mul_f32_e32 v31, 0x437f0000, v31
	v_cvt_pk_u8_f32 v30, v30, 2, v34
	v_max_f32_e32 v31, 1.0, v31
	v_cvt_pk_u8_f32 v30, v31, 3, v30
	v_mul_f32_e32 v31, 0x437f0000, v32
	v_max_f32_e32 v31, 1.0, v31
	v_mul_f32_e32 v32, 0x437f0000, v33
	v_cvt_pk_u8_f32 v31, v31, 0, 0
	v_max_f32_e32 v32, 1.0, v32
	v_mul_f32_e32 v28, 0x437f0000, v28
	v_cvt_pk_u8_f32 v31, v32, 1, v31
	v_max_f32_e32 v28, 1.0, v28
	v_mul_f32_e32 v29, 0x437f0000, v29
	v_cvt_pk_u8_f32 v28, v28, 2, v31
	v_max_f32_e32 v29, 1.0, v29
	v_cvt_pk_u8_f32 v31, v29, 3, v28
	global_store_dwordx2 v[24:25], v[30:31], off

; DI unsigned pk2(float lo, float hi) { f32x2 v = {lo, hi}; bf16x2_t b = __builtin_convertvector(v, bf16x2_t); return __builtin_bit_cast(unsigned, b); }
; DI float sigmoidf_(float x) { return __builtin_amdgcn_rcpf(1.0f + __builtin_amdgcn_exp2f(x * -1.4426950408889634f)); }
;     DI void operator()(const AccT& acc, const Unit& u, int wr, int wc, int fr, int fq) const {
;     ...
;                 for (int bj = 0; bj < 2; ++bj) { f32x4 v0 = acc[ai][bj][m][0] + bv[bj][0], v1 = acc[ai][bj][m][1] + bv[bj][1];
;                     if (gate) {
; #pragma unroll
;                         for (int j = 0; j < 4; ++j) { v0[j] = sigmoidf_(v0[j]); v1[j] = sigmoidf_(v1[j]); } }
;                     if (gate) {
;                         u32x2 q; q.x = pack_gate4(v0[0], v0[1], v0[2], v0[3]); q.y = pack_gate4(v1[0], v1[1], v1[2], v1[3]);
;                         *(u32x2*)((unsigned char*)G + (size_t)(row0 + ai * HALF + m * 16) * NGATE + col0 + bj * HALF) = q;
;                     } else {
;                         u32x4 w; w.x = pk2(v0[0], v0[1]); w.y = pk2(v0[2], v0[3]); w.z = pk2(v1[0], v1[1]); w.w = pk2(v1[2], v1[3]);
;                         *(u32x4*)(rowp + bj * HALF) = w; } } }
.LBB0_263:
	v_cvt_pk_bf16_f32 v28, v20, v21
	v_cvt_pk_bf16_f32 v29, v22, v23
	v_cvt_pk_bf16_f32 v30, v16, v17
	v_cvt_pk_bf16_f32 v31, v18, v19
	global_store_dwordx4 v[26:27], v[28:31], off offset:256
	s_cbranch_execz .LBB0_267
	s_branch .LBB0_268

; DI unsigned pack_gate4(float a, float b, float c, float d) {
;     unsigned w = 0u;
;     w = __builtin_amdgcn_cvt_pk_u8_f32(fmaxf(a * 255.f, 1.f), 0, w); w = __builtin_amdgcn_cvt_pk_u8_f32(fmaxf(b * 255.f, 1.f), 1, w);
;     w = __builtin_amdgcn_cvt_pk_u8_f32(fmaxf(c * 255.f, 1.f), 2, w); w = __builtin_amdgcn_cvt_pk_u8_f32(fmaxf(d * 255.f, 1.f), 3, w);
;     return w;
; }
;     DI void operator()(const AccT& acc, const Unit& u, int wr, int wc, int fr, int fq) const {
;     ...
;                     if (gate) {
;                         u32x2 q; q.x = pack_gate4(v0[0], v0[1], v0[2], v0[3]); q.y = pack_gate4(v1[0], v1[1], v1[2], v1[3]);
;                         *(u32x2*)((unsigned char*)G + (size_t)(row0 + ai * HALF + m * 16) * NGATE + col0 + bj * HALF) = q;
.LBB0_267:
	v_mul_f32_e32 v20, 0x437f0000, v20
	v_mul_f32_e32 v16, 0x437f0000, v16
	v_max_f32_e32 v20, 1.0, v20
	v_mul_f32_e32 v21, 0x437f0000, v21
	v_max_f32_e32 v16, 1.0, v16
	v_mul_f32_e32 v17, 0x437f0000, v17
	v_cvt_pk_u8_f32 v20, v20, 0, 0
	v_max_f32_e32 v21, 1.0, v21
	v_cvt_pk_u8_f32 v16, v16, 0, 0
	v_max_f32_e32 v17, 1.0, v17
	v_cvt_pk_u8_f32 v20, v21, 1, v20
	v_mul_f32_e32 v21, 0x437f0000, v22
	v_cvt_pk_u8_f32 v16, v17, 1, v16
	v_mul_f32_e32 v17, 0x437f0000, v18
	v_max_f32_e32 v21, 1.0, v21
	v_max_f32_e32 v17, 1.0, v17
	v_cvt_pk_u8_f32 v20, v21, 2, v20
	v_mul_f32_e32 v21, 0x437f0000, v23
	v_cvt_pk_u8_f32 v16, v17, 2, v16
	v_mul_f32_e32 v17, 0x437f0000, v19
	v_max_f32_e32 v21, 1.0, v21
	v_max_f32_e32 v17, 1.0, v17
	v_cvt_pk_u8_f32 v20, v21, 3, v20
	v_cvt_pk_u8_f32 v21, v17, 3, v16
	global_store_dwordx2 v[24:25], v[20:21], off offset:128

; DI unsigned pk2(float lo, float hi) { f32x2 v = {lo, hi}; bf16x2_t b = __builtin_convertvector(v, bf16x2_t); return __builtin_bit_cast(unsigned, b); }
; DI float sigmoidf_(float x) { return __builtin_amdgcn_rcpf(1.0f + __builtin_amdgcn_exp2f(x * -1.4426950408889634f)); }
;     DI void operator()(const AccT& acc, const Unit& u, int wr, int wc, int fr, int fq) const {
;     ...
;             for (int m = 0; m < 4; ++m) { bf16_t* rowp = base + (size_t)(row0 + ai * HALF + m * 16) * ldc + col0;
; #pragma unroll
;                 for (int bj = 0; bj < 2; ++bj) { f32x4 v0 = acc[ai][bj][m][0] + bv[bj][0], v1 = acc[ai][bj][m][1] + bv[bj][1];
;                     if (gate) {
; #pragma unroll
;                         for (int j = 0; j < 4; ++j) { v0[j] = sigmoidf_(v0[j]); v1[j] = sigmoidf_(v1[j]); } }
;                     if (gate) {
;                         u32x2 q; q.x = pack_gate4(v0[0], v0[1], v0[2], v0[3]); q.y = pack_gate4(v1[0], v1[1], v1[2], v1[3]);
;                         *(u32x2*)((unsigned char*)G + (size_t)(row0 + ai * HALF + m * 16) * NGATE + col0 + bj * HALF) = q;
;                     } else {
;                         u32x4 w; w.x = pk2(v0[0], v0[1]); w.y = pk2(v0[2], v0[3]); w.z = pk2(v1[0], v1[1]); w.w = pk2(v1[2], v1[3]);
;                         *(u32x4*)(rowp + bj * HALF) = w; } } }
.LBB0_272:
	v_add_u32_e32 v8, 0xb0, v176
	v_ashrrev_i32_e32 v9, 31, v8
	v_mul_lo_u32 v9, s30, v9
	v_mul_lo_u32 v20, s31, v8
	v_mad_u64_u32 v[10:11], s[2:3], s30, v8, 0
	v_add3_u32 v11, v11, v9, v20
	v_lshl_add_u64 v[10:11], v[10:11], 1, v[136:137]
	s_and_b64 vcc, exec, s[36:37]
	s_mov_b64 s[2:3], -1
	s_cbranch_vccnz .LBB0_274
	v_cvt_pk_bf16_f32 v20, v18, v19
	v_cvt_pk_bf16_f32 v21, v14, v15
	v_cvt_pk_bf16_f32 v22, v16, v17
	v_cvt_pk_bf16_f32 v23, v12, v13
	s_mov_b64 s[2:3], 0
	global_store_dwordx4 v[10:11], v[20:23], off
.LBB0_274:
	v_mad_i64_i32 v[8:9], s[22:23], v8, s20, 0
	v_lshl_add_u64 v[8:9], s[4:5], 0, v[8:9]
	s_andn2_b64 vcc, exec, s[2:3]
	v_lshl_add_u64 v[8:9], v[8:9], 0, v[154:155]
	s_cbranch_vccnz .LBB0_276
	v_mul_f32_e32 v18, 0x437f0000, v18
	v_max_f32_e32 v18, 1.0, v18
	v_mul_f32_e32 v19, 0x437f0000, v19
	v_cvt_pk_u8_f32 v18, v18, 0, 0
	v_max_f32_e32 v19, 1.0, v19
	v_mul_f32_e32 v14, 0x437f0000, v14
	v_cvt_pk_u8_f32 v18, v19, 1, v18
	v_max_f32_e32 v14, 1.0, v14
	v_mul_f32_e32 v15, 0x437f0000, v15
	v_cvt_pk_u8_f32 v14, v14, 2, v18
	v_max_f32_e32 v15, 1.0, v15
	v_cvt_pk_u8_f32 v14, v15, 3, v14
	v_mul_f32_e32 v15, 0x437f0000, v16
	v_max_f32_e32 v15, 1.0, v15
	v_mul_f32_e32 v16, 0x437f0000, v17
	v_cvt_pk_u8_f32 v15, v15, 0, 0
	v_max_f32_e32 v16, 1.0, v16
	v_mul_f32_e32 v12, 0x437f0000, v12
	v_cvt_pk_u8_f32 v15, v16, 1, v15
	v_max_f32_e32 v12, 1.0, v12
	v_mul_f32_e32 v13, 0x437f0000, v13
	v_cvt_pk_u8_f32 v12, v12, 2, v15
	v_max_f32_e32 v13, 1.0, v13
	v_cvt_pk_u8_f32 v15, v13, 3, v12
	global_store_dwordx2 v[8:9], v[14:15], off

; DI unsigned pk2(float lo, float hi) { f32x2 v = {lo, hi}; bf16x2_t b = __builtin_convertvector(v, bf16x2_t); return __builtin_bit_cast(unsigned, b); }
; DI float sigmoidf_(float x) { return __builtin_amdgcn_rcpf(1.0f + __builtin_amdgcn_exp2f(x * -1.4426950408889634f)); }
;     DI void operator()(const AccT& acc, const Unit& u, int wr, int wc, int fr, int fq) const {
;     ...
;                 for (int bj = 0; bj < 2; ++bj) { f32x4 v0 = acc[ai][bj][m][0] + bv[bj][0], v1 = acc[ai][bj][m][1] + bv[bj][1];
;                     if (gate) {
; #pragma unroll
;                         for (int j = 0; j < 4; ++j) { v0[j] = sigmoidf_(v0[j]); v1[j] = sigmoidf_(v1[j]); } }
;                     if (gate) {
;                         u32x2 q; q.x = pack_gate4(v0[0], v0[1], v0[2], v0[3]); q.y = pack_gate4(v1[0], v1[1], v1[2], v1[3]);
;                         *(u32x2*)((unsigned char*)G + (size_t)(row0 + ai * HALF + m * 16) * NGATE + col0 + bj * HALF) = q;
;                     } else {
;                         u32x4 w; w.x = pk2(v0[0], v0[1]); w.y = pk2(v0[2], v0[3]); w.z = pk2(v1[0], v1[1]); w.w = pk2(v1[2], v1[3]);
;                         *(u32x4*)(rowp + bj * HALF) = w; } } }
.LBB0_279:
	v_cvt_pk_bf16_f32 v12, v4, v5
	v_cvt_pk_bf16_f32 v13, v6, v7
	v_cvt_pk_bf16_f32 v14, v0, v1
	v_cvt_pk_bf16_f32 v15, v2, v3
	global_store_dwordx4 v[10:11], v[12:15], off offset:256
	s_cbranch_execnz .LBB0_136
	s_branch .LBB0_283

; DI unsigned pack_gate4(float a, float b, float c, float d) {
;     unsigned w = 0u;
;     w = __builtin_amdgcn_cvt_pk_u8_f32(fmaxf(a * 255.f, 1.f), 0, w); w = __builtin_amdgcn_cvt_pk_u8_f32(fmaxf(b * 255.f, 1.f), 1, w);
;     w = __builtin_amdgcn_cvt_pk_u8_f32(fmaxf(c * 255.f, 1.f), 2, w); w = __builtin_amdgcn_cvt_pk_u8_f32(fmaxf(d * 255.f, 1.f), 3, w);
;     return w;
;     DI void operator()(const AccT& acc, const Unit& u, int wr, int wc, int fr, int fq) const {
;     ...
;                     if (gate) {
;                         u32x2 q; q.x = pack_gate4(v0[0], v0[1], v0[2], v0[3]); q.y = pack_gate4(v1[0], v1[1], v1[2], v1[3]);
;                         *(u32x2*)((unsigned char*)G + (size_t)(row0 + ai * HALF + m * 16) * NGATE + col0 + bj * HALF) = q;
.LBB0_283:
	v_mul_f32_e32 v4, 0x437f0000, v4
	v_mul_f32_e32 v0, 0x437f0000, v0
	v_max_f32_e32 v4, 1.0, v4
	v_mul_f32_e32 v5, 0x437f0000, v5
	v_max_f32_e32 v0, 1.0, v0
	v_mul_f32_e32 v1, 0x437f0000, v1
	v_cvt_pk_u8_f32 v4, v4, 0, 0
	v_max_f32_e32 v5, 1.0, v5
	v_cvt_pk_u8_f32 v0, v0, 0, 0
	v_max_f32_e32 v1, 1.0, v1
	v_cvt_pk_u8_f32 v4, v5, 1, v4
	v_mul_f32_e32 v5, 0x437f0000, v6
	v_cvt_pk_u8_f32 v0, v1, 1, v0
	v_mul_f32_e32 v1, 0x437f0000, v2
	v_max_f32_e32 v5, 1.0, v5
	v_max_f32_e32 v1, 1.0, v1
	v_cvt_pk_u8_f32 v4, v5, 2, v4
	v_mul_f32_e32 v5, 0x437f0000, v7
	v_cvt_pk_u8_f32 v0, v1, 2, v0
	v_mul_f32_e32 v1, 0x437f0000, v3
	v_max_f32_e32 v5, 1.0, v5
	v_max_f32_e32 v1, 1.0, v1
	v_cvt_pk_u8_f32 v4, v5, 3, v4
	v_cvt_pk_u8_f32 v5, v1, 3, v0
	global_store_dwordx2 v[8:9], v[4:5], off offset:128
	s_branch .LBB0_136

; DI void post_token(int tok, int lane, LAS float* cs  , const bf16_t* P, const int* positions,
;                    const float* gq, const float* gk, const float* gmq, const float* cinb,
;                    bf16_t* Q, bf16_t* Kb, bf16_t* IQ, bf16_t* IK, float* IW, bf16_t* U, bf16_t* MQ) {
;     const bf16_t* prow = P + (size_t)tok * NPROJ;
;     const u32x4 rq0 = *(const u32x4*)(prow + PC_Q + 16 * lane), rq1 = *(const u32x4*)(prow + PC_Q + 16 * lane + 8);
;     const u32x4 rk0 = *(const u32x4*)(prow + PC_K + 16 * (lane & 15)), rk1 = *(const u32x4*)(prow + PC_K + 16 * (lane & 15) + 8);
;     const u32x4 ri0 = *(const u32x4*)(prow + PC_IQ + 16 * lane), ri1 = *(const u32x4*)(prow + PC_IQ + 16 * lane + 8);
;     const u32x4 rj0 = *(const u32x4*)(prow + PC_IK + 16 * (lane & 3)), rj1 = *(const u32x4*)(prow + PC_IK + 16 * (lane & 3) + 8);
;     const unsigned short rw = prow[PC_IW + (lane & 15)];
;     const u32x4 rga = *(const u32x4*)(prow + PC_GLU + 8 * lane), rgg = *(const u32x4*)(prow + PC_GLU + 512 + 8 * lane);
;     const u32x4 rm0 = *(const u32x4*)(prow + PC_MQ + 16 * (lane & 31)), rm1 = *(const u32x4*)(prow + PC_MQ + 16 * (lane & 31) + 8);
;     const int posv = positions[tok];
;     if (lane < 16) {
;         const float inv = exp2f(-(float)lane * (1.0f / 16.0f) * 18.931568569324174f);
;         const float ang = (float)posv * inv;
;         const double xd = (double)ang; const double kq = rint(xd * 0.15915494309189535); const float rf = (float)fma(-kq, 6.283185307179586, xd);
;         cs[lane] = __cosf(rf); cs[16 + lane] = __sinf(rf);
;     }
.LBB0_343:
	v_lshl_add_u64 v[0:1], s[44:45], 0, v[88:89]
	v_add_co_u32_e32 v0, vcc, 0x13d00000, v0
	v_lshl_add_u64 v[2:3], s[44:45], 0, v[90:91]
	s_nop 0
	v_addc_co_u32_e32 v1, vcc, 0, v1, vcc
	v_add_co_u32_e32 v2, vcc, 0x13d00000, v2
	global_load_dwordx4 v[48:51], v[0:1], off
	global_load_dwordx4 v[40:43], v[0:1], off offset:16
	v_addc_co_u32_e32 v3, vcc, 0, v3, vcc
	global_load_dwordx4 v[36:39], v[2:3], off offset:2048
	global_load_dwordx4 v[32:35], v[2:3], off offset:2064
	global_load_dwordx4 v[24:27], v[0:1], off offset:3072
	global_load_dwordx4 v[28:31], v[0:1], off offset:3088
	v_lshl_add_u64 v[0:1], s[44:45], 0, v[98:99]
	v_add_co_u32_e32 v0, vcc, 0x13d01000, v0
	v_lshl_add_u64 v[2:3], s[44:45], 0, v[94:95]
	s_nop 0
	v_addc_co_u32_e32 v1, vcc, 0, v1, vcc
	s_waitcnt lgkmcnt(0)
	global_load_dwordx4 v[16:19], v[0:1], off offset:1024
	global_load_dwordx4 v[20:23], v[0:1], off offset:1040
	v_lshl_add_u64 v[0:1], s[44:45], 0, v[96:97]
	v_add_co_u32_e32 v2, vcc, 0x13d01000, v2
	s_nop 1
	v_addc_co_u32_e32 v3, vcc, 0, v3, vcc
	global_load_ushort v119, v[0:1], off
	global_load_dwordx4 v[8:11], v[2:3], off offset:1536
	v_lshl_add_u64 v[0:1], s[44:45], 0, v[92:93]
	v_add_co_u32_e32 v0, vcc, 0x13d01000, v0
	s_nop 1
	v_addc_co_u32_e32 v1, vcc, 0, v1, vcc
	global_load_dwordx4 v[12:15], v[2:3], off offset:2560
	global_load_dwordx4 v[4:7], v[0:1], off offset:3584
	s_nop 0
	global_load_dwordx4 v[0:3], v[0:1], off offset:3600
	s_and_saveexec_b64 s[0:1], s[38:39]
	s_cbranch_execz .LBB0_345
	global_load_dword v44, v161, s[30:31]
	s_mov_b32 s2, 0x6dc9c883
	s_mov_b32 s3, 0x3fc45f30
	s_waitcnt vmcnt(0)
	v_cvt_f32_i32_e32 v44, v44
	v_mul_f32_e32 v44, v114, v44
	v_cvt_f64_f32_e32 v[44:45], v44
	v_mul_f64 v[46:47], v[44:45], s[2:3]
	s_mov_b32 s2, 0x54442d18
	v_rndne_f64_e32 v[46:47], v[46:47]
	s_mov_b32 s3, 0xc01921fb
	v_fmac_f64_e32 v[44:45], s[2:3], v[46:47]
	v_cvt_f32_f64_e32 v44, v[44:45]
	v_mul_f32_e32 v44, 0.15915494, v44
	v_cos_f32_e32 v45, v44
	v_sin_f32_e32 v44, v44
	ds_write2_b32 v115, v45, v44 offset1:16

; DI void store16(bf16_t* p, const float* v) { *(u32x4*)p = pack8(v); *(u32x4*)(p + 8) = pack8(v + 8); }
; DI void post_token(int tok, int lane, LAS float* cs  , const bf16_t* P, const int* positions,
;                    const float* gq, const float* gk, const float* gmq, const float* cinb,
;                    bf16_t* Q, bf16_t* Kb, bf16_t* IQ, bf16_t* IK, float* IW, bf16_t* U, bf16_t* MQ) {
;     ...
;         store16(Q + (size_t)tok * 1024 + 16 * lane, v);
;     }
;     {
;         const int ln = lane & 15;
;         unpack8(rk0, v); unpack8(rk1, v + 8);
;         float ss = 0.f;
; #pragma unroll
;         for (int i = 0; i < 16; ++i) ss += v[i] * v[i];
;         ss += __shfl_xor(ss, 1); ss += __shfl_xor(ss, 2); ss += __shfl_xor(ss, 4);
;         const float rs = rsqrtf(ss * (1.f / 128.f) + EPS_);
;         const int d0 = 16 * (ln & 7);
; #pragma unroll
;         for (int i = 0; i < 16; ++i) v[i] = v[i] * rs * gk[d0 + i];
;         const int sub = ln & 7;
; #pragma unroll
;         for (int i = 0; i < 16; ++i) { const float oth = __shfl_xor(v[i], 1); const float c = cs[i], s = cs[16 + i];
;             if (sub == 0) v[i] = v[i] * c - oth * s; else if (sub == 1) v[i] = v[i] * c + oth * s; }
.LBB0_441:
	s_or_b64 exec, exec, s[0:1]
	v_lshl_add_u64 v[56:57], s[44:45], 0, v[86:87]
	s_mov_b32 s0, 0x1c500000
	s_waitcnt lgkmcnt(0)
	v_cvt_pk_bf16_f32 v47, v52, v53
	v_add_co_u32_e32 v52, vcc, s0, v56
	v_cvt_pk_bf16_f32 v44, v100, v101
	v_cvt_pk_bf16_f32 v45, v62, v63
	v_cvt_pk_bf16_f32 v46, v60, v61
	v_addc_co_u32_e32 v53, vcc, 0, v57, vcc
	global_store_dwordx4 v[52:53], v[44:47], off
	v_lshlrev_b32_e32 v58, 16, v36
	v_and_b32_e32 v59, 0xffff0000, v36
	v_cvt_pk_bf16_f32 v44, v50, v51
	v_cvt_pk_bf16_f32 v45, v48, v49
	v_cvt_pk_bf16_f32 v46, v42, v43
	v_cvt_pk_bf16_f32 v47, v40, v41
	global_store_dwordx4 v[52:53], v[44:47], off offset:16
	global_load_dwordx4 v[52:55], v[70:71], off
	s_nop 0
	global_load_dwordx4 v[48:51], v[70:71], off offset:16
	global_load_dwordx4 v[40:43], v[70:71], off offset:48
	global_load_dwordx4 v[44:47], v[70:71], off offset:32
	v_pk_mul_f32 v[60:61], v[58:59], v[58:59]
	v_lshlrev_b32_e32 v36, 16, v37
	v_and_b32_e32 v37, 0xffff0000, v37
	v_pk_mul_f32 v[106:107], v[36:37], v[36:37]
	v_add_f32_e32 v60, v60, v61
	v_lshlrev_b32_e32 v62, 16, v38
	v_and_b32_e32 v63, 0xffff0000, v38
	v_add_f32_e32 v60, v106, v60
	v_pk_mul_f32 v[108:109], v[62:63], v[62:63]
	v_add_f32_e32 v60, v107, v60
	v_lshlrev_b32_e32 v38, 16, v39
	v_and_b32_e32 v39, 0xffff0000, v39
	v_add_f32_e32 v60, v108, v60
	v_pk_mul_f32 v[110:111], v[38:39], v[38:39]
	v_add_f32_e32 v60, v109, v60
	v_lshlrev_b32_e32 v100, 16, v32
	v_and_b32_e32 v101, 0xffff0000, v32
	v_add_f32_e32 v60, v110, v60
	v_pk_mul_f32 v[112:113], v[100:101], v[100:101]
	v_add_f32_e32 v60, v111, v60
	v_lshlrev_b32_e32 v32, 16, v33
	v_and_b32_e32 v33, 0xffff0000, v33
	v_add_f32_e32 v60, v112, v60
	v_pk_mul_f32 v[120:121], v[32:33], v[32:33]
	v_add_f32_e32 v60, v113, v60
	v_lshlrev_b32_e32 v104, 16, v34
	v_and_b32_e32 v105, 0xffff0000, v34
	v_add_f32_e32 v60, v120, v60
	v_pk_mul_f32 v[122:123], v[104:105], v[104:105]
	v_add_f32_e32 v60, v121, v60
	v_lshlrev_b32_e32 v102, 16, v35
	v_and_b32_e32 v103, 0xffff0000, v35
	v_add_f32_e32 v60, v122, v60
	v_pk_mul_f32 v[34:35], v[102:103], v[102:103]
	v_add_f32_e32 v60, v123, v60
	v_add_f32_e32 v34, v34, v60
	v_add_f32_e32 v34, v35, v34
	ds_bpermute_b32 v35, v67, v34
	s_waitcnt lgkmcnt(0)
	v_add_f32_e32 v34, v34, v35
	ds_bpermute_b32 v35, v118, v34
	s_waitcnt lgkmcnt(0)
	v_add_f32_e32 v34, v34, v35
	ds_bpermute_b32 v35, v117, v34
	s_waitcnt lgkmcnt(0)
	v_add_f32_e32 v34, v34, v35
	v_fmamk_f32 v34, v34, 0x3c000000, v187
	v_mul_f32_e32 v35, 0x4b800000, v34
	v_cmp_gt_f32_e32 vcc, s97, v34
	s_nop 1
	v_cndmask_b32_e32 v34, v34, v35, vcc
	v_rsq_f32_e32 v34, v34
	s_nop 0
	v_mul_f32_e32 v35, 0x45800000, v34
	v_cndmask_b32_e32 v106, v34, v35, vcc
	v_mov_b32_e32 v107, v106
	v_pk_mul_f32 v[34:35], v[106:107], v[58:59] op_sel_hi:[0,1]
	v_pk_mul_f32 v[32:33], v[106:107], v[32:33]
	v_cmp_lt_i32_e32 vcc, 0, v116
	s_waitcnt vmcnt(0)
	v_pk_mul_f32 v[58:59], v[52:53], v[34:35]
	v_pk_mul_f32 v[34:35], v[106:107], v[36:37]
	ds_bpermute_b32 v61, v67, v58
	v_pk_mul_f32 v[54:55], v[54:55], v[34:35]
	v_pk_mul_f32 v[34:35], v[106:107], v[62:63]
	v_pk_mul_f32 v[36:37], v[32:33], v[46:47]
	v_pk_mul_f32 v[52:53], v[48:49], v[34:35]
	v_pk_mul_f32 v[34:35], v[106:107], v[38:39]
	v_pk_mul_f32 v[32:33], v[106:107], v[104:105]
	v_pk_mul_f32 v[48:49], v[50:51], v[34:35]
	v_pk_mul_f32 v[34:35], v[106:107], v[100:101]
	s_nop 0
	v_pk_mul_f32 v[38:39], v[44:45], v[34:35]
	v_mov_b32_e32 v34, s5
	ds_read2_b32 v[44:45], v34 offset1:16
	v_pk_mul_f32 v[34:35], v[32:33], v[40:41]
	v_pk_mul_f32 v[32:33], v[106:107], v[102:103]
	s_nop 0
	v_pk_mul_f32 v[32:33], v[32:33], v[42:43]
	s_and_saveexec_b64 s[0:1], vcc
	s_xor_b64 s[0:1], exec, s[0:1]
	s_cbranch_execz .LBB0_445
	v_cmp_eq_u32_e32 vcc, 1, v116
	s_and_saveexec_b64 s[2:3], vcc
	s_cbranch_execz .LBB0_444
	v_mov_b32_e32 v60, v58
	s_waitcnt lgkmcnt(0)
	v_pk_mul_f32 v[40:41], v[60:61], v[44:45]
	s_nop 0
	v_add_f32_e32 v58, v40, v41

; DI void store16(bf16_t* p, const float* v) { *(u32x4*)p = pack8(v); *(u32x4*)(p + 8) = pack8(v + 8); }
; DI void post_token(int tok, int lane, LAS float* cs  , const bf16_t* P, const int* positions,
;                    const float* gq, const float* gk, const float* gmq, const float* cinb,
;                    bf16_t* Q, bf16_t* Kb, bf16_t* IQ, bf16_t* IK, float* IW, bf16_t* U, bf16_t* MQ) {
;     ...
;         for (int i = 0; i < 16; ++i) { const float oth = __shfl_xor(v[i], 1); const float c = cs[i], s = cs[16 + i];
;             if (sub == 0) v[i] = v[i] * c - oth * s; else if (sub == 1) v[i] = v[i] * c + oth * s; }
;         if (lane < 16) store16(Kb + (size_t)tok * 256 + 16 * ln, v);
.LBB0_536:
	v_lshl_add_u64 v[44:45], s[44:45], 0, v[76:77]
	v_add_co_u32_e32 v44, vcc, 0x20900000, v44
	v_cvt_pk_bf16_f32 v40, v58, v59
	s_waitcnt lgkmcnt(1)
	v_cvt_pk_bf16_f32 v41, v54, v55
	s_waitcnt lgkmcnt(0)
	v_cvt_pk_bf16_f32 v42, v52, v53
	v_cvt_pk_bf16_f32 v43, v48, v49
	v_addc_co_u32_e32 v45, vcc, 0, v45, vcc
	global_store_dwordx4 v[44:45], v[40:43], off
	v_cvt_pk_bf16_f32 v38, v38, v39
	v_cvt_pk_bf16_f32 v39, v36, v37
	v_cvt_pk_bf16_f32 v40, v34, v35
	v_cvt_pk_bf16_f32 v41, v32, v33
	global_store_dwordx4 v[44:45], v[38:41], off offset:16

; DI void store16(bf16_t* p, const float* v) { *(u32x4*)p = pack8(v); *(u32x4*)(p + 8) = pack8(v + 8); }
; DI void post_token(int tok, int lane, LAS float* cs  , const bf16_t* P, const int* positions,
;                    const float* gq, const float* gk, const float* gmq, const float* cinb,
;                    bf16_t* Q, bf16_t* Kb, bf16_t* IQ, bf16_t* IK, float* IW, bf16_t* U, bf16_t* MQ) {
;     ...
;         store16(IQ + (size_t)tok * 1024 + 16 * lane, v);
;     }
;     {
;         const int ln = lane & 3;
;         unpack8(rj0, v); unpack8(rj1, v + 8);
;         if (ln == 0) {
; #pragma unroll
;             for (int i = 0; i < 8; ++i) { const float c = cs[2 * i], s = cs[16 + 2 * i]; const float a = v[i], b = v[i + 8]; v[i] = a * c - b * s; v[i + 8] = b * c + a * s; }
;         }
.LBB0_539:
	s_or_b64 exec, exec, s[0:1]
	s_mov_b32 s0, 0x1e500000
	v_cvt_pk_bf16_f32 v45, v34, v37
	v_add_co_u32_e32 v34, vcc, s0, v56
	v_cvt_pk_bf16_f32 v42, v42, v43
	v_cvt_pk_bf16_f32 v43, v40, v41
	v_cvt_pk_bf16_f32 v44, v38, v39
	v_addc_co_u32_e32 v35, vcc, 0, v57, vcc
	v_cvt_pk_bf16_f32 v30, v32, v33
	v_cvt_pk_bf16_f32 v31, v24, v25
	v_cvt_pk_bf16_f32 v32, v28, v29
	v_cvt_pk_bf16_f32 v33, v26, v36
	global_store_dwordx4 v[34:35], v[42:45], off
	global_store_dwordx4 v[34:35], v[30:33], off offset:16
	v_lshlrev_b32_e32 v26, 16, v19
	v_lshlrev_b32_e32 v34, 16, v16
	v_and_b32_e32 v35, 0xffff0000, v16
	v_lshlrev_b32_e32 v24, 16, v20
	v_and_b32_e32 v25, 0xffff0000, v20
	v_lshlrev_b32_e32 v32, 16, v17
	v_and_b32_e32 v33, 0xffff0000, v17
	v_lshlrev_b32_e32 v16, 16, v21
	v_and_b32_e32 v17, 0xffff0000, v21
	v_lshlrev_b32_e32 v30, 16, v18
	v_and_b32_e32 v31, 0xffff0000, v18
	v_lshlrev_b32_e32 v20, 16, v22
	v_and_b32_e32 v21, 0xffff0000, v22
	v_lshlrev_b32_e32 v18, 16, v23
	v_and_b32_e32 v29, 0xffff0000, v19
	v_and_b32_e32 v28, 0xffff0000, v23
	s_and_saveexec_b64 s[0:1], s[40:41]
	s_cbranch_execz .LBB0_547
	v_mov_b32_e32 v19, s5
	ds_read2_b32 v[22:23], v19 offset0:16 offset1:18
	ds_read2_b32 v[36:37], v19 offset1:2
	ds_read2_b32 v[38:39], v19 offset0:4 offset1:6
	ds_read2_b32 v[40:41], v19 offset0:8 offset1:10
	ds_read2_b32 v[42:43], v19 offset0:12 offset1:14
	s_waitcnt lgkmcnt(0)
	v_pk_mul_f32 v[44:45], v[22:23], v[24:25]
	v_pk_mul_f32 v[22:23], v[22:23], v[34:35]
	v_pk_fma_f32 v[44:45], v[36:37], v[34:35], v[44:45] neg_lo:[0,0,1] neg_hi:[0,0,1]
	v_pk_fma_f32 v[24:25], v[36:37], v[24:25], v[22:23]
	ds_read2_b32 v[22:23], v19 offset0:20 offset1:22
	v_mov_b32_e32 v27, v29
	s_waitcnt lgkmcnt(0)
	v_pk_mul_f32 v[34:35], v[22:23], v[16:17]
	v_pk_mul_f32 v[22:23], v[22:23], v[32:33]
	v_pk_fma_f32 v[36:37], v[38:39], v[32:33], v[34:35] neg_lo:[0,0,1] neg_hi:[0,0,1]
	v_pk_fma_f32 v[16:17], v[38:39], v[16:17], v[22:23]
	ds_read2_b32 v[22:23], v19 offset0:24 offset1:26
	v_mov_b32_e32 v34, v44
	v_mov_b32_e32 v35, v45
	s_waitcnt lgkmcnt(0)
	v_pk_mul_f32 v[32:33], v[22:23], v[20:21]
	v_pk_mul_f32 v[22:23], v[22:23], v[30:31]
	v_pk_fma_f32 v[38:39], v[40:41], v[30:31], v[32:33] neg_lo:[0,0,1] neg_hi:[0,0,1]
	v_pk_fma_f32 v[20:21], v[40:41], v[20:21], v[22:23]
	ds_read2_b32 v[22:23], v19 offset0:28 offset1:30
	v_mov_b32_e32 v19, v28
	v_mul_f32_e32 v30, v42, v18
	s_waitcnt lgkmcnt(0)
	v_mul_f32_e32 v32, v22, v26
	v_pk_mul_f32 v[18:19], v[22:23], v[18:19]
	v_mov_b32_e32 v22, v43
	v_pk_fma_f32 v[26:27], v[42:43], v[26:27], v[18:19] neg_lo:[0,0,1] neg_hi:[0,0,1]
	v_pk_mul_f32 v[18:19], v[22:23], v[28:29]
	v_mov_b32_e32 v29, v27
	v_mov_b32_e32 v31, v18
	v_mov_b32_e32 v33, v19
	v_pk_add_f32 v[18:19], v[30:31], v[32:33]
	v_mov_b32_e32 v32, v36
	v_mov_b32_e32 v33, v37
	v_mov_b32_e32 v30, v38
	v_mov_b32_e32 v31, v39
	v_mov_b32_e32 v28, v19
	s_or_b64 exec, exec, s[0:1]
	s_and_saveexec_b64 s[0:1], s[42:43]
	s_cbranch_execnz .LBB0_548

; DI float bf2f(unsigned short b) { return __uint_as_float(((unsigned)b) << 16); }
; DI u32x4 pack8(const float* v) { u32x4 w; w.x = pk2(v[0], v[1]); w.y = pk2(v[2], v[3]); w.z = pk2(v[4], v[5]); w.w = pk2(v[6], v[7]); return w; }
; DI float sigmoidf_(float x) { return __builtin_amdgcn_rcpf(1.0f + __builtin_amdgcn_exp2f(x * -1.4426950408889634f)); }
; DI void store16(bf16_t* p, const float* v) { *(u32x4*)p = pack8(v); *(u32x4*)(p + 8) = pack8(v + 8); }
; DI void post_token(int tok, int lane, LAS float* cs  , const bf16_t* P, const int* positions,
;                    const float* gq, const float* gk, const float* gmq, const float* cinb,
;                    bf16_t* Q, bf16_t* Kb, bf16_t* IQ, bf16_t* IK, float* IW, bf16_t* U, bf16_t* MQ) {
;     ...
;     if (lane < 16) IW[(size_t)tok * 16 + lane] = bf2f(rw) * 0.03125f;
;     {
;         float a[8], gt[8], o[8];
;         unpack8(rga, a);
;         unpack8(rgg, gt);
; #pragma unroll
;         for (int i = 0; i < 8; ++i) o[i] = (a[i] + cinb[8 * lane + i]) * sigmoidf_(gt[i] + cinb[512 + 8 * lane + i]);
;         *(u32x4*)(U + (size_t)tok * 512 + 8 * lane) = pack8(o);
;     }
;     {
;         const int ln = lane & 31;
;         unpack8(rm0, v); unpack8(rm1, v + 8);
;         float ss = 0.f;
; #pragma unroll
;         for (int i = 0; i < 16; ++i) ss += v[i] * v[i];
;         ss += __shfl_xor(ss, 1); ss += __shfl_xor(ss, 2); ss += __shfl_xor(ss, 4);
;         const float rs = rsqrtf(ss * (1.f / 128.f) + EPS_);
;         const int d0 = 16 * (ln & 7);
; #pragma unroll
;         for (int i = 0; i < 16; ++i) v[i] = v[i] * rs * gmq[d0 + i];
;         if (lane < 32) store16(MQ + (size_t)tok * 512 + 16 * ln, v);
.LBB0_542:
	v_lshlrev_b32_e32 v16, 16, v119
	v_mul_f32_e32 v18, 0x3d000000, v16
	v_lshl_add_u64 v[16:17], s[44:45], 0, v[80:81]
	global_store_dword v[16:17], v18, off
.LBB0_543:
	s_or_b64 exec, exec, s[0:1]
	v_lshlrev_b32_e32 v16, 16, v12
	v_and_b32_e32 v17, 0xffff0000, v12
	v_lshlrev_b32_e32 v30, 16, v13
	v_and_b32_e32 v31, 0xffff0000, v13
	v_lshlrev_b32_e32 v32, 16, v14
	v_and_b32_e32 v33, 0xffff0000, v14
	v_lshlrev_b32_e32 v34, 16, v15
	v_and_b32_e32 v35, 0xffff0000, v15
	global_load_dwordx4 v[12:15], v[72:73], off offset:2064
	global_load_dwordx4 v[18:21], v[72:73], off offset:2048
	v_lshlrev_b32_e32 v28, 16, v8
	v_and_b32_e32 v29, 0xffff0000, v8
	s_waitcnt vmcnt(0)
	v_add_f32_e32 v16, v18, v16
	v_mul_f32_e32 v16, 0xbfb8aa3b, v16
	v_exp_f32_e32 v16, v16
	v_add_f32_e32 v8, v20, v30
	v_mul_f32_e32 v8, 0xbfb8aa3b, v8
	v_exp_f32_e32 v8, v8
	v_add_f32_e32 v16, 1.0, v16
	v_rcp_f32_e32 v26, v16
	v_add_f32_e32 v16, v19, v17
	v_mul_f32_e32 v16, 0xbfb8aa3b, v16
	v_exp_f32_e32 v16, v16
	v_add_f32_e32 v8, 1.0, v8
	v_rcp_f32_e32 v20, v8
	v_add_f32_e32 v8, v21, v31
	v_add_f32_e32 v16, 1.0, v16
	v_rcp_f32_e32 v27, v16
	global_load_dwordx4 v[16:19], v[72:73], off offset:16
	global_load_dwordx4 v[22:25], v[72:73], off
	v_mul_f32_e32 v8, 0xbfb8aa3b, v8
	v_exp_f32_e32 v8, v8
	s_waitcnt vmcnt(0)
	v_pk_add_f32 v[22:23], v[22:23], v[28:29]
	v_add_f32_e32 v8, 1.0, v8
	v_rcp_f32_e32 v21, v8
	v_lshlrev_b32_e32 v8, 16, v9
	v_and_b32_e32 v9, 0xffff0000, v9
	v_pk_add_f32 v[8:9], v[24:25], v[8:9]
	v_pk_mul_f32 v[22:23], v[22:23], v[26:27]
	v_pk_mul_f32 v[20:21], v[8:9], v[20:21]
	v_add_f32_e32 v8, v12, v32
	v_add_f32_e32 v9, v13, v33
	v_mul_f32_e32 v8, 0xbfb8aa3b, v8
	v_mul_f32_e32 v9, 0xbfb8aa3b, v9
	v_exp_f32_e32 v8, v8
	v_exp_f32_e32 v9, v9
	v_lshlrev_b32_e32 v12, 16, v10
	v_and_b32_e32 v13, 0xffff0000, v10
	v_add_f32_e32 v8, 1.0, v8
	v_add_f32_e32 v9, 1.0, v9
	v_rcp_f32_e32 v8, v8
	v_rcp_f32_e32 v9, v9
	v_pk_add_f32 v[12:13], v[16:17], v[12:13]
	v_lshlrev_b32_e32 v10, 16, v11
	v_and_b32_e32 v11, 0xffff0000, v11
	v_pk_mul_f32 v[12:13], v[12:13], v[8:9]
	v_add_f32_e32 v8, v14, v34
	v_add_f32_e32 v9, v15, v35
	v_mul_f32_e32 v8, 0xbfb8aa3b, v8
	v_mul_f32_e32 v9, 0xbfb8aa3b, v9
	v_exp_f32_e32 v8, v8
	v_exp_f32_e32 v9, v9
	v_pk_add_f32 v[10:11], v[18:19], v[10:11]
	v_add_f32_e32 v8, 1.0, v8
	v_add_f32_e32 v9, 1.0, v9
	v_rcp_f32_e32 v8, v8
	v_rcp_f32_e32 v9, v9
	s_nop 0
	v_pk_mul_f32 v[14:15], v[10:11], v[8:9]
	s_nop 0
	v_cvt_pk_bf16_f32 v11, v14, v15
	v_lshlrev_b32_e32 v14, 16, v4
	v_and_b32_e32 v15, 0xffff0000, v4
	v_lshlrev_b32_e32 v4, 16, v5
	v_and_b32_e32 v5, 0xffff0000, v5
	v_pk_mul_f32 v[16:17], v[14:15], v[14:15]
	v_cvt_pk_bf16_f32 v8, v22, v23
	v_cvt_pk_bf16_f32 v9, v20, v21
	v_cvt_pk_bf16_f32 v10, v12, v13
	v_lshl_add_u64 v[12:13], s[44:45], 0, v[84:85]
	v_pk_mul_f32 v[18:19], v[4:5], v[4:5]
	v_add_f32_e32 v16, v16, v17
	global_store_dwordx4 v[12:13], v[8:11], off
	v_add_f32_e32 v16, v18, v16
	v_add_f32_e32 v16, v19, v16
	v_lshlrev_b32_e32 v8, 16, v6
	v_and_b32_e32 v9, 0xffff0000, v6
	v_pk_mul_f32 v[20:21], v[8:9], v[8:9]
	v_lshlrev_b32_e32 v6, 16, v7
	v_and_b32_e32 v7, 0xffff0000, v7
	v_add_f32_e32 v16, v20, v16
	v_pk_mul_f32 v[22:23], v[6:7], v[6:7]
	v_add_f32_e32 v16, v21, v16
	v_lshlrev_b32_e32 v10, 16, v0
	v_and_b32_e32 v11, 0xffff0000, v0
	v_add_f32_e32 v16, v22, v16
	v_pk_mul_f32 v[24:25], v[10:11], v[10:11]
	v_add_f32_e32 v16, v23, v16
	v_lshlrev_b32_e32 v0, 16, v1
	v_and_b32_e32 v1, 0xffff0000, v1
	v_add_f32_e32 v16, v24, v16
	v_pk_mul_f32 v[26:27], v[0:1], v[0:1]
	v_add_f32_e32 v16, v25, v16
	v_lshlrev_b32_e32 v12, 16, v2
	v_and_b32_e32 v13, 0xffff0000, v2
	v_add_f32_e32 v16, v26, v16
	v_pk_mul_f32 v[28:29], v[12:13], v[12:13]
	v_add_f32_e32 v16, v27, v16
	v_lshlrev_b32_e32 v2, 16, v3
	v_and_b32_e32 v3, 0xffff0000, v3
	v_add_f32_e32 v16, v28, v16
	v_pk_mul_f32 v[30:31], v[2:3], v[2:3]
	v_add_f32_e32 v16, v29, v16
	v_add_f32_e32 v16, v30, v16
	v_add_f32_e32 v16, v31, v16
	ds_bpermute_b32 v17, v67, v16
	s_waitcnt lgkmcnt(0)
	v_add_f32_e32 v16, v16, v17
	ds_bpermute_b32 v17, v118, v16
	s_waitcnt lgkmcnt(0)
	v_add_f32_e32 v16, v16, v17
	ds_bpermute_b32 v17, v117, v16
	s_and_saveexec_b64 s[0:1], s[36:37]
	s_cbranch_execz .LBB0_342
	s_waitcnt lgkmcnt(0)
	v_add_f32_e32 v16, v16, v17
	v_fmamk_f32 v16, v16, 0x3c000000, v187
	v_cmp_gt_f32_e32 vcc, s97, v16
	v_mul_f32_e32 v17, 0x4b800000, v16
	s_mov_b32 s2, 0x22c00000
	v_cndmask_b32_e32 v16, v16, v17, vcc
	v_rsq_f32_e32 v16, v16
	s_nop 0
	v_mul_f32_e32 v17, 0x45800000, v16
	v_cndmask_b32_e32 v30, v16, v17, vcc
	v_pk_mul_f32 v[32:33], v[30:31], v[14:15] op_sel_hi:[0,1]
	global_load_dwordx4 v[14:17], v[74:75], off offset:48
	global_load_dwordx4 v[18:21], v[74:75], off offset:32
	global_load_dwordx4 v[22:25], v[74:75], off offset:16
	global_load_dwordx4 v[26:29], v[74:75], off
	v_pk_mul_f32 v[10:11], v[30:31], v[10:11] op_sel_hi:[0,1]
	v_pk_mul_f32 v[0:1], v[30:31], v[0:1] op_sel_hi:[0,1]
	v_pk_mul_f32 v[4:5], v[30:31], v[4:5] op_sel_hi:[0,1]
	v_pk_mul_f32 v[8:9], v[30:31], v[8:9] op_sel_hi:[0,1]
	v_pk_mul_f32 v[6:7], v[30:31], v[6:7] op_sel_hi:[0,1]
	s_waitcnt vmcnt(0)
	v_pk_mul_f32 v[10:11], v[10:11], v[18:19]
	v_pk_mul_f32 v[18:19], v[0:1], v[20:21]
	v_pk_mul_f32 v[0:1], v[30:31], v[12:13] op_sel_hi:[0,1]
	v_pk_mul_f32 v[12:13], v[0:1], v[14:15]
	v_pk_mul_f32 v[0:1], v[30:31], v[2:3] op_sel_hi:[0,1]
	v_pk_mul_f32 v[4:5], v[4:5], v[28:29]
	v_pk_mul_f32 v[14:15], v[0:1], v[16:17]
	v_lshl_add_u64 v[16:17], s[44:45], 0, v[82:83]
	v_pk_mul_f32 v[26:27], v[32:33], v[26:27]
	v_pk_mul_f32 v[8:9], v[8:9], v[22:23]
	v_pk_mul_f32 v[6:7], v[6:7], v[24:25]
	v_cvt_pk_bf16_f32 v1, v4, v5
	v_add_co_u32_e32 v4, vcc, s2, v16
	v_cvt_pk_bf16_f32 v0, v26, v27
	v_cvt_pk_bf16_f32 v2, v8, v9
	v_cvt_pk_bf16_f32 v3, v6, v7
	v_addc_co_u32_e32 v5, vcc, 0, v17, vcc
	global_store_dwordx4 v[4:5], v[0:3], off
	s_nop 1
	v_cvt_pk_bf16_f32 v0, v10, v11
	v_cvt_pk_bf16_f32 v1, v18, v19
	v_cvt_pk_bf16_f32 v2, v12, v13
	v_cvt_pk_bf16_f32 v3, v14, v15
	global_store_dwordx4 v[4:5], v[0:3], off offset:16
	s_branch .LBB0_342

; DI void store16(bf16_t* p, const float* v) { *(u32x4*)p = pack8(v); *(u32x4*)(p + 8) = pack8(v + 8); }
; DI void post_token(int tok, int lane, LAS float* cs  , const bf16_t* P, const int* positions,
;                    const float* gq, const float* gk, const float* gmq, const float* cinb,
;                    bf16_t* Q, bf16_t* Kb, bf16_t* IQ, bf16_t* IK, float* IW, bf16_t* U, bf16_t* MQ) {
;     ...
;         if (lane < 4) store16(IK + (size_t)tok * 64 + 16 * ln, v);
.LBB0_548:
	v_lshl_add_u64 v[22:23], s[44:45], 0, v[78:79]
	v_cvt_pk_bf16_f32 v37, v26, v29
	v_add_co_u32_e32 v26, vcc, 0x21900000, v22
	v_cvt_pk_bf16_f32 v34, v34, v35
	v_cvt_pk_bf16_f32 v35, v32, v33
	v_cvt_pk_bf16_f32 v36, v30, v31
	v_addc_co_u32_e32 v27, vcc, 0, v23, vcc
	v_cvt_pk_bf16_f32 v22, v24, v25
	v_cvt_pk_bf16_f32 v23, v16, v17
	v_cvt_pk_bf16_f32 v24, v20, v21
	v_cvt_pk_bf16_f32 v25, v18, v28
	global_store_dwordx4 v[26:27], v[34:37], off
	global_store_dwordx4 v[26:27], v[22:25], off offset:16
	s_or_b64 exec, exec, s[0:1]
	s_and_saveexec_b64 s[0:1], s[38:39]
	s_cbranch_execnz .LBB0_542
	s_branch .LBB0_543

; DI void transpose64x128(const bf16_t* src, int pitch, bf16_t* dst, int dpitch, int lane) {
;     const bf16_t* sp = src + (size_t)lane * pitch;
;     u32x4 wq[16];
; #pragma unroll
;     for (int c = 0; c < 16; ++c) wq[c] = *(const u32x4*)(sp + 8 * c);
; #pragma unroll
;     for (int c = 0; c < 16; ++c) {
;         const u32x4 w = wq[c];
;         bf16_t* dp = dst + (size_t)(8 * c) * dpitch + lane;
;         dp[0] = (bf16_t)(w.x & 0xffffu); dp[dpitch] = (bf16_t)(w.x >> 16);
;         dp[2 * (size_t)dpitch] = (bf16_t)(w.y & 0xffffu); dp[3 * (size_t)dpitch] = (bf16_t)(w.y >> 16);
;         dp[4 * (size_t)dpitch] = (bf16_t)(w.z & 0xffffu); dp[5 * (size_t)dpitch] = (bf16_t)(w.z >> 16);
;         dp[6 * (size_t)dpitch] = (bf16_t)(w.w & 0xffffu); dp[7 * (size_t)dpitch] = (bf16_t)(w.w >> 16);
;     }
; __global__ void __launch_bounds__(512, 2) fwd_megakernel(Args args) {
;     ...
;             for (int it = gw; it < 512; it += NGW) {
;                 const int bk = it >> 6, tt = it & 63, b = bk >> 1, kvh = bk & 1;
;                 transpose64x128(P + ((size_t)b * S_ + 64 * tt) * NPROJ + PC_V + kvh * 128, NPROJ, VT + (size_t)bk * 128 * S_ + 64 * tt, S_, lane);
.LBB0_551:
	s_ashr_i32 s10, s3, 7
	s_ashr_i32 s11, s10, 31
	s_lshl_b64 s[10:11], s[10:11], 12
	s_and_b32 s5, s2, 0xfc0
	s_or_b32 s7, s10, s5
	s_mul_i32 s10, s11, 0x2200
	s_mul_hi_u32 s11, s7, 0x2200
	s_ashr_i32 s6, s3, 6
	s_add_i32 s11, s11, s10
	s_mulk_i32 s7, 0x2200
	s_add_u32 s7, s44, s7
	s_addc_u32 s11, s45, s11
	s_lshl_b32 s10, s6, 8
	s_and_b32 s10, s10, 0x100
	s_add_u32 s10, s7, s10
	s_addc_u32 s11, s11, 0
	s_ashr_i32 s7, s6, 31
	s_lshl_b64 s[6:7], s[6:7], 20
	s_add_u32 s6, s0, s6
	s_addc_u32 s7, s1, s7
	s_lshl_b32 s5, s5, 1
	s_add_u32 s6, s6, s5
	v_lshl_add_u64 v[0:1], s[10:11], 0, v[160:161]
	s_mov_b64 s[10:11], 0x13d00a00
	s_mov_b32 s5, 0x13d00000
	v_lshl_add_u64 v[2:3], v[0:1], 0, s[10:11]
	v_add_co_u32_e32 v0, vcc, s5, v0
	s_addc_u32 s7, s7, 0
	s_nop 0
	v_addc_co_u32_e32 v1, vcc, 0, v1, vcc
	global_load_dwordx4 v[68:71], v[0:1], off offset:2560
	global_load_dwordx4 v[56:59], v[2:3], off offset:16
	global_load_dwordx4 v[52:55], v[2:3], off offset:32
	global_load_dwordx4 v[48:51], v[2:3], off offset:48
	global_load_dwordx4 v[44:47], v[2:3], off offset:64
	global_load_dwordx4 v[40:43], v[2:3], off offset:80
	global_load_dwordx4 v[36:39], v[2:3], off offset:96
	global_load_dwordx4 v[32:35], v[2:3], off offset:112
	global_load_dwordx4 v[28:31], v[2:3], off offset:128
	global_load_dwordx4 v[24:27], v[2:3], off offset:144
	global_load_dwordx4 v[20:23], v[2:3], off offset:160
	s_waitcnt lgkmcnt(0)
	global_load_dwordx4 v[16:19], v[2:3], off offset:176
	global_load_dwordx4 v[12:15], v[2:3], off offset:192
	global_load_dwordx4 v[8:11], v[2:3], off offset:208
	global_load_dwordx4 v[4:7], v[2:3], off offset:224
	s_nop 0
	global_load_dwordx4 v[0:3], v[2:3], off offset:240
	v_mov_b32_e32 v61, v161
	v_lshl_add_u64 v[62:63], s[6:7], 0, v[60:61]
	v_add_co_u32_e32 v72, vcc, s57, v62
	s_mov_b32 s5, 0x12000
	s_nop 0
	v_addc_co_u32_e32 v73, vcc, 0, v63, vcc
	s_add_i32 s3, s3, s96
	s_add_i32 s2, s2, s12
	s_cmpk_gt_i32 s3, 0x1ff
	s_waitcnt vmcnt(0)
	global_store_short_d16_hi v[72:73], v68, off
	v_add_co_u32_e32 v72, vcc, s13, v62
	global_store_short v[62:63], v68, off
	s_nop 0
	v_addc_co_u32_e32 v73, vcc, 0, v63, vcc
	global_store_short v[72:73], v69, off
	v_add_co_u32_e32 v72, vcc, s17, v62
	s_nop 1
	v_addc_co_u32_e32 v73, vcc, 0, v63, vcc
	v_add_co_u32_e32 v68, vcc, s19, v62
	global_store_short_d16_hi v[72:73], v69, off
	s_nop 0
	v_addc_co_u32_e32 v69, vcc, 0, v63, vcc
	global_store_short v[68:69], v70, off
	v_add_co_u32_e32 v68, vcc, s22, v62
	s_nop 1
	v_addc_co_u32_e32 v69, vcc, 0, v63, vcc
	global_store_short_d16_hi v[68:69], v70, off
	v_add_co_u32_e32 v68, vcc, s23, v62
	s_nop 1
	v_addc_co_u32_e32 v69, vcc, 0, v63, vcc
	global_store_short v[68:69], v71, off
	v_add_co_u32_e32 v68, vcc, s29, v62
	s_nop 1
	v_addc_co_u32_e32 v69, vcc, 0, v63, vcc
	global_store_short_d16_hi v[68:69], v71, off
	v_add_co_u32_e32 v68, vcc, s16, v62
	s_nop 1
	v_addc_co_u32_e32 v69, vcc, 0, v63, vcc
	global_store_short v[68:69], v56, off
	v_add_co_u32_e32 v68, vcc, s5, v62
	s_mov_b32 s5, 0x14000
	s_nop 0
	v_addc_co_u32_e32 v69, vcc, 0, v63, vcc
	global_store_short_d16_hi v[68:69], v56, off
	v_add_co_u32_e32 v68, vcc, s5, v62
	s_mov_b32 s5, 0x16000
	s_nop 0
	v_addc_co_u32_e32 v69, vcc, 0, v63, vcc
	global_store_short v[68:69], v57, off
	v_add_co_u32_e32 v68, vcc, s5, v62
	s_mov_b32 s5, 0x1a000
	s_nop 0
	v_addc_co_u32_e32 v69, vcc, 0, v63, vcc
	v_add_co_u32_e32 v56, vcc, s18, v62
	global_store_short_d16_hi v[68:69], v57, off
	s_nop 0
	v_addc_co_u32_e32 v57, vcc, 0, v63, vcc
	global_store_short v[56:57], v58, off
	v_add_co_u32_e32 v56, vcc, s5, v62
	s_mov_b32 s5, 0x1c000
	s_nop 0
	v_addc_co_u32_e32 v57, vcc, 0, v63, vcc
	global_store_short_d16_hi v[56:57], v58, off
	v_add_co_u32_e32 v56, vcc, s5, v62
	s_mov_b32 s5, 0x1e000
	s_nop 0
	v_addc_co_u32_e32 v57, vcc, 0, v63, vcc
	global_store_short v[56:57], v59, off
	v_add_co_u32_e32 v56, vcc, s5, v62
	s_mov_b32 s5, 0x20000
	s_nop 0
	v_addc_co_u32_e32 v57, vcc, 0, v63, vcc
	global_store_short_d16_hi v[56:57], v59, off
	v_add_co_u32_e32 v56, vcc, s5, v62
	s_mov_b32 s5, 0x22000
	s_nop 0
	v_addc_co_u32_e32 v57, vcc, 0, v63, vcc
	global_store_short v[56:57], v52, off
	v_add_co_u32_e32 v56, vcc, s5, v62
	s_mov_b32 s5, 0x24000
	s_nop 0
	v_addc_co_u32_e32 v57, vcc, 0, v63, vcc
	global_store_short_d16_hi v[56:57], v52, off
	v_add_co_u32_e32 v56, vcc, s5, v62
	s_mov_b32 s5, 0x26000
	s_nop 0
	v_addc_co_u32_e32 v57, vcc, 0, v63, vcc
	global_store_short v[56:57], v53, off
	v_add_co_u32_e32 v56, vcc, s5, v62
	s_mov_b32 s5, 0x28000
	s_nop 0
	v_addc_co_u32_e32 v57, vcc, 0, v63, vcc
	v_add_co_u32_e32 v52, vcc, s5, v62
	global_store_short_d16_hi v[56:57], v53, off
	s_nop 0
	v_addc_co_u32_e32 v53, vcc, 0, v63, vcc
	s_mov_b32 s5, 0x2a000
	global_store_short v[52:53], v54, off
	v_add_co_u32_e32 v52, vcc, s5, v62
	s_mov_b32 s5, 0x2c000
	s_nop 0
	v_addc_co_u32_e32 v53, vcc, 0, v63, vcc
	global_store_short_d16_hi v[52:53], v54, off
	v_add_co_u32_e32 v52, vcc, s5, v62
	s_mov_b32 s5, 0x2e000
	s_nop 0
	v_addc_co_u32_e32 v53, vcc, 0, v63, vcc
	global_store_short v[52:53], v55, off
	v_add_co_u32_e32 v52, vcc, s5, v62
	s_mov_b32 s5, 0x30000
	s_nop 0
	v_addc_co_u32_e32 v53, vcc, 0, v63, vcc
	global_store_short_d16_hi v[52:53], v55, off
	v_add_co_u32_e32 v52, vcc, s5, v62
	s_mov_b32 s5, 0x32000
	s_nop 0
	v_addc_co_u32_e32 v53, vcc, 0, v63, vcc
	global_store_short v[52:53], v48, off
	v_add_co_u32_e32 v52, vcc, s5, v62
	s_mov_b32 s5, 0x34000
	s_nop 0
	v_addc_co_u32_e32 v53, vcc, 0, v63, vcc
	global_store_short_d16_hi v[52:53], v48, off
	v_add_co_u32_e32 v52, vcc, s5, v62
	s_mov_b32 s5, 0x36000
	s_nop 0
	v_addc_co_u32_e32 v53, vcc, 0, v63, vcc
; DI void transpose64x128(const bf16_t* src, int pitch, bf16_t* dst, int dpitch, int lane) {
;     const bf16_t* sp = src + (size_t)lane * pitch;
;     u32x4 wq[16];
; #pragma unroll
;     for (int c = 0; c < 16; ++c) wq[c] = *(const u32x4*)(sp + 8 * c);
; #pragma unroll
;     for (int c = 0; c < 16; ++c) {
;         const u32x4 w = wq[c];
;         bf16_t* dp = dst + (size_t)(8 * c) * dpitch + lane;
;         dp[0] = (bf16_t)(w.x & 0xffffu); dp[dpitch] = (bf16_t)(w.x >> 16);
;         dp[2 * (size_t)dpitch] = (bf16_t)(w.y & 0xffffu); dp[3 * (size_t)dpitch] = (bf16_t)(w.y >> 16);
;         dp[4 * (size_t)dpitch] = (bf16_t)(w.z & 0xffffu); dp[5 * (size_t)dpitch] = (bf16_t)(w.z >> 16);
;         dp[6 * (size_t)dpitch] = (bf16_t)(w.w & 0xffffu); dp[7 * (size_t)dpitch] = (bf16_t)(w.w >> 16);
;     }
	global_store_short v[52:53], v49, off
	v_add_co_u32_e32 v52, vcc, s5, v62
	s_mov_b32 s5, 0x38000
	s_nop 0
	v_addc_co_u32_e32 v53, vcc, 0, v63, vcc
	v_add_co_u32_e32 v48, vcc, s5, v62
	global_store_short_d16_hi v[52:53], v49, off
	s_nop 0
	v_addc_co_u32_e32 v49, vcc, 0, v63, vcc
	s_mov_b32 s5, 0x3a000
	global_store_short v[48:49], v50, off
	v_add_co_u32_e32 v48, vcc, s5, v62
	s_mov_b32 s5, 0x3c000
	s_nop 0
	v_addc_co_u32_e32 v49, vcc, 0, v63, vcc
	global_store_short_d16_hi v[48:49], v50, off
	v_add_co_u32_e32 v48, vcc, s5, v62
	s_mov_b32 s5, 0x3e000
	s_nop 0
	v_addc_co_u32_e32 v49, vcc, 0, v63, vcc
	global_store_short v[48:49], v51, off
	v_add_co_u32_e32 v48, vcc, s5, v62
	s_mov_b32 s5, 0x40000
	s_nop 0
	v_addc_co_u32_e32 v49, vcc, 0, v63, vcc
	global_store_short_d16_hi v[48:49], v51, off
	v_add_co_u32_e32 v48, vcc, s5, v62
	s_mov_b32 s5, 0x42000
	s_nop 0
	v_addc_co_u32_e32 v49, vcc, 0, v63, vcc
	global_store_short v[48:49], v44, off
	v_add_co_u32_e32 v48, vcc, s5, v62
	s_mov_b32 s5, 0x44000
	s_nop 0
	v_addc_co_u32_e32 v49, vcc, 0, v63, vcc
	global_store_short_d16_hi v[48:49], v44, off
	v_add_co_u32_e32 v48, vcc, s5, v62
	s_mov_b32 s5, 0x46000
	s_nop 0
	v_addc_co_u32_e32 v49, vcc, 0, v63, vcc
	global_store_short v[48:49], v45, off
	v_add_co_u32_e32 v48, vcc, s5, v62
	s_mov_b32 s5, 0x48000
	s_nop 0
	v_addc_co_u32_e32 v49, vcc, 0, v63, vcc
	v_add_co_u32_e32 v44, vcc, s5, v62
	global_store_short_d16_hi v[48:49], v45, off
	s_nop 0
	v_addc_co_u32_e32 v45, vcc, 0, v63, vcc
	s_mov_b32 s5, 0x4a000
	global_store_short v[44:45], v46, off
	v_add_co_u32_e32 v44, vcc, s5, v62
	s_mov_b32 s5, 0x4c000
	s_nop 0
	v_addc_co_u32_e32 v45, vcc, 0, v63, vcc
	global_store_short_d16_hi v[44:45], v46, off
	v_add_co_u32_e32 v44, vcc, s5, v62
	s_mov_b32 s5, 0x4e000
	s_nop 0
	v_addc_co_u32_e32 v45, vcc, 0, v63, vcc
	global_store_short v[44:45], v47, off
	v_add_co_u32_e32 v44, vcc, s5, v62
	s_mov_b32 s5, 0x50000
	s_nop 0
	v_addc_co_u32_e32 v45, vcc, 0, v63, vcc
	global_store_short_d16_hi v[44:45], v47, off
	v_add_co_u32_e32 v44, vcc, s5, v62
	s_mov_b32 s5, 0x52000
	s_nop 0
	v_addc_co_u32_e32 v45, vcc, 0, v63, vcc
	global_store_short v[44:45], v40, off
	v_add_co_u32_e32 v44, vcc, s5, v62
	s_mov_b32 s5, 0x54000
	s_nop 0
	v_addc_co_u32_e32 v45, vcc, 0, v63, vcc
	global_store_short_d16_hi v[44:45], v40, off
	v_add_co_u32_e32 v44, vcc, s5, v62
	s_mov_b32 s5, 0x56000
	s_nop 0
	v_addc_co_u32_e32 v45, vcc, 0, v63, vcc
	global_store_short v[44:45], v41, off
	v_add_co_u32_e32 v44, vcc, s5, v62
	s_mov_b32 s5, 0x58000
	s_nop 0
	v_addc_co_u32_e32 v45, vcc, 0, v63, vcc
	v_add_co_u32_e32 v40, vcc, s5, v62
	global_store_short_d16_hi v[44:45], v41, off
	s_nop 0
	v_addc_co_u32_e32 v41, vcc, 0, v63, vcc
	s_mov_b32 s5, 0x5a000
	global_store_short v[40:41], v42, off
	v_add_co_u32_e32 v40, vcc, s5, v62
	s_mov_b32 s5, 0x5c000
	s_nop 0
	v_addc_co_u32_e32 v41, vcc, 0, v63, vcc
	global_store_short_d16_hi v[40:41], v42, off
	v_add_co_u32_e32 v40, vcc, s5, v62
	s_mov_b32 s5, 0x5e000
	s_nop 0
	v_addc_co_u32_e32 v41, vcc, 0, v63, vcc
	global_store_short v[40:41], v43, off
	v_add_co_u32_e32 v40, vcc, s5, v62
	s_mov_b32 s5, 0x60000
	s_nop 0
	v_addc_co_u32_e32 v41, vcc, 0, v63, vcc
	global_store_short_d16_hi v[40:41], v43, off
	v_add_co_u32_e32 v40, vcc, s5, v62
	s_mov_b32 s5, 0x62000
	s_nop 0
	v_addc_co_u32_e32 v41, vcc, 0, v63, vcc
	global_store_short v[40:41], v36, off
	v_add_co_u32_e32 v40, vcc, s5, v62
	s_mov_b32 s5, 0x64000
	s_nop 0
	v_addc_co_u32_e32 v41, vcc, 0, v63, vcc
	global_store_short_d16_hi v[40:41], v36, off
	v_add_co_u32_e32 v40, vcc, s5, v62
	s_mov_b32 s5, 0x66000
	s_nop 0
	v_addc_co_u32_e32 v41, vcc, 0, v63, vcc
	global_store_short v[40:41], v37, off
	v_add_co_u32_e32 v40, vcc, s5, v62
	s_mov_b32 s5, 0x68000
	s_nop 0
	v_addc_co_u32_e32 v41, vcc, 0, v63, vcc
	v_add_co_u32_e32 v36, vcc, s5, v62
	global_store_short_d16_hi v[40:41], v37, off
	s_nop 0
	v_addc_co_u32_e32 v37, vcc, 0, v63, vcc
	s_mov_b32 s5, 0x6a000
	global_store_short v[36:37], v38, off
	v_add_co_u32_e32 v36, vcc, s5, v62
	s_mov_b32 s5, 0x6c000
	s_nop 0
	v_addc_co_u32_e32 v37, vcc, 0, v63, vcc
	global_store_short_d16_hi v[36:37], v38, off
	v_add_co_u32_e32 v36, vcc, s5, v62
	s_mov_b32 s5, 0x6e000
	s_nop 0
	v_addc_co_u32_e32 v37, vcc, 0, v63, vcc
	global_store_short v[36:37], v39, off
	v_add_co_u32_e32 v36, vcc, s5, v62
	s_mov_b32 s5, 0x70000
	s_nop 0
	v_addc_co_u32_e32 v37, vcc, 0, v63, vcc
	global_store_short_d16_hi v[36:37], v39, off
	v_add_co_u32_e32 v36, vcc, s5, v62
	s_mov_b32 s5, 0x72000
	s_nop 0
	v_addc_co_u32_e32 v37, vcc, 0, v63, vcc
	global_store_short v[36:37], v32, off
	v_add_co_u32_e32 v36, vcc, s5, v62
	s_mov_b32 s5, 0x74000
	s_nop 0
	v_addc_co_u32_e32 v37, vcc, 0, v63, vcc
	global_store_short_d16_hi v[36:37], v32, off
	v_add_co_u32_e32 v36, vcc, s5, v62
	s_mov_b32 s5, 0x76000
	s_nop 0
	v_addc_co_u32_e32 v37, vcc, 0, v63, vcc
	global_store_short v[36:37], v33, off
	v_add_co_u32_e32 v36, vcc, s5, v62
	s_mov_b32 s5, 0x78000
	s_nop 0
	v_addc_co_u32_e32 v37, vcc, 0, v63, vcc
	v_add_co_u32_e32 v32, vcc, s5, v62
	global_store_short_d16_hi v[36:37], v33, off
	s_nop 0
	v_addc_co_u32_e32 v33, vcc, 0, v63, vcc
	s_mov_b32 s5, 0x7a000
	global_store_short v[32:33], v34, off
	v_add_co_u32_e32 v32, vcc, s5, v62
	s_mov_b32 s5, 0x7c000
	s_nop 0
	v_addc_co_u32_e32 v33, vcc, 0, v63, vcc
	global_store_short_d16_hi v[32:33], v34, off
	v_add_co_u32_e32 v32, vcc, s5, v62
	s_mov_b32 s5, 0x7e000
	s_nop 0
	v_addc_co_u32_e32 v33, vcc, 0, v63, vcc
	global_store_short v[32:33], v35, off
	v_add_co_u32_e32 v32, vcc, s5, v62
	s_mov_b32 s5, 0x80000
	s_nop 0
	v_addc_co_u32_e32 v33, vcc, 0, v63, vcc
	global_store_short_d16_hi v[32:33], v35, off
; DI void transpose64x128(const bf16_t* src, int pitch, bf16_t* dst, int dpitch, int lane) {
;     const bf16_t* sp = src + (size_t)lane * pitch;
;     u32x4 wq[16];
; #pragma unroll
;     for (int c = 0; c < 16; ++c) wq[c] = *(const u32x4*)(sp + 8 * c);
; #pragma unroll
;     for (int c = 0; c < 16; ++c) {
;         const u32x4 w = wq[c];
;         bf16_t* dp = dst + (size_t)(8 * c) * dpitch + lane;
;         dp[0] = (bf16_t)(w.x & 0xffffu); dp[dpitch] = (bf16_t)(w.x >> 16);
;         dp[2 * (size_t)dpitch] = (bf16_t)(w.y & 0xffffu); dp[3 * (size_t)dpitch] = (bf16_t)(w.y >> 16);
;         dp[4 * (size_t)dpitch] = (bf16_t)(w.z & 0xffffu); dp[5 * (size_t)dpitch] = (bf16_t)(w.z >> 16);
;         dp[6 * (size_t)dpitch] = (bf16_t)(w.w & 0xffffu); dp[7 * (size_t)dpitch] = (bf16_t)(w.w >> 16);
;     }
	v_add_co_u32_e32 v32, vcc, s5, v62
	s_mov_b32 s5, 0x82000
	s_nop 0
	v_addc_co_u32_e32 v33, vcc, 0, v63, vcc
	global_store_short v[32:33], v28, off
	v_add_co_u32_e32 v32, vcc, s5, v62
	s_mov_b32 s5, 0x84000
	s_nop 0
	v_addc_co_u32_e32 v33, vcc, 0, v63, vcc
	global_store_short_d16_hi v[32:33], v28, off
	v_add_co_u32_e32 v32, vcc, s5, v62
	s_mov_b32 s5, 0x86000
	s_nop 0
	v_addc_co_u32_e32 v33, vcc, 0, v63, vcc
	global_store_short v[32:33], v29, off
	v_add_co_u32_e32 v32, vcc, s5, v62
	s_mov_b32 s5, 0x88000
	s_nop 0
	v_addc_co_u32_e32 v33, vcc, 0, v63, vcc
	v_add_co_u32_e32 v28, vcc, s5, v62
	global_store_short_d16_hi v[32:33], v29, off
	s_nop 0
	v_addc_co_u32_e32 v29, vcc, 0, v63, vcc
	s_mov_b32 s5, 0x8a000
	global_store_short v[28:29], v30, off
	v_add_co_u32_e32 v28, vcc, s5, v62
	s_mov_b32 s5, 0x8c000
	s_nop 0
	v_addc_co_u32_e32 v29, vcc, 0, v63, vcc
	global_store_short_d16_hi v[28:29], v30, off
	v_add_co_u32_e32 v28, vcc, s5, v62
	s_mov_b32 s5, 0x8e000
	s_nop 0
	v_addc_co_u32_e32 v29, vcc, 0, v63, vcc
	global_store_short v[28:29], v31, off
	v_add_co_u32_e32 v28, vcc, s5, v62
	s_mov_b32 s5, 0x90000
	s_nop 0
	v_addc_co_u32_e32 v29, vcc, 0, v63, vcc
	global_store_short_d16_hi v[28:29], v31, off
	v_add_co_u32_e32 v28, vcc, s5, v62
	s_mov_b32 s5, 0x92000
	s_nop 0
	v_addc_co_u32_e32 v29, vcc, 0, v63, vcc
	global_store_short v[28:29], v24, off
	v_add_co_u32_e32 v28, vcc, s5, v62
	s_mov_b32 s5, 0x94000
	s_nop 0
	v_addc_co_u32_e32 v29, vcc, 0, v63, vcc
	global_store_short_d16_hi v[28:29], v24, off
	v_add_co_u32_e32 v28, vcc, s5, v62
	s_mov_b32 s5, 0x96000
	s_nop 0
	v_addc_co_u32_e32 v29, vcc, 0, v63, vcc
	global_store_short v[28:29], v25, off
	v_add_co_u32_e32 v28, vcc, s5, v62
	s_mov_b32 s5, 0x98000
	s_nop 0
	v_addc_co_u32_e32 v29, vcc, 0, v63, vcc
	v_add_co_u32_e32 v24, vcc, s5, v62
	global_store_short_d16_hi v[28:29], v25, off
	s_nop 0
	v_addc_co_u32_e32 v25, vcc, 0, v63, vcc
	s_mov_b32 s5, 0x9a000
	global_store_short v[24:25], v26, off
	v_add_co_u32_e32 v24, vcc, s5, v62
	s_mov_b32 s5, 0x9c000
	s_nop 0
	v_addc_co_u32_e32 v25, vcc, 0, v63, vcc
	global_store_short_d16_hi v[24:25], v26, off
	v_add_co_u32_e32 v24, vcc, s5, v62
	s_mov_b32 s5, 0x9e000
	s_nop 0
	v_addc_co_u32_e32 v25, vcc, 0, v63, vcc
	global_store_short v[24:25], v27, off
	v_add_co_u32_e32 v24, vcc, s5, v62
	s_mov_b32 s5, 0xa0000
	s_nop 0
	v_addc_co_u32_e32 v25, vcc, 0, v63, vcc
	global_store_short_d16_hi v[24:25], v27, off
	v_add_co_u32_e32 v24, vcc, s5, v62
	s_mov_b32 s5, 0xa2000
	s_nop 0
	v_addc_co_u32_e32 v25, vcc, 0, v63, vcc
	global_store_short v[24:25], v20, off
	v_add_co_u32_e32 v24, vcc, s5, v62
	s_mov_b32 s5, 0xa4000
	s_nop 0
	v_addc_co_u32_e32 v25, vcc, 0, v63, vcc
	global_store_short_d16_hi v[24:25], v20, off
	v_add_co_u32_e32 v24, vcc, s5, v62
	s_mov_b32 s5, 0xa6000
	s_nop 0
	v_addc_co_u32_e32 v25, vcc, 0, v63, vcc
	global_store_short v[24:25], v21, off
	v_add_co_u32_e32 v24, vcc, s5, v62
	s_mov_b32 s5, 0xa8000
	s_nop 0
	v_addc_co_u32_e32 v25, vcc, 0, v63, vcc
	v_add_co_u32_e32 v20, vcc, s5, v62
	global_store_short_d16_hi v[24:25], v21, off
	s_nop 0
	v_addc_co_u32_e32 v21, vcc, 0, v63, vcc
	s_mov_b32 s5, 0xaa000
	global_store_short v[20:21], v22, off
	v_add_co_u32_e32 v20, vcc, s5, v62
	s_mov_b32 s5, 0xac000
	s_nop 0
	v_addc_co_u32_e32 v21, vcc, 0, v63, vcc
	global_store_short_d16_hi v[20:21], v22, off
	v_add_co_u32_e32 v20, vcc, s5, v62
	s_mov_b32 s5, 0xae000
	s_nop 0
	v_addc_co_u32_e32 v21, vcc, 0, v63, vcc
	global_store_short v[20:21], v23, off
	v_add_co_u32_e32 v20, vcc, s5, v62
	s_mov_b32 s5, 0xb0000
	s_nop 0
	v_addc_co_u32_e32 v21, vcc, 0, v63, vcc
	global_store_short_d16_hi v[20:21], v23, off
	v_add_co_u32_e32 v20, vcc, s5, v62
	s_mov_b32 s5, 0xb2000
	s_nop 0
	v_addc_co_u32_e32 v21, vcc, 0, v63, vcc
	s_waitcnt lgkmcnt(0)
; DI void transpose64x128(const bf16_t* src, int pitch, bf16_t* dst, int dpitch, int lane) {
;     const bf16_t* sp = src + (size_t)lane * pitch;
;     u32x4 wq[16];
; #pragma unroll
;     for (int c = 0; c < 16; ++c) wq[c] = *(const u32x4*)(sp + 8 * c);
; #pragma unroll
;     for (int c = 0; c < 16; ++c) {
;         const u32x4 w = wq[c];
;         bf16_t* dp = dst + (size_t)(8 * c) * dpitch + lane;
;         dp[0] = (bf16_t)(w.x & 0xffffu); dp[dpitch] = (bf16_t)(w.x >> 16);
;         dp[2 * (size_t)dpitch] = (bf16_t)(w.y & 0xffffu); dp[3 * (size_t)dpitch] = (bf16_t)(w.y >> 16);
;         dp[4 * (size_t)dpitch] = (bf16_t)(w.z & 0xffffu); dp[5 * (size_t)dpitch] = (bf16_t)(w.z >> 16);
;         dp[6 * (size_t)dpitch] = (bf16_t)(w.w & 0xffffu); dp[7 * (size_t)dpitch] = (bf16_t)(w.w >> 16);
;     }
	global_store_short v[20:21], v16, off
	v_add_co_u32_e32 v20, vcc, s5, v62
	s_mov_b32 s5, 0xb4000
	s_nop 0
	v_addc_co_u32_e32 v21, vcc, 0, v63, vcc
	global_store_short_d16_hi v[20:21], v16, off
	v_add_co_u32_e32 v20, vcc, s5, v62
	s_mov_b32 s5, 0xb6000
	s_nop 0
	v_addc_co_u32_e32 v21, vcc, 0, v63, vcc
	global_store_short v[20:21], v17, off
	v_add_co_u32_e32 v20, vcc, s5, v62
	s_mov_b32 s5, 0xb8000
	s_nop 0
	v_addc_co_u32_e32 v21, vcc, 0, v63, vcc
	v_add_co_u32_e32 v16, vcc, s5, v62
	global_store_short_d16_hi v[20:21], v17, off
	s_nop 0
	v_addc_co_u32_e32 v17, vcc, 0, v63, vcc
	s_mov_b32 s5, 0xba000
	global_store_short v[16:17], v18, off
	v_add_co_u32_e32 v16, vcc, s5, v62
	s_mov_b32 s5, 0xbc000
	s_nop 0
	v_addc_co_u32_e32 v17, vcc, 0, v63, vcc
	global_store_short_d16_hi v[16:17], v18, off
	v_add_co_u32_e32 v16, vcc, s5, v62
	s_mov_b32 s5, 0xbe000
	s_nop 0
	v_addc_co_u32_e32 v17, vcc, 0, v63, vcc
	global_store_short v[16:17], v19, off
	v_add_co_u32_e32 v16, vcc, s5, v62
	s_mov_b32 s5, 0xc0000
	s_nop 0
	v_addc_co_u32_e32 v17, vcc, 0, v63, vcc
	global_store_short_d16_hi v[16:17], v19, off
	v_add_co_u32_e32 v16, vcc, s5, v62
	s_mov_b32 s5, 0xc2000
	s_nop 0
	v_addc_co_u32_e32 v17, vcc, 0, v63, vcc
	global_store_short v[16:17], v12, off
	v_add_co_u32_e32 v16, vcc, s5, v62
	s_mov_b32 s5, 0xc4000
	s_nop 0
	v_addc_co_u32_e32 v17, vcc, 0, v63, vcc
	global_store_short_d16_hi v[16:17], v12, off
	v_add_co_u32_e32 v16, vcc, s5, v62
	s_mov_b32 s5, 0xc6000
	s_nop 0
	v_addc_co_u32_e32 v17, vcc, 0, v63, vcc
	global_store_short v[16:17], v13, off
	v_add_co_u32_e32 v16, vcc, s5, v62
	s_mov_b32 s5, 0xc8000
	s_nop 0
	v_addc_co_u32_e32 v17, vcc, 0, v63, vcc
	v_add_co_u32_e32 v12, vcc, s5, v62
	global_store_short_d16_hi v[16:17], v13, off
	s_nop 0
	v_addc_co_u32_e32 v13, vcc, 0, v63, vcc
	s_mov_b32 s5, 0xca000
	global_store_short v[12:13], v14, off
	v_add_co_u32_e32 v12, vcc, s5, v62
	s_mov_b32 s5, 0xcc000
	s_nop 0
	v_addc_co_u32_e32 v13, vcc, 0, v63, vcc
	global_store_short_d16_hi v[12:13], v14, off
	v_add_co_u32_e32 v12, vcc, s5, v62
	s_mov_b32 s5, 0xce000
	s_nop 0
	v_addc_co_u32_e32 v13, vcc, 0, v63, vcc
	global_store_short v[12:13], v15, off
	v_add_co_u32_e32 v12, vcc, s5, v62
	s_mov_b32 s5, 0xd0000
	s_nop 0
	v_addc_co_u32_e32 v13, vcc, 0, v63, vcc
	global_store_short_d16_hi v[12:13], v15, off
	v_add_co_u32_e32 v12, vcc, s5, v62
	s_mov_b32 s5, 0xd2000
	s_nop 0
	v_addc_co_u32_e32 v13, vcc, 0, v63, vcc
	global_store_short v[12:13], v8, off
	v_add_co_u32_e32 v12, vcc, s5, v62
	s_mov_b32 s5, 0xd4000
	s_nop 0
	v_addc_co_u32_e32 v13, vcc, 0, v63, vcc
	global_store_short_d16_hi v[12:13], v8, off
	v_add_co_u32_e32 v12, vcc, s5, v62
	s_mov_b32 s5, 0xd6000
	s_nop 0
	v_addc_co_u32_e32 v13, vcc, 0, v63, vcc
	global_store_short v[12:13], v9, off
	v_add_co_u32_e32 v12, vcc, s5, v62
	s_mov_b32 s5, 0xd8000
	s_nop 0
	v_addc_co_u32_e32 v13, vcc, 0, v63, vcc
	v_add_co_u32_e32 v8, vcc, s5, v62
	global_store_short_d16_hi v[12:13], v9, off
	s_nop 0
	v_addc_co_u32_e32 v9, vcc, 0, v63, vcc
	s_mov_b32 s5, 0xda000
	global_store_short v[8:9], v10, off
	v_add_co_u32_e32 v8, vcc, s5, v62
	s_mov_b32 s5, 0xdc000
	s_nop 0
	v_addc_co_u32_e32 v9, vcc, 0, v63, vcc
	global_store_short_d16_hi v[8:9], v10, off
	v_add_co_u32_e32 v8, vcc, s5, v62
	s_mov_b32 s5, 0xde000
	s_nop 0
	v_addc_co_u32_e32 v9, vcc, 0, v63, vcc
	global_store_short v[8:9], v11, off
	v_add_co_u32_e32 v8, vcc, s5, v62
	s_mov_b32 s5, 0xe0000
	s_nop 0
	v_addc_co_u32_e32 v9, vcc, 0, v63, vcc
	global_store_short_d16_hi v[8:9], v11, off
	v_add_co_u32_e32 v8, vcc, s5, v62
	s_mov_b32 s5, 0xe2000
	s_nop 0
	v_addc_co_u32_e32 v9, vcc, 0, v63, vcc
	global_store_short v[8:9], v4, off
	v_add_co_u32_e32 v8, vcc, s5, v62
	s_mov_b32 s5, 0xe4000
	s_nop 0
	v_addc_co_u32_e32 v9, vcc, 0, v63, vcc
	global_store_short_d16_hi v[8:9], v4, off
	v_add_co_u32_e32 v8, vcc, s5, v62
	s_mov_b32 s5, 0xe6000
	s_nop 0
	v_addc_co_u32_e32 v9, vcc, 0, v63, vcc
	global_store_short v[8:9], v5, off
	v_add_co_u32_e32 v8, vcc, s5, v62
	s_mov_b32 s5, 0xe8000
	s_nop 0
	v_addc_co_u32_e32 v9, vcc, 0, v63, vcc
	v_add_co_u32_e32 v4, vcc, s5, v62
	global_store_short_d16_hi v[8:9], v5, off
	s_nop 0
	v_addc_co_u32_e32 v5, vcc, 0, v63, vcc
	s_mov_b32 s5, 0xea000
	global_store_short v[4:5], v6, off
	v_add_co_u32_e32 v4, vcc, s5, v62
	s_mov_b32 s5, 0xec000
	s_nop 0
	v_addc_co_u32_e32 v5, vcc, 0, v63, vcc
	global_store_short_d16_hi v[4:5], v6, off
	v_add_co_u32_e32 v4, vcc, s5, v62
	s_mov_b32 s5, 0xee000
	s_nop 0
	v_addc_co_u32_e32 v5, vcc, 0, v63, vcc
	global_store_short v[4:5], v7, off
	v_add_co_u32_e32 v4, vcc, s5, v62
	s_mov_b32 s5, 0xf0000
	s_nop 0
	v_addc_co_u32_e32 v5, vcc, 0, v63, vcc
	global_store_short_d16_hi v[4:5], v7, off
	v_add_co_u32_e32 v4, vcc, s5, v62
	s_mov_b32 s5, 0xf2000
	s_nop 0
	v_addc_co_u32_e32 v5, vcc, 0, v63, vcc
	global_store_short v[4:5], v0, off
	v_add_co_u32_e32 v4, vcc, s5, v62
	s_mov_b32 s5, 0xf4000
	s_nop 0
	v_addc_co_u32_e32 v5, vcc, 0, v63, vcc
	global_store_short_d16_hi v[4:5], v0, off
	v_add_co_u32_e32 v4, vcc, s5, v62
	s_mov_b32 s5, 0xf6000
	s_nop 0
	v_addc_co_u32_e32 v5, vcc, 0, v63, vcc
	global_store_short v[4:5], v1, off
	v_add_co_u32_e32 v4, vcc, s5, v62
	s_mov_b32 s5, 0xf8000
	s_nop 0
	v_addc_co_u32_e32 v5, vcc, 0, v63, vcc
	v_add_co_u32_e32 v0, vcc, s5, v62
	global_store_short_d16_hi v[4:5], v1, off
	s_nop 0
	v_addc_co_u32_e32 v1, vcc, 0, v63, vcc
	s_mov_b32 s5, 0xfa000
	global_store_short v[0:1], v2, off
	v_add_co_u32_e32 v0, vcc, s5, v62
	s_nop 1
	v_addc_co_u32_e32 v1, vcc, 0, v63, vcc
	global_store_short_d16_hi v[0:1], v2, off
	v_add_co_u32_e32 v0, vcc, 0xfc000, v62
	s_nop 1
	v_addc_co_u32_e32 v1, vcc, 0, v63, vcc
	global_store_short v[0:1], v3, off
	v_add_co_u32_e32 v0, vcc, 0xfe000, v62
	s_nop 1
	v_addc_co_u32_e32 v1, vcc, 0, v63, vcc
	global_store_short_d16_hi v[0:1], v3, off
	s_cbranch_scc0 .LBB0_551

; DI void load16(const bf16_t* p, float* v) { unpack8(*(const u32x4*)p, v); unpack8(*(const u32x4*)(p + 8), v + 8); }
; DI void store16(bf16_t* p, const float* v) { *(u32x4*)p = pack8(v); *(u32x4*)(p + 8) = pack8(v + 8); }
; DI void post_memrow(int row, int lane, const bf16_t* MKV, const float* gmk, bf16_t* MK) {
;     float v[16];
;     const int ln = lane & 31;
;     load16(MKV + (size_t)row * 1024 + 16 * ln, v);
;     float ss = 0.f;
; #pragma unroll
;     for (int i = 0; i < 16; ++i) ss += v[i] * v[i];
;     ss += __shfl_xor(ss, 1); ss += __shfl_xor(ss, 2); ss += __shfl_xor(ss, 4);
;     const float rs = rsqrtf(ss * (1.f / 128.f) + EPS_);
;     const int d0 = 16 * (ln & 7);
; #pragma unroll
;     for (int i = 0; i < 16; ++i) v[i] = v[i] * rs * gmk[d0 + i];
;     if (lane < 32) store16(MK + (size_t)row * 512 + 16 * ln, v);
; }
.LBB0_555:
	v_lshl_add_u64 v[2:3], s[4:5], 0, v[160:161]
	v_add_co_u32_e32 v6, vcc, 0x24600000, v2
	s_nop 1
	v_addc_co_u32_e32 v7, vcc, 0, v3, vcc
	global_load_dwordx4 v[2:5], v[6:7], off
	global_load_dwordx4 v[12:15], v[6:7], off offset:16
	s_waitcnt vmcnt(0) lgkmcnt(0)
	v_lshlrev_b32_e32 v16, 16, v2
	v_and_b32_e32 v17, 0xffff0000, v2
	v_lshlrev_b32_e32 v8, 16, v3
	v_and_b32_e32 v9, 0xffff0000, v3
	v_pk_mul_f32 v[22:23], v[16:17], v[16:17]
	v_pk_mul_f32 v[24:25], v[8:9], v[8:9]
	v_add_f32_e32 v21, v22, v23
	v_lshlrev_b32_e32 v6, 16, v4
	v_and_b32_e32 v7, 0xffff0000, v4
	v_add_f32_e32 v21, v24, v21
	v_pk_mul_f32 v[26:27], v[6:7], v[6:7]
	v_add_f32_e32 v21, v25, v21
	v_lshlrev_b32_e32 v4, 16, v5
	v_and_b32_e32 v5, 0xffff0000, v5
	v_add_f32_e32 v21, v26, v21
	v_pk_mul_f32 v[28:29], v[4:5], v[4:5]
	v_add_f32_e32 v21, v27, v21
	v_lshlrev_b32_e32 v2, 16, v12
	v_and_b32_e32 v3, 0xffff0000, v12
	v_add_f32_e32 v21, v28, v21
	v_pk_mul_f32 v[30:31], v[2:3], v[2:3]
	v_add_f32_e32 v21, v29, v21
	v_lshlrev_b32_e32 v10, 16, v13
	v_and_b32_e32 v11, 0xffff0000, v13
	v_add_f32_e32 v21, v30, v21
	v_pk_mul_f32 v[32:33], v[10:11], v[10:11]
	v_add_f32_e32 v21, v31, v21
	v_lshlrev_b32_e32 v12, 16, v14
	v_and_b32_e32 v13, 0xffff0000, v14
	v_add_f32_e32 v21, v32, v21
	v_pk_mul_f32 v[34:35], v[12:13], v[12:13]
	v_add_f32_e32 v21, v33, v21
	v_lshlrev_b32_e32 v14, 16, v15
	v_and_b32_e32 v15, 0xffff0000, v15
	v_add_f32_e32 v21, v34, v21
	v_pk_mul_f32 v[36:37], v[14:15], v[14:15]
	v_add_f32_e32 v21, v35, v21
	v_add_f32_e32 v21, v36, v21
	v_add_f32_e32 v21, v37, v21
	ds_bpermute_b32 v22, v18, v21
	s_waitcnt lgkmcnt(0)
	v_add_f32_e32 v21, v21, v22
	ds_bpermute_b32 v22, v19, v21
	s_waitcnt lgkmcnt(0)
	v_add_f32_e32 v21, v21, v22
	ds_bpermute_b32 v22, v20, v21
	s_and_saveexec_b64 s[6:7], s[36:37]
	s_cbranch_execz .LBB0_554
	s_waitcnt lgkmcnt(0)
	v_add_f32_e32 v21, v21, v22
	v_fmamk_f32 v21, v21, 0x3c000000, v187
	v_cmp_gt_f32_e32 vcc, s97, v21
	v_mul_f32_e32 v22, 0x4b800000, v21
	s_mov_b32 s3, 0x23c00000
	v_cndmask_b32_e32 v21, v21, v22, vcc
	v_rsq_f32_e32 v21, v21
	s_nop 0
	v_mul_f32_e32 v22, 0x45800000, v21
	v_cndmask_b32_e32 v38, v21, v22, vcc
	global_load_dwordx4 v[22:25], v[0:1], off offset:48
	global_load_dwordx4 v[26:29], v[0:1], off offset:32
	global_load_dwordx4 v[30:33], v[0:1], off offset:16
	global_load_dwordx4 v[34:37], v[0:1], off
	v_pk_mul_f32 v[2:3], v[38:39], v[2:3] op_sel_hi:[0,1]
	v_pk_mul_f32 v[6:7], v[38:39], v[6:7] op_sel_hi:[0,1]
	v_pk_mul_f32 v[16:17], v[38:39], v[16:17] op_sel_hi:[0,1]
	v_pk_mul_f32 v[8:9], v[38:39], v[8:9] op_sel_hi:[0,1]
	v_pk_mul_f32 v[4:5], v[38:39], v[4:5] op_sel_hi:[0,1]
	s_waitcnt vmcnt(2)
	v_pk_mul_f32 v[26:27], v[2:3], v[26:27]
	v_pk_mul_f32 v[2:3], v[38:39], v[10:11] op_sel_hi:[0,1]
	v_pk_mul_f32 v[10:11], v[2:3], v[28:29]
	v_pk_mul_f32 v[2:3], v[38:39], v[12:13] op_sel_hi:[0,1]
	s_waitcnt vmcnt(1)
	v_pk_mul_f32 v[6:7], v[6:7], v[30:31]
	v_pk_mul_f32 v[12:13], v[2:3], v[22:23]
	v_lshl_add_u64 v[22:23], s[0:1], 0, v[160:161]
	s_waitcnt vmcnt(0)
	v_pk_mul_f32 v[16:17], v[16:17], v[34:35]
	v_pk_mul_f32 v[8:9], v[8:9], v[36:37]
	v_pk_mul_f32 v[30:31], v[4:5], v[32:33]
	v_pk_mul_f32 v[2:3], v[38:39], v[14:15] op_sel_hi:[0,1]
	v_cvt_pk_bf16_f32 v4, v6, v7
	v_add_co_u32_e32 v6, vcc, s3, v22
	v_pk_mul_f32 v[14:15], v[2:3], v[24:25]
	v_cvt_pk_bf16_f32 v2, v16, v17
	v_cvt_pk_bf16_f32 v3, v8, v9
	v_cvt_pk_bf16_f32 v5, v30, v31
	v_addc_co_u32_e32 v7, vcc, 0, v23, vcc
	global_store_dwordx4 v[6:7], v[2:5], off
	s_nop 1
	v_cvt_pk_bf16_f32 v2, v26, v27
	v_cvt_pk_bf16_f32 v3, v10, v11
	v_cvt_pk_bf16_f32 v4, v12, v13
	v_cvt_pk_bf16_f32 v5, v14, v15
	global_store_dwordx4 v[6:7], v[2:5], off offset:16
	s_branch .LBB0_554

; DI void transpose64x128(const bf16_t* src, int pitch, bf16_t* dst, int dpitch, int lane) {
;     const bf16_t* sp = src + (size_t)lane * pitch;
;     u32x4 wq[16];
; #pragma unroll
;     for (int c = 0; c < 16; ++c) wq[c] = *(const u32x4*)(sp + 8 * c);
; #pragma unroll
;     for (int c = 0; c < 16; ++c) {
;         const u32x4 w = wq[c];
;         bf16_t* dp = dst + (size_t)(8 * c) * dpitch + lane;
;         dp[0] = (bf16_t)(w.x & 0xffffu); dp[dpitch] = (bf16_t)(w.x >> 16);
;         dp[2 * (size_t)dpitch] = (bf16_t)(w.y & 0xffffu); dp[3 * (size_t)dpitch] = (bf16_t)(w.y >> 16);
;         dp[4 * (size_t)dpitch] = (bf16_t)(w.z & 0xffffu); dp[5 * (size_t)dpitch] = (bf16_t)(w.z >> 16);
;         dp[6 * (size_t)dpitch] = (bf16_t)(w.w & 0xffffu); dp[7 * (size_t)dpitch] = (bf16_t)(w.w >> 16);
;     }
.LBB0_559:
	s_ashr_i32 s6, s8, 4
	s_ashr_i32 s7, s6, 31
	s_ashr_i32 s4, s8, 2
	s_and_b32 s3, s2, 0xc0
	s_lshl_b64 s[6:7], s[6:7], 19
	s_add_u32 s5, s44, s6
	s_addc_u32 s6, s45, s7
	s_lshl_b32 s7, s3, 11
	s_add_u32 s5, s5, s7
	s_addc_u32 s7, s6, 0
	s_lshl_b32 s6, s4, 8
	s_and_b32 s6, s6, 0x300
	s_add_u32 s6, s5, s6
	s_addc_u32 s7, s7, 0
	s_ashr_i32 s5, s4, 31
	s_lshl_b64 s[4:5], s[4:5], 16
	s_add_u32 s4, s0, s4
	s_addc_u32 s5, s1, s5
	s_lshl_b32 s3, s3, 1
	s_add_u32 s4, s4, s3
	v_lshl_add_u64 v[0:1], s[6:7], 0, v[160:161]
	s_mov_b64 s[6:7], 0x24600400
	s_mov_b32 s3, 0x24600000
	v_lshl_add_u64 v[2:3], v[0:1], 0, s[6:7]
	v_add_co_u32_e32 v0, vcc, s3, v0
	s_addc_u32 s5, s5, 0
	s_nop 0
	v_addc_co_u32_e32 v1, vcc, 0, v1, vcc
	global_load_dwordx4 v[32:35], v[0:1], off offset:1024
	global_load_dwordx4 v[36:39], v[2:3], off offset:16
	global_load_dwordx4 v[40:43], v[2:3], off offset:32
	global_load_dwordx4 v[44:47], v[2:3], off offset:48
	global_load_dwordx4 v[48:51], v[2:3], off offset:64
	global_load_dwordx4 v[52:55], v[2:3], off offset:80
	global_load_dwordx4 v[56:59], v[2:3], off offset:96
	global_load_dwordx4 v[60:63], v[2:3], off offset:112
	global_load_dwordx4 v[64:67], v[2:3], off offset:128
	global_load_dwordx4 v[24:27], v[2:3], off offset:144
	s_waitcnt lgkmcnt(0)
	global_load_dwordx4 v[20:23], v[2:3], off offset:160
	global_load_dwordx4 v[16:19], v[2:3], off offset:176
	global_load_dwordx4 v[12:15], v[2:3], off offset:192
	global_load_dwordx4 v[8:11], v[2:3], off offset:208
	global_load_dwordx4 v[4:7], v[2:3], off offset:224
	s_nop 0
	global_load_dwordx4 v[0:3], v[2:3], off offset:240
	v_mov_b32_e32 v29, v161
	v_lshl_add_u64 v[30:31], s[4:5], 0, v[28:29]
	s_movk_i32 s3, 0x1000
	s_add_i32 s8, s8, s96
	s_add_i32 s2, s2, s12
	s_cmp_gt_i32 s8, 63
	s_waitcnt vmcnt(0)
	global_store_short v[30:31], v32, off
	global_store_short_d16_hi v[30:31], v32, off offset:512
	global_store_short v[30:31], v33, off offset:1024
	global_store_short_d16_hi v[30:31], v33, off offset:1536
	global_store_short v[30:31], v34, off offset:2048
	global_store_short_d16_hi v[30:31], v34, off offset:2560
	global_store_short v[30:31], v35, off offset:3072
	global_store_short_d16_hi v[30:31], v35, off offset:3584
	v_add_co_u32_e32 v32, vcc, s3, v30
	s_movk_i32 s3, 0x3000
	s_nop 0
	v_addc_co_u32_e32 v33, vcc, 0, v31, vcc
	global_store_short v[32:33], v36, off
	global_store_short_d16_hi v[32:33], v36, off offset:512
	global_store_short v[32:33], v37, off offset:1024
	global_store_short_d16_hi v[32:33], v37, off offset:1536
	global_store_short v[32:33], v38, off offset:2048
	global_store_short_d16_hi v[32:33], v38, off offset:2560
	global_store_short v[32:33], v39, off offset:3072
	global_store_short_d16_hi v[32:33], v39, off offset:3584
	v_add_co_u32_e32 v32, vcc, s57, v30
	s_nop 1
	v_addc_co_u32_e32 v33, vcc, 0, v31, vcc
	global_store_short v[32:33], v40, off
	global_store_short_d16_hi v[32:33], v40, off offset:512
	global_store_short v[32:33], v41, off offset:1024
	global_store_short_d16_hi v[32:33], v41, off offset:1536
	global_store_short v[32:33], v42, off offset:2048
	global_store_short_d16_hi v[32:33], v42, off offset:2560
	global_store_short v[32:33], v43, off offset:3072
	global_store_short_d16_hi v[32:33], v43, off offset:3584
	v_add_co_u32_e32 v32, vcc, s3, v30
	s_movk_i32 s3, 0x5000
	s_nop 0
	v_addc_co_u32_e32 v33, vcc, 0, v31, vcc
	global_store_short v[32:33], v44, off
	global_store_short_d16_hi v[32:33], v44, off offset:512
	global_store_short v[32:33], v45, off offset:1024
	global_store_short_d16_hi v[32:33], v45, off offset:1536
	global_store_short v[32:33], v46, off offset:2048
	global_store_short_d16_hi v[32:33], v46, off offset:2560
	global_store_short v[32:33], v47, off offset:3072
	global_store_short_d16_hi v[32:33], v47, off offset:3584
	v_add_co_u32_e32 v32, vcc, s13, v30
	s_nop 1
	v_addc_co_u32_e32 v33, vcc, 0, v31, vcc
	global_store_short v[32:33], v48, off
	global_store_short_d16_hi v[32:33], v48, off offset:512
	global_store_short v[32:33], v49, off offset:1024
	global_store_short_d16_hi v[32:33], v49, off offset:1536
	global_store_short v[32:33], v50, off offset:2048
	global_store_short_d16_hi v[32:33], v50, off offset:2560
	global_store_short v[32:33], v51, off offset:3072
	global_store_short_d16_hi v[32:33], v51, off offset:3584
	v_add_co_u32_e32 v32, vcc, s3, v30
	s_movk_i32 s3, 0x7000
	s_nop 0
	v_addc_co_u32_e32 v33, vcc, 0, v31, vcc
	global_store_short v[32:33], v52, off
	global_store_short_d16_hi v[32:33], v52, off offset:512
	global_store_short v[32:33], v53, off offset:1024
	global_store_short_d16_hi v[32:33], v53, off offset:1536
	global_store_short v[32:33], v54, off offset:2048
	global_store_short_d16_hi v[32:33], v54, off offset:2560
	global_store_short v[32:33], v55, off offset:3072
	global_store_short_d16_hi v[32:33], v55, off offset:3584
	v_add_co_u32_e32 v32, vcc, s10, v30
	s_nop 1
	v_addc_co_u32_e32 v33, vcc, 0, v31, vcc
	global_store_short v[32:33], v56, off
	global_store_short_d16_hi v[32:33], v56, off offset:512
	global_store_short v[32:33], v57, off offset:1024
	global_store_short_d16_hi v[32:33], v57, off offset:1536
	global_store_short v[32:33], v58, off offset:2048
	global_store_short_d16_hi v[32:33], v58, off offset:2560
	global_store_short v[32:33], v59, off offset:3072
	global_store_short_d16_hi v[32:33], v59, off offset:3584
	v_add_co_u32_e32 v32, vcc, s3, v30
	s_mov_b32 s3, 0x9000
	s_nop 0
	v_addc_co_u32_e32 v33, vcc, 0, v31, vcc
	global_store_short v[32:33], v60, off
	global_store_short_d16_hi v[32:33], v60, off offset:512
	global_store_short v[32:33], v61, off offset:1024
	global_store_short_d16_hi v[32:33], v61, off offset:1536
	global_store_short v[32:33], v62, off offset:2048
	global_store_short_d16_hi v[32:33], v62, off offset:2560
	global_store_short v[32:33], v63, off offset:3072
	global_store_short_d16_hi v[32:33], v63, off offset:3584
	v_add_co_u32_e32 v32, vcc, s11, v30
	s_nop 1
	v_addc_co_u32_e32 v33, vcc, 0, v31, vcc
	global_store_short v[32:33], v64, off
	global_store_short_d16_hi v[32:33], v64, off offset:512
	global_store_short v[32:33], v65, off offset:1024
	global_store_short_d16_hi v[32:33], v65, off offset:1536
	global_store_short v[32:33], v66, off offset:2048
	global_store_short_d16_hi v[32:33], v66, off offset:2560
	global_store_short v[32:33], v67, off offset:3072
	global_store_short_d16_hi v[32:33], v67, off offset:3584
	v_add_co_u32_e32 v32, vcc, s3, v30
	s_mov_b32 s3, 0xb000
	s_nop 0
	v_addc_co_u32_e32 v33, vcc, 0, v31, vcc
	global_store_short v[32:33], v24, off
	global_store_short_d16_hi v[32:33], v24, off offset:512
	global_store_short v[32:33], v25, off offset:1024
	global_store_short_d16_hi v[32:33], v25, off offset:1536
	global_store_short v[32:33], v26, off offset:2048
	global_store_short_d16_hi v[32:33], v26, off offset:2560
	global_store_short v[32:33], v27, off offset:3072
	global_store_short_d16_hi v[32:33], v27, off offset:3584
	v_add_co_u32_e32 v24, vcc, s16, v30
	s_nop 1
	v_addc_co_u32_e32 v25, vcc, 0, v31, vcc
	s_waitcnt lgkmcnt(0)
; DI void transpose64x128(const bf16_t* src, int pitch, bf16_t* dst, int dpitch, int lane) {
;     const bf16_t* sp = src + (size_t)lane * pitch;
;     u32x4 wq[16];
; #pragma unroll
;     for (int c = 0; c < 16; ++c) wq[c] = *(const u32x4*)(sp + 8 * c);
; #pragma unroll
;     for (int c = 0; c < 16; ++c) {
;         const u32x4 w = wq[c];
;         bf16_t* dp = dst + (size_t)(8 * c) * dpitch + lane;
;         dp[0] = (bf16_t)(w.x & 0xffffu); dp[dpitch] = (bf16_t)(w.x >> 16);
;         dp[2 * (size_t)dpitch] = (bf16_t)(w.y & 0xffffu); dp[3 * (size_t)dpitch] = (bf16_t)(w.y >> 16);
;         dp[4 * (size_t)dpitch] = (bf16_t)(w.z & 0xffffu); dp[5 * (size_t)dpitch] = (bf16_t)(w.z >> 16);
;         dp[6 * (size_t)dpitch] = (bf16_t)(w.w & 0xffffu); dp[7 * (size_t)dpitch] = (bf16_t)(w.w >> 16);
;     }
	global_store_short v[24:25], v20, off
	global_store_short_d16_hi v[24:25], v20, off offset:512
	global_store_short v[24:25], v21, off offset:1024
	global_store_short_d16_hi v[24:25], v21, off offset:1536
	global_store_short v[24:25], v22, off offset:2048
	global_store_short_d16_hi v[24:25], v22, off offset:2560
	global_store_short v[24:25], v23, off offset:3072
	global_store_short_d16_hi v[24:25], v23, off offset:3584
	v_add_co_u32_e32 v20, vcc, s3, v30
	s_mov_b32 s3, 0xd000
	s_nop 0
	v_addc_co_u32_e32 v21, vcc, 0, v31, vcc
	global_store_short v[20:21], v16, off
	global_store_short_d16_hi v[20:21], v16, off offset:512
	global_store_short v[20:21], v17, off offset:1024
	global_store_short_d16_hi v[20:21], v17, off offset:1536
	global_store_short v[20:21], v18, off offset:2048
	global_store_short_d16_hi v[20:21], v18, off offset:2560
	global_store_short v[20:21], v19, off offset:3072
	global_store_short_d16_hi v[20:21], v19, off offset:3584
	v_add_co_u32_e32 v16, vcc, s17, v30
	s_nop 1
	v_addc_co_u32_e32 v17, vcc, 0, v31, vcc
	global_store_short v[16:17], v12, off
	global_store_short_d16_hi v[16:17], v12, off offset:512
	global_store_short v[16:17], v13, off offset:1024
	global_store_short_d16_hi v[16:17], v13, off offset:1536
	global_store_short v[16:17], v14, off offset:2048
	global_store_short_d16_hi v[16:17], v14, off offset:2560
	global_store_short v[16:17], v15, off offset:3072
	global_store_short_d16_hi v[16:17], v15, off offset:3584
	v_add_co_u32_e32 v12, vcc, s3, v30
	s_mov_b32 s3, 0xf000
	s_nop 0
	v_addc_co_u32_e32 v13, vcc, 0, v31, vcc
	global_store_short v[12:13], v8, off
	global_store_short_d16_hi v[12:13], v8, off offset:512
	global_store_short v[12:13], v9, off offset:1024
	global_store_short_d16_hi v[12:13], v9, off offset:1536
	global_store_short v[12:13], v10, off offset:2048
	global_store_short_d16_hi v[12:13], v10, off offset:2560
	global_store_short v[12:13], v11, off offset:3072
	global_store_short_d16_hi v[12:13], v11, off offset:3584
	v_add_co_u32_e32 v8, vcc, s18, v30
	s_nop 1
	v_addc_co_u32_e32 v9, vcc, 0, v31, vcc
	global_store_short v[8:9], v4, off
	global_store_short_d16_hi v[8:9], v4, off offset:512
	global_store_short v[8:9], v5, off offset:1024
	global_store_short_d16_hi v[8:9], v5, off offset:1536
	global_store_short v[8:9], v6, off offset:2048
	global_store_short_d16_hi v[8:9], v6, off offset:2560
	global_store_short v[8:9], v7, off offset:3072
	global_store_short_d16_hi v[8:9], v7, off offset:3584
	v_add_co_u32_e32 v4, vcc, s3, v30
	s_nop 1
	v_addc_co_u32_e32 v5, vcc, 0, v31, vcc
	global_store_short v[4:5], v0, off
	global_store_short_d16_hi v[4:5], v0, off offset:512
	global_store_short v[4:5], v1, off offset:1024
	global_store_short_d16_hi v[4:5], v1, off offset:1536
	global_store_short v[4:5], v2, off offset:2048
	global_store_short_d16_hi v[4:5], v2, off offset:2560
	global_store_short v[4:5], v3, off offset:3072
	global_store_short_d16_hi v[4:5], v3, off offset:3584
	s_cbranch_scc0 .LBB0_559

; #define IDX_LOADG(dst, grp_) do { _Pragma("unroll") for (int tt = 0; tt < 4; ++tt) { const bf16_t* p_ = ikl + (size_t)(64 * (grp_) + 16 * tt) * 64; dst[tt][0] = *(const bf16x8*)p_; dst[tt][1] = *(const bf16x8*)(p_ + 32); } } while (0)
; DI void idx_rows(LAS unsigned char* lds, int b, int tg, const bf16_t* IQ, const bf16_t* IK, const float* IW, unsigned long long* maskT) {
;     ...
;         __syncthreads();
;         if (wave < ngrp) IDX_LOADG(bA, wave);
;         for (int grp = wave; grp < ngrp; grp += 16) {
;             if (grp + 8 < ngrp) IDX_LOADG(bB, grp + 8);
;             IDX_COMPUTE(bA, grp);
;             if (grp + 8 < ngrp) {
;                 if (grp + 16 < ngrp) IDX_LOADG(bA, grp + 16);
;                 IDX_COMPUTE(bB, grp + 8);
.LBB0_623:
	s_add_i32 s7, s15, 8
	s_cmp_le_i32 s7, s0
	s_cselect_b64 s[8:9], -1, 0
	s_cmp_gt_i32 s7, s0
	s_cbranch_scc1 .LBB0_625
	s_add_i32 s16, s6, 0xfffffdd0
	s_ashr_i32 s17, s16, 31
	s_lshl_b64 s[16:17], s[16:17], 7
	v_lshl_add_u64 v[128:129], v[172:173], 0, s[16:17]
	s_add_i32 s16, s6, 0xfffffde0
	s_ashr_i32 s17, s16, 31
	s_lshl_b64 s[16:17], s[16:17], 7
	v_lshl_add_u64 v[136:137], v[172:173], 0, s[16:17]
	s_add_i32 s16, s6, 0xfffffdf0
	s_ashr_i32 s17, s16, 31
	s_lshl_b64 s[16:17], s[16:17], 7
	v_lshl_add_u64 v[144:145], v[172:173], 0, s[16:17]
	s_add_i32 s16, s6, 0xfffffe00
	s_ashr_i32 s17, s16, 31
	s_lshl_b64 s[16:17], s[16:17], 7
	v_lshl_add_u64 v[152:153], v[172:173], 0, s[16:17]
	global_load_dwordx4 v[132:135], v[128:129], off
	s_nop 0
	global_load_dwordx4 v[128:131], v[128:129], off offset:64
	s_nop 0
	global_load_dwordx4 v[140:143], v[136:137], off
	s_nop 0
	global_load_dwordx4 v[136:139], v[136:137], off offset:64
	s_nop 0
	global_load_dwordx4 v[148:151], v[144:145], off
	s_nop 0
	global_load_dwordx4 v[144:147], v[144:145], off offset:64
	s_nop 0
	global_load_dwordx4 v[156:159], v[152:153], off
	s_nop 0
	global_load_dwordx4 v[152:155], v[152:153], off offset:64
.LBB0_625:
	s_waitcnt vmcnt(0) lgkmcnt(0)
	v_mfma_f32_16x16x32_bf16 v[178:181], v[0:3], v[96:99], 0
	v_add_u32_e32 v175, s6, v174
	v_add_u32_e32 v176, 0xfffffbd0, v175
	v_cmp_ge_i32_e32 vcc, s1, v176
	v_mfma_f32_16x16x32_bf16 v[182:185], v[0:3], v[104:107], 0
	v_add_u32_e32 v166, 0xffff0000, v160
	s_add_i32 s15, s15, 16
	v_mfma_f32_16x16x32_bf16 v[194:197], v[0:3], v[112:115], 0
	v_mfma_f32_16x16x32_bf16 v[198:201], v[0:3], v[120:123], 0
	v_mfma_f32_16x16x32_bf16 v[178:181], v[4:7], v[100:103], v[178:181]
	v_mfma_f32_16x16x32_bf16 v[182:185], v[4:7], v[108:111], v[182:185]
	v_mfma_f32_16x16x32_bf16 v[194:197], v[4:7], v[116:119], v[194:197]
	s_nop 5
	v_max_i32_e32 v180, 0, v180
	v_max_i32_e32 v181, 0, v181
	v_max_i32_e32 v178, 0, v178
	v_mfma_f32_16x16x32_bf16 v[198:201], v[4:7], v[124:127], v[198:201]
	v_max_i32_e32 v179, 0, v179
	v_pk_mul_f32 v[180:181], v[10:11], v[180:181]
	s_nop 0
	v_pk_fma_f32 v[178:179], v[8:9], v[178:179], v[180:181]
	v_max_i32_e32 v180, 0, v182
	v_max_i32_e32 v181, 0, v183
	v_max_i32_e32 v182, 0, v184
	v_max_i32_e32 v183, 0, v185
	v_pk_mul_f32 v[182:183], v[10:11], v[182:183]
	v_max_i32_e32 v184, 0, v196
	v_max_i32_e32 v185, 0, v197
	v_pk_fma_f32 v[180:181], v[8:9], v[180:181], v[182:183]
	v_max_i32_e32 v182, 0, v194
	v_max_i32_e32 v183, 0, v195
	v_pk_mul_f32 v[184:185], v[10:11], v[184:185]
	v_max_i32_e32 v194, 0, v200
	v_max_i32_e32 v195, 0, v201
	v_pk_add_f32 v[178:179], v[178:179], v[178:179] op_sel:[0,1] op_sel_hi:[1,0]
	v_pk_add_f32 v[180:181], v[180:181], v[180:181] op_sel:[0,1] op_sel_hi:[1,0]
	v_pk_fma_f32 v[182:183], v[8:9], v[182:183], v[184:185]
	v_max_i32_e32 v184, 0, v198
	v_max_i32_e32 v185, 0, v199
	v_pk_mul_f32 v[194:195], v[10:11], v[194:195]
	v_permlane16_swap_b32_e32 v178, v180
	v_pk_fma_f32 v[184:185], v[8:9], v[184:185], v[194:195]
	v_pk_add_f32 v[182:183], v[182:183], v[182:183] op_sel:[0,1] op_sel_hi:[1,0]
	v_pk_add_f32 v[184:185], v[184:185], v[184:185] op_sel:[0,1] op_sel_hi:[1,0]
	v_add_f32_e32 v167, v178, v180
	v_mfma_f32_16x16x32_bf16 v[178:181], v[12:15], v[96:99], 0
	v_permlane16_swap_b32_e32 v182, v184
	v_add_f32_e32 v168, v182, v184
	v_mfma_f32_16x16x32_bf16 v[182:185], v[12:15], v[104:107], 0
	s_nop 0
	v_permlane32_swap_b32_e32 v167, v168
	v_add_f32_e32 v167, v167, v168
	v_mfma_f32_16x16x32_bf16 v[194:197], v[12:15], v[112:115], 0
	v_ashrrev_i32_e32 v168, 31, v167
	v_bitop3_b32 v167, v168, v167, s33 bitop3:0x36
	v_cndmask_b32_e32 v167, 0, v167, vcc
	v_mfma_f32_16x16x32_bf16 v[198:201], v[12:15], v[120:123], 0
	ds_write_b32 v166, v167
	v_cmp_ge_i32_e32 vcc, s4, v176
	v_mfma_f32_16x16x32_bf16 v[178:181], v[16:19], v[100:103], v[178:181]
	v_mfma_f32_16x16x32_bf16 v[182:185], v[16:19], v[108:111], v[182:185]
	v_mfma_f32_16x16x32_bf16 v[194:197], v[16:19], v[116:119], v[194:197]
	s_nop 5
	v_max_i32_e32 v180, 0, v180
	v_max_i32_e32 v181, 0, v181
	v_max_i32_e32 v178, 0, v178
	v_mfma_f32_16x16x32_bf16 v[198:201], v[16:19], v[124:127], v[198:201]
	v_max_i32_e32 v179, 0, v179
	v_pk_mul_f32 v[180:181], v[22:23], v[180:181]
	s_nop 0
	v_pk_fma_f32 v[178:179], v[20:21], v[178:179], v[180:181]
	v_max_i32_e32 v180, 0, v182
	v_max_i32_e32 v181, 0, v183
	v_max_i32_e32 v182, 0, v184
	v_max_i32_e32 v183, 0, v185
	v_pk_mul_f32 v[182:183], v[22:23], v[182:183]
	v_max_i32_e32 v184, 0, v196
	v_max_i32_e32 v185, 0, v197
	v_pk_fma_f32 v[180:181], v[20:21], v[180:181], v[182:183]
	v_max_i32_e32 v182, 0, v194
	v_max_i32_e32 v183, 0, v195
	v_pk_mul_f32 v[184:185], v[22:23], v[184:185]
	v_max_i32_e32 v194, 0, v200
	v_max_i32_e32 v195, 0, v201
	v_pk_add_f32 v[178:179], v[178:179], v[178:179] op_sel:[0,1] op_sel_hi:[1,0]
	v_pk_add_f32 v[180:181], v[180:181], v[180:181] op_sel:[0,1] op_sel_hi:[1,0]
	v_pk_fma_f32 v[182:183], v[20:21], v[182:183], v[184:185]
	v_max_i32_e32 v184, 0, v198
	v_max_i32_e32 v185, 0, v199
	v_pk_mul_f32 v[194:195], v[22:23], v[194:195]
	v_permlane16_swap_b32_e32 v178, v180
	v_pk_fma_f32 v[184:185], v[20:21], v[184:185], v[194:195]
	v_pk_add_f32 v[182:183], v[182:183], v[182:183] op_sel:[0,1] op_sel_hi:[1,0]
	v_pk_add_f32 v[184:185], v[184:185], v[184:185] op_sel:[0,1] op_sel_hi:[1,0]
	v_add_f32_e32 v166, v178, v180
	v_mfma_f32_16x16x32_bf16 v[178:181], v[24:27], v[96:99], 0
	v_permlane16_swap_b32_e32 v182, v184
	v_add_f32_e32 v167, v182, v184
	v_mfma_f32_16x16x32_bf16 v[182:185], v[24:27], v[104:107], 0
	s_nop 0
	v_permlane32_swap_b32_e32 v166, v167
	v_add_f32_e32 v166, v166, v167
	v_mfma_f32_16x16x32_bf16 v[194:197], v[24:27], v[112:115], 0
	v_ashrrev_i32_e32 v167, 31, v166
	v_bitop3_b32 v166, v167, v166, s33 bitop3:0x36
	v_cndmask_b32_e32 v166, 0, v166, vcc
	v_mfma_f32_16x16x32_bf16 v[198:201], v[24:27], v[120:123], 0
	v_add_u32_e32 v167, 0xffff4000, v160
	ds_write_b32 v167, v166
	v_cmp_ge_i32_e32 vcc, s5, v176
	v_mfma_f32_16x16x32_bf16 v[178:181], v[28:31], v[100:103], v[178:181]
	v_mfma_f32_16x16x32_bf16 v[182:185], v[28:31], v[108:111], v[182:185]
	v_mfma_f32_16x16x32_bf16 v[194:197], v[28:31], v[116:119], v[194:197]
	s_nop 5
	v_max_i32_e32 v180, 0, v180
	v_max_i32_e32 v181, 0, v181
	v_max_i32_e32 v178, 0, v178
	v_mfma_f32_16x16x32_bf16 v[198:201], v[28:31], v[124:127], v[198:201]
	v_max_i32_e32 v179, 0, v179
	v_pk_mul_f32 v[180:181], v[34:35], v[180:181]
	s_nop 0
	v_pk_fma_f32 v[178:179], v[32:33], v[178:179], v[180:181]
	v_max_i32_e32 v180, 0, v182
	v_max_i32_e32 v181, 0, v183
	v_max_i32_e32 v182, 0, v184
	v_max_i32_e32 v183, 0, v185
	v_pk_mul_f32 v[182:183], v[34:35], v[182:183]
	v_max_i32_e32 v184, 0, v196
	v_max_i32_e32 v185, 0, v197
	v_pk_fma_f32 v[180:181], v[32:33], v[180:181], v[182:183]
	v_max_i32_e32 v182, 0, v194
	v_max_i32_e32 v183, 0, v195
	v_pk_mul_f32 v[184:185], v[34:35], v[184:185]
	v_max_i32_e32 v194, 0, v200
	v_max_i32_e32 v195, 0, v201
	v_pk_add_f32 v[178:179], v[178:179], v[178:179] op_sel:[0,1] op_sel_hi:[1,0]
	v_pk_add_f32 v[180:181], v[180:181], v[180:181] op_sel:[0,1] op_sel_hi:[1,0]
	v_pk_fma_f32 v[182:183], v[32:33], v[182:183], v[184:185]
	v_max_i32_e32 v184, 0, v198
	v_max_i32_e32 v185, 0, v199
	v_pk_mul_f32 v[194:195], v[34:35], v[194:195]
	v_permlane16_swap_b32_e32 v178, v180
	v_pk_fma_f32 v[184:185], v[32:33], v[184:185], v[194:195]
	v_pk_add_f32 v[182:183], v[182:183], v[182:183] op_sel:[0,1] op_sel_hi:[1,0]
	v_pk_add_f32 v[184:185], v[184:185], v[184:185] op_sel:[0,1] op_sel_hi:[1,0]
	v_add_f32_e32 v166, v178, v180
	v_mfma_f32_16x16x32_bf16 v[178:181], v[36:39], v[96:99], 0
	v_permlane16_swap_b32_e32 v182, v184
	v_add_f32_e32 v167, v182, v184
	v_mfma_f32_16x16x32_bf16 v[182:185], v[36:39], v[104:107], 0
	s_nop 0
	v_permlane32_swap_b32_e32 v166, v167
	v_add_f32_e32 v166, v166, v167
	v_mfma_f32_16x16x32_bf16 v[194:197], v[36:39], v[112:115], 0
	v_ashrrev_i32_e32 v167, 31, v166
	v_bitop3_b32 v166, v167, v166, s33 bitop3:0x36
	v_cndmask_b32_e32 v166, 0, v166, vcc
	v_mfma_f32_16x16x32_bf16 v[198:201], v[36:39], v[120:123], 0
	v_add_u32_e32 v167, 0xffff8000, v160
	ds_write_b32 v167, v166
	v_cmp_ge_i32_e32 vcc, s10, v176
	v_mfma_f32_16x16x32_bf16 v[178:181], v[40:43], v[100:103], v[178:181]
	v_mfma_f32_16x16x32_bf16 v[182:185], v[40:43], v[108:111], v[182:185]
	v_mfma_f32_16x16x32_bf16 v[194:197], v[40:43], v[116:119], v[194:197]
	s_nop 5
	v_max_i32_e32 v180, 0, v180
	v_max_i32_e32 v181, 0, v181
	v_max_i32_e32 v178, 0, v178
	v_mfma_f32_16x16x32_bf16 v[198:201], v[40:43], v[124:127], v[198:201]
	v_max_i32_e32 v179, 0, v179
	v_pk_mul_f32 v[180:181], v[46:47], v[180:181]
	s_nop 0
	v_pk_fma_f32 v[178:179], v[44:45], v[178:179], v[180:181]
	v_max_i32_e32 v180, 0, v182
	v_max_i32_e32 v181, 0, v183
	v_max_i32_e32 v182, 0, v184
	v_max_i32_e32 v183, 0, v185
	v_pk_mul_f32 v[182:183], v[46:47], v[182:183]
	v_max_i32_e32 v184, 0, v196
	v_max_i32_e32 v185, 0, v197
	v_pk_fma_f32 v[180:181], v[44:45], v[180:181], v[182:183]
	v_max_i32_e32 v182, 0, v194
	v_max_i32_e32 v183, 0, v195
	v_pk_mul_f32 v[184:185], v[46:47], v[184:185]
	v_max_i32_e32 v194, 0, v200
	v_max_i32_e32 v195, 0, v201
	v_pk_add_f32 v[178:179], v[178:179], v[178:179] op_sel:[0,1] op_sel_hi:[1,0]
	v_pk_add_f32 v[180:181], v[180:181], v[180:181] op_sel:[0,1] op_sel_hi:[1,0]
	v_pk_fma_f32 v[182:183], v[44:45], v[182:183], v[184:185]
	v_max_i32_e32 v184, 0, v198
	v_max_i32_e32 v185, 0, v199
	v_pk_mul_f32 v[194:195], v[46:47], v[194:195]
	v_permlane16_swap_b32_e32 v178, v180
	v_pk_fma_f32 v[184:185], v[44:45], v[184:185], v[194:195]
	v_pk_add_f32 v[182:183], v[182:183], v[182:183] op_sel:[0,1] op_sel_hi:[1,0]
	v_pk_add_f32 v[184:185], v[184:185], v[184:185] op_sel:[0,1] op_sel_hi:[1,0]
	v_add_f32_e32 v166, v178, v180
	v_mfma_f32_16x16x32_bf16 v[178:181], v[48:51], v[96:99], 0
	v_permlane16_swap_b32_e32 v182, v184
	v_add_f32_e32 v167, v182, v184
	v_mfma_f32_16x16x32_bf16 v[182:185], v[48:51], v[104:107], 0
	s_nop 0
	v_permlane32_swap_b32_e32 v166, v167
	v_add_f32_e32 v166, v166, v167
	v_mfma_f32_16x16x32_bf16 v[194:197], v[48:51], v[112:115], 0
	v_ashrrev_i32_e32 v167, 31, v166
	v_bitop3_b32 v166, v167, v166, s33 bitop3:0x36
	v_cndmask_b32_e32 v166, 0, v166, vcc
	v_mfma_f32_16x16x32_bf16 v[198:201], v[48:51], v[120:123], 0
	v_add_u32_e32 v167, 0xffffc000, v160
	ds_write_b32 v167, v166
	v_cmp_ge_i32_e32 vcc, s11, v176
	v_mfma_f32_16x16x32_bf16 v[178:181], v[52:55], v[100:103], v[178:181]
	v_mfma_f32_16x16x32_bf16 v[182:185], v[52:55], v[108:111], v[182:185]
	v_mfma_f32_16x16x32_bf16 v[194:197], v[52:55], v[116:119], v[194:197]
	s_nop 5
	v_max_i32_e32 v180, 0, v180
	v_max_i32_e32 v181, 0, v181
	v_max_i32_e32 v178, 0, v178
	v_mfma_f32_16x16x32_bf16 v[198:201], v[52:55], v[124:127], v[198:201]
	v_max_i32_e32 v179, 0, v179
	v_pk_mul_f32 v[180:181], v[58:59], v[180:181]
	s_nop 0
	v_pk_fma_f32 v[178:179], v[56:57], v[178:179], v[180:181]
	v_max_i32_e32 v180, 0, v182
	v_max_i32_e32 v181, 0, v183
	v_max_i32_e32 v182, 0, v184
	v_max_i32_e32 v183, 0, v185
	v_pk_mul_f32 v[182:183], v[58:59], v[182:183]
	v_max_i32_e32 v184, 0, v196
	v_max_i32_e32 v185, 0, v197
	v_pk_fma_f32 v[180:181], v[56:57], v[180:181], v[182:183]
	v_max_i32_e32 v182, 0, v194
	v_max_i32_e32 v183, 0, v195
	v_pk_mul_f32 v[184:185], v[58:59], v[184:185]
	v_max_i32_e32 v194, 0, v200
	v_max_i32_e32 v195, 0, v201
	v_pk_add_f32 v[178:179], v[178:179], v[178:179] op_sel:[0,1] op_sel_hi:[1,0]
	v_pk_add_f32 v[180:181], v[180:181], v[180:181] op_sel:[0,1] op_sel_hi:[1,0]
	v_pk_fma_f32 v[182:183], v[56:57], v[182:183], v[184:185]
	v_max_i32_e32 v184, 0, v198
	v_max_i32_e32 v185, 0, v199
	v_pk_mul_f32 v[194:195], v[58:59], v[194:195]
	v_permlane16_swap_b32_e32 v178, v180
	v_pk_fma_f32 v[184:185], v[56:57], v[184:185], v[194:195]
	v_pk_add_f32 v[182:183], v[182:183], v[182:183] op_sel:[0,1] op_sel_hi:[1,0]
	v_pk_add_f32 v[184:185], v[184:185], v[184:185] op_sel:[0,1] op_sel_hi:[1,0]
	v_add_f32_e32 v166, v178, v180
	v_mfma_f32_16x16x32_bf16 v[178:181], v[60:63], v[96:99], 0
	v_permlane16_swap_b32_e32 v182, v184
	v_add_f32_e32 v167, v182, v184
	v_mfma_f32_16x16x32_bf16 v[182:185], v[60:63], v[104:107], 0
	s_nop 0
	v_permlane32_swap_b32_e32 v166, v167
	v_add_f32_e32 v166, v166, v167
	v_mfma_f32_16x16x32_bf16 v[194:197], v[60:63], v[112:115], 0
	v_ashrrev_i32_e32 v167, 31, v166
	v_bitop3_b32 v166, v167, v166, s33 bitop3:0x36
	v_cndmask_b32_e32 v166, 0, v166, vcc
	v_mfma_f32_16x16x32_bf16 v[198:201], v[60:63], v[120:123], 0
	v_cmp_ge_i32_e32 vcc, s12, v176
	v_mfma_f32_16x16x32_bf16 v[178:181], v[64:67], v[100:103], v[178:181]
	v_mfma_f32_16x16x32_bf16 v[182:185], v[64:67], v[108:111], v[182:185]
	v_mfma_f32_16x16x32_bf16 v[194:197], v[64:67], v[116:119], v[194:197]
	s_nop 5
	v_max_i32_e32 v180, 0, v180
	v_max_i32_e32 v181, 0, v181
	v_max_i32_e32 v178, 0, v178
	v_mfma_f32_16x16x32_bf16 v[198:201], v[64:67], v[124:127], v[198:201]
	v_max_i32_e32 v179, 0, v179
	v_pk_mul_f32 v[180:181], v[70:71], v[180:181]
	s_nop 0
	v_pk_fma_f32 v[178:179], v[68:69], v[178:179], v[180:181]
	v_max_i32_e32 v180, 0, v182
	v_max_i32_e32 v181, 0, v183
	v_max_i32_e32 v182, 0, v184
	v_max_i32_e32 v183, 0, v185
	v_pk_mul_f32 v[182:183], v[70:71], v[182:183]
	v_max_i32_e32 v184, 0, v196
	v_max_i32_e32 v185, 0, v197
	v_pk_fma_f32 v[180:181], v[68:69], v[180:181], v[182:183]
	v_max_i32_e32 v182, 0, v194
	v_max_i32_e32 v183, 0, v195
	v_pk_mul_f32 v[184:185], v[70:71], v[184:185]
	v_max_i32_e32 v194, 0, v200
	v_max_i32_e32 v195, 0, v201
	v_pk_add_f32 v[178:179], v[178:179], v[178:179] op_sel:[0,1] op_sel_hi:[1,0]
	v_pk_add_f32 v[180:181], v[180:181], v[180:181] op_sel:[0,1] op_sel_hi:[1,0]
	v_pk_fma_f32 v[182:183], v[68:69], v[182:183], v[184:185]
	v_max_i32_e32 v184, 0, v198
	v_max_i32_e32 v185, 0, v199
	v_pk_mul_f32 v[194:195], v[70:71], v[194:195]
	v_permlane16_swap_b32_e32 v178, v180
	v_pk_fma_f32 v[184:185], v[68:69], v[184:185], v[194:195]
	v_pk_add_f32 v[182:183], v[182:183], v[182:183] op_sel:[0,1] op_sel_hi:[1,0]
	v_pk_add_f32 v[184:185], v[184:185], v[184:185] op_sel:[0,1] op_sel_hi:[1,0]
	v_add_f32_e32 v167, v178, v180
	v_mfma_f32_16x16x32_bf16 v[178:181], v[72:75], v[96:99], 0
	v_permlane16_swap_b32_e32 v182, v184
	v_add_f32_e32 v168, v182, v184
	v_mfma_f32_16x16x32_bf16 v[182:185], v[72:75], v[104:107], 0
	s_nop 0
	v_permlane32_swap_b32_e32 v167, v168
	v_add_f32_e32 v167, v167, v168
	v_mfma_f32_16x16x32_bf16 v[194:197], v[72:75], v[112:115], 0
	v_ashrrev_i32_e32 v168, 31, v167
	v_bitop3_b32 v167, v168, v167, s33 bitop3:0x36
	v_cndmask_b32_e32 v167, 0, v167, vcc
	v_mfma_f32_16x16x32_bf16 v[198:201], v[72:75], v[120:123], 0
	ds_write2st64_b32 v160, v166, v167 offset1:64
	v_cmp_ge_i32_e32 vcc, s13, v176
	v_mfma_f32_16x16x32_bf16 v[178:181], v[76:79], v[100:103], v[178:181]
	v_mfma_f32_16x16x32_bf16 v[182:185], v[76:79], v[108:111], v[182:185]
	v_mfma_f32_16x16x32_bf16 v[194:197], v[76:79], v[116:119], v[194:197]
	s_nop 5
	v_max_i32_e32 v180, 0, v180
	v_max_i32_e32 v181, 0, v181
	v_max_i32_e32 v178, 0, v178
	v_mfma_f32_16x16x32_bf16 v[198:201], v[76:79], v[124:127], v[198:201]
	v_max_i32_e32 v179, 0, v179
	v_pk_mul_f32 v[180:181], v[82:83], v[180:181]
	s_nop 0
	v_pk_fma_f32 v[178:179], v[80:81], v[178:179], v[180:181]
	v_max_i32_e32 v180, 0, v182
	v_max_i32_e32 v181, 0, v183
	v_max_i32_e32 v182, 0, v184
	v_max_i32_e32 v183, 0, v185
	v_pk_mul_f32 v[182:183], v[82:83], v[182:183]
	v_max_i32_e32 v184, 0, v196
	v_max_i32_e32 v185, 0, v197
	v_pk_fma_f32 v[180:181], v[80:81], v[180:181], v[182:183]
	v_max_i32_e32 v182, 0, v194
	v_max_i32_e32 v183, 0, v195
	v_pk_mul_f32 v[184:185], v[82:83], v[184:185]
; #define IDX_LOADG(dst, grp_) do { _Pragma("unroll") for (int tt = 0; tt < 4; ++tt) { const bf16_t* p_ = ikl + (size_t)(64 * (grp_) + 16 * tt) * 64; dst[tt][0] = *(const bf16x8*)p_; dst[tt][1] = *(const bf16x8*)(p_ + 32); } } while (0)
; DI void idx_rows(LAS unsigned char* lds, int b, int tg, const bf16_t* IQ, const bf16_t* IK, const float* IW, unsigned long long* maskT) {
;     ...
;         __syncthreads();
;         if (wave < ngrp) IDX_LOADG(bA, wave);
;         for (int grp = wave; grp < ngrp; grp += 16) {
;             if (grp + 8 < ngrp) IDX_LOADG(bB, grp + 8);
;             IDX_COMPUTE(bA, grp);
;             if (grp + 8 < ngrp) {
;                 if (grp + 16 < ngrp) IDX_LOADG(bA, grp + 16);
;                 IDX_COMPUTE(bB, grp + 8);
;             }
	v_max_i32_e32 v194, 0, v200
	v_max_i32_e32 v195, 0, v201
	v_pk_add_f32 v[178:179], v[178:179], v[178:179] op_sel:[0,1] op_sel_hi:[1,0]
	v_pk_add_f32 v[180:181], v[180:181], v[180:181] op_sel:[0,1] op_sel_hi:[1,0]
	v_pk_fma_f32 v[182:183], v[80:81], v[182:183], v[184:185]
	v_max_i32_e32 v184, 0, v198
	v_max_i32_e32 v185, 0, v199
	v_pk_mul_f32 v[194:195], v[82:83], v[194:195]
	v_permlane16_swap_b32_e32 v178, v180
	v_pk_fma_f32 v[184:185], v[80:81], v[184:185], v[194:195]
	v_pk_add_f32 v[182:183], v[182:183], v[182:183] op_sel:[0,1] op_sel_hi:[1,0]
	v_pk_add_f32 v[184:185], v[184:185], v[184:185] op_sel:[0,1] op_sel_hi:[1,0]
	v_add_f32_e32 v166, v178, v180
	v_mfma_f32_16x16x32_bf16 v[178:181], v[84:87], v[96:99], 0
	v_permlane16_swap_b32_e32 v182, v184
	v_add_f32_e32 v167, v182, v184
	v_mfma_f32_16x16x32_bf16 v[182:185], v[84:87], v[104:107], 0
	s_nop 0
	v_permlane32_swap_b32_e32 v166, v167
	v_add_f32_e32 v166, v166, v167
	v_mfma_f32_16x16x32_bf16 v[194:197], v[84:87], v[112:115], 0
	v_ashrrev_i32_e32 v167, 31, v166
	v_bitop3_b32 v166, v167, v166, s33 bitop3:0x36
	v_cndmask_b32_e32 v166, 0, v166, vcc
	v_mfma_f32_16x16x32_bf16 v[198:201], v[84:87], v[120:123], 0
	v_cmp_ge_i32_e32 vcc, s14, v176
	v_mfma_f32_16x16x32_bf16 v[178:181], v[88:91], v[100:103], v[178:181]
	v_mfma_f32_16x16x32_bf16 v[182:185], v[88:91], v[108:111], v[182:185]
	v_mfma_f32_16x16x32_bf16 v[194:197], v[88:91], v[116:119], v[194:197]
	s_nop 5
	v_max_i32_e32 v180, 0, v180
	v_max_i32_e32 v181, 0, v181
	v_max_i32_e32 v178, 0, v178
	v_mfma_f32_16x16x32_bf16 v[198:201], v[88:91], v[124:127], v[198:201]
	v_max_i32_e32 v179, 0, v179
	v_pk_mul_f32 v[180:181], v[94:95], v[180:181]
	s_nop 0
	v_pk_fma_f32 v[178:179], v[92:93], v[178:179], v[180:181]
	v_max_i32_e32 v180, 0, v182
	v_max_i32_e32 v181, 0, v183
	v_max_i32_e32 v182, 0, v184
	v_max_i32_e32 v183, 0, v185
	v_pk_mul_f32 v[182:183], v[94:95], v[182:183]
	v_max_i32_e32 v184, 0, v196
	v_max_i32_e32 v185, 0, v197
	v_pk_fma_f32 v[180:181], v[92:93], v[180:181], v[182:183]
	v_max_i32_e32 v182, 0, v194
	v_max_i32_e32 v183, 0, v195
	v_pk_mul_f32 v[184:185], v[94:95], v[184:185]
	v_max_i32_e32 v194, 0, v200
	v_max_i32_e32 v195, 0, v201
	v_pk_fma_f32 v[182:183], v[92:93], v[182:183], v[184:185]
	v_max_i32_e32 v184, 0, v198
	v_max_i32_e32 v185, 0, v199
	v_pk_mul_f32 v[194:195], v[94:95], v[194:195]
	v_pk_add_f32 v[178:179], v[178:179], v[178:179] op_sel:[0,1] op_sel_hi:[1,0]
	v_pk_fma_f32 v[184:185], v[92:93], v[184:185], v[194:195]
	v_pk_add_f32 v[180:181], v[180:181], v[180:181] op_sel:[0,1] op_sel_hi:[1,0]
	v_pk_add_f32 v[182:183], v[182:183], v[182:183] op_sel:[0,1] op_sel_hi:[1,0]
	v_pk_add_f32 v[184:185], v[184:185], v[184:185] op_sel:[0,1] op_sel_hi:[1,0]
	v_permlane16_swap_b32_e32 v178, v180
	s_nop 0
	v_permlane16_swap_b32_e32 v182, v184
	v_add_f32_e32 v167, v178, v180
	v_add_f32_e32 v168, v182, v184
	s_nop 1
	v_permlane32_swap_b32_e32 v167, v168
	v_add_f32_e32 v167, v167, v168
	v_ashrrev_i32_e32 v168, 31, v167
	v_bitop3_b32 v167, v168, v167, s33 bitop3:0x36
	v_cndmask_b32_e32 v167, 0, v167, vcc
	s_andn2_b64 vcc, exec, s[8:9]
	ds_write2st64_b32 v160, v166, v167 offset0:128 offset1:192
	s_cbranch_vccnz .LBB0_622
	s_cmp_gt_i32 s15, s0
	s_cbranch_scc1 .LBB0_621
	s_sub_i32 s8, s6, 48
	s_ashr_i32 s9, s8, 31
	s_lshl_b64 s[8:9], s[8:9], 7
	v_lshl_add_u64 v[100:101], v[172:173], 0, s[8:9]
	s_sub_i32 s8, s6, 32
	s_ashr_i32 s9, s8, 31
	s_lshl_b64 s[8:9], s[8:9], 7
	v_lshl_add_u64 v[108:109], v[172:173], 0, s[8:9]
	s_add_i32 s8, s6, -16
	s_ashr_i32 s9, s8, 31
	s_lshl_b64 s[8:9], s[8:9], 7
	s_ashr_i32 s7, s6, 31
	v_lshl_add_u64 v[116:117], v[172:173], 0, s[8:9]
	s_lshl_b64 s[8:9], s[6:7], 7
	v_lshl_add_u64 v[124:125], v[172:173], 0, s[8:9]
	global_load_dwordx4 v[96:99], v[100:101], off
	s_nop 0
	global_load_dwordx4 v[100:103], v[100:101], off offset:64
	s_nop 0
	global_load_dwordx4 v[104:107], v[108:109], off
	s_nop 0
	global_load_dwordx4 v[108:111], v[108:109], off offset:64
	s_nop 0
	global_load_dwordx4 v[112:115], v[116:117], off
	s_nop 0
	global_load_dwordx4 v[116:119], v[116:117], off offset:64
	s_nop 0
	global_load_dwordx4 v[120:123], v[124:125], off
	s_nop 0
	global_load_dwordx4 v[124:127], v[124:125], off offset:64
	s_branch .LBB0_621

; DI void idx_rows(LAS unsigned char* lds, int b, int tg, const bf16_t* IQ, const bf16_t* IK, const float* IW, unsigned long long* maskT) {
;     ...
;     const unsigned long long myword = ((unsigned long long)mhi << 32) | mlo;
;     if (lane <= imax) maskT[((size_t)b * 64 + lane) * S_ + t] = myword;
.LBB0_1158:
	v_cmp_ge_i32_e32 vcc, s7, v174
	s_and_saveexec_b64 s[0:1], vcc
	v_readlane_b32 s72, v255, 13
	v_readlane_b32 s74, v255, 15
	v_readlane_b32 s73, v255, 14
	v_readlane_b32 s75, v255, 16
	s_cbranch_execz .LBB0_1160
	s_ashr_i32 s7, s6, 31
	s_lshl_b32 s2, s29, 21
	v_readlane_b32 s3, v255, 32
	s_add_u32 s2, s3, s2
	v_readlane_b32 s3, v255, 33
	s_addc_u32 s3, s3, 0
	v_lshlrev_b32_e32 v160, 15, v174
	s_waitcnt lgkmcnt(0)
	v_lshl_add_u64 v[2:3], s[2:3], 0, v[160:161]
	v_lshl_add_u64 v[2:3], s[6:7], 3, v[2:3]
	global_store_dwordx2 v[2:3], v[0:1], off

; #define LAS __attribute__((address_space(3)))
; DI int fresh_tid() { int t = threadIdx.x; asm volatile("" : "+v"(t)); return t; }
; template <bool MASK>
; DI void attn_unit(LAS unsigned char* lds, const bf16_t* qrow, const bf16_t* kbase, int kpitch, const bf16_t* vtbase, int vtpitch, int ntiles,
;                   const unsigned long long* maskp, bf16_t* orow, float c1, float c2) {
;     const int tid = fresh_tid(), lane = tid & 63, r = lane & 31, h = lane >> 5;
;     bf16x8 qf[8];
; #pragma unroll
;     for (int ks = 0; ks < 8; ++ks) qf[ks] = *(const bf16x8*)(qrow + 16 * ks + 8 * h);
;     f32x16 o[4];
; #pragma unroll
;     for (int d = 0; d < 4; ++d)
; #pragma unroll
;         for (int i = 0; i < 16; ++i) o[d][i] = 0.f;
;     float l = 0.f;
;     u32x4 pk[2], pv[2];
;     const int ke0 = tid, ke1 = tid + 512;
;     const bf16_t* kg0 = kbase + (size_t)(ke0 >> 4) * kpitch + (ke0 & 15) * 8; const bf16_t* kg1 = kbase + (size_t)(ke1 >> 4) * kpitch + (ke1 & 15) * 8;
;     const int kl0 = (ke0 >> 4) * AK_PITCH + (ke0 & 15) * 16, kl1 = (ke1 >> 4) * AK_PITCH + (ke1 & 15) * 16;
;     const bf16_t* vg0 = vtbase + (size_t)(ke0 >> 3) * vtpitch + (ke0 & 7) * 8; const bf16_t* vg1 = vtbase + (size_t)(ke1 >> 3) * vtpitch + (ke1 & 7) * 8;
;     const int vl0 = AK_BYTES + (ke0 >> 3) * AV_PITCH + (ke0 & 7) * 16, vl1 = AK_BYTES + (ke1 >> 3) * AV_PITCH + (ke1 & 7) * 16;
;     pk[0] = *(const u32x4*)kg0; pk[1] = *(const u32x4*)kg1; pv[0] = *(const u32x4*)vg0; pv[1] = *(const u32x4*)vg1;
;     {
;         LAS unsigned char* nb = lds;
;         *(LAS u32x4*)(nb + kl0) = pk[0]; *(LAS u32x4*)(nb + kl1) = pk[1];
;         *(LAS u32x2*)(nb + vl0) = (u32x2){pv[0].x, pv[0].y}; *(LAS u32x2*)(nb + vl0 + 8) = (u32x2){pv[0].z, pv[0].w};
;         *(LAS u32x2*)(nb + vl1) = (u32x2){pv[1].x, pv[1].y}; *(LAS u32x2*)(nb + vl1 + 8) = (u32x2){pv[1].z, pv[1].w};
;     }
;     unsigned long long mw_next = ~0ull;
;     if (MASK) mw_next = maskp[0];
;     __syncthreads();
.LBB0_1165:
	s_ashr_i32 s6, s16, 4
	s_lshl_b32 s7, s16, 8
	s_ashr_i32 s2, s16, 6
	s_and_b32 s70, s7, 0xf00
	s_lshl_b32 s7, s6, 7
	s_ashr_i32 s3, s2, 31
	v_lshl_add_u64 v[0:1], v[144:145], 0, s[70:71]
	s_and_b32 s17, s7, 0x180
	s_lshl_b64 s[8:9], s[2:3], 21
	v_lshlrev_b64 v[0:1], 9, v[0:1]
	s_lshl_b32 s70, s17, 1
	s_lshl_b64 s[10:11], s[2:3], 18
	v_lshl_add_u64 v[148:149], s[8:9], 0, v[0:1]
	s_add_u32 s2, s12, s10
	v_mov_b32_e32 v14, v186
	v_lshl_add_u64 v[0:1], v[148:149], 1, s[0:1]
	s_addc_u32 s3, s13, s11
	v_lshl_add_u64 v[0:1], v[0:1], 0, s[70:71]
	v_bfe_u32 v2, v14, 5, 1
	v_ashrrev_i32_e32 v4, 4, v14
	s_add_u32 s18, s2, s70
	v_lshlrev_b32_e32 v160, 4, v2
	v_add_u32_e32 v15, 0x200, v14
	v_ashrrev_i32_e32 v5, 31, v4
	s_addc_u32 s19, s3, 0
	s_ashr_i32 s7, s6, 31
	v_lshl_add_u64 v[0:1], v[0:1], 0, v[160:161]
	v_lshlrev_b64 v[24:25], 10, v[4:5]
	v_lshlrev_b32_e32 v5, 4, v14
	v_ashrrev_i32_e32 v6, 4, v15
	s_lshl_b64 s[8:9], s[6:7], 16
	v_lshlrev_b32_e32 v146, 3, v2
	global_load_dwordx4 v[124:127], v[0:1], off
	global_load_dwordx4 v[120:123], v[0:1], off offset:32
	global_load_dwordx4 v[116:119], v[0:1], off offset:64
	global_load_dwordx4 v[112:115], v[0:1], off offset:96
	global_load_dwordx4 v[108:111], v[0:1], off offset:128
	global_load_dwordx4 v[104:107], v[0:1], off offset:160
	global_load_dwordx4 v[100:103], v[0:1], off offset:192
	global_load_dwordx4 v[96:99], v[0:1], off offset:224
	v_lshl_add_u64 v[2:3], s[18:19], 0, v[24:25]
	v_and_b32_e32 v0, 0xf0, v5
	v_mov_b32_e32 v1, v161
	v_ashrrev_i32_e32 v7, 31, v6
	v_ashrrev_i32_e32 v26, 3, v14
	s_add_u32 s2, s14, s8
	v_lshl_add_u64 v[8:9], v[2:3], 0, v[0:1]
	v_lshlrev_b64 v[2:3], 10, v[6:7]
	s_movk_i32 s7, 0x110
	v_ashrrev_i32_e32 v27, 31, v26
	v_ashrrev_i32_e32 v28, 3, v15
	s_addc_u32 s3, s15, s9
	v_lshl_add_u64 v[10:11], s[18:19], 0, v[2:3]
	v_mad_u64_u32 v[152:153], s[18:19], v6, s7, v[0:1]
	v_lshlrev_b64 v[6:7], 9, v[26:27]
	v_ashrrev_i32_e32 v29, 31, v28
	v_lshl_add_u64 v[12:13], v[10:11], 0, v[0:1]
	v_mad_u64_u32 v[150:151], s[18:19], v4, s7, v[0:1]
	v_lshl_add_u64 v[10:11], s[2:3], 0, v[6:7]
	v_and_b32_e32 v4, 0x70, v5
	v_mov_b32_e32 v5, v161
	v_lshlrev_b64 v[30:31], 9, v[28:29]
	v_lshl_add_u64 v[16:17], v[10:11], 0, v[4:5]
	v_lshl_add_u64 v[10:11], s[2:3], 0, v[30:31]
	v_lshl_add_u64 v[20:21], v[10:11], 0, v[4:5]
	v_and_b32_e32 v32, 31, v14
	global_load_dwordx4 v[8:11], v[8:9], off
	s_nop 0
	global_load_dwordx4 v[12:15], v[12:13], off
	s_nop 0
	global_load_dwordx4 v[16:19], v[16:17], off
	s_nop 0
	global_load_dwordx4 v[20:23], v[20:21], off
	s_movk_i32 s7, 0x88
	v_mad_u64_u32 v[154:155], s[2:3], v26, s7, v[4:5]
	v_mad_u64_u32 v[156:157], s[2:3], v28, s7, v[4:5]
	v_add_u32_e32 v1, 0, v150
	s_add_u32 s2, s10, 0x23c10000
	s_addc_u32 s3, s11, 0
	s_lshl_b32 s6, s6, 8
	s_and_b32 s6, s6, 0x300
	v_lshl_add_u64 v[158:159], s[2:3], 0, v[24:25]
	v_lshl_add_u64 v[172:173], s[2:3], 0, v[2:3]
	s_add_u32 s2, s8, 0x23d00080
	s_addc_u32 s3, s9, 0
	v_lshl_add_u64 v[174:175], s[2:3], 0, v[6:7]
	v_lshl_add_u64 v[176:177], s[2:3], 0, v[30:31]
	v_mov_b32_e32 v151, 0
	v_mul_u32_u24_e32 v153, 0x110, v32
	v_mul_u32_u24_e32 v147, 0x88, v32
	v_or3_b32 v158, v158, s6, v0
	v_or3_b32 v172, v172, s6, v0
	v_or_b32_e32 v174, v174, v4
	v_or_b32_e32 v176, v176, v4
	s_mov_b32 s3, 0
	v_mov_b32_e32 v0, 0
	v_mov_b32_e32 v2, v151
	v_mov_b32_e32 v3, v151
	v_mov_b32_e32 v4, v151
	v_mov_b32_e32 v5, v151
	v_mov_b32_e32 v6, v151
	v_mov_b32_e32 v7, v151
	v_mov_b32_e32 v24, v151
	v_mov_b32_e32 v25, v151
	v_mov_b32_e32 v26, v151
	v_mov_b32_e32 v27, v151
	v_mov_b32_e32 v28, v151
	v_mov_b32_e32 v29, v151
	v_mov_b32_e32 v30, v151
	v_mov_b32_e32 v31, v151
	v_mov_b32_e32 v32, 0
	v_mov_b32_e32 v33, v151
	v_mov_b32_e32 v34, v151
	v_mov_b32_e32 v35, v151
	v_mov_b32_e32 v36, v151
	v_mov_b32_e32 v37, v151
	v_mov_b32_e32 v38, v151
	v_mov_b32_e32 v39, v151
	v_mov_b32_e32 v40, v151
	v_mov_b32_e32 v41, v151
	v_mov_b32_e32 v42, v151
	v_mov_b32_e32 v43, v151
	v_mov_b32_e32 v44, v151
	v_mov_b32_e32 v45, v151
	v_mov_b32_e32 v46, v151
	v_mov_b32_e32 v47, v151
	v_mov_b32_e32 v48, 0
	v_mov_b32_e32 v49, v151
	v_mov_b32_e32 v50, v151
	v_mov_b32_e32 v51, v151
	v_mov_b32_e32 v52, v151
	v_mov_b32_e32 v53, v151
	v_mov_b32_e32 v54, v151
	v_mov_b32_e32 v55, v151
	v_mov_b32_e32 v56, v151
	v_mov_b32_e32 v57, v151
	v_mov_b32_e32 v58, v151
	v_mov_b32_e32 v59, v151
	v_mov_b32_e32 v60, v151
	v_mov_b32_e32 v61, v151
	v_mov_b32_e32 v62, v151
	v_mov_b32_e32 v63, v151
	s_waitcnt vmcnt(0) lgkmcnt(0)
	ds_write_b128 v1, v[8:11]
	v_add_u32_e32 v1, 0, v152
	ds_write_b128 v1, v[12:15]
	v_add_u32_e32 v1, 0, v154
	v_add_u32_e32 v1, 0x4400, v1
	ds_write2_b64 v1, v[16:17], v[18:19] offset1:1
	v_add_u32_e32 v1, 0, v156
	v_add_u32_e32 v1, 0x4400, v1
	ds_write2_b64 v1, v[20:21], v[22:23] offset1:1
	v_mov_b32_e32 v1, v151
	v_mov_b32_e32 v8, v151
	v_mov_b32_e32 v9, v151
	v_mov_b32_e32 v10, v151
	v_mov_b32_e32 v11, v151
	v_mov_b32_e32 v12, v151
	v_mov_b32_e32 v13, v151
	v_mov_b32_e32 v14, v151
	v_mov_b32_e32 v15, v151
	v_mov_b32_e32 v16, 0
	v_mov_b32_e32 v17, v151
	v_mov_b32_e32 v18, v151
	v_mov_b32_e32 v19, v151
	v_mov_b32_e32 v20, v151
	v_mov_b32_e32 v21, v151
	v_mov_b32_e32 v22, v151
	v_mov_b32_e32 v23, v151
	s_waitcnt lgkmcnt(0)
	s_barrier
; #define LAS __attribute__((address_space(3)))
; template <bool MASK>
; DI void attn_unit(LAS unsigned char* lds, const bf16_t* qrow, const bf16_t* kbase, int kpitch, const bf16_t* vtbase, int vtpitch, int ntiles,
;                   const unsigned long long* maskp, bf16_t* orow, float c1, float c2) {
;     ...
;     for (int kt = 0; kt < ntiles; ++kt) {
;         const bool more = kt + 1 < ntiles;
;         if (more) {
;             const size_t ko = (size_t)(kt + 1) * 64 * kpitch; const int vo = (kt + 1) * 64;
;             pk[0] = *(const u32x4*)(kg0 + ko); pk[1] = *(const u32x4*)(kg1 + ko); pv[0] = *(const u32x4*)(vg0 + vo); pv[1] = *(const u32x4*)(vg1 + vo);
;         }
;         const unsigned long long mw = mw_next;
;         if (MASK && more) mw_next = maskp[(size_t)(kt + 1) * S_];
;         LAS unsigned char* buf = lds + (kt & 1) * ABUF;
;         f32x16 xs[2];
; #pragma unroll
;         for (int sub = 0; sub < 2; ++sub) {
; #pragma unroll
;             for (int i = 0; i < 16; ++i) xs[sub][i] = 0.f;
;             __builtin_amdgcn_s_setprio(1);
; #pragma unroll
;             for (int ks = 0; ks < 8; ++ks) {
;                 const bf16x8 a = *(const LAS bf16x8*)(buf + (32 * sub + r) * AK_PITCH + ks * 32 + h * 16);
;                 xs[sub] = __builtin_amdgcn_mfma_f32_32x32x16_bf16(a, qf[ks], xs[sub], 0, 0, 0);
;             }
;             __builtin_amdgcn_s_setprio(0);
;         }
; #pragma unroll
;         for (int sub = 0; sub < 2; ++sub) {
;             const unsigned mws = ((unsigned)(mw >> (32 * sub))) >> (4 * h);
;             float pe[16];
; #pragma unroll
;             for (int i = 0; i < 16; ++i) {
;                 float p = __builtin_amdgcn_exp2f(xs[sub][i] * c1 - c2);
;                 if (MASK) { const int m = __builtin_amdgcn_sbfe((int)mws, (i & 3) + 8 * (i >> 2), 1); p = __uint_as_float(__float_as_uint(p) & (unsigned)m); }
;                 l += p; pe[i] = p;
;             }
;             u32x4 p0, p1;
;             p0.x = pk2(pe[0], pe[1]); p0.y = pk2(pe[2], pe[3]); p0.z = pk2(pe[4], pe[5]); p0.w = pk2(pe[6], pe[7]);
;             p1.x = pk2(pe[8], pe[9]); p1.y = pk2(pe[10], pe[11]); p1.z = pk2(pe[12], pe[13]); p1.w = pk2(pe[14], pe[15]);
;             const bf16x8 pb0 = __builtin_bit_cast(bf16x8, p0), pb1 = __builtin_bit_cast(bf16x8, p1);
; #pragma unroll
;             for (int dt = 0; dt < 4; ++dt) {
.LBB0_1166:
	v_lshl_add_u64 v[70:71], s[30:31], 0, v[158:159]
	v_lshl_add_u64 v[64:65], s[30:31], 0, v[176:177]
	v_lshl_add_u64 v[66:67], s[30:31], 0, v[174:175]
	v_lshl_add_u64 v[68:69], s[30:31], 0, v[172:173]
	global_load_dwordx4 v[140:143], v[70:71], off
	global_load_dwordx4 v[136:139], v[68:69], off
	global_load_dwordx4 v[132:135], v[66:67], off
	global_load_dwordx4 v[128:131], v[64:65], off
	s_add_i32 s2, s3, 1
	s_bitcmp1_b32 s3, 0
	s_cselect_b32 s3, 0x8800, 0
	s_add_i32 s3, s3, 0
	s_setprio 1
	v_add3_u32 v155, s3, v160, v153
	ds_read_b128 v[64:67], v155
	s_waitcnt lgkmcnt(0)
	v_mfma_f32_32x32x16_bf16 v[80:95], v[64:67], v[124:127], 0
	ds_read_b128 v[64:67], v155 offset:32
	s_waitcnt lgkmcnt(0)
	v_mfma_f32_32x32x16_bf16 v[80:95], v[64:67], v[120:123], v[80:95]
	ds_read_b128 v[64:67], v155 offset:64
	s_waitcnt lgkmcnt(0)
	v_mfma_f32_32x32x16_bf16 v[80:95], v[64:67], v[116:119], v[80:95]
	ds_read_b128 v[64:67], v155 offset:96
	s_waitcnt lgkmcnt(0)
	v_mfma_f32_32x32x16_bf16 v[80:95], v[64:67], v[112:115], v[80:95]
	ds_read_b128 v[64:67], v155 offset:128
	s_waitcnt lgkmcnt(0)
	v_mfma_f32_32x32x16_bf16 v[80:95], v[64:67], v[108:111], v[80:95]
	ds_read_b128 v[64:67], v155 offset:160
	s_waitcnt lgkmcnt(0)
	v_mfma_f32_32x32x16_bf16 v[80:95], v[64:67], v[104:107], v[80:95]
	ds_read_b128 v[64:67], v155 offset:192
	s_waitcnt lgkmcnt(0)
	v_mfma_f32_32x32x16_bf16 v[80:95], v[64:67], v[100:103], v[80:95]
	ds_read_b128 v[64:67], v155 offset:224
	s_waitcnt lgkmcnt(0)
	v_mfma_f32_32x32x16_bf16 v[80:95], v[64:67], v[96:99], v[80:95]
	s_setprio 0
	s_setprio 1
	ds_read_b128 v[64:67], v155 offset:8704
	ds_read_b128 v[180:183], v155 offset:8736
	s_waitcnt lgkmcnt(0)
	v_mfma_f32_32x32x16_bf16 v[64:79], v[64:67], v[124:127], 0
	v_mfma_f32_32x32x16_bf16 v[64:79], v[180:183], v[120:123], v[64:79]
	ds_read_b128 v[180:183], v155 offset:8768
	s_waitcnt lgkmcnt(0)
	v_mfma_f32_32x32x16_bf16 v[64:79], v[180:183], v[116:119], v[64:79]
	ds_read_b128 v[180:183], v155 offset:8800
	s_waitcnt lgkmcnt(0)
	v_mfma_f32_32x32x16_bf16 v[64:79], v[180:183], v[112:115], v[64:79]
	ds_read_b128 v[180:183], v155 offset:8832
	s_waitcnt lgkmcnt(0)
	v_mfma_f32_32x32x16_bf16 v[64:79], v[180:183], v[108:111], v[64:79]
	ds_read_b128 v[180:183], v155 offset:8864
	s_waitcnt lgkmcnt(0)
	v_mfma_f32_32x32x16_bf16 v[64:79], v[180:183], v[104:107], v[64:79]
	ds_read_b128 v[180:183], v155 offset:8896
	s_waitcnt lgkmcnt(0)
	v_mfma_f32_32x32x16_bf16 v[64:79], v[180:183], v[100:103], v[64:79]
	ds_read_b128 v[180:183], v155 offset:8928
	s_waitcnt lgkmcnt(0)
	v_mfma_f32_32x32x16_bf16 v[64:79], v[180:183], v[96:99], v[64:79]
	s_setprio 0
	v_fma_f32 v80, v80, s95, -v171
	v_exp_f32_e32 v155, v80
	v_fma_f32 v80, v81, s95, -v171
	v_exp_f32_e32 v157, v80
	v_fma_f32 v80, v82, s95, -v171
	v_exp_f32_e32 v166, v80
	v_fma_f32 v80, v83, s95, -v171
	v_exp_f32_e32 v167, v80
	v_fma_f32 v80, v84, s95, -v171
	v_exp_f32_e32 v168, v80
	v_fma_f32 v80, v85, s95, -v171
	v_exp_f32_e32 v169, v80
	v_fma_f32 v80, v86, s95, -v171
	v_exp_f32_e32 v179, v80
	v_fma_f32 v80, v87, s95, -v171
	v_exp_f32_e32 v180, v80
	v_fma_f32 v80, v88, s95, -v171
	v_exp_f32_e32 v181, v80
	v_fma_f32 v80, v89, s95, -v171
	v_exp_f32_e32 v182, v80
	v_fma_f32 v80, v90, s95, -v171
	v_exp_f32_e32 v183, v80
	v_fma_f32 v80, v91, s95, -v171
	v_exp_f32_e32 v184, v80
	v_fma_f32 v80, v92, s95, -v171
	v_exp_f32_e32 v185, v80
	v_fma_f32 v80, v93, s95, -v171
	v_add3_u32 v200, s3, v146, v147
	v_exp_f32_e32 v190, v80
	v_fma_f32 v80, v94, s95, -v171
	v_add_u32_e32 v201, 0x4000, v200
	v_exp_f32_e32 v191, v80
	v_fma_f32 v80, v95, s95, -v171
	ds_read2_b64 v[88:91], v201 offset0:128 offset1:130
	ds_read2_b64 v[92:95], v201 offset0:132 offset1:134
	v_exp_f32_e32 v199, v80
	v_cvt_pk_bf16_f32 v80, v155, v157
	v_cvt_pk_bf16_f32 v81, v166, v167
	v_cvt_pk_bf16_f32 v82, v168, v169
	v_cvt_pk_bf16_f32 v83, v179, v180
	v_cvt_pk_bf16_f32 v84, v181, v182
	v_cvt_pk_bf16_f32 v85, v183, v184
	s_waitcnt lgkmcnt(0)
	v_mfma_f32_32x32x16_bf16 v[48:63], v[88:91], v[80:83], v[48:63]
	v_cvt_pk_bf16_f32 v86, v185, v190
	v_cvt_pk_bf16_f32 v87, v191, v199
	v_add_u32_e32 v202, 0x5000, v200
	v_add_u32_e32 v203, 0x6000, v200
	v_add_u32_e32 v200, 0x7000, v200
	v_fma_f32 v64, v64, s95, -v171
	s_bitcmp1_b32 s2, 0
	v_mfma_f32_32x32x16_bf16 v[48:63], v[92:95], v[84:87], v[48:63]
	ds_read2_b64 v[88:91], v202 offset0:160 offset1:162
	ds_read2_b64 v[92:95], v202 offset0:164 offset1:166
	s_cselect_b32 s3, 0x8800, 0
	s_add_i32 s3, s3, 0
	v_lshl_add_u64 v[158:159], v[158:159], 0, s[88:89]
	v_lshl_add_u64 v[172:173], v[172:173], 0, s[88:89]
	v_lshl_add_u64 v[174:175], v[174:175], 0, s[78:79]
	v_lshl_add_u64 v[176:177], v[176:177], 0, s[78:79]
	s_waitcnt lgkmcnt(0)
	v_mfma_f32_32x32x16_bf16 v[32:47], v[88:91], v[80:83], v[32:47]
	s_cmp_lg_u32 s2, 3
	v_mfma_f32_32x32x16_bf16 v[32:47], v[92:95], v[84:87], v[32:47]
	ds_read2_b64 v[88:91], v203 offset0:192 offset1:194
	ds_read2_b64 v[92:95], v203 offset0:196 offset1:198
	s_waitcnt lgkmcnt(0)
	v_mfma_f32_32x32x16_bf16 v[16:31], v[88:91], v[80:83], v[16:31]
	v_mfma_f32_32x32x16_bf16 v[16:31], v[92:95], v[84:87], v[16:31]
	ds_read2_b64 v[88:91], v200 offset0:224 offset1:226
	ds_read2_b64 v[92:95], v200 offset0:228 offset1:230
	s_waitcnt lgkmcnt(0)
; template <bool MASK>
; DI void attn_unit(LAS unsigned char* lds, const bf16_t* qrow, const bf16_t* kbase, int kpitch, const bf16_t* vtbase, int vtpitch, int ntiles,
;                   const unsigned long long* maskp, bf16_t* orow, float c1, float c2) {
;     ...
;         for (int sub = 0; sub < 2; ++sub) {
;             const unsigned mws = ((unsigned)(mw >> (32 * sub))) >> (4 * h);
;             float pe[16];
; #pragma unroll
;             for (int i = 0; i < 16; ++i) {
;                 float p = __builtin_amdgcn_exp2f(xs[sub][i] * c1 - c2);
;                 if (MASK) { const int m = __builtin_amdgcn_sbfe((int)mws, (i & 3) + 8 * (i >> 2), 1); p = __uint_as_float(__float_as_uint(p) & (unsigned)m); }
;                 l += p; pe[i] = p;
;             }
;             u32x4 p0, p1;
;             p0.x = pk2(pe[0], pe[1]); p0.y = pk2(pe[2], pe[3]); p0.z = pk2(pe[4], pe[5]); p0.w = pk2(pe[6], pe[7]);
;             p1.x = pk2(pe[8], pe[9]); p1.y = pk2(pe[10], pe[11]); p1.z = pk2(pe[12], pe[13]); p1.w = pk2(pe[14], pe[15]);
;             const bf16x8 pb0 = __builtin_bit_cast(bf16x8, p0), pb1 = __builtin_bit_cast(bf16x8, p1);
; #pragma unroll
;             for (int dt = 0; dt < 4; ++dt) {
;                 const LAS unsigned char* vp = buf + AK_BYTES + (32 * dt + r) * AV_PITCH + (32 * sub + 4 * h) * 2;
;                 const s16x4 lo0 = *(const LAS s16x4*)(vp), hi0 = *(const LAS s16x4*)(vp + 16);
;                 const s16x4 lo1 = *(const LAS s16x4*)(vp + 32), hi1 = *(const LAS s16x4*)(vp + 48);
;                 const bf16x8 va0 = __builtin_shufflevector(lo0, hi0, 0, 1, 2, 3, 4, 5, 6, 7);
;                 const bf16x8 va1 = __builtin_shufflevector(lo1, hi1, 0, 1, 2, 3, 4, 5, 6, 7);
;                 o[dt] = __builtin_amdgcn_mfma_f32_32x32x16_bf16(va0, pb0, o[dt], 0, 0, 0);
;                 o[dt] = __builtin_amdgcn_mfma_f32_32x32x16_bf16(va1, pb1, o[dt], 0, 0, 0);
;             }
;         }
;         if (more) {
;             LAS unsigned char* nb = lds + ((kt + 1) & 1) * ABUF;
;             *(LAS u32x4*)(nb + kl0) = pk[0]; *(LAS u32x4*)(nb + kl1) = pk[1];
;             *(LAS u32x2*)(nb + vl0) = (u32x2){pv[0].x, pv[0].y}; *(LAS u32x2*)(nb + vl0 + 8) = (u32x2){pv[0].z, pv[0].w};
;             *(LAS u32x2*)(nb + vl1) = (u32x2){pv[1].x, pv[1].y}; *(LAS u32x2*)(nb + vl1 + 8) = (u32x2){pv[1].z, pv[1].w};
;         }
;         __syncthreads();
	v_mfma_f32_32x32x16_bf16 v[0:15], v[88:91], v[80:83], v[0:15]
	v_exp_f32_e32 v81, v64
	v_fma_f32 v64, v65, s95, -v171
	v_exp_f32_e32 v82, v64
	v_fma_f32 v64, v66, s95, -v171
	v_exp_f32_e32 v83, v64
	v_fma_f32 v64, v67, s95, -v171
	v_add_f32_e32 v80, v151, v155
	v_mfma_f32_32x32x16_bf16 v[0:15], v[92:95], v[84:87], v[0:15]
	v_exp_f32_e32 v84, v64
	v_fma_f32 v64, v68, s95, -v171
	v_exp_f32_e32 v85, v64
	v_fma_f32 v64, v69, s95, -v171
	v_exp_f32_e32 v86, v64
	v_fma_f32 v64, v70, s95, -v171
	v_exp_f32_e32 v87, v64
	v_fma_f32 v64, v71, s95, -v171
	v_exp_f32_e32 v88, v64
	v_fma_f32 v64, v72, s95, -v171
	v_exp_f32_e32 v89, v64
	v_fma_f32 v64, v73, s95, -v171
	v_exp_f32_e32 v90, v64
	v_fma_f32 v64, v74, s95, -v171
	v_exp_f32_e32 v91, v64
	v_fma_f32 v64, v75, s95, -v171
	v_exp_f32_e32 v92, v64
	v_fma_f32 v64, v76, s95, -v171
	v_exp_f32_e32 v93, v64
	v_fma_f32 v64, v77, s95, -v171
	v_exp_f32_e32 v94, v64
	v_fma_f32 v64, v78, s95, -v171
	v_exp_f32_e32 v95, v64
	v_fma_f32 v64, v79, s95, -v171
	ds_read2_b64 v[72:75], v201 offset0:136 offset1:138
	ds_read2_b64 v[76:79], v201 offset0:140 offset1:142
	v_exp_f32_e32 v151, v64
	v_cvt_pk_bf16_f32 v64, v81, v82
	v_cvt_pk_bf16_f32 v65, v83, v84
	v_cvt_pk_bf16_f32 v66, v85, v86
	v_cvt_pk_bf16_f32 v67, v87, v88
	v_cvt_pk_bf16_f32 v68, v89, v90
	v_cvt_pk_bf16_f32 v69, v91, v92
	s_waitcnt lgkmcnt(0)
	v_mfma_f32_32x32x16_bf16 v[48:63], v[72:75], v[64:67], v[48:63]
	v_cvt_pk_bf16_f32 v70, v93, v94
	v_cvt_pk_bf16_f32 v71, v95, v151
	v_add_f32_e32 v80, v157, v80
	v_add_f32_e32 v80, v166, v80
	v_add_f32_e32 v80, v167, v80
	v_add_f32_e32 v80, v168, v80
	v_add_f32_e32 v80, v169, v80
	v_mfma_f32_32x32x16_bf16 v[48:63], v[76:79], v[68:71], v[48:63]
	ds_read2_b64 v[72:75], v202 offset0:168 offset1:170
	ds_read2_b64 v[76:79], v202 offset0:172 offset1:174
	v_add_f32_e32 v80, v179, v80
	v_add_f32_e32 v80, v180, v80
	v_add_f32_e32 v80, v181, v80
	v_add_f32_e32 v80, v182, v80
	v_add_f32_e32 v80, v183, v80
	v_add_f32_e32 v80, v184, v80
	s_waitcnt lgkmcnt(0)
	v_mfma_f32_32x32x16_bf16 v[32:47], v[72:75], v[64:67], v[32:47]
	v_add_f32_e32 v80, v185, v80
	v_add_f32_e32 v80, v190, v80
	v_add_f32_e32 v80, v191, v80
	v_add_f32_e32 v80, v199, v80
	v_mfma_f32_32x32x16_bf16 v[32:47], v[76:79], v[68:71], v[32:47]
	ds_read2_b64 v[72:75], v203 offset0:200 offset1:202
	ds_read2_b64 v[76:79], v203 offset0:204 offset1:206
	s_waitcnt lgkmcnt(0)
	v_mfma_f32_32x32x16_bf16 v[16:31], v[72:75], v[64:67], v[16:31]
	v_mfma_f32_32x32x16_bf16 v[16:31], v[76:79], v[68:71], v[16:31]
	ds_read2_b64 v[72:75], v200 offset0:232 offset1:234
	ds_read2_b64 v[76:79], v200 offset0:236 offset1:238
	s_waitcnt lgkmcnt(0)
	v_mfma_f32_32x32x16_bf16 v[0:15], v[72:75], v[64:67], v[0:15]
	v_add_f32_e32 v64, v80, v81
	v_add_f32_e32 v64, v82, v64
	v_add_f32_e32 v64, v83, v64
	v_add_f32_e32 v64, v84, v64
	v_add_f32_e32 v64, v85, v64
	v_add_f32_e32 v64, v86, v64
	v_add_f32_e32 v64, v87, v64
	v_add_f32_e32 v64, v88, v64
	v_add_f32_e32 v64, v89, v64
	v_add_f32_e32 v64, v90, v64
	v_add_f32_e32 v64, v91, v64
	v_add_f32_e32 v64, v92, v64
	v_add_f32_e32 v64, v93, v64
	v_mfma_f32_32x32x16_bf16 v[0:15], v[76:79], v[68:71], v[0:15]
	v_add_f32_e32 v64, v94, v64
	v_add_f32_e32 v64, v95, v64
	v_add_f32_e32 v151, v151, v64
	v_add_u32_e32 v64, s3, v150
	s_waitcnt vmcnt(0)
	ds_write_b128 v64, v[140:143]
	v_add_u32_e32 v64, s3, v152
	ds_write_b128 v64, v[136:139]
	v_add_u32_e32 v64, s3, v154
	v_add_u32_e32 v64, 0x4400, v64
	ds_write2_b64 v64, v[132:133], v[134:135] offset1:1
	v_add_u32_e32 v64, s3, v156
	v_add_u32_e32 v64, 0x4400, v64
	s_mov_b32 s3, s2
	ds_write2_b64 v64, v[128:129], v[130:131] offset1:1
	s_waitcnt lgkmcnt(0)
	s_barrier
	s_cbranch_scc1 .LBB0_1166
	v_lshl_add_u64 v[64:65], v[148:149], 1, s[4:5]
	s_lshl_b32 s70, s17, 1
	v_lshl_add_u64 v[128:129], v[64:65], 0, s[70:71]
	v_add_u32_e32 v130, 0, v160
	s_setprio 1
	v_add_u32_e32 v131, v130, v153
	ds_read_b128 v[64:67], v131 offset:34816
	s_waitcnt lgkmcnt(0)
	v_mfma_f32_32x32x16_bf16 v[80:95], v[64:67], v[124:127], 0
	ds_read_b128 v[64:67], v131 offset:34848
	s_waitcnt lgkmcnt(0)
	v_mfma_f32_32x32x16_bf16 v[80:95], v[64:67], v[120:123], v[80:95]
	ds_read_b128 v[64:67], v131 offset:34880
	s_waitcnt lgkmcnt(0)
	v_mfma_f32_32x32x16_bf16 v[80:95], v[64:67], v[116:119], v[80:95]
	ds_read_b128 v[64:67], v131 offset:34912
	s_waitcnt lgkmcnt(0)
	v_mfma_f32_32x32x16_bf16 v[80:95], v[64:67], v[112:115], v[80:95]
	ds_read_b128 v[64:67], v131 offset:34944
	s_waitcnt lgkmcnt(0)
	v_mfma_f32_32x32x16_bf16 v[80:95], v[64:67], v[108:111], v[80:95]
	ds_read_b128 v[64:67], v131 offset:34976
	s_waitcnt lgkmcnt(0)
	v_mfma_f32_32x32x16_bf16 v[80:95], v[64:67], v[104:107], v[80:95]
	ds_read_b128 v[64:67], v131 offset:35008
	s_waitcnt lgkmcnt(0)
	v_mfma_f32_32x32x16_bf16 v[80:95], v[64:67], v[100:103], v[80:95]
	ds_read_b128 v[64:67], v131 offset:35040
	s_waitcnt lgkmcnt(0)
	v_mfma_f32_32x32x16_bf16 v[80:95], v[64:67], v[96:99], v[80:95]
	s_setprio 0
	s_setprio 1
	ds_read_b128 v[64:67], v131 offset:43520
	s_waitcnt lgkmcnt(0)
	v_mfma_f32_32x32x16_bf16 v[64:79], v[64:67], v[124:127], 0
	ds_read_b128 v[124:127], v131 offset:43552
	s_waitcnt lgkmcnt(0)
	v_mfma_f32_32x32x16_bf16 v[64:79], v[124:127], v[120:123], v[64:79]
	ds_read_b128 v[120:123], v131 offset:43584
	s_waitcnt lgkmcnt(0)
	v_mfma_f32_32x32x16_bf16 v[64:79], v[120:123], v[116:119], v[64:79]
	ds_read_b128 v[116:119], v131 offset:43616
	s_waitcnt lgkmcnt(0)
	v_mfma_f32_32x32x16_bf16 v[64:79], v[116:119], v[112:115], v[64:79]
	ds_read_b128 v[112:115], v131 offset:43648
	s_waitcnt lgkmcnt(0)
	v_mfma_f32_32x32x16_bf16 v[64:79], v[112:115], v[108:111], v[64:79]
	ds_read_b128 v[108:111], v131 offset:43680
	s_waitcnt lgkmcnt(0)
; template <bool MASK>
; DI void attn_unit(LAS unsigned char* lds, const bf16_t* qrow, const bf16_t* kbase, int kpitch, const bf16_t* vtbase, int vtpitch, int ntiles,
;                   const unsigned long long* maskp, bf16_t* orow, float c1, float c2) {
;     ...
;         f32x16 xs[2];
; #pragma unroll
;         for (int sub = 0; sub < 2; ++sub) {
; #pragma unroll
;             for (int i = 0; i < 16; ++i) xs[sub][i] = 0.f;
;             __builtin_amdgcn_s_setprio(1);
; #pragma unroll
;             for (int ks = 0; ks < 8; ++ks) {
;                 const bf16x8 a = *(const LAS bf16x8*)(buf + (32 * sub + r) * AK_PITCH + ks * 32 + h * 16);
;                 xs[sub] = __builtin_amdgcn_mfma_f32_32x32x16_bf16(a, qf[ks], xs[sub], 0, 0, 0);
;             }
;             __builtin_amdgcn_s_setprio(0);
;         }
; #pragma unroll
;         for (int sub = 0; sub < 2; ++sub) {
;             const unsigned mws = ((unsigned)(mw >> (32 * sub))) >> (4 * h);
;             float pe[16];
; #pragma unroll
;             for (int i = 0; i < 16; ++i) {
;                 float p = __builtin_amdgcn_exp2f(xs[sub][i] * c1 - c2);
;                 if (MASK) { const int m = __builtin_amdgcn_sbfe((int)mws, (i & 3) + 8 * (i >> 2), 1); p = __uint_as_float(__float_as_uint(p) & (unsigned)m); }
;                 l += p; pe[i] = p;
;             }
;             u32x4 p0, p1;
;             p0.x = pk2(pe[0], pe[1]); p0.y = pk2(pe[2], pe[3]); p0.z = pk2(pe[4], pe[5]); p0.w = pk2(pe[6], pe[7]);
;             p1.x = pk2(pe[8], pe[9]); p1.y = pk2(pe[10], pe[11]); p1.z = pk2(pe[12], pe[13]); p1.w = pk2(pe[14], pe[15]);
;             const bf16x8 pb0 = __builtin_bit_cast(bf16x8, p0), pb1 = __builtin_bit_cast(bf16x8, p1);
; #pragma unroll
;             for (int dt = 0; dt < 4; ++dt) {
;                 const LAS unsigned char* vp = buf + AK_BYTES + (32 * dt + r) * AV_PITCH + (32 * sub + 4 * h) * 2;
;                 const s16x4 lo0 = *(const LAS s16x4*)(vp), hi0 = *(const LAS s16x4*)(vp + 16);
;                 const s16x4 lo1 = *(const LAS s16x4*)(vp + 32), hi1 = *(const LAS s16x4*)(vp + 48);
;                 const bf16x8 va0 = __builtin_shufflevector(lo0, hi0, 0, 1, 2, 3, 4, 5, 6, 7);
;                 const bf16x8 va1 = __builtin_shufflevector(lo1, hi1, 0, 1, 2, 3, 4, 5, 6, 7);
;                 o[dt] = __builtin_amdgcn_mfma_f32_32x32x16_bf16(va0, pb0, o[dt], 0, 0, 0);
	v_mfma_f32_32x32x16_bf16 v[64:79], v[108:111], v[104:107], v[64:79]
	ds_read_b128 v[104:107], v131 offset:43712
	s_waitcnt lgkmcnt(0)
	v_mfma_f32_32x32x16_bf16 v[64:79], v[104:107], v[100:103], v[64:79]
	ds_read_b128 v[100:103], v131 offset:43744
	s_waitcnt lgkmcnt(0)
	v_mfma_f32_32x32x16_bf16 v[64:79], v[100:103], v[96:99], v[64:79]
	s_setprio 0
	v_fma_f32 v80, v80, s95, -v171
	v_sub_u32_e32 v106, v130, v146
	v_exp_f32_e32 v96, v80
	v_fma_f32 v80, v81, s95, -v171
	v_exp_f32_e32 v97, v80
	v_fma_f32 v80, v82, s95, -v171
	v_fma_f32 v81, v83, s95, -v171
	v_fma_f32 v82, v84, s95, -v171
	v_fma_f32 v83, v85, s95, -v171
	v_fma_f32 v84, v86, s95, -v171
	v_fma_f32 v85, v87, s95, -v171
	v_fma_f32 v86, v88, s95, -v171
	v_fma_f32 v88, v90, s95, -v171
	v_fma_f32 v90, v92, s95, -v171
	v_fma_f32 v92, v94, s95, -v171
	v_add_u32_e32 v94, v106, v147
	v_exp_f32_e32 v80, v80
	v_exp_f32_e32 v81, v81
	v_exp_f32_e32 v82, v82
	v_exp_f32_e32 v83, v83
	v_exp_f32_e32 v84, v84
	v_exp_f32_e32 v85, v85
	v_fma_f32 v87, v89, s95, -v171
	v_fma_f32 v89, v91, s95, -v171
	v_fma_f32 v91, v93, s95, -v171
	v_fma_f32 v93, v95, s95, -v171
	v_add_u32_e32 v95, 0xc800, v94
	ds_read2_b64 v[106:109], v95 offset0:128 offset1:130
	ds_read2_b64 v[110:113], v95 offset0:132 offset1:134
	v_cvt_pk_bf16_f32 v98, v96, v97
	v_cvt_pk_bf16_f32 v99, v80, v81
	v_cvt_pk_bf16_f32 v100, v82, v83
	v_cvt_pk_bf16_f32 v101, v84, v85
	v_exp_f32_e32 v86, v86
	v_exp_f32_e32 v87, v87
	s_waitcnt lgkmcnt(1)
	v_mfma_f32_32x32x16_bf16 v[48:63], v[106:109], v[98:101], v[48:63]
	v_exp_f32_e32 v88, v88
	v_exp_f32_e32 v89, v89
	v_exp_f32_e32 v90, v90
	v_exp_f32_e32 v91, v91
	v_exp_f32_e32 v92, v92
	v_exp_f32_e32 v93, v93
	v_cvt_pk_bf16_f32 v102, v86, v87
	v_cvt_pk_bf16_f32 v103, v88, v89
	v_cvt_pk_bf16_f32 v104, v90, v91
	v_cvt_pk_bf16_f32 v105, v92, v93
	v_add_u32_e32 v114, 0xd800, v94
	v_add_u32_e32 v115, 0xe800, v94
	s_waitcnt lgkmcnt(0)
	v_mfma_f32_32x32x16_bf16 v[48:63], v[110:113], v[102:105], v[48:63]
	ds_read2_b64 v[106:109], v114 offset0:160 offset1:162
	ds_read2_b64 v[110:113], v114 offset0:164 offset1:166
	v_add_u32_e32 v94, 0xf800, v94
	v_fma_f32 v64, v64, s95, -v171
	v_mov_b32_e32 v147, v161
	s_add_i32 s16, s16, s66
	s_cmpk_gt_i32 s16, 0xff
	s_waitcnt lgkmcnt(1)
	v_mfma_f32_32x32x16_bf16 v[32:47], v[106:109], v[98:101], v[32:47]
	s_waitcnt lgkmcnt(0)
	v_mfma_f32_32x32x16_bf16 v[32:47], v[110:113], v[102:105], v[32:47]
	ds_read2_b64 v[106:109], v115 offset0:192 offset1:194
	ds_read2_b64 v[110:113], v115 offset0:196 offset1:198
	s_waitcnt lgkmcnt(1)
	v_mfma_f32_32x32x16_bf16 v[16:31], v[106:109], v[98:101], v[16:31]
	s_waitcnt lgkmcnt(0)
	v_mfma_f32_32x32x16_bf16 v[16:31], v[110:113], v[102:105], v[16:31]
	ds_read2_b64 v[106:109], v94 offset0:224 offset1:226
	ds_read2_b64 v[110:113], v94 offset0:228 offset1:230
	s_waitcnt lgkmcnt(1)
	v_mfma_f32_32x32x16_bf16 v[0:15], v[106:109], v[98:101], v[0:15]
	v_exp_f32_e32 v98, v64
	v_fma_f32 v64, v65, s95, -v171
	v_exp_f32_e32 v99, v64
	v_fma_f32 v64, v66, s95, -v171
	v_exp_f32_e32 v100, v64
	v_fma_f32 v64, v67, s95, -v171
	v_exp_f32_e32 v101, v64
	v_fma_f32 v64, v68, s95, -v171
	s_waitcnt lgkmcnt(0)
	v_mfma_f32_32x32x16_bf16 v[0:15], v[110:113], v[102:105], v[0:15]
	v_exp_f32_e32 v102, v64
	v_fma_f32 v64, v69, s95, -v171
	v_exp_f32_e32 v103, v64
	v_fma_f32 v64, v70, s95, -v171
	v_exp_f32_e32 v104, v64
	v_fma_f32 v64, v71, s95, -v171
	v_exp_f32_e32 v105, v64
	v_fma_f32 v64, v72, s95, -v171
	v_exp_f32_e32 v106, v64
	v_fma_f32 v64, v73, s95, -v171
	v_exp_f32_e32 v107, v64
	v_fma_f32 v64, v74, s95, -v171
	v_exp_f32_e32 v108, v64
	v_fma_f32 v64, v75, s95, -v171
	v_exp_f32_e32 v109, v64
	v_fma_f32 v64, v76, s95, -v171
	v_exp_f32_e32 v110, v64
	v_fma_f32 v64, v77, s95, -v171
	v_exp_f32_e32 v111, v64
	v_fma_f32 v64, v78, s95, -v171
	v_exp_f32_e32 v112, v64
	v_fma_f32 v64, v79, s95, -v171
	ds_read2_b64 v[72:75], v95 offset0:136 offset1:138
	ds_read2_b64 v[76:79], v95 offset0:140 offset1:142
	v_exp_f32_e32 v113, v64
	v_cvt_pk_bf16_f32 v64, v98, v99
	v_cvt_pk_bf16_f32 v65, v100, v101
	v_cvt_pk_bf16_f32 v66, v102, v103
	v_cvt_pk_bf16_f32 v67, v104, v105
	v_cvt_pk_bf16_f32 v68, v106, v107
	v_cvt_pk_bf16_f32 v69, v108, v109
	s_waitcnt lgkmcnt(1)
	v_mfma_f32_32x32x16_bf16 v[48:63], v[72:75], v[64:67], v[48:63]
	v_cvt_pk_bf16_f32 v70, v110, v111
	v_cvt_pk_bf16_f32 v71, v112, v113
	s_waitcnt lgkmcnt(0)
	s_nop 0
	v_mfma_f32_32x32x16_bf16 v[48:63], v[76:79], v[68:71], v[48:63]
	ds_read2_b64 v[72:75], v114 offset0:168 offset1:170
	ds_read2_b64 v[76:79], v114 offset0:172 offset1:174
	s_waitcnt lgkmcnt(1)
	v_mfma_f32_32x32x16_bf16 v[32:47], v[72:75], v[64:67], v[32:47]
	s_waitcnt lgkmcnt(0)
	v_mfma_f32_32x32x16_bf16 v[32:47], v[76:79], v[68:71], v[32:47]
	ds_read2_b64 v[72:75], v115 offset0:200 offset1:202
	ds_read2_b64 v[76:79], v115 offset0:204 offset1:206
	s_waitcnt lgkmcnt(1)
	v_mfma_f32_32x32x16_bf16 v[16:31], v[72:75], v[64:67], v[16:31]
	s_waitcnt lgkmcnt(0)
	v_mfma_f32_32x32x16_bf16 v[16:31], v[76:79], v[68:71], v[16:31]
	ds_read2_b64 v[72:75], v94 offset0:232 offset1:234
	ds_read2_b64 v[76:79], v94 offset0:236 offset1:238
	s_waitcnt lgkmcnt(0)
	s_barrier
; DI unsigned pk2(float lo, float hi) { f32x2 v = {lo, hi}; bf16x2_t b = __builtin_convertvector(v, bf16x2_t); return __builtin_bit_cast(unsigned, b); }
; template <bool MASK>
; DI void attn_unit(LAS unsigned char* lds, const bf16_t* qrow, const bf16_t* kbase, int kpitch, const bf16_t* vtbase, int vtpitch, int ntiles,
;                   const unsigned long long* maskp, bf16_t* orow, float c1, float c2) {
;     ...
;         __syncthreads();
;     }
;     l += __shfl_xor(l, 32);
;     const float inv = 1.0f / l;
; #pragma unroll
;     for (int dt = 0; dt < 4; ++dt)
; #pragma unroll
;         for (int ig = 0; ig < 4; ++ig) {
;             u32x2 w; w.x = pk2(o[dt][4 * ig] * inv, o[dt][4 * ig + 1] * inv); w.y = pk2(o[dt][4 * ig + 2] * inv, o[dt][4 * ig + 3] * inv);
;             *(u32x2*)(orow + 32 * dt + 8 * ig + 4 * h) = w;
;         }
	v_mfma_f32_32x32x16_bf16 v[0:15], v[72:75], v[64:67], v[0:15]
	v_add_f32_e32 v64, v151, v96
	v_add_f32_e32 v64, v97, v64
	v_add_f32_e32 v64, v80, v64
	v_add_f32_e32 v64, v81, v64
	v_add_f32_e32 v64, v82, v64
	v_add_f32_e32 v64, v83, v64
	v_add_f32_e32 v64, v84, v64
	v_add_f32_e32 v64, v85, v64
	v_add_f32_e32 v64, v86, v64
	v_add_f32_e32 v64, v87, v64
	v_add_f32_e32 v64, v88, v64
	v_add_f32_e32 v64, v89, v64
	v_add_f32_e32 v64, v90, v64
	v_add_f32_e32 v64, v91, v64
	v_add_f32_e32 v64, v92, v64
	v_add_f32_e32 v64, v93, v64
	v_add_f32_e32 v64, v64, v98
	v_add_f32_e32 v64, v99, v64
	v_add_f32_e32 v64, v100, v64
	v_add_f32_e32 v64, v101, v64
	v_add_f32_e32 v64, v102, v64
	v_add_f32_e32 v64, v103, v64
	v_add_f32_e32 v64, v104, v64
	v_add_f32_e32 v64, v105, v64
	v_add_f32_e32 v64, v106, v64
	v_add_f32_e32 v64, v107, v64
	v_add_f32_e32 v64, v108, v64
	v_add_f32_e32 v64, v109, v64
	v_add_f32_e32 v64, v110, v64
	v_add_f32_e32 v64, v111, v64
	v_add_f32_e32 v64, v112, v64
	v_add_f32_e32 v64, v113, v64
	ds_bpermute_b32 v65, v198, v64
	v_mfma_f32_32x32x16_bf16 v[0:15], v[76:79], v[68:71], v[0:15]
	s_waitcnt lgkmcnt(0)
	v_add_f32_e32 v64, v64, v65
	v_div_scale_f32 v65, s[2:3], v64, v64, 1.0
	v_rcp_f32_e32 v66, v65
	s_nop 0
	v_fma_f32 v67, -v65, v66, 1.0
	v_fmac_f32_e32 v66, v67, v66
	v_div_scale_f32 v67, vcc, 1.0, v64, 1.0
	v_mul_f32_e32 v68, v67, v66
	v_fma_f32 v69, -v65, v68, v67
	v_fmac_f32_e32 v68, v69, v66
	v_fma_f32 v65, -v65, v68, v67
	v_div_fmas_f32 v65, v65, v66, v68
	v_div_fixup_f32 v64, v65, v64, 1.0
	v_pk_mul_f32 v[48:49], v[48:49], v[64:65] op_sel_hi:[1,0]
	v_pk_mul_f32 v[50:51], v[50:51], v[64:65] op_sel_hi:[1,0]
	v_pk_mul_f32 v[32:33], v[32:33], v[64:65] op_sel_hi:[1,0]
	v_pk_mul_f32 v[34:35], v[34:35], v[64:65] op_sel_hi:[1,0]
	v_pk_mul_f32 v[16:17], v[16:17], v[64:65] op_sel_hi:[1,0]
	v_pk_mul_f32 v[18:19], v[18:19], v[64:65] op_sel_hi:[1,0]
	v_pk_mul_f32 v[0:1], v[0:1], v[64:65] op_sel_hi:[1,0]
	v_pk_mul_f32 v[2:3], v[2:3], v[64:65] op_sel_hi:[1,0]
	v_lshl_add_u64 v[66:67], v[128:129], 0, v[146:147]
	v_cvt_pk_bf16_f32 v48, v48, v49
	v_cvt_pk_bf16_f32 v49, v50, v51
	v_cvt_pk_bf16_f32 v32, v32, v33
	v_cvt_pk_bf16_f32 v33, v34, v35
	v_cvt_pk_bf16_f32 v16, v16, v17
	v_cvt_pk_bf16_f32 v17, v18, v19
	v_cvt_pk_bf16_f32 v0, v0, v1
	v_cvt_pk_bf16_f32 v1, v2, v3
	global_store_dwordx2 v[66:67], v[48:49], off
	v_pk_mul_f32 v[48:49], v[52:53], v[64:65] op_sel_hi:[1,0]
	v_pk_mul_f32 v[50:51], v[54:55], v[64:65] op_sel_hi:[1,0]
	global_store_dwordx2 v[66:67], v[32:33], off offset:64
	v_pk_mul_f32 v[32:33], v[36:37], v[64:65] op_sel_hi:[1,0]
	v_pk_mul_f32 v[34:35], v[38:39], v[64:65] op_sel_hi:[1,0]
	global_store_dwordx2 v[66:67], v[16:17], off offset:128
	v_pk_mul_f32 v[16:17], v[20:21], v[64:65] op_sel_hi:[1,0]
	v_pk_mul_f32 v[18:19], v[22:23], v[64:65] op_sel_hi:[1,0]
	global_store_dwordx2 v[66:67], v[0:1], off offset:192
	v_pk_mul_f32 v[0:1], v[4:5], v[64:65] op_sel_hi:[1,0]
	v_pk_mul_f32 v[2:3], v[6:7], v[64:65] op_sel_hi:[1,0]
	v_cvt_pk_bf16_f32 v48, v48, v49
	v_cvt_pk_bf16_f32 v49, v50, v51
	v_cvt_pk_bf16_f32 v32, v32, v33
	v_cvt_pk_bf16_f32 v33, v34, v35
	v_cvt_pk_bf16_f32 v16, v16, v17
	v_cvt_pk_bf16_f32 v17, v18, v19
	v_cvt_pk_bf16_f32 v0, v0, v1
	v_cvt_pk_bf16_f32 v1, v2, v3
	global_store_dwordx2 v[66:67], v[48:49], off offset:16
	v_pk_mul_f32 v[48:49], v[56:57], v[64:65] op_sel_hi:[1,0]
	v_pk_mul_f32 v[50:51], v[58:59], v[64:65] op_sel_hi:[1,0]
	global_store_dwordx2 v[66:67], v[32:33], off offset:80
	v_pk_mul_f32 v[32:33], v[40:41], v[64:65] op_sel_hi:[1,0]
	v_pk_mul_f32 v[34:35], v[42:43], v[64:65] op_sel_hi:[1,0]
	global_store_dwordx2 v[66:67], v[16:17], off offset:144
	v_pk_mul_f32 v[16:17], v[24:25], v[64:65] op_sel_hi:[1,0]
	v_pk_mul_f32 v[18:19], v[26:27], v[64:65] op_sel_hi:[1,0]
	global_store_dwordx2 v[66:67], v[0:1], off offset:208
	v_pk_mul_f32 v[0:1], v[8:9], v[64:65] op_sel_hi:[1,0]
	v_pk_mul_f32 v[2:3], v[10:11], v[64:65] op_sel_hi:[1,0]
	v_cvt_pk_bf16_f32 v48, v48, v49
	v_cvt_pk_bf16_f32 v49, v50, v51
	v_cvt_pk_bf16_f32 v32, v32, v33
	v_cvt_pk_bf16_f32 v33, v34, v35
	v_cvt_pk_bf16_f32 v16, v16, v17
	v_cvt_pk_bf16_f32 v17, v18, v19
	v_cvt_pk_bf16_f32 v0, v0, v1
	v_cvt_pk_bf16_f32 v1, v2, v3
	global_store_dwordx2 v[66:67], v[48:49], off offset:32
	v_pk_mul_f32 v[48:49], v[60:61], v[64:65] op_sel_hi:[1,0]
	v_pk_mul_f32 v[50:51], v[62:63], v[64:65] op_sel_hi:[1,0]
	global_store_dwordx2 v[66:67], v[32:33], off offset:96
	v_pk_mul_f32 v[32:33], v[44:45], v[64:65] op_sel_hi:[1,0]
	v_pk_mul_f32 v[34:35], v[46:47], v[64:65] op_sel_hi:[1,0]
	global_store_dwordx2 v[66:67], v[16:17], off offset:160
	v_pk_mul_f32 v[16:17], v[28:29], v[64:65] op_sel_hi:[1,0]
	v_pk_mul_f32 v[18:19], v[30:31], v[64:65] op_sel_hi:[1,0]
	global_store_dwordx2 v[66:67], v[0:1], off offset:224
	v_pk_mul_f32 v[0:1], v[12:13], v[64:65] op_sel_hi:[1,0]
	v_pk_mul_f32 v[2:3], v[14:15], v[64:65] op_sel_hi:[1,0]
	v_cvt_pk_bf16_f32 v48, v48, v49
	v_cvt_pk_bf16_f32 v49, v50, v51
	v_cvt_pk_bf16_f32 v32, v32, v33
	v_cvt_pk_bf16_f32 v33, v34, v35
	v_cvt_pk_bf16_f32 v16, v16, v17
	v_cvt_pk_bf16_f32 v17, v18, v19
	v_cvt_pk_bf16_f32 v0, v0, v1
	v_cvt_pk_bf16_f32 v1, v2, v3
	global_store_dwordx2 v[66:67], v[48:49], off offset:48
	global_store_dwordx2 v[66:67], v[32:33], off offset:112
	global_store_dwordx2 v[66:67], v[16:17], off offset:176
	global_store_dwordx2 v[66:67], v[0:1], off offset:240
	s_cbranch_scc0 .LBB0_1165

; #define LAS __attribute__((address_space(3)))
; DI void conv_block(LAS unsigned char* lds, int b, int tb, int tid, const bf16_t* U, const float* cb, const float* lg, const float* lb, bf16_t* CC) {
;     ...
;     for (int i = tid; i < 62 * 64; i += 512) {
;         const int row = i >> 6, part = i & 63, ts = t00 - 30 + row;
;         u32x4 v = {0u, 0u, 0u, 0u};
;         if (ts >= 0) v = *(const u32x4*)(U + ((size_t)b * S_ + ts) * 512 + part * 8);
;         *(LAS u32x4*)(ut + row * 1024 + part * 16) = v;
;     }
.LBB0_1178:
	v_ashrrev_i32_e32 v7, 6, v6
	v_add_u32_e32 v160, s11, v7
	v_cmp_lt_i32_e64 s[38:39], -1, v160
	v_mov_b32_e32 v0, 0
	v_mov_b32_e32 v1, 0
	v_mov_b32_e32 v2, 0
	v_mov_b32_e32 v3, 0
	s_and_saveexec_b64 s[6:7], s[38:39]
	s_cbranch_execz .LBB0_1177
	v_lshlrev_b64 v[0:1], 10, v[160:161]
	v_lshl_add_u64 v[0:1], v[4:5], 0, v[0:1]
	global_load_dwordx4 v[0:3], v[0:1], off
	s_branch .LBB0_1177

; #define LAS __attribute__((address_space(3)))
; DI void conv_block(LAS unsigned char* lds, int b, int tb, int tid, const bf16_t* U, const float* cb, const float* lg, const float* lb, bf16_t* CC) {
;     ...
; #pragma unroll 2
;     for (int j = 0; j < 34; ++j) {
;         float uv[8];
;         unpack8(*(const LAS u32x4*)(up + j * 1024), uv);
; #pragma unroll
;         for (int tt = 0; tt < 4; ++tt) {
;             const LAS float* wp = wl + (j - tt + 3) * 512;
;             const f32x4 w0 = *(const LAS f32x4*)wp, w1 = *(const LAS f32x4*)(wp + 4);
;             acc[tt][0] += w0.x * uv[0]; acc[tt][1] += w0.y * uv[1]; acc[tt][2] += w0.z * uv[2]; acc[tt][3] += w0.w * uv[3];
;             acc[tt][4] += w1.x * uv[4]; acc[tt][5] += w1.y * uv[5]; acc[tt][6] += w1.z * uv[6]; acc[tt][7] += w1.w * uv[7];
;         }
;     }
;     float bb[8], gg[8], be[8];
; #pragma unroll
;     for (int k = 0; k < 8; ++k) { bb[k] = cb[c0 + k]; gg[k] = lg[c0 + k]; be[k] = lb[c0 + k]; }
; #pragma unroll
;     for (int tt = 0; tt < 4; ++tt) {
;         float s = 0.f;
; #pragma unroll
;         for (int k = 0; k < 8; ++k) { acc[tt][k] += bb[k]; s += acc[tt][k]; }
;         const float mean = wave_sum(s) * (1.f / 512.f);
;         float q = 0.f;
; #pragma unroll
;         for (int k = 0; k < 8; ++k) { const float d = acc[tt][k] - mean; q += d * d; }
;         const float rstd = rsqrtf(wave_sum(q) * (1.f / 512.f) + EPS_);
.LBB0_1181:
	v_add_u32_e32 v1, 0xfffffc00, v0
	ds_read_b128 v[2:5], v1
	v_add_u32_e32 v1, s1, v75
	ds_read_b128 v[6:9], v1 offset:6144
	ds_read_b128 v[10:13], v1 offset:6160
	s_addk_i32 s1, 0x1000
	s_cmp_lg_u32 s1, 0x11000
	s_waitcnt lgkmcnt(0)
	v_lshlrev_b32_e32 v22, 16, v2
	v_and_b32_e32 v23, 0xffff0000, v2
	v_lshlrev_b32_e32 v70, 16, v3
	v_and_b32_e32 v71, 0xffff0000, v3
	v_lshlrev_b32_e32 v72, 16, v4
	v_and_b32_e32 v73, 0xffff0000, v4
	v_lshlrev_b32_e32 v78, 16, v5
	v_and_b32_e32 v79, 0xffff0000, v5
	ds_read_b128 v[2:5], v1 offset:4096
	ds_read_b128 v[14:17], v1 offset:4112
	ds_read_b128 v[18:21], v1 offset:2048
	ds_read_b128 v[66:69], v1 offset:2064
	v_pk_fma_f32 v[64:65], v[6:7], v[22:23], v[64:65]
	v_pk_fma_f32 v[62:63], v[8:9], v[70:71], v[62:63]
	v_pk_fma_f32 v[60:61], v[10:11], v[72:73], v[60:61]
	s_waitcnt lgkmcnt(0)
	v_pk_fma_f32 v[82:83], v[18:19], v[22:23], v[48:49]
	v_pk_fma_f32 v[84:85], v[20:21], v[70:71], v[46:47]
	v_pk_fma_f32 v[86:87], v[66:67], v[72:73], v[44:45]
	v_pk_fma_f32 v[88:89], v[68:69], v[78:79], v[50:51]
	ds_read_b128 v[44:47], v1
	ds_read_b128 v[48:51], v1 offset:16
	v_pk_fma_f32 v[80:81], v[12:13], v[78:79], v[34:35]
	v_pk_fma_f32 v[58:59], v[2:3], v[22:23], v[58:59]
	v_pk_fma_f32 v[56:57], v[4:5], v[70:71], v[56:57]
	v_pk_fma_f32 v[54:55], v[14:15], v[72:73], v[54:55]
	v_pk_fma_f32 v[52:53], v[16:17], v[78:79], v[52:53]
	s_waitcnt lgkmcnt(0)
	v_pk_fma_f32 v[22:23], v[44:45], v[22:23], v[42:43]
	v_pk_fma_f32 v[70:71], v[46:47], v[70:71], v[40:41]
	v_pk_fma_f32 v[72:73], v[48:49], v[72:73], v[38:39]
	v_pk_fma_f32 v[78:79], v[50:51], v[78:79], v[36:37]
	ds_read_b128 v[34:37], v0
	ds_read_b128 v[38:41], v1 offset:8192
	ds_read_b128 v[42:45], v1 offset:8208
	v_add_u32_e32 v0, 0x800, v0
	s_waitcnt lgkmcnt(0)
	v_lshlrev_b32_e32 v90, 16, v34
	v_and_b32_e32 v91, 0xffff0000, v34
	v_pk_fma_f32 v[64:65], v[38:39], v[90:91], v[64:65]
	v_lshlrev_b32_e32 v38, 16, v35
	v_and_b32_e32 v39, 0xffff0000, v35
	v_lshlrev_b32_e32 v92, 16, v36
	v_and_b32_e32 v93, 0xffff0000, v36
	v_lshlrev_b32_e32 v36, 16, v37
	v_and_b32_e32 v37, 0xffff0000, v37
	v_pk_fma_f32 v[62:63], v[40:41], v[38:39], v[62:63]
	v_pk_fma_f32 v[60:61], v[42:43], v[92:93], v[60:61]
	v_pk_fma_f32 v[34:35], v[44:45], v[36:37], v[80:81]
	v_pk_fma_f32 v[58:59], v[6:7], v[90:91], v[58:59]
	v_pk_fma_f32 v[56:57], v[8:9], v[38:39], v[56:57]
	v_pk_fma_f32 v[54:55], v[10:11], v[92:93], v[54:55]
	v_pk_fma_f32 v[52:53], v[12:13], v[36:37], v[52:53]
	v_pk_fma_f32 v[48:49], v[2:3], v[90:91], v[82:83]
	v_pk_fma_f32 v[46:47], v[4:5], v[38:39], v[84:85]
	v_pk_fma_f32 v[44:45], v[14:15], v[92:93], v[86:87]
	v_pk_fma_f32 v[50:51], v[16:17], v[36:37], v[88:89]
	v_pk_fma_f32 v[42:43], v[18:19], v[90:91], v[22:23]
	v_pk_fma_f32 v[40:41], v[20:21], v[38:39], v[70:71]
	v_pk_fma_f32 v[38:39], v[66:67], v[92:93], v[72:73]
	v_pk_fma_f32 v[36:37], v[68:69], v[36:37], v[78:79]
	s_cbranch_scc1 .LBB0_1181
	global_load_dwordx4 v[20:23], v[26:27], off offset:16
	global_load_dwordx4 v[16:19], v[26:27], off
	global_load_dwordx4 v[0:3], v[28:29], off offset:16
	global_load_dwordx4 v[8:11], v[28:29], off
	global_load_dwordx4 v[4:7], v[30:31], off offset:16
	global_load_dwordx4 v[12:15], v[30:31], off
	s_ashr_i32 s1, s0, 31
	s_lshl_b64 s[0:1], s[0:1], 12
	s_or_b32 s0, s0, s9
	s_ashr_i32 s3, s2, 31
	s_add_u32 s0, s0, s2
	s_addc_u32 s1, s1, s3
	s_lshl_b64 s[0:1], s[0:1], 10
	s_add_i32 s8, s8, s66
	s_cmpk_gt_i32 s8, 0x1ff
	s_waitcnt vmcnt(0)
	v_pk_add_f32 v[60:61], v[60:61], v[20:21]
	v_pk_add_f32 v[64:65], v[64:65], v[16:17]
	v_pk_add_f32 v[58:59], v[58:59], v[16:17]
	v_add_f32_e32 v66, 0, v64
	v_add_f32_e32 v72, 0, v58
	v_pk_add_f32 v[62:63], v[62:63], v[18:19]
	v_add_f32_e32 v66, v66, v65
	v_pk_add_f32 v[56:57], v[56:57], v[18:19]
	v_add_f32_e32 v72, v72, v59
	v_add_f32_e32 v66, v66, v62
	v_add_f32_e32 v72, v72, v56
	v_add_f32_e32 v66, v66, v63
	v_pk_add_f32 v[54:55], v[54:55], v[20:21]
	v_add_f32_e32 v72, v72, v57
	v_add_f32_e32 v66, v66, v60
	v_add_f32_e32 v72, v72, v54
	v_pk_add_f32 v[34:35], v[34:35], v[22:23]
	v_add_f32_e32 v66, v66, v61
	v_pk_add_f32 v[52:53], v[52:53], v[22:23]
	v_add_f32_e32 v72, v72, v55
	v_add_f32_e32 v66, v66, v34
	v_add_f32_e32 v72, v72, v52
	v_add_f32_e32 v66, v66, v35
	v_add_f32_e32 v72, v72, v53
	ds_bpermute_b32 v67, v193, v66
	ds_bpermute_b32 v73, v193, v72
	v_pk_add_f32 v[48:49], v[48:49], v[16:17]
	v_pk_add_f32 v[16:17], v[42:43], v[16:17]
	v_pk_add_f32 v[44:45], v[44:45], v[20:21]
	s_waitcnt lgkmcnt(1)
	v_add_f32_e32 v66, v66, v67
	s_waitcnt lgkmcnt(0)
	v_add_f32_e32 v72, v72, v73
	ds_bpermute_b32 v67, v194, v66
	ds_bpermute_b32 v73, v194, v72
	v_pk_add_f32 v[38:39], v[38:39], v[20:21]
	v_add_f32_e32 v20, 0, v16
	v_pk_add_f32 v[46:47], v[46:47], v[18:19]
	s_waitcnt lgkmcnt(1)
	v_add_f32_e32 v66, v66, v67
	s_waitcnt lgkmcnt(0)
	v_add_f32_e32 v72, v72, v73
	ds_bpermute_b32 v67, v195, v66
	ds_bpermute_b32 v73, v195, v72
	v_pk_add_f32 v[18:19], v[40:41], v[18:19]
	v_add_f32_e32 v20, v20, v17
	v_add_f32_e32 v20, v20, v18
	s_waitcnt lgkmcnt(1)
	v_add_f32_e32 v66, v66, v67
	s_waitcnt lgkmcnt(0)
	v_add_f32_e32 v72, v72, v73
	ds_bpermute_b32 v67, v196, v66
	ds_bpermute_b32 v73, v196, v72
	v_add_f32_e32 v20, v20, v19
	v_add_f32_e32 v20, v20, v38
	v_pk_add_f32 v[36:37], v[36:37], v[22:23]
	s_waitcnt lgkmcnt(1)
	v_add_f32_e32 v66, v66, v67
	s_waitcnt lgkmcnt(0)
	v_add_f32_e32 v72, v72, v73
	ds_bpermute_b32 v67, v197, v66
	ds_bpermute_b32 v73, v197, v72
	v_add_f32_e32 v20, v20, v39
	v_add_f32_e32 v20, v20, v36
	v_add_f32_e32 v20, v20, v37
	s_waitcnt lgkmcnt(1)
	v_add_f32_e32 v66, v66, v67
	s_waitcnt lgkmcnt(0)
; DI u32x4 pack8(const float* v) { u32x4 w; w.x = pk2(v[0], v[1]); w.y = pk2(v[2], v[3]); w.z = pk2(v[4], v[5]); w.w = pk2(v[6], v[7]); return w; }
; DI float sigmoidf_(float x) { return __builtin_amdgcn_rcpf(1.0f + __builtin_amdgcn_exp2f(x * -1.4426950408889634f)); }
; DI void conv_block(LAS unsigned char* lds, int b, int tb, int tid, const bf16_t* U, const float* cb, const float* lg, const float* lb, bf16_t* CC) {
;     ...
; #pragma unroll
;     for (int tt = 0; tt < 4; ++tt) {
;         float s = 0.f;
; #pragma unroll
;         for (int k = 0; k < 8; ++k) { acc[tt][k] += bb[k]; s += acc[tt][k]; }
;         const float mean = wave_sum(s) * (1.f / 512.f);
;         float q = 0.f;
; #pragma unroll
;         for (int k = 0; k < 8; ++k) { const float d = acc[tt][k] - mean; q += d * d; }
;         const float rstd = rsqrtf(wave_sum(q) * (1.f / 512.f) + EPS_);
;         float o[8];
; #pragma unroll
;         for (int k = 0; k < 8; ++k) { const float y = (acc[tt][k] - mean) * rstd * gg[k] + be[k]; o[k] = y * sigmoidf_(y); }
;         *(u32x4*)(CC + ((size_t)b * S_ + t00 + wave * 4 + tt) * 512 + c0) = pack8(o);
	v_add_f32_e32 v72, v72, v73
	ds_bpermute_b32 v67, v198, v66
	ds_bpermute_b32 v73, v198, v72
	ds_bpermute_b32 v21, v193, v20
	s_waitcnt lgkmcnt(2)
	v_add_f32_e32 v66, v66, v67
	s_waitcnt lgkmcnt(1)
	v_add_f32_e32 v72, v72, v73
	v_mul_f32_e32 v68, 0x3b000000, v66
	v_mul_f32_e32 v72, 0x3b000000, v72
	v_pk_add_f32 v[66:67], v[64:65], v[68:69] op_sel_hi:[1,0] neg_lo:[0,1] neg_hi:[0,1]
	v_pk_add_f32 v[58:59], v[58:59], v[72:73] op_sel_hi:[1,0] neg_lo:[0,1] neg_hi:[0,1]
	v_mov_b32_e32 v83, v67
	v_mov_b32_e32 v82, v59
	v_pk_add_f32 v[64:65], v[62:63], v[68:69] op_sel_hi:[1,0] neg_lo:[0,1] neg_hi:[0,1]
	v_pk_add_f32 v[56:57], v[56:57], v[72:73] op_sel_hi:[1,0] neg_lo:[0,1] neg_hi:[0,1]
	v_mov_b32_e32 v80, v58
	v_mov_b32_e32 v81, v66
	v_pk_mul_f32 v[82:83], v[82:83], v[82:83]
	v_pk_add_f32 v[62:63], v[60:61], v[68:69] op_sel_hi:[1,0] neg_lo:[0,1] neg_hi:[0,1]
	v_pk_add_f32 v[54:55], v[54:55], v[72:73] op_sel_hi:[1,0] neg_lo:[0,1] neg_hi:[0,1]
	v_pk_fma_f32 v[80:81], v[80:81], v[80:81], v[82:83]
	v_mov_b32_e32 v82, v56
	v_mov_b32_e32 v83, v64
	v_pk_mul_f32 v[70:71], v[62:63], v[62:63]
	v_pk_mul_f32 v[78:79], v[54:55], v[54:55]
	v_pk_fma_f32 v[80:81], v[82:83], v[82:83], v[80:81]
	v_mov_b32_e32 v82, v57
	v_mov_b32_e32 v83, v65
	v_pk_add_f32 v[60:61], v[34:35], v[68:69] op_sel_hi:[1,0] neg_lo:[0,1] neg_hi:[0,1]
	v_pk_fma_f32 v[80:81], v[82:83], v[82:83], v[80:81]
	v_mov_b32_e32 v82, v78
	v_mov_b32_e32 v83, v70
	v_pk_add_f32 v[72:73], v[52:53], v[72:73] op_sel_hi:[1,0] neg_lo:[0,1] neg_hi:[0,1]
	v_pk_mul_f32 v[68:69], v[60:61], v[60:61]
	v_pk_add_f32 v[80:81], v[82:83], v[80:81]
	v_pk_mul_f32 v[52:53], v[72:73], v[72:73]
	v_mov_b32_e32 v70, v79
	v_pk_add_f32 v[70:71], v[70:71], v[80:81]
	v_mov_b32_e32 v78, v52
	v_mov_b32_e32 v79, v68
	v_pk_add_f32 v[70:71], v[78:79], v[70:71]
	v_mov_b32_e32 v68, v53
	v_pk_add_f32 v[52:53], v[68:69], v[70:71]
	ds_bpermute_b32 v69, v193, v53
	ds_bpermute_b32 v68, v193, v52
	v_lshl_add_u64 v[34:35], v[32:33], 0, s[0:1]
	s_mov_b32 s0, 0x3b000000
	s_waitcnt lgkmcnt(2)
	v_add_f32_e32 v20, v20, v21
	ds_bpermute_b32 v21, v194, v20
	s_waitcnt lgkmcnt(1)
	v_pk_add_f32 v[52:53], v[52:53], v[68:69]
	ds_bpermute_b32 v69, v194, v53
	ds_bpermute_b32 v68, v194, v52
	s_waitcnt lgkmcnt(2)
	v_add_f32_e32 v20, v20, v21
	ds_bpermute_b32 v21, v195, v20
	s_waitcnt lgkmcnt(1)
	v_pk_add_f32 v[52:53], v[52:53], v[68:69]
	ds_bpermute_b32 v69, v195, v53
	ds_bpermute_b32 v68, v195, v52
	s_waitcnt lgkmcnt(2)
	v_add_f32_e32 v20, v20, v21
	ds_bpermute_b32 v21, v196, v20
	s_waitcnt lgkmcnt(1)
	v_pk_add_f32 v[52:53], v[52:53], v[68:69]
	ds_bpermute_b32 v69, v196, v53
	ds_bpermute_b32 v68, v196, v52
	s_waitcnt lgkmcnt(2)
	v_add_f32_e32 v20, v20, v21
	ds_bpermute_b32 v21, v197, v20
	s_waitcnt lgkmcnt(1)
	v_pk_add_f32 v[52:53], v[52:53], v[68:69]
	ds_bpermute_b32 v69, v197, v53
	ds_bpermute_b32 v68, v197, v52
	s_waitcnt lgkmcnt(2)
	v_add_f32_e32 v20, v20, v21
	ds_bpermute_b32 v21, v198, v20
	s_waitcnt lgkmcnt(1)
	v_pk_add_f32 v[52:53], v[52:53], v[68:69]
	ds_bpermute_b32 v69, v198, v53
	ds_bpermute_b32 v68, v198, v52
	s_waitcnt lgkmcnt(2)
	v_add_f32_e32 v20, v20, v21
	v_mul_f32_e32 v40, 0x3b000000, v20
	v_pk_add_f32 v[20:21], v[18:19], v[40:41] op_sel_hi:[1,0] neg_lo:[0,1] neg_hi:[0,1]
	v_pk_add_f32 v[18:19], v[38:39], v[40:41] op_sel_hi:[1,0] neg_lo:[0,1] neg_hi:[0,1]
	s_waitcnt lgkmcnt(0)
	v_pk_add_f32 v[68:69], v[52:53], v[68:69]
	v_mov_b64_e32 v[52:53], s[16:17]
	v_pk_fma_f32 v[68:69], v[68:69], s[0:1], v[52:53] op_sel_hi:[1,0,0]
	v_pk_mul_f32 v[38:39], v[18:19], v[18:19]
	v_mul_f32_e32 v70, 0x4b800000, v69
	v_cmp_gt_f32_e64 s[40:41], s97, v69
	v_cmp_gt_f32_e64 s[38:39], s97, v68
	s_nop 0
	v_cndmask_b32_e64 v69, v69, v70, s[40:41]
	v_rsq_f32_e32 v69, v69
	s_nop 0
	v_mul_f32_e32 v70, 0x45800000, v69
	v_cndmask_b32_e64 v70, v69, v70, s[40:41]
	v_pk_mul_f32 v[66:67], v[66:67], v[70:71] op_sel_hi:[1,0]
	v_pk_mul_f32 v[64:65], v[64:65], v[70:71] op_sel_hi:[1,0]
	v_pk_fma_f32 v[66:67], v[8:9], v[66:67], v[12:13]
	v_pk_fma_f32 v[64:65], v[10:11], v[64:65], v[14:15]
	v_mul_f32_e32 v69, 0xbfb8aa3b, v66
	v_exp_f32_e32 v69, v69
	v_pk_mul_f32 v[62:63], v[62:63], v[70:71] op_sel_hi:[1,0]
	v_pk_mul_f32 v[60:61], v[60:61], v[70:71] op_sel_hi:[1,0]
	v_pk_fma_f32 v[62:63], v[0:1], v[62:63], v[4:5]
	v_add_f32_e32 v69, 1.0, v69
	v_rcp_f32_e32 v78, v69
	v_mul_f32_e32 v69, 0xbfb8aa3b, v67
	v_exp_f32_e32 v69, v69
	v_pk_fma_f32 v[60:61], v[2:3], v[60:61], v[6:7]
	v_add_f32_e32 v69, 1.0, v69
	v_rcp_f32_e32 v79, v69
	v_mul_f32_e32 v69, 0xbfb8aa3b, v64
	v_exp_f32_e32 v69, v69
	v_pk_mul_f32 v[66:67], v[66:67], v[78:79]
	v_add_f32_e32 v69, 1.0, v69
	v_rcp_f32_e32 v78, v69
	v_mul_f32_e32 v69, 0xbfb8aa3b, v65
	v_exp_f32_e32 v69, v69
	s_nop 0
	v_add_f32_e32 v69, 1.0, v69
	v_rcp_f32_e32 v79, v69
	v_mul_f32_e32 v69, 0xbfb8aa3b, v62
	v_exp_f32_e32 v69, v69
	v_pk_mul_f32 v[64:65], v[64:65], v[78:79]
	v_add_f32_e32 v69, 1.0, v69
	v_rcp_f32_e32 v78, v69
	v_mul_f32_e32 v69, 0xbfb8aa3b, v63
	v_exp_f32_e32 v69, v69
	s_nop 0
	v_add_f32_e32 v69, 1.0, v69
	v_rcp_f32_e32 v79, v69
	v_mul_f32_e32 v69, 0xbfb8aa3b, v60
	v_exp_f32_e32 v69, v69
	v_pk_mul_f32 v[62:63], v[62:63], v[78:79]
	s_nop 0
	v_cvt_pk_bf16_f32 v62, v62, v63
	v_add_f32_e32 v69, 1.0, v69
	v_rcp_f32_e32 v70, v69
	v_mul_f32_e32 v69, 0xbfb8aa3b, v61
	v_exp_f32_e32 v69, v69
	s_nop 0
	v_add_f32_e32 v69, 1.0, v69
	v_rcp_f32_e32 v71, v69
	s_nop 0
	v_pk_mul_f32 v[70:71], v[60:61], v[70:71]
	v_cvt_pk_bf16_f32 v60, v66, v67
	v_cvt_pk_bf16_f32 v61, v64, v65
	v_cvt_pk_bf16_f32 v63, v70, v71
	global_store_dwordx4 v[34:35], v[60:63], off
	s_nop 1
	v_mul_f32_e32 v60, 0x4b800000, v68
	v_cndmask_b32_e64 v60, v68, v60, s[38:39]
	v_rsq_f32_e32 v60, v60
; DI u32x4 pack8(const float* v) { u32x4 w; w.x = pk2(v[0], v[1]); w.y = pk2(v[2], v[3]); w.z = pk2(v[4], v[5]); w.w = pk2(v[6], v[7]); return w; }
; DI float sigmoidf_(float x) { return __builtin_amdgcn_rcpf(1.0f + __builtin_amdgcn_exp2f(x * -1.4426950408889634f)); }
; DI void conv_block(LAS unsigned char* lds, int b, int tb, int tid, const bf16_t* U, const float* cb, const float* lg, const float* lb, bf16_t* CC) {
;     ...
; #pragma unroll
;     for (int tt = 0; tt < 4; ++tt) {
;         float s = 0.f;
; #pragma unroll
;         for (int k = 0; k < 8; ++k) { acc[tt][k] += bb[k]; s += acc[tt][k]; }
;         const float mean = wave_sum(s) * (1.f / 512.f);
;         float q = 0.f;
; #pragma unroll
;         for (int k = 0; k < 8; ++k) { const float d = acc[tt][k] - mean; q += d * d; }
;         const float rstd = rsqrtf(wave_sum(q) * (1.f / 512.f) + EPS_);
;         float o[8];
; #pragma unroll
;         for (int k = 0; k < 8; ++k) { const float y = (acc[tt][k] - mean) * rstd * gg[k] + be[k]; o[k] = y * sigmoidf_(y); }
;         *(u32x4*)(CC + ((size_t)b * S_ + t00 + wave * 4 + tt) * 512 + c0) = pack8(o);
	s_nop 0
	v_mul_f32_e32 v61, 0x45800000, v60
	v_cndmask_b32_e64 v60, v60, v61, s[38:39]
	v_pk_mul_f32 v[58:59], v[58:59], v[60:61] op_sel_hi:[1,0]
	s_nop 0
	v_pk_fma_f32 v[58:59], v[8:9], v[58:59], v[12:13]
	s_nop 0
	v_mul_f32_e32 v61, 0xbfb8aa3b, v58
	v_exp_f32_e32 v61, v61
	s_nop 0
	v_add_f32_e32 v61, 1.0, v61
	v_rcp_f32_e32 v62, v61
	v_mul_f32_e32 v61, 0xbfb8aa3b, v59
	v_exp_f32_e32 v61, v61
	s_nop 0
	v_add_f32_e32 v61, 1.0, v61
	v_pk_mul_f32 v[56:57], v[56:57], v[60:61] op_sel_hi:[1,0]
	v_rcp_f32_e32 v63, v61
	v_pk_fma_f32 v[56:57], v[10:11], v[56:57], v[14:15]
	v_pk_mul_f32 v[58:59], v[58:59], v[62:63]
	v_mul_f32_e32 v61, 0xbfb8aa3b, v56
	v_exp_f32_e32 v61, v61
	s_nop 0
	v_add_f32_e32 v61, 1.0, v61
	v_rcp_f32_e32 v62, v61
	v_mul_f32_e32 v61, 0xbfb8aa3b, v57
	v_exp_f32_e32 v61, v61
	s_nop 0
	v_add_f32_e32 v61, 1.0, v61
	v_pk_mul_f32 v[54:55], v[54:55], v[60:61] op_sel_hi:[1,0]
	v_rcp_f32_e32 v63, v61
	v_pk_fma_f32 v[54:55], v[0:1], v[54:55], v[4:5]
	v_pk_mul_f32 v[56:57], v[56:57], v[62:63]
	v_mul_f32_e32 v61, 0xbfb8aa3b, v54
	v_exp_f32_e32 v61, v61
	s_nop 0
	v_add_f32_e32 v61, 1.0, v61
	v_rcp_f32_e32 v62, v61
	v_mul_f32_e32 v61, 0xbfb8aa3b, v55
	v_exp_f32_e32 v61, v61
	s_nop 0
	v_add_f32_e32 v61, 1.0, v61
	v_rcp_f32_e32 v63, v61
	s_nop 0
	v_pk_mul_f32 v[62:63], v[54:55], v[62:63]
	v_pk_mul_f32 v[54:55], v[72:73], v[60:61] op_sel_hi:[1,0]
	s_nop 0
	v_pk_fma_f32 v[54:55], v[2:3], v[54:55], v[6:7]
	s_nop 0
	v_mul_f32_e32 v60, 0xbfb8aa3b, v54
	v_mul_f32_e32 v61, 0xbfb8aa3b, v55
	v_exp_f32_e32 v60, v60
	v_exp_f32_e32 v61, v61
	v_add_f32_e32 v60, 1.0, v60
	v_add_f32_e32 v61, 1.0, v61
	v_rcp_f32_e32 v60, v60
	v_rcp_f32_e32 v61, v61
	s_nop 0
	v_pk_mul_f32 v[60:61], v[54:55], v[60:61]
	v_cvt_pk_bf16_f32 v54, v58, v59
	v_cvt_pk_bf16_f32 v55, v56, v57
	v_cvt_pk_bf16_f32 v56, v62, v63
	v_cvt_pk_bf16_f32 v57, v60, v61
	global_store_dwordx4 v[34:35], v[54:57], off offset:1024
	s_nop 1
	v_pk_add_f32 v[54:55], v[50:51], v[22:23]
	v_add_f32_e32 v50, 0, v48
	v_add_f32_e32 v50, v50, v49
	v_add_f32_e32 v50, v50, v46
	v_add_f32_e32 v50, v50, v47
	v_add_f32_e32 v50, v50, v44
	v_add_f32_e32 v50, v50, v45
	v_add_f32_e32 v50, v50, v54
	v_add_f32_e32 v50, v50, v55
	ds_bpermute_b32 v51, v193, v50
	v_pk_add_f32 v[22:23], v[16:17], v[40:41] op_sel_hi:[1,0] neg_lo:[0,1] neg_hi:[0,1]
	s_waitcnt lgkmcnt(0)
	v_add_f32_e32 v50, v50, v51
	ds_bpermute_b32 v51, v194, v50
	v_mov_b32_e32 v42, v23
	v_mov_b32_e32 v16, v22
	s_waitcnt lgkmcnt(0)
	v_add_f32_e32 v50, v50, v51
	ds_bpermute_b32 v51, v195, v50
	s_waitcnt lgkmcnt(0)
	v_add_f32_e32 v50, v50, v51
	ds_bpermute_b32 v51, v196, v50
	s_waitcnt lgkmcnt(0)
	v_add_f32_e32 v50, v50, v51
	ds_bpermute_b32 v51, v197, v50
	s_waitcnt lgkmcnt(0)
	v_add_f32_e32 v50, v50, v51
	ds_bpermute_b32 v51, v198, v50
	s_waitcnt lgkmcnt(0)
	v_add_f32_e32 v50, v50, v51
	v_mul_f32_e32 v56, 0x3b000000, v50
	v_pk_add_f32 v[50:51], v[48:49], v[56:57] op_sel_hi:[1,0] neg_lo:[0,1] neg_hi:[0,1]
	v_pk_add_f32 v[48:49], v[46:47], v[56:57] op_sel_hi:[1,0] neg_lo:[0,1] neg_hi:[0,1]
	v_mov_b32_e32 v43, v51
	v_mov_b32_e32 v17, v50
	v_pk_mul_f32 v[42:43], v[42:43], v[42:43]
	v_pk_add_f32 v[46:47], v[44:45], v[56:57] op_sel_hi:[1,0] neg_lo:[0,1] neg_hi:[0,1]
	v_pk_fma_f32 v[16:17], v[16:17], v[16:17], v[42:43]
	v_mov_b32_e32 v42, v20
	v_mov_b32_e32 v43, v48
	v_pk_mul_f32 v[58:59], v[46:47], v[46:47]
	v_pk_fma_f32 v[16:17], v[42:43], v[42:43], v[16:17]
	v_mov_b32_e32 v42, v21
	v_mov_b32_e32 v43, v49
	v_pk_fma_f32 v[16:17], v[42:43], v[42:43], v[16:17]
	v_mov_b32_e32 v42, v38
	v_mov_b32_e32 v43, v58
	v_pk_add_f32 v[44:45], v[54:55], v[56:57] op_sel_hi:[1,0] neg_lo:[0,1] neg_hi:[0,1]
	v_pk_add_f32 v[42:43], v[42:43], v[16:17]
	v_pk_add_f32 v[16:17], v[36:37], v[40:41] op_sel_hi:[1,0] neg_lo:[0,1] neg_hi:[0,1]
	v_pk_mul_f32 v[54:55], v[44:45], v[44:45]
	v_pk_mul_f32 v[36:37], v[16:17], v[16:17]
	v_mov_b32_e32 v58, v39
	v_pk_add_f32 v[38:39], v[58:59], v[42:43]
	v_mov_b32_e32 v40, v36
	v_mov_b32_e32 v41, v54
	v_pk_add_f32 v[38:39], v[40:41], v[38:39]
	v_mov_b32_e32 v54, v37
	v_pk_add_f32 v[36:37], v[54:55], v[38:39]
	ds_bpermute_b32 v39, v193, v37
	ds_bpermute_b32 v38, v193, v36
	s_waitcnt lgkmcnt(0)
	v_pk_add_f32 v[36:37], v[36:37], v[38:39]
	ds_bpermute_b32 v39, v194, v37
	ds_bpermute_b32 v38, v194, v36
	s_waitcnt lgkmcnt(0)
	v_pk_add_f32 v[36:37], v[36:37], v[38:39]
	ds_bpermute_b32 v39, v195, v37
	ds_bpermute_b32 v38, v195, v36
	s_waitcnt lgkmcnt(0)
	v_pk_add_f32 v[36:37], v[36:37], v[38:39]
	ds_bpermute_b32 v39, v196, v37
	ds_bpermute_b32 v38, v196, v36
	s_waitcnt lgkmcnt(0)
; DI u32x4 pack8(const float* v) { u32x4 w; w.x = pk2(v[0], v[1]); w.y = pk2(v[2], v[3]); w.z = pk2(v[4], v[5]); w.w = pk2(v[6], v[7]); return w; }
; DI float sigmoidf_(float x) { return __builtin_amdgcn_rcpf(1.0f + __builtin_amdgcn_exp2f(x * -1.4426950408889634f)); }
; DI void conv_block(LAS unsigned char* lds, int b, int tb, int tid, const bf16_t* U, const float* cb, const float* lg, const float* lb, bf16_t* CC) {
;     ...
; #pragma unroll
;     for (int tt = 0; tt < 4; ++tt) {
;         float s = 0.f;
; #pragma unroll
;         for (int k = 0; k < 8; ++k) { acc[tt][k] += bb[k]; s += acc[tt][k]; }
;         const float mean = wave_sum(s) * (1.f / 512.f);
;         float q = 0.f;
; #pragma unroll
;         for (int k = 0; k < 8; ++k) { const float d = acc[tt][k] - mean; q += d * d; }
;         const float rstd = rsqrtf(wave_sum(q) * (1.f / 512.f) + EPS_);
;         float o[8];
; #pragma unroll
;         for (int k = 0; k < 8; ++k) { const float y = (acc[tt][k] - mean) * rstd * gg[k] + be[k]; o[k] = y * sigmoidf_(y); }
;         *(u32x4*)(CC + ((size_t)b * S_ + t00 + wave * 4 + tt) * 512 + c0) = pack8(o);
;     }
	v_pk_add_f32 v[36:37], v[36:37], v[38:39]
	ds_bpermute_b32 v39, v197, v37
	ds_bpermute_b32 v38, v197, v36
	s_waitcnt lgkmcnt(0)
	v_pk_add_f32 v[36:37], v[36:37], v[38:39]
	ds_bpermute_b32 v39, v198, v37
	ds_bpermute_b32 v38, v198, v36
	s_waitcnt lgkmcnt(0)
	v_pk_add_f32 v[36:37], v[36:37], v[38:39]
	s_nop 0
	v_pk_fma_f32 v[40:41], v[36:37], s[0:1], v[52:53] op_sel_hi:[1,0,0]
	s_nop 0
	v_mul_f32_e32 v36, 0x4b800000, v41
	v_cmp_gt_f32_e64 s[40:41], s97, v41
	v_cmp_gt_f32_e64 s[38:39], s97, v40
	s_nop 0
	v_cndmask_b32_e64 v36, v41, v36, s[40:41]
	v_rsq_f32_e32 v36, v36
	s_nop 0
	v_mul_f32_e32 v37, 0x45800000, v36
	v_cndmask_b32_e64 v36, v36, v37, s[40:41]
	v_pk_mul_f32 v[38:39], v[50:51], v[36:37] op_sel_hi:[1,0]
	s_nop 0
	v_pk_fma_f32 v[38:39], v[8:9], v[38:39], v[12:13]
	s_nop 0
	v_mul_f32_e32 v37, 0xbfb8aa3b, v38
	v_exp_f32_e32 v37, v37
	s_nop 0
	v_add_f32_e32 v37, 1.0, v37
	v_rcp_f32_e32 v42, v37
	v_mul_f32_e32 v37, 0xbfb8aa3b, v39
	v_exp_f32_e32 v37, v37
	s_nop 0
	v_add_f32_e32 v37, 1.0, v37
	v_rcp_f32_e32 v43, v37
	s_nop 0
	v_pk_mul_f32 v[38:39], v[38:39], v[42:43]
	v_pk_mul_f32 v[42:43], v[48:49], v[36:37] op_sel_hi:[1,0]
	s_nop 0
	v_pk_fma_f32 v[42:43], v[10:11], v[42:43], v[14:15]
	s_nop 0
	v_mul_f32_e32 v37, 0xbfb8aa3b, v42
	v_exp_f32_e32 v37, v37
	s_nop 0
	v_add_f32_e32 v37, 1.0, v37
	v_rcp_f32_e32 v48, v37
	v_mul_f32_e32 v37, 0xbfb8aa3b, v43
	v_exp_f32_e32 v37, v37
	s_nop 0
	v_add_f32_e32 v37, 1.0, v37
	v_pk_mul_f32 v[46:47], v[46:47], v[36:37] op_sel_hi:[1,0]
	v_rcp_f32_e32 v49, v37
	v_pk_fma_f32 v[46:47], v[0:1], v[46:47], v[4:5]
	v_pk_mul_f32 v[42:43], v[42:43], v[48:49]
	v_mul_f32_e32 v37, 0xbfb8aa3b, v46
	v_exp_f32_e32 v37, v37
	s_nop 0
	v_add_f32_e32 v37, 1.0, v37
	v_rcp_f32_e32 v48, v37
	v_mul_f32_e32 v37, 0xbfb8aa3b, v47
	v_exp_f32_e32 v37, v37
	s_nop 0
	v_add_f32_e32 v37, 1.0, v37
	v_rcp_f32_e32 v49, v37
	v_pk_mul_f32 v[36:37], v[44:45], v[36:37] op_sel_hi:[1,0]
	v_pk_mul_f32 v[46:47], v[46:47], v[48:49]
	v_pk_fma_f32 v[36:37], v[2:3], v[36:37], v[6:7]
	s_nop 0
	v_mul_f32_e32 v41, 0xbfb8aa3b, v36
	v_exp_f32_e32 v41, v41
	s_nop 0
	v_add_f32_e32 v41, 1.0, v41
	v_rcp_f32_e32 v44, v41
	v_mul_f32_e32 v41, 0xbfb8aa3b, v37
	v_exp_f32_e32 v41, v41
	s_nop 0
	v_add_f32_e32 v41, 1.0, v41
	v_rcp_f32_e32 v45, v41
	s_nop 0
	v_pk_mul_f32 v[44:45], v[36:37], v[44:45]
	v_cvt_pk_bf16_f32 v36, v38, v39
	v_cvt_pk_bf16_f32 v37, v42, v43
	v_cvt_pk_bf16_f32 v38, v46, v47
	v_cvt_pk_bf16_f32 v39, v44, v45
	global_store_dwordx4 v[34:35], v[36:39], off offset:2048
	s_nop 1
	v_mul_f32_e32 v36, 0x4b800000, v40
	v_cndmask_b32_e64 v36, v40, v36, s[38:39]
	v_rsq_f32_e32 v36, v36
	s_nop 0
	v_mul_f32_e32 v37, 0x45800000, v36
	v_cndmask_b32_e64 v36, v36, v37, s[38:39]
	v_pk_mul_f32 v[22:23], v[22:23], v[36:37] op_sel_hi:[1,0]
	s_nop 0
	v_pk_fma_f32 v[8:9], v[8:9], v[22:23], v[12:13]
	s_nop 0
	v_mul_f32_e32 v12, 0xbfb8aa3b, v8
	v_mul_f32_e32 v13, 0xbfb8aa3b, v9
	v_exp_f32_e32 v12, v12
	v_exp_f32_e32 v13, v13
	v_add_f32_e32 v12, 1.0, v12
	v_add_f32_e32 v13, 1.0, v13
	v_rcp_f32_e32 v12, v12
	v_rcp_f32_e32 v13, v13
	s_nop 0
	v_pk_mul_f32 v[8:9], v[8:9], v[12:13]
	v_pk_mul_f32 v[12:13], v[20:21], v[36:37] op_sel_hi:[1,0]
	s_nop 0
	v_pk_fma_f32 v[10:11], v[10:11], v[12:13], v[14:15]
	s_nop 0
	v_mul_f32_e32 v12, 0xbfb8aa3b, v10
	v_mul_f32_e32 v13, 0xbfb8aa3b, v11
	v_exp_f32_e32 v12, v12
	v_exp_f32_e32 v13, v13
	v_add_f32_e32 v12, 1.0, v12
	v_add_f32_e32 v13, 1.0, v13
	v_rcp_f32_e32 v12, v12
	v_rcp_f32_e32 v13, v13
	s_nop 0
	v_pk_mul_f32 v[10:11], v[10:11], v[12:13]
	v_pk_mul_f32 v[12:13], v[18:19], v[36:37] op_sel_hi:[1,0]
	s_nop 0
	v_pk_fma_f32 v[0:1], v[0:1], v[12:13], v[4:5]
	s_nop 0
	v_mul_f32_e32 v4, 0xbfb8aa3b, v0
	v_mul_f32_e32 v5, 0xbfb8aa3b, v1
	v_exp_f32_e32 v4, v4
	v_exp_f32_e32 v5, v5
	v_add_f32_e32 v4, 1.0, v4
	v_add_f32_e32 v5, 1.0, v5
	v_rcp_f32_e32 v4, v4
	v_rcp_f32_e32 v5, v5
	s_nop 0
	v_pk_mul_f32 v[4:5], v[0:1], v[4:5]
	v_pk_mul_f32 v[0:1], v[16:17], v[36:37] op_sel_hi:[1,0]
	s_nop 0
	v_pk_fma_f32 v[0:1], v[2:3], v[0:1], v[6:7]
	s_nop 0
	v_mul_f32_e32 v2, 0xbfb8aa3b, v0
	v_mul_f32_e32 v3, 0xbfb8aa3b, v1
	v_exp_f32_e32 v2, v2
	v_exp_f32_e32 v3, v3
	v_add_f32_e32 v2, 1.0, v2
	v_add_f32_e32 v3, 1.0, v3
	v_rcp_f32_e32 v2, v2
	v_rcp_f32_e32 v3, v3
	s_nop 0
	v_pk_mul_f32 v[6:7], v[0:1], v[2:3]
	v_cvt_pk_bf16_f32 v0, v8, v9
	v_cvt_pk_bf16_f32 v1, v10, v11
	v_cvt_pk_bf16_f32 v2, v4, v5
	v_cvt_pk_bf16_f32 v3, v6, v7
	global_store_dwordx4 v[34:35], v[0:3], off offset:3072
	s_cbranch_scc0 .LBB0_1175

; DI unsigned pk2(float lo, float hi) { f32x2 v = {lo, hi}; bf16x2_t b = __builtin_convertvector(v, bf16x2_t); return __builtin_bit_cast(unsigned, b); }
; template <bool MASK>
; DI void attn_unit(LAS unsigned char* lds, const bf16_t* qrow, const bf16_t* kbase, int kpitch, const bf16_t* vtbase, int vtpitch, int ntiles,
;                   const unsigned long long* maskp, bf16_t* orow, float c1, float c2) {
;     ...
;     l += __shfl_xor(l, 32);
;     const float inv = 1.0f / l;
; #pragma unroll
;     for (int dt = 0; dt < 4; ++dt)
; #pragma unroll
;         for (int ig = 0; ig < 4; ++ig) {
;             u32x2 w; w.x = pk2(o[dt][4 * ig] * inv, o[dt][4 * ig + 1] * inv); w.y = pk2(o[dt][4 * ig + 2] * inv, o[dt][4 * ig + 3] * inv);
;             *(u32x2*)(orow + 32 * dt + 8 * ig + 4 * h) = w;
;         }
.LBB0_1238:
	ds_bpermute_b32 v65, v198, v149
	v_lshl_add_u64 v[66:67], v[144:145], 1, s[6:7]
	v_lshl_add_u64 v[68:69], v[66:67], 0, s[70:71]
	s_waitcnt lgkmcnt(0)
	v_add_f32_e32 v65, v149, v65
	v_div_scale_f32 v66, s[2:3], v65, v65, 1.0
	v_rcp_f32_e32 v67, v66
	s_nop 0
	v_fma_f32 v70, -v66, v67, 1.0
	v_fmac_f32_e32 v67, v70, v67
	v_div_scale_f32 v70, vcc, 1.0, v65, 1.0
	v_mul_f32_e32 v71, v70, v67
	v_fma_f32 v72, -v66, v71, v70
	v_fmac_f32_e32 v71, v72, v67
	v_fma_f32 v66, -v66, v71, v70
	v_div_fmas_f32 v66, v66, v67, v71
	v_div_fixup_f32 v66, v66, v65, 1.0
	v_mov_b32_e32 v65, v161
	v_pk_mul_f32 v[48:49], v[48:49], v[66:67] op_sel_hi:[1,0]
	v_pk_mul_f32 v[50:51], v[50:51], v[66:67] op_sel_hi:[1,0]
	v_pk_mul_f32 v[32:33], v[32:33], v[66:67] op_sel_hi:[1,0]
	v_pk_mul_f32 v[34:35], v[34:35], v[66:67] op_sel_hi:[1,0]
	v_pk_mul_f32 v[16:17], v[16:17], v[66:67] op_sel_hi:[1,0]
	v_pk_mul_f32 v[18:19], v[18:19], v[66:67] op_sel_hi:[1,0]
	v_pk_mul_f32 v[0:1], v[0:1], v[66:67] op_sel_hi:[1,0]
	v_pk_mul_f32 v[2:3], v[2:3], v[66:67] op_sel_hi:[1,0]
	v_lshl_add_u64 v[64:65], v[64:65], 1, v[68:69]
	v_cvt_pk_bf16_f32 v48, v48, v49
	v_cvt_pk_bf16_f32 v49, v50, v51
	v_cvt_pk_bf16_f32 v32, v32, v33
	v_cvt_pk_bf16_f32 v33, v34, v35
	v_cvt_pk_bf16_f32 v16, v16, v17
	v_cvt_pk_bf16_f32 v17, v18, v19
	v_cvt_pk_bf16_f32 v0, v0, v1
	v_cvt_pk_bf16_f32 v1, v2, v3
	global_store_dwordx2 v[64:65], v[48:49], off
	v_pk_mul_f32 v[48:49], v[52:53], v[66:67] op_sel_hi:[1,0]
	v_pk_mul_f32 v[50:51], v[54:55], v[66:67] op_sel_hi:[1,0]
	global_store_dwordx2 v[64:65], v[32:33], off offset:64
	v_pk_mul_f32 v[32:33], v[36:37], v[66:67] op_sel_hi:[1,0]
	v_pk_mul_f32 v[34:35], v[38:39], v[66:67] op_sel_hi:[1,0]
	global_store_dwordx2 v[64:65], v[16:17], off offset:128
	v_pk_mul_f32 v[16:17], v[20:21], v[66:67] op_sel_hi:[1,0]
	v_pk_mul_f32 v[18:19], v[22:23], v[66:67] op_sel_hi:[1,0]
	global_store_dwordx2 v[64:65], v[0:1], off offset:192
	v_pk_mul_f32 v[0:1], v[4:5], v[66:67] op_sel_hi:[1,0]
	v_pk_mul_f32 v[2:3], v[6:7], v[66:67] op_sel_hi:[1,0]
	v_cvt_pk_bf16_f32 v48, v48, v49
	v_cvt_pk_bf16_f32 v49, v50, v51
	v_cvt_pk_bf16_f32 v32, v32, v33
	v_cvt_pk_bf16_f32 v33, v34, v35
	v_cvt_pk_bf16_f32 v16, v16, v17
	v_cvt_pk_bf16_f32 v17, v18, v19
	v_cvt_pk_bf16_f32 v0, v0, v1
	v_cvt_pk_bf16_f32 v1, v2, v3
	global_store_dwordx2 v[64:65], v[48:49], off offset:16
	v_pk_mul_f32 v[48:49], v[56:57], v[66:67] op_sel_hi:[1,0]
	v_pk_mul_f32 v[50:51], v[58:59], v[66:67] op_sel_hi:[1,0]
	global_store_dwordx2 v[64:65], v[32:33], off offset:80
	v_pk_mul_f32 v[32:33], v[40:41], v[66:67] op_sel_hi:[1,0]
	v_pk_mul_f32 v[34:35], v[42:43], v[66:67] op_sel_hi:[1,0]
	global_store_dwordx2 v[64:65], v[16:17], off offset:144
	v_pk_mul_f32 v[16:17], v[24:25], v[66:67] op_sel_hi:[1,0]
	v_pk_mul_f32 v[18:19], v[26:27], v[66:67] op_sel_hi:[1,0]
	global_store_dwordx2 v[64:65], v[0:1], off offset:208
	v_pk_mul_f32 v[0:1], v[8:9], v[66:67] op_sel_hi:[1,0]
	v_pk_mul_f32 v[2:3], v[10:11], v[66:67] op_sel_hi:[1,0]
	v_cvt_pk_bf16_f32 v48, v48, v49
	v_cvt_pk_bf16_f32 v49, v50, v51
	v_cvt_pk_bf16_f32 v32, v32, v33
	v_cvt_pk_bf16_f32 v33, v34, v35
	v_cvt_pk_bf16_f32 v16, v16, v17
	v_cvt_pk_bf16_f32 v17, v18, v19
	v_cvt_pk_bf16_f32 v0, v0, v1
	v_cvt_pk_bf16_f32 v1, v2, v3
	global_store_dwordx2 v[64:65], v[48:49], off offset:32
	v_pk_mul_f32 v[48:49], v[60:61], v[66:67] op_sel_hi:[1,0]
	v_pk_mul_f32 v[50:51], v[62:63], v[66:67] op_sel_hi:[1,0]
	global_store_dwordx2 v[64:65], v[32:33], off offset:96
	v_pk_mul_f32 v[32:33], v[44:45], v[66:67] op_sel_hi:[1,0]
	v_pk_mul_f32 v[34:35], v[46:47], v[66:67] op_sel_hi:[1,0]
	global_store_dwordx2 v[64:65], v[16:17], off offset:160
	v_pk_mul_f32 v[16:17], v[28:29], v[66:67] op_sel_hi:[1,0]
	v_pk_mul_f32 v[18:19], v[30:31], v[66:67] op_sel_hi:[1,0]
	global_store_dwordx2 v[64:65], v[0:1], off offset:224
	v_pk_mul_f32 v[0:1], v[12:13], v[66:67] op_sel_hi:[1,0]
	v_pk_mul_f32 v[2:3], v[14:15], v[66:67] op_sel_hi:[1,0]
	v_cvt_pk_bf16_f32 v48, v48, v49
	v_cvt_pk_bf16_f32 v49, v50, v51
	v_cvt_pk_bf16_f32 v32, v32, v33
	v_cvt_pk_bf16_f32 v33, v34, v35
	v_cvt_pk_bf16_f32 v16, v16, v17
	v_cvt_pk_bf16_f32 v17, v18, v19
	v_cvt_pk_bf16_f32 v0, v0, v1
	v_cvt_pk_bf16_f32 v1, v2, v3
	global_store_dwordx2 v[64:65], v[48:49], off offset:48
	global_store_dwordx2 v[64:65], v[32:33], off offset:112
	global_store_dwordx2 v[64:65], v[16:17], off offset:176
	global_store_dwordx2 v[64:65], v[0:1], off offset:240

; #define LAS __attribute__((address_space(3)))
; template <bool MASK>
; DI void attn_unit(LAS unsigned char* lds, const bf16_t* qrow, const bf16_t* kbase, int kpitch, const bf16_t* vtbase, int vtpitch, int ntiles,
;                   const unsigned long long* maskp, bf16_t* orow, float c1, float c2) {
;     ...
;     const int ke0 = tid, ke1 = tid + 512;
;     const bf16_t* kg0 = kbase + (size_t)(ke0 >> 4) * kpitch + (ke0 & 15) * 8; const bf16_t* kg1 = kbase + (size_t)(ke1 >> 4) * kpitch + (ke1 & 15) * 8;
;     const int kl0 = (ke0 >> 4) * AK_PITCH + (ke0 & 15) * 16, kl1 = (ke1 >> 4) * AK_PITCH + (ke1 & 15) * 16;
;     const bf16_t* vg0 = vtbase + (size_t)(ke0 >> 3) * vtpitch + (ke0 & 7) * 8; const bf16_t* vg1 = vtbase + (size_t)(ke1 >> 3) * vtpitch + (ke1 & 7) * 8;
;     const int vl0 = AK_BYTES + (ke0 >> 3) * AV_PITCH + (ke0 & 7) * 16, vl1 = AK_BYTES + (ke1 >> 3) * AV_PITCH + (ke1 & 7) * 16;
;     pk[0] = *(const u32x4*)kg0; pk[1] = *(const u32x4*)kg1; pv[0] = *(const u32x4*)vg0; pv[1] = *(const u32x4*)vg1;
;     {
;         LAS unsigned char* nb = lds;
;         *(LAS u32x4*)(nb + kl0) = pk[0]; *(LAS u32x4*)(nb + kl1) = pk[1];
;         *(LAS u32x2*)(nb + vl0) = (u32x2){pv[0].x, pv[0].y}; *(LAS u32x2*)(nb + vl0 + 8) = (u32x2){pv[0].z, pv[0].w};
;         *(LAS u32x2*)(nb + vl1) = (u32x2){pv[1].x, pv[1].y}; *(LAS u32x2*)(nb + vl1 + 8) = (u32x2){pv[1].z, pv[1].w};
;     }
;     unsigned long long mw_next = ~0ull;
;     if (MASK) mw_next = maskp[0];
;     __syncthreads();
; __global__ void __launch_bounds__(512, 2) fwd_megakernel(Args args) {
;     ...
;             for (int k = 0; k < (512 + G - 1) / G; ++k) {
;                 const int it = k * G + c;
;                 if (it < 512) {
;                     const int kk = it / 256, cc = it % 256;
;                     const int bk = cc & 7, j = cc >> 3, qb = kk ? (63 - j) : j, b = bk >> 1, kvh = bk & 1;
;                     const int gh = wave & 3, half = wave >> 2, hq = kvh * 4 + gh;
;                     const int tq = qb * 64 + half * 32 + (lane & 31);
;                     const size_t qr = (size_t)b * S_ + tq;
;     ...
;                     attn_unit<true>(lds, Q + qr * 1024 + hq * 128, Kb + (size_t)b * S_ * 256 + kvh * 128, 256, VT + (size_t)bk * 128 * S_, S_, qb + 1,
;                                     MASK + (size_t)b * 64 * S_ + tq, OA + qr * 1024 + hq * 128, 0.08838834764831845f * 1.4426950408889634f, c2a);
.LBB0_1240:
	s_mul_i32 s2, s15, s66
	s_add_i32 s2, s2, s86
	s_cmpk_gt_i32 s2, 0x1ff
	s_cbranch_scc1 .LBB0_1239
	s_ashr_i32 s3, s2, 31
	s_lshr_b32 s3, s3, 24
	s_add_i32 s3, s2, s3
	s_and_b32 s3, s3, 0xffffff00
	s_sub_i32 s3, s2, s3
	s_ashr_i32 s16, s3, 3
	s_and_b32 s17, s3, 7
	s_addk_i32 s2, 0xff
	s_sub_i32 s18, 63, s16
	s_cmpk_lt_u32 s2, 0x1ff
	s_cselect_b32 s16, s16, s18
	s_lshl_b32 s18, s16, 6
	s_bfe_u32 s2, s3, 0x20001
	s_and_b32 s3, s3, 1
	v_add_u32_e32 v66, s18, v179
	v_ashrrev_i32_e32 v67, 31, v66
	s_lshl_b32 s18, s3, 9
	s_lshl_b32 s70, s2, 22
	v_lshlrev_b64 v[0:1], 10, v[66:67]
	s_or_b32 s18, s18, s8
	v_lshl_add_u64 v[144:145], v[0:1], 0, s[70:71]
	s_lshl_b32 s70, s18, 1
	s_lshl_b32 s18, s2, 21
	s_add_u32 s2, s9, s18
	s_addc_u32 s19, s10, 0
	s_lshl_b32 s22, s3, 8
	v_mov_b32_e32 v65, v186
	s_add_u32 s2, s2, s22
	s_addc_u32 s3, s19, 0
	v_add_u32_e32 v16, 0x200, v65
	v_ashrrev_i32_e32 v0, 4, v65
	s_lshl_b32 s19, s17, 20
	v_ashrrev_i32_e32 v1, 31, v0
	v_ashrrev_i32_e32 v6, 4, v16
	v_ashrrev_i32_e32 v10, 3, v65
	v_ashrrev_i32_e32 v16, 3, v16
	s_add_u32 s30, s11, s19
	v_lshlrev_b64 v[68:69], 9, v[0:1]
	v_lshlrev_b32_e32 v1, 4, v65
	v_ashrrev_i32_e32 v7, 31, v6
	v_ashrrev_i32_e32 v11, 31, v10
	v_ashrrev_i32_e32 v17, 31, v16
	s_addc_u32 s31, s12, 0
	v_lshl_add_u64 v[2:3], s[2:3], 0, v[68:69]
	v_and_b32_e32 v4, 0xf0, v1
	v_mov_b32_e32 v5, v161
	v_lshlrev_b64 v[70:71], 9, v[6:7]
	v_lshlrev_b64 v[72:73], 13, v[10:11]
	v_lshlrev_b64 v[74:75], 13, v[16:17]
	v_lshl_add_u64 v[2:3], v[2:3], 0, v[4:5]
	v_lshl_add_u64 v[8:9], s[2:3], 0, v[70:71]
	v_lshl_add_u64 v[12:13], s[30:31], 0, v[72:73]
	v_and_b32_e32 v14, 0x70, v1
	v_mov_b32_e32 v15, v161
	v_lshl_add_u64 v[18:19], s[30:31], 0, v[74:75]
	v_lshl_add_u64 v[8:9], v[8:9], 0, v[4:5]
	v_lshl_add_u64 v[12:13], v[12:13], 0, v[14:15]
	v_lshl_add_u64 v[18:19], v[18:19], 0, v[14:15]
	global_load_dwordx4 v[96:99], v[2:3], off
	global_load_dwordx4 v[100:103], v[8:9], off
	global_load_dwordx4 v[104:107], v[12:13], off
	global_load_dwordx4 v[108:111], v[18:19], off
	s_movk_i32 s17, 0x110
	v_mad_u64_u32 v[146:147], s[2:3], v0, s17, v[4:5]
	v_mad_u64_u32 v[148:149], s[2:3], v6, s17, v[4:5]
	s_movk_i32 s17, 0x88
	v_mad_u64_u32 v[150:151], s[2:3], v10, s17, v[14:15]
	v_mad_u64_u32 v[152:153], s[2:3], v16, s17, v[14:15]
	v_add_u32_e32 v0, 0, v150
	v_add_u32_e32 v1, 0, v152
	v_bfe_u32 v76, v65, 5, 1
	v_add_u32_e32 v4, 0x4400, v0
	v_add_u32_e32 v5, 0x4400, v1
	v_lshl_add_u64 v[0:1], v[144:145], 1, s[4:5]
	v_lshlrev_b32_e32 v160, 4, v76
	v_lshl_add_u64 v[0:1], v[0:1], 0, s[70:71]
	v_lshl_add_u64 v[0:1], v[0:1], 0, v[160:161]
	global_load_dwordx4 v[112:115], v[0:1], off
	global_load_dwordx4 v[116:119], v[0:1], off offset:32
	global_load_dwordx4 v[120:123], v[0:1], off offset:64
	global_load_dwordx4 v[124:127], v[0:1], off offset:96
	global_load_dwordx4 v[128:131], v[0:1], off offset:128
	global_load_dwordx4 v[132:135], v[0:1], off offset:160
	global_load_dwordx4 v[136:139], v[0:1], off offset:192
	global_load_dwordx4 v[140:143], v[0:1], off offset:224
	s_add_u32 s2, s13, s18
	v_add_u32_e32 v2, 0, v146
	s_addc_u32 s3, s14, 0
	v_add_u32_e32 v3, 0, v148
	v_lshl_add_u64 v[0:1], v[66:67], 3, s[2:3]
	s_mov_b64 s[2:3], -1
	s_cmp_gt_i32 s16, -1
	v_lshlrev_b32_e32 v147, 2, v76
	s_waitcnt vmcnt(0) lgkmcnt(0)
	ds_write_b128 v2, v[96:99]
	ds_write_b128 v3, v[100:103]
	ds_write2_b64 v4, v[104:105], v[106:107] offset1:1
	ds_write2_b64 v5, v[108:109], v[110:111] offset1:1
	global_load_dwordx2 v[176:177], v[0:1], off
	s_waitcnt lgkmcnt(0)
	s_barrier
	s_cbranch_scc1 .LBB0_1243
	v_lshlrev_b32_e32 v64, 2, v76
	s_mov_b64 s[2:3], 0

.LBB0_1319:
	s_add_i32 s65, s2, 2
	s_add_u32 s52, s50, 0x100
	s_addc_u32 s53, s51, 0
	s_add_i32 s87, 0, 0x10000
	v_add_u32_e32 v209, s87, v202
	ds_read_b128 v[130:133], v209
	ds_read_b128 v[134:137], v209 offset:1024
	ds_read_b128 v[138:141], v209 offset:2048
	ds_read_b128 v[142:145], v209 offset:3072
	s_cmp_eq_u32 s13, s2
	s_cselect_b32 s55, s57, s53
	s_cselect_b32 s54, s15, s52
	s_cselect_b32 s70, 0x200, s12
	s_cselect_b32 s2, vcc_lo, s58
	s_cselect_b32 s3, vcc_hi, s64
	s_add_u32 s22, s50, s18
	s_addc_u32 s23, s51, s19
	s_add_i32 s17, s60, 0xc000
	v_add_u32_e32 v158, v170, v128
	s_mov_b32 m0, s17
	s_add_i32 s86, s60, 0xe000
	ds_read_b128 v[146:149], v203
	ds_read_b128 v[150:153], v203 offset:1024
	ds_read_b128 v[154:157], v203 offset:2048
	ds_read_b128 v[174:177], v203 offset:3072
	ds_read_b128 v[178:181], v203 offset:4096
	ds_read_b128 v[182:185], v203 offset:5120
	ds_read_b128 v[212:215], v203 offset:6144
	ds_read_b128 v[216:219], v203 offset:7168
	global_load_lds_dwordx4 v158, s[22:23]
	v_add_u32_e32 v158, v172, v129
	s_mov_b32 m0, s86
	s_nop 0
	global_load_lds_dwordx4 v158, s[22:23]
	s_waitcnt lgkmcnt(8)
	s_barrier
	s_waitcnt lgkmcnt(0)
	s_setprio 1
	s_waitcnt lgkmcnt(0)
	v_mfma_f32_16x16x32_bf16 v[124:127], v[130:133], v[146:149], v[124:127]
	v_mfma_f32_16x16x32_bf16 v[120:123], v[138:141], v[146:149], v[120:123]
	v_mfma_f32_16x16x32_bf16 v[116:119], v[130:133], v[154:157], v[116:119]
	v_mfma_f32_16x16x32_bf16 v[112:115], v[138:141], v[154:157], v[112:115]
	v_mfma_f32_16x16x32_bf16 v[108:111], v[130:133], v[178:181], v[108:111]
	v_mfma_f32_16x16x32_bf16 v[104:107], v[138:141], v[178:181], v[104:107]
	v_mfma_f32_16x16x32_bf16 v[96:99], v[130:133], v[212:215], v[96:99]
	v_mfma_f32_16x16x32_bf16 v[92:95], v[138:141], v[212:215], v[92:95]
	v_mfma_f32_16x16x32_bf16 v[124:127], v[134:137], v[150:153], v[124:127]
	v_mfma_f32_16x16x32_bf16 v[120:123], v[142:145], v[150:153], v[120:123]
	v_mfma_f32_16x16x32_bf16 v[116:119], v[134:137], v[174:177], v[116:119]
	v_mfma_f32_16x16x32_bf16 v[112:115], v[142:145], v[174:177], v[112:115]
	v_mfma_f32_16x16x32_bf16 v[108:111], v[134:137], v[182:185], v[108:111]
	v_mfma_f32_16x16x32_bf16 v[104:107], v[142:145], v[182:185], v[104:107]
	v_mfma_f32_16x16x32_bf16 v[96:99], v[134:137], v[216:219], v[96:99]
	v_mfma_f32_16x16x32_bf16 v[92:95], v[142:145], v[216:219], v[92:95]
	s_setprio 0
	s_barrier
	s_add_i32 s37, 0, 0x14000
	s_add_i32 s87, s87, s59
	v_add_u32_e32 v210, s37, v202
	v_mad_u64_u32 v[158:159], s[22:23], s70, v199, v[170:171]
	s_mov_b32 m0, s87
	s_add_i32 s36, s87, 0x2000
	ds_read_b128 v[220:223], v210
	ds_read_b128 v[224:227], v210 offset:1024
	ds_read_b128 v[228:231], v210 offset:2048
	ds_read_b128 v[232:235], v210 offset:3072
	global_load_lds_dwordx4 v158, s[2:3]
	v_mad_u64_u32 v[236:237], s[22:23], s70, v200, v[172:173]
	s_mov_b32 m0, s36
	v_mov_b32_e32 v159, v161
	global_load_lds_dwordx4 v236, s[2:3]
	s_barrier
	s_waitcnt lgkmcnt(0)
	v_mov_b32_e32 v237, v161
	v_lshl_add_u64 v[238:239], s[2:3], 0, v[158:159]
	v_lshl_add_u64 v[240:241], s[2:3], 0, v[236:237]
	s_setprio 1
	s_waitcnt lgkmcnt(0)
	v_mfma_f32_16x16x32_bf16 v[44:47], v[220:223], v[146:149], v[44:47]
	v_mfma_f32_16x16x32_bf16 v[40:43], v[228:231], v[146:149], v[40:43]
	v_mfma_f32_16x16x32_bf16 v[36:39], v[220:223], v[154:157], v[36:39]
	v_mfma_f32_16x16x32_bf16 v[32:35], v[228:231], v[154:157], v[32:35]
	v_mfma_f32_16x16x32_bf16 v[100:103], v[220:223], v[178:181], v[100:103]
	v_mfma_f32_16x16x32_bf16 v[88:91], v[228:231], v[178:181], v[88:91]
	v_mfma_f32_16x16x32_bf16 v[84:87], v[220:223], v[212:215], v[84:87]
	v_mfma_f32_16x16x32_bf16 v[80:83], v[228:231], v[212:215], v[80:83]
	v_mfma_f32_16x16x32_bf16 v[44:47], v[224:227], v[150:153], v[44:47]
	v_mfma_f32_16x16x32_bf16 v[40:43], v[232:235], v[150:153], v[40:43]
	v_mfma_f32_16x16x32_bf16 v[36:39], v[224:227], v[174:177], v[36:39]
	v_mfma_f32_16x16x32_bf16 v[32:35], v[232:235], v[174:177], v[32:35]
	v_mfma_f32_16x16x32_bf16 v[100:103], v[224:227], v[182:185], v[100:103]
	v_mfma_f32_16x16x32_bf16 v[88:91], v[232:235], v[182:185], v[88:91]
	v_mfma_f32_16x16x32_bf16 v[84:87], v[224:227], v[216:219], v[84:87]
	v_mfma_f32_16x16x32_bf16 v[80:83], v[232:235], v[216:219], v[80:83]
	s_setprio 0
	s_mov_b32 m0, s60
	v_mad_u64_u32 v[242:243], s[22:23], s70, v171, v[170:171]
	s_barrier
	ds_read_b128 v[146:149], v203 offset:16384
	ds_read_b128 v[150:153], v203 offset:17408
	ds_read_b128 v[154:157], v203 offset:18432
	ds_read_b128 v[174:177], v203 offset:19456
	ds_read_b128 v[178:181], v203 offset:20480
	ds_read_b128 v[182:185], v203 offset:21504
	ds_read_b128 v[212:215], v203 offset:22528
	ds_read_b128 v[216:219], v203 offset:23552
	global_load_lds_dwordx4 v242, s[54:55]
	v_mad_u64_u32 v[244:245], s[22:23], s70, v173, v[172:173]
	s_mov_b32 m0, s61
	v_mov_b32_e32 v243, v161
	global_load_lds_dwordx4 v244, s[54:55]
	s_barrier
	s_waitcnt lgkmcnt(0)
	v_mov_b32_e32 v245, v161
	v_lshl_add_u64 v[246:247], s[54:55], 0, v[242:243]
	v_lshl_add_u64 v[248:249], s[54:55], 0, v[244:245]
	s_setprio 1
	s_waitcnt lgkmcnt(0)
	v_mfma_f32_16x16x32_bf16 v[76:79], v[130:133], v[146:149], v[76:79]
	s_lshl_b64 s[22:23], s[70:71], 8
	v_mfma_f32_16x16x32_bf16 v[72:75], v[138:141], v[146:149], v[72:75]
	v_mfma_f32_16x16x32_bf16 v[64:67], v[130:133], v[154:157], v[64:67]
	v_mfma_f32_16x16x32_bf16 v[60:63], v[138:141], v[154:157], v[60:63]
	v_mfma_f32_16x16x32_bf16 v[28:31], v[130:133], v[178:181], v[28:31]
	v_mfma_f32_16x16x32_bf16 v[24:27], v[138:141], v[178:181], v[24:27]
	v_mfma_f32_16x16x32_bf16 v[12:15], v[130:133], v[212:215], v[12:15]
	v_mfma_f32_16x16x32_bf16 v[8:11], v[138:141], v[212:215], v[8:11]
	v_mfma_f32_16x16x32_bf16 v[76:79], v[134:137], v[150:153], v[76:79]
	v_mfma_f32_16x16x32_bf16 v[72:75], v[142:145], v[150:153], v[72:75]
	v_mfma_f32_16x16x32_bf16 v[64:67], v[134:137], v[174:177], v[64:67]
	v_mfma_f32_16x16x32_bf16 v[60:63], v[142:145], v[174:177], v[60:63]
	v_mfma_f32_16x16x32_bf16 v[28:31], v[134:137], v[182:185], v[28:31]
	v_mfma_f32_16x16x32_bf16 v[24:27], v[142:145], v[182:185], v[24:27]
	v_mfma_f32_16x16x32_bf16 v[12:15], v[134:137], v[216:219], v[12:15]
	v_mfma_f32_16x16x32_bf16 v[8:11], v[142:145], v[216:219], v[8:11]
	s_setprio 0
	s_barrier
	s_add_u32 s2, s2, s22
	s_addc_u32 s3, s3, s23
	s_add_i32 s37, s37, s59
	s_mov_b32 m0, s37
	s_add_i32 s70, s37, 0x2000
	global_load_lds_dwordx4 v158, s[2:3]
	s_mov_b32 m0, s70
	v_lshl_add_u64 v[158:159], s[2:3], 0, v[158:159]
	global_load_lds_dwordx4 v236, s[2:3]
	s_waitcnt vmcnt(6)
	v_lshl_add_u64 v[250:251], s[2:3], 0, v[236:237]
	s_barrier
	s_setprio 1
	v_mfma_f32_16x16x32_bf16 v[68:71], v[220:223], v[146:149], v[68:71]
	v_mfma_f32_16x16x32_bf16 v[56:59], v[228:231], v[146:149], v[56:59]
	v_mfma_f32_16x16x32_bf16 v[52:55], v[220:223], v[154:157], v[52:55]
	v_mfma_f32_16x16x32_bf16 v[48:51], v[228:231], v[154:157], v[48:51]
	v_mfma_f32_16x16x32_bf16 v[20:23], v[220:223], v[178:181], v[20:23]
	v_mfma_f32_16x16x32_bf16 v[16:19], v[228:231], v[178:181], v[16:19]
	v_mfma_f32_16x16x32_bf16 v[4:7], v[220:223], v[212:215], v[4:7]
	v_mfma_f32_16x16x32_bf16 v[0:3], v[228:231], v[212:215], v[0:3]
	v_mfma_f32_16x16x32_bf16 v[68:71], v[224:227], v[150:153], v[68:71]
	v_mfma_f32_16x16x32_bf16 v[56:59], v[232:235], v[150:153], v[56:59]
	v_mfma_f32_16x16x32_bf16 v[52:55], v[224:227], v[174:177], v[52:55]
	v_mfma_f32_16x16x32_bf16 v[48:51], v[232:235], v[174:177], v[48:51]
	v_mfma_f32_16x16x32_bf16 v[20:23], v[224:227], v[182:185], v[20:23]
	v_mfma_f32_16x16x32_bf16 v[16:19], v[232:235], v[182:185], v[16:19]
	v_mfma_f32_16x16x32_bf16 v[4:7], v[224:227], v[216:219], v[4:7]
	v_mfma_f32_16x16x32_bf16 v[0:3], v[232:235], v[216:219], v[0:3]
	s_setprio 0
	s_add_i32 s50, 0, 0x18000
	v_add_u32_e32 v211, s50, v202
	s_barrier
	ds_read_b128 v[130:133], v211
	ds_read_b128 v[134:137], v211 offset:1024
	ds_read_b128 v[138:141], v211 offset:2048
	ds_read_b128 v[142:145], v211 offset:3072
	s_add_u32 s2, s54, s22
	s_addc_u32 s3, s55, s23
	s_mov_b32 m0, s62
	ds_read_b128 v[146:149], v203 offset:32768
	ds_read_b128 v[150:153], v203 offset:33792
	ds_read_b128 v[154:157], v203 offset:34816
	ds_read_b128 v[174:177], v203 offset:35840
	ds_read_b128 v[178:181], v203 offset:36864
	ds_read_b128 v[182:185], v203 offset:37888
	ds_read_b128 v[214:217], v203 offset:38912
	ds_read_b128 v[218:221], v203 offset:39936
	global_load_lds_dwordx4 v242, s[2:3]
	s_mov_b32 m0, s63
	s_nop 0
	global_load_lds_dwordx4 v244, s[2:3]
	s_waitcnt lgkmcnt(8)
	s_barrier
	s_waitcnt lgkmcnt(0)
	s_setprio 1
	s_waitcnt lgkmcnt(0)
	v_mfma_f32_16x16x32_bf16 v[124:127], v[130:133], v[146:149], v[124:127]
	v_mfma_f32_16x16x32_bf16 v[120:123], v[138:141], v[146:149], v[120:123]
	v_mfma_f32_16x16x32_bf16 v[116:119], v[130:133], v[154:157], v[116:119]
	v_mfma_f32_16x16x32_bf16 v[112:115], v[138:141], v[154:157], v[112:115]
	v_mfma_f32_16x16x32_bf16 v[108:111], v[130:133], v[178:181], v[108:111]
	v_mfma_f32_16x16x32_bf16 v[104:107], v[138:141], v[178:181], v[104:107]
	v_mfma_f32_16x16x32_bf16 v[96:99], v[130:133], v[214:217], v[96:99]
	v_mfma_f32_16x16x32_bf16 v[92:95], v[138:141], v[214:217], v[92:95]
	v_mfma_f32_16x16x32_bf16 v[124:127], v[134:137], v[150:153], v[124:127]
	v_mfma_f32_16x16x32_bf16 v[120:123], v[142:145], v[150:153], v[120:123]
	v_mfma_f32_16x16x32_bf16 v[116:119], v[134:137], v[174:177], v[116:119]
	v_mfma_f32_16x16x32_bf16 v[112:115], v[142:145], v[174:177], v[112:115]
	v_mfma_f32_16x16x32_bf16 v[108:111], v[134:137], v[182:185], v[108:111]
	v_mfma_f32_16x16x32_bf16 v[104:107], v[142:145], v[182:185], v[104:107]
	v_mfma_f32_16x16x32_bf16 v[96:99], v[134:137], v[218:221], v[96:99]
	v_mfma_f32_16x16x32_bf16 v[92:95], v[142:145], v[218:221], v[92:95]
	s_setprio 0
	s_barrier
	s_add_i32 s22, 0, 0x1c000
	s_add_i32 s54, s50, s59
	v_add_u32_e32 v212, s22, v202
	v_lshl_add_u64 v[238:239], v[238:239], 0, s[78:79]
	s_mov_b32 m0, s54
	s_add_i32 s55, s54, 0x2000
	ds_read_b128 v[222:225], v212
	ds_read_b128 v[226:229], v212 offset:1024
	ds_read_b128 v[230:233], v212 offset:2048
	ds_read_b128 v[234:237], v212 offset:3072
	global_load_lds_dwordx4 v[238:239], off
	v_lshl_add_u64 v[238:239], v[240:241], 0, s[78:79]
	s_mov_b32 m0, s55
	s_nop 0
	global_load_lds_dwordx4 v[238:239], off
	s_barrier
	s_waitcnt lgkmcnt(0)
	s_setprio 1
	s_waitcnt lgkmcnt(0)
	v_mfma_f32_16x16x32_bf16 v[44:47], v[222:225], v[146:149], v[44:47]
	v_mfma_f32_16x16x32_bf16 v[40:43], v[230:233], v[146:149], v[40:43]
	v_mfma_f32_16x16x32_bf16 v[36:39], v[222:225], v[154:157], v[36:39]
	v_mfma_f32_16x16x32_bf16 v[32:35], v[230:233], v[154:157], v[32:35]
	v_mfma_f32_16x16x32_bf16 v[100:103], v[222:225], v[178:181], v[100:103]
	v_mfma_f32_16x16x32_bf16 v[88:91], v[230:233], v[178:181], v[88:91]
	v_mfma_f32_16x16x32_bf16 v[84:87], v[222:225], v[214:217], v[84:87]
	v_mfma_f32_16x16x32_bf16 v[80:83], v[230:233], v[214:217], v[80:83]
	v_mfma_f32_16x16x32_bf16 v[44:47], v[226:229], v[150:153], v[44:47]
	v_mfma_f32_16x16x32_bf16 v[40:43], v[234:237], v[150:153], v[40:43]
	v_mfma_f32_16x16x32_bf16 v[36:39], v[226:229], v[174:177], v[36:39]
	v_mfma_f32_16x16x32_bf16 v[32:35], v[234:237], v[174:177], v[32:35]
	v_mfma_f32_16x16x32_bf16 v[100:103], v[226:229], v[182:185], v[100:103]
	v_mfma_f32_16x16x32_bf16 v[88:91], v[234:237], v[182:185], v[88:91]
	v_mfma_f32_16x16x32_bf16 v[84:87], v[226:229], v[218:221], v[84:87]
	v_mfma_f32_16x16x32_bf16 v[80:83], v[234:237], v[218:221], v[80:83]
	s_setprio 0
	s_mov_b32 m0, s74
	v_lshl_add_u64 v[238:239], v[246:247], 0, s[78:79]
	s_barrier
	ds_read_b128 v[146:149], v203 offset:49152
	ds_read_b128 v[150:153], v203 offset:50176
	ds_read_b128 v[154:157], v203 offset:51200
	ds_read_b128 v[174:177], v203 offset:52224
	ds_read_b128 v[178:181], v203 offset:53248
	ds_read_b128 v[182:185], v203 offset:54272
	ds_read_b128 v[214:217], v203 offset:55296
	ds_read_b128 v[218:221], v203 offset:56320
	global_load_lds_dwordx4 v[238:239], off
	v_lshl_add_u64 v[238:239], v[248:249], 0, s[78:79]
	s_mov_b32 m0, s75
	s_nop 0
	global_load_lds_dwordx4 v[238:239], off
	s_barrier
;     DI void mid(AccT& acc, const Unit& u, int seg, int wr, int wc, int fr, int fq) const {
;         const int row0 = u.pm * BM + wr * 64 + fr, col0 = u.pn * BM + wc * 32 + 8 * fq;
;         const unsigned char* pa = (const unsigned char*)G + (size_t)row0 * NGATE + seg * 2048 + col0;
; #pragma unroll
;         for (int ai = 0; ai < 2; ++ai) {
; #pragma unroll
;             for (int mh = 0; mh < 2; ++mh) {
;                 u32x2 ra[2][2], rb[2][2];
; #pragma unroll
;                 for (int mm = 0; mm < 2; ++mm)
; #pragma unroll
;                     for (int bj = 0; bj < 2; ++bj) { const unsigned char* p = pa + (size_t)(mm * 16) * NGATE + bj * HALF; ra[mm][bj] = *(const u32x2*)p; rb[mm][bj] = *(const u32x2*)(p + 2048); }
; #pragma unroll
;                 for (int mm = 0; mm < 2; ++mm)
; #pragma unroll
;                     for (int bj = 0; bj < 2; ++bj) {
;                         float ga[8], gb[8];
;                         unpack_gate8(ra[mm][bj], ga); unpack_gate8(rb[mm][bj], gb);
;                         const int m = 2 * mh + mm;
; #pragma unroll
;                         for (int j = 0; j < 4; ++j) { const float r0 = ga[j] * __builtin_amdgcn_rcpf(gb[j]), r1 = ga[4 + j] * __builtin_amdgcn_rcpf(gb[4 + j]);
;                             acc[ai][bj][m][0][j] *= r0; acc[ai][bj][m][1][j] *= r1; } }
	s_waitcnt lgkmcnt(0)
	s_setprio 1
	s_waitcnt lgkmcnt(0)
	v_mfma_f32_16x16x32_bf16 v[76:79], v[130:133], v[146:149], v[76:79]
	v_mfma_f32_16x16x32_bf16 v[72:75], v[138:141], v[146:149], v[72:75]
	v_mfma_f32_16x16x32_bf16 v[64:67], v[130:133], v[154:157], v[64:67]
	v_mfma_f32_16x16x32_bf16 v[60:63], v[138:141], v[154:157], v[60:63]
	v_mfma_f32_16x16x32_bf16 v[28:31], v[130:133], v[178:181], v[28:31]
	v_mfma_f32_16x16x32_bf16 v[24:27], v[138:141], v[178:181], v[24:27]
	v_mfma_f32_16x16x32_bf16 v[12:15], v[130:133], v[214:217], v[12:15]
	v_mfma_f32_16x16x32_bf16 v[8:11], v[138:141], v[214:217], v[8:11]
	v_mfma_f32_16x16x32_bf16 v[76:79], v[134:137], v[150:153], v[76:79]
	v_mfma_f32_16x16x32_bf16 v[72:75], v[142:145], v[150:153], v[72:75]
	v_mfma_f32_16x16x32_bf16 v[64:67], v[134:137], v[174:177], v[64:67]
	v_mfma_f32_16x16x32_bf16 v[60:63], v[142:145], v[174:177], v[60:63]
	v_mfma_f32_16x16x32_bf16 v[28:31], v[134:137], v[182:185], v[28:31]
	v_mfma_f32_16x16x32_bf16 v[24:27], v[142:145], v[182:185], v[24:27]
	v_mfma_f32_16x16x32_bf16 v[12:15], v[134:137], v[218:221], v[12:15]
	v_mfma_f32_16x16x32_bf16 v[8:11], v[142:145], v[218:221], v[8:11]
	s_setprio 0
	s_barrier
	s_add_i32 s22, s22, s59
	v_lshl_add_u64 v[130:131], v[158:159], 0, s[78:79]
	s_mov_b32 m0, s22
	s_add_i32 s23, s22, 0x2000
	global_load_lds_dwordx4 v[130:131], off
	v_lshl_add_u64 v[130:131], v[250:251], 0, s[78:79]
	s_mov_b32 m0, s23
	s_nop 0
	global_load_lds_dwordx4 v[130:131], off
	s_waitcnt vmcnt(6)
	s_barrier
	s_setprio 1
	v_mfma_f32_16x16x32_bf16 v[68:71], v[222:225], v[146:149], v[68:71]
	v_mfma_f32_16x16x32_bf16 v[56:59], v[230:233], v[146:149], v[56:59]
	v_mfma_f32_16x16x32_bf16 v[52:55], v[222:225], v[154:157], v[52:55]
	v_mfma_f32_16x16x32_bf16 v[48:51], v[230:233], v[154:157], v[48:51]
	v_mfma_f32_16x16x32_bf16 v[20:23], v[222:225], v[178:181], v[20:23]
	v_mfma_f32_16x16x32_bf16 v[16:19], v[230:233], v[178:181], v[16:19]
	v_mfma_f32_16x16x32_bf16 v[4:7], v[222:225], v[214:217], v[4:7]
	v_mfma_f32_16x16x32_bf16 v[0:3], v[230:233], v[214:217], v[0:3]
	v_mfma_f32_16x16x32_bf16 v[68:71], v[226:229], v[150:153], v[68:71]
	v_mfma_f32_16x16x32_bf16 v[56:59], v[234:237], v[150:153], v[56:59]
	v_mfma_f32_16x16x32_bf16 v[52:55], v[226:229], v[174:177], v[52:55]
	v_mfma_f32_16x16x32_bf16 v[48:51], v[234:237], v[174:177], v[48:51]
	v_mfma_f32_16x16x32_bf16 v[20:23], v[226:229], v[182:185], v[20:23]
	v_mfma_f32_16x16x32_bf16 v[16:19], v[234:237], v[182:185], v[16:19]
	v_mfma_f32_16x16x32_bf16 v[4:7], v[226:229], v[218:221], v[4:7]
	v_mfma_f32_16x16x32_bf16 v[0:3], v[234:237], v[218:221], v[0:3]
	s_setprio 0
	s_add_u32 s58, s58, 0x100
	s_addc_u32 s64, s64, 0
	s_cmp_ge_u32 s65, s5
	s_mov_b64 s[50:51], s[52:53]
	s_mov_b32 s2, s65
	s_barrier
	s_cbranch_scc0 .LBB0_1319
	v_lshl_add_u32 v178, s14, 8, v201
	v_lshl_or_b32 v176, s16, 8, v208
	v_mov_b64_e32 v[128:129], s[44:45]
	s_movk_i32 s2, 0x1800
	v_mad_i64_i32 v[128:129], s[2:3], v178, s2, v[128:129]
	v_ashrrev_i32_e32 v177, 31, v176
	v_lshl_add_u64 v[174:175], v[128:129], 0, v[176:177]
	global_load_dwordx2 v[128:129], v[174:175], off
	global_load_dwordx2 v[130:131], v[174:175], off offset:2048
	global_load_dwordx2 v[132:133], v[174:175], off offset:128
	global_load_dwordx2 v[134:135], v[174:175], off offset:2176
	v_add_co_u32_e32 v136, vcc, 0x18000, v174
	v_lshl_add_u64 v[182:183], v[174:175], 0, s[24:25]
	s_nop 0
	v_addc_co_u32_e32 v137, vcc, 0, v175, vcc
	global_load_dwordx2 v[144:145], v[136:137], off
	global_load_dwordx2 v[146:147], v[136:137], off offset:2048
	global_load_dwordx2 v[148:149], v[136:137], off offset:128
	global_load_dwordx2 v[150:151], v[136:137], off offset:2176
	s_mov_b64 s[2:3], 0x800
	v_lshl_add_u64 v[180:181], v[174:175], 0, s[2:3]
	s_add_u32 s2, s29, s48
	s_addc_u32 s3, s76, s49
	s_add_u32 s16, s30, s10
	v_ashrrev_i32_e32 v179, 31, v178
	s_addc_u32 s18, s31, s11
	s_mov_b32 s5, -2
	s_mov_b64 s[10:11], 0
	s_waitcnt vmcnt(0) lgkmcnt(0)
	v_cvt_f32_ubyte2_e32 v138, v130
	v_cvt_f32_ubyte3_e32 v139, v130
	v_cvt_f32_ubyte0_e32 v136, v130
	v_cvt_f32_ubyte1_e32 v137, v130
	v_rcp_iflag_f32_e32 v138, v138
	v_rcp_iflag_f32_e32 v139, v139
	v_cvt_f32_ubyte0_e32 v140, v131
	v_cvt_f32_ubyte1_e32 v141, v131
	v_cvt_f32_ubyte2_e32 v142, v131
	v_cvt_f32_ubyte3_e32 v143, v131
	v_rcp_iflag_f32_e32 v130, v136
	v_rcp_iflag_f32_e32 v131, v137
	v_rcp_iflag_f32_e32 v136, v140
	v_rcp_iflag_f32_e32 v137, v141
	v_rcp_iflag_f32_e32 v152, v142
	v_rcp_iflag_f32_e32 v153, v143
	v_cvt_f32_ubyte3_e32 v141, v128
	v_cvt_f32_ubyte2_e32 v140, v128
	v_cvt_f32_ubyte1_e32 v143, v128
	v_cvt_f32_ubyte0_e32 v142, v128
	v_pk_mul_f32 v[138:139], v[138:139], v[140:141]
	v_pk_mul_f32 v[130:131], v[130:131], v[142:143]
	v_pk_mul_f32 v[142:143], v[126:127], v[138:139]
	v_cvt_f32_ubyte1_e32 v127, v129
	v_cvt_f32_ubyte0_e32 v126, v129
	v_pk_mul_f32 v[140:141], v[124:125], v[130:131]
	v_cvt_f32_ubyte3_e32 v125, v129
	v_cvt_f32_ubyte2_e32 v124, v129
	v_pk_mul_f32 v[126:127], v[136:137], v[126:127]
	v_pk_mul_f32 v[124:125], v[152:153], v[124:125]
	v_pk_mul_f32 v[136:137], v[120:121], v[126:127]
	v_cvt_f32_ubyte0_e32 v120, v134
	v_cvt_f32_ubyte1_e32 v121, v134
	v_pk_mul_f32 v[138:139], v[122:123], v[124:125]
	v_cvt_f32_ubyte2_e32 v124, v134
	v_cvt_f32_ubyte3_e32 v125, v134
	v_rcp_iflag_f32_e32 v120, v120
	v_rcp_iflag_f32_e32 v121, v121
	v_cvt_f32_ubyte2_e32 v126, v135
	v_cvt_f32_ubyte3_e32 v127, v135
	v_rcp_iflag_f32_e32 v124, v124
	v_rcp_iflag_f32_e32 v125, v125
	v_cvt_f32_ubyte0_e32 v122, v135
	v_cvt_f32_ubyte1_e32 v123, v135
	v_rcp_iflag_f32_e32 v126, v126
	v_rcp_iflag_f32_e32 v127, v127
	v_rcp_iflag_f32_e32 v122, v122
	v_rcp_iflag_f32_e32 v123, v123
;     DI void mid(AccT& acc, const Unit& u, int seg, int wr, int wc, int fr, int fq) const {
;         const int row0 = u.pm * BM + wr * 64 + fr, col0 = u.pn * BM + wc * 32 + 8 * fq;
;         const unsigned char* pa = (const unsigned char*)G + (size_t)row0 * NGATE + seg * 2048 + col0;
; #pragma unroll
;         for (int ai = 0; ai < 2; ++ai) {
; #pragma unroll
;             for (int mh = 0; mh < 2; ++mh) {
;                 u32x2 ra[2][2], rb[2][2];
; #pragma unroll
;                 for (int mm = 0; mm < 2; ++mm)
; #pragma unroll
;                     for (int bj = 0; bj < 2; ++bj) { const unsigned char* p = pa + (size_t)(mm * 16) * NGATE + bj * HALF; ra[mm][bj] = *(const u32x2*)p; rb[mm][bj] = *(const u32x2*)(p + 2048); }
; #pragma unroll
;                 for (int mm = 0; mm < 2; ++mm)
; #pragma unroll
;                     for (int bj = 0; bj < 2; ++bj) {
;                         float ga[8], gb[8];
;                         unpack_gate8(ra[mm][bj], ga); unpack_gate8(rb[mm][bj], gb);
;                         const int m = 2 * mh + mm;
; #pragma unroll
;                         for (int j = 0; j < 4; ++j) { const float r0 = ga[j] * __builtin_amdgcn_rcpf(gb[j]), r1 = ga[4 + j] * __builtin_amdgcn_rcpf(gb[4 + j]);
;                             acc[ai][bj][m][0][j] *= r0; acc[ai][bj][m][1][j] *= r1; } }
;                 pa += (size_t)(mh == 1 ? 96 : 32) * NGATE;
;                 asm volatile("" : "+v"(pa));
;             } }
	v_cvt_f32_ubyte1_e32 v131, v132
	v_cvt_f32_ubyte0_e32 v130, v132
	v_cvt_f32_ubyte3_e32 v129, v132
	v_cvt_f32_ubyte2_e32 v128, v132
	v_pk_mul_f32 v[120:121], v[120:121], v[130:131]
	v_pk_mul_f32 v[124:125], v[124:125], v[128:129]
	v_pk_mul_f32 v[44:45], v[44:45], v[120:121]
	v_cvt_f32_ubyte3_e32 v121, v133
	v_cvt_f32_ubyte2_e32 v120, v133
	v_pk_mul_f32 v[46:47], v[46:47], v[124:125]
	v_cvt_f32_ubyte1_e32 v125, v133
	v_cvt_f32_ubyte0_e32 v124, v133
	v_pk_mul_f32 v[120:121], v[126:127], v[120:121]
	v_pk_mul_f32 v[122:123], v[122:123], v[124:125]
	v_pk_mul_f32 v[42:43], v[42:43], v[120:121]
	v_cvt_f32_ubyte0_e32 v120, v146
	v_cvt_f32_ubyte1_e32 v121, v146
	v_cvt_f32_ubyte2_e32 v124, v146
	v_cvt_f32_ubyte3_e32 v125, v146
	v_rcp_iflag_f32_e32 v120, v120
	v_rcp_iflag_f32_e32 v121, v121
	v_rcp_iflag_f32_e32 v124, v124
	v_rcp_iflag_f32_e32 v125, v125
	v_pk_mul_f32 v[40:41], v[40:41], v[122:123]
	v_cvt_f32_ubyte0_e32 v122, v147
	v_cvt_f32_ubyte1_e32 v123, v147
	v_cvt_f32_ubyte2_e32 v126, v147
	v_cvt_f32_ubyte3_e32 v127, v147
	v_rcp_iflag_f32_e32 v122, v122
	v_rcp_iflag_f32_e32 v123, v123
	v_rcp_iflag_f32_e32 v126, v126
	v_rcp_iflag_f32_e32 v127, v127
	v_cvt_f32_ubyte3_e32 v129, v144
	v_cvt_f32_ubyte2_e32 v128, v144
	v_cvt_f32_ubyte1_e32 v131, v144
	v_cvt_f32_ubyte0_e32 v130, v144
	v_pk_mul_f32 v[120:121], v[120:121], v[130:131]
	v_pk_mul_f32 v[124:125], v[124:125], v[128:129]
	v_pk_mul_f32 v[132:133], v[116:117], v[120:121]
	v_pk_mul_f32 v[134:135], v[118:119], v[124:125]
	v_cvt_f32_ubyte3_e32 v117, v145
	v_cvt_f32_ubyte2_e32 v116, v145
	v_cvt_f32_ubyte1_e32 v119, v145
	v_cvt_f32_ubyte0_e32 v118, v145
	v_pk_mul_f32 v[118:119], v[122:123], v[118:119]
	v_pk_mul_f32 v[116:117], v[126:127], v[116:117]
	v_pk_mul_f32 v[128:129], v[112:113], v[118:119]
	v_pk_mul_f32 v[130:131], v[114:115], v[116:117]
	v_cvt_f32_ubyte0_e32 v112, v150
	v_cvt_f32_ubyte1_e32 v113, v150
	v_cvt_f32_ubyte2_e32 v116, v150
	v_cvt_f32_ubyte3_e32 v117, v150
	v_rcp_iflag_f32_e32 v112, v112
	v_rcp_iflag_f32_e32 v113, v113
	v_rcp_iflag_f32_e32 v116, v116
	v_rcp_iflag_f32_e32 v117, v117
	v_cvt_f32_ubyte0_e32 v114, v151
	v_cvt_f32_ubyte1_e32 v115, v151
	v_cvt_f32_ubyte2_e32 v118, v151
	v_cvt_f32_ubyte3_e32 v119, v151
	v_rcp_iflag_f32_e32 v114, v114
	v_rcp_iflag_f32_e32 v115, v115
	v_rcp_iflag_f32_e32 v118, v118
	v_rcp_iflag_f32_e32 v119, v119
	v_cvt_f32_ubyte3_e32 v121, v148
	v_cvt_f32_ubyte2_e32 v120, v148
	v_cvt_f32_ubyte1_e32 v123, v148
	v_cvt_f32_ubyte0_e32 v122, v148
	v_pk_mul_f32 v[112:113], v[112:113], v[122:123]
	v_pk_mul_f32 v[116:117], v[116:117], v[120:121]
	v_pk_mul_f32 v[36:37], v[36:37], v[112:113]
	v_pk_mul_f32 v[38:39], v[38:39], v[116:117]
	v_cvt_f32_ubyte3_e32 v113, v149
	v_cvt_f32_ubyte2_e32 v112, v149
	v_cvt_f32_ubyte1_e32 v117, v149
	v_cvt_f32_ubyte0_e32 v116, v149
	v_pk_mul_f32 v[114:115], v[114:115], v[116:117]
	v_pk_mul_f32 v[112:113], v[118:119], v[112:113]
	v_pk_mul_f32 v[32:33], v[32:33], v[114:115]
	v_pk_mul_f32 v[34:35], v[34:35], v[112:113]
	global_load_dwordx2 v[114:115], v[182:183], off
	global_load_dwordx2 v[116:117], v[182:183], off offset:2048
	global_load_dwordx2 v[112:113], v[182:183], off offset:128
	global_load_dwordx2 v[118:119], v[182:183], off offset:2176
	v_add_co_u32_e32 v120, vcc, s21, v182
	s_waitcnt vmcnt(0) lgkmcnt(0)
	v_cvt_f32_ubyte1_e32 v149, v114
	v_addc_co_u32_e32 v121, vcc, 0, v183, vcc
	global_load_dwordx2 v[144:145], v[120:121], off
	global_load_dwordx2 v[146:147], v[120:121], off offset:2048
	global_load_dwordx2 v[184:185], v[120:121], off offset:128
	global_load_dwordx2 v[214:215], v[120:121], off offset:2176
	v_cvt_f32_ubyte0_e32 v120, v116
	v_cvt_f32_ubyte1_e32 v121, v116
	v_cvt_f32_ubyte2_e32 v122, v116
	v_cvt_f32_ubyte3_e32 v123, v116
	v_cvt_f32_ubyte0_e32 v124, v117
	v_cvt_f32_ubyte1_e32 v125, v117
	v_cvt_f32_ubyte2_e32 v126, v117
	v_cvt_f32_ubyte3_e32 v127, v117
	v_rcp_iflag_f32_e32 v116, v120
	v_rcp_iflag_f32_e32 v117, v121
	v_rcp_iflag_f32_e32 v120, v124
	v_rcp_iflag_f32_e32 v121, v125
	v_rcp_iflag_f32_e32 v122, v122
	v_rcp_iflag_f32_e32 v124, v126
	v_rcp_iflag_f32_e32 v123, v123
	v_rcp_iflag_f32_e32 v125, v127
	v_cvt_f32_ubyte0_e32 v148, v114
	v_pk_mul_f32 v[116:117], v[116:117], v[148:149]
	v_cvt_f32_ubyte3_e32 v127, v114
	v_cvt_f32_ubyte2_e32 v126, v114
	v_pk_mul_f32 v[156:157], v[108:109], v[116:117]
	v_cvt_f32_ubyte3_e32 v109, v115
	v_cvt_f32_ubyte2_e32 v108, v115
	v_pk_mul_f32 v[122:123], v[122:123], v[126:127]
	v_pk_mul_f32 v[108:109], v[124:125], v[108:109]
	v_pk_mul_f32 v[158:159], v[110:111], v[122:123]
	v_cvt_f32_ubyte1_e32 v111, v115
	v_cvt_f32_ubyte0_e32 v110, v115
	v_pk_mul_f32 v[154:155], v[106:107], v[108:109]
	v_cvt_f32_ubyte2_e32 v108, v118
	v_cvt_f32_ubyte3_e32 v109, v118
	v_pk_mul_f32 v[110:111], v[120:121], v[110:111]
	v_rcp_iflag_f32_e32 v108, v108
	v_rcp_iflag_f32_e32 v109, v109
	v_pk_mul_f32 v[152:153], v[104:105], v[110:111]
	v_cvt_f32_ubyte0_e32 v104, v118
	v_cvt_f32_ubyte1_e32 v105, v118
	v_cvt_f32_ubyte0_e32 v106, v119
	v_cvt_f32_ubyte1_e32 v107, v119
	v_rcp_iflag_f32_e32 v104, v104
	v_rcp_iflag_f32_e32 v106, v106
	v_rcp_iflag_f32_e32 v105, v105
	v_rcp_iflag_f32_e32 v107, v107
	v_cvt_f32_ubyte2_e32 v110, v119
	v_cvt_f32_ubyte3_e32 v111, v119
	v_cvt_f32_ubyte3_e32 v115, v112
	v_cvt_f32_ubyte2_e32 v114, v112
	v_rcp_iflag_f32_e32 v110, v110
	v_rcp_iflag_f32_e32 v111, v111
	v_pk_mul_f32 v[108:109], v[108:109], v[114:115]
	v_cvt_f32_ubyte1_e32 v117, v112
	v_cvt_f32_ubyte0_e32 v116, v112
	v_pk_mul_f32 v[126:127], v[102:103], v[108:109]
	v_cvt_f32_ubyte1_e32 v103, v113
	v_cvt_f32_ubyte0_e32 v102, v113
	v_pk_mul_f32 v[104:105], v[104:105], v[116:117]
	v_pk_mul_f32 v[102:103], v[106:107], v[102:103]
	v_pk_mul_f32 v[124:125], v[100:101], v[104:105]
	v_cvt_f32_ubyte3_e32 v101, v113
	v_cvt_f32_ubyte2_e32 v100, v113
	v_pk_mul_f32 v[120:121], v[88:89], v[102:103]
	v_pk_mul_f32 v[100:101], v[110:111], v[100:101]
	s_waitcnt vmcnt(0) lgkmcnt(0)
;     DI void mid(AccT& acc, const Unit& u, int seg, int wr, int wc, int fr, int fq) const {
;         const int row0 = u.pm * BM + wr * 64 + fr, col0 = u.pn * BM + wc * 32 + 8 * fq;
;         const unsigned char* pa = (const unsigned char*)G + (size_t)row0 * NGATE + seg * 2048 + col0;
; #pragma unroll
;         for (int ai = 0; ai < 2; ++ai) {
; #pragma unroll
;             for (int mh = 0; mh < 2; ++mh) {
;                 u32x2 ra[2][2], rb[2][2];
; #pragma unroll
;                 for (int mm = 0; mm < 2; ++mm)
; #pragma unroll
;                     for (int bj = 0; bj < 2; ++bj) { const unsigned char* p = pa + (size_t)(mm * 16) * NGATE + bj * HALF; ra[mm][bj] = *(const u32x2*)p; rb[mm][bj] = *(const u32x2*)(p + 2048); }
; #pragma unroll
;                 for (int mm = 0; mm < 2; ++mm)
; #pragma unroll
;                     for (int bj = 0; bj < 2; ++bj) {
;                         float ga[8], gb[8];
;                         unpack_gate8(ra[mm][bj], ga); unpack_gate8(rb[mm][bj], gb);
;                         const int m = 2 * mh + mm;
; #pragma unroll
;                         for (int j = 0; j < 4; ++j) { const float r0 = ga[j] * __builtin_amdgcn_rcpf(gb[j]), r1 = ga[4 + j] * __builtin_amdgcn_rcpf(gb[4 + j]);
;                             acc[ai][bj][m][0][j] *= r0; acc[ai][bj][m][1][j] *= r1; } }
;                 pa += (size_t)(mh == 1 ? 96 : 32) * NGATE;
;                 asm volatile("" : "+v"(pa));
;             } }
	v_cvt_f32_ubyte1_e32 v107, v144
	v_cvt_f32_ubyte0_e32 v88, v146
	v_cvt_f32_ubyte1_e32 v89, v146
	v_rcp_iflag_f32_e32 v88, v88
	v_rcp_iflag_f32_e32 v89, v89
	v_pk_mul_f32 v[122:123], v[90:91], v[100:101]
	v_cvt_f32_ubyte0_e32 v90, v147
	v_cvt_f32_ubyte1_e32 v91, v147
	v_rcp_iflag_f32_e32 v90, v90
	v_rcp_iflag_f32_e32 v91, v91
	v_cvt_f32_ubyte2_e32 v102, v147
	v_cvt_f32_ubyte3_e32 v103, v147
	v_cvt_f32_ubyte0_e32 v106, v144
	v_rcp_iflag_f32_e32 v102, v102
	v_rcp_iflag_f32_e32 v103, v103
	v_pk_mul_f32 v[88:89], v[88:89], v[106:107]
	v_cvt_f32_ubyte2_e32 v100, v146
	v_pk_mul_f32 v[148:149], v[96:97], v[88:89]
	v_cvt_f32_ubyte1_e32 v97, v145
	v_cvt_f32_ubyte0_e32 v96, v145
	v_pk_mul_f32 v[90:91], v[90:91], v[96:97]
	v_cvt_f32_ubyte3_e32 v101, v146
	v_cvt_f32_ubyte3_e32 v105, v144
	v_cvt_f32_ubyte2_e32 v104, v144
	v_cvt_f32_ubyte3_e32 v89, v145
	v_cvt_f32_ubyte2_e32 v88, v145
	v_pk_mul_f32 v[144:145], v[92:93], v[90:91]
	v_cvt_f32_ubyte2_e32 v92, v214
	v_cvt_f32_ubyte3_e32 v93, v214
	v_rcp_iflag_f32_e32 v100, v100
	v_rcp_iflag_f32_e32 v101, v101
	v_pk_mul_f32 v[88:89], v[102:103], v[88:89]
	v_rcp_iflag_f32_e32 v92, v92
	v_rcp_iflag_f32_e32 v93, v93
	v_pk_mul_f32 v[146:147], v[94:95], v[88:89]
	v_cvt_f32_ubyte0_e32 v88, v214
	v_cvt_f32_ubyte1_e32 v89, v214
	v_cvt_f32_ubyte0_e32 v90, v215
	v_cvt_f32_ubyte1_e32 v91, v215
	v_rcp_iflag_f32_e32 v88, v88
	v_rcp_iflag_f32_e32 v90, v90
	v_rcp_iflag_f32_e32 v89, v89
	v_rcp_iflag_f32_e32 v91, v91
	v_cvt_f32_ubyte2_e32 v94, v215
	v_cvt_f32_ubyte3_e32 v95, v215
	v_cvt_f32_ubyte3_e32 v97, v184
	v_cvt_f32_ubyte2_e32 v96, v184
	v_pk_mul_f32 v[100:101], v[100:101], v[104:105]
	v_rcp_iflag_f32_e32 v94, v94
	v_rcp_iflag_f32_e32 v95, v95
	v_pk_mul_f32 v[92:93], v[92:93], v[96:97]
	v_pk_mul_f32 v[150:151], v[98:99], v[100:101]
	v_cvt_f32_ubyte1_e32 v99, v184
	v_cvt_f32_ubyte0_e32 v98, v184
	v_pk_mul_f32 v[118:119], v[86:87], v[92:93]
	v_cvt_f32_ubyte1_e32 v87, v185
	v_cvt_f32_ubyte0_e32 v86, v185
	v_pk_mul_f32 v[88:89], v[88:89], v[98:99]
	v_pk_mul_f32 v[86:87], v[90:91], v[86:87]
	v_pk_mul_f32 v[116:117], v[84:85], v[88:89]
	v_cvt_f32_ubyte3_e32 v85, v185
	v_cvt_f32_ubyte2_e32 v84, v185
	v_pk_mul_f32 v[112:113], v[80:81], v[86:87]
	v_lshl_add_u64 v[80:81], v[182:183], 0, s[26:27]
	v_pk_mul_f32 v[84:85], v[94:95], v[84:85]
	s_nop 0
	v_pk_mul_f32 v[114:115], v[82:83], v[84:85]
	global_load_dwordx2 v[84:85], v[80:81], off
	global_load_dwordx2 v[86:87], v[80:81], off offset:2048
	global_load_dwordx2 v[82:83], v[80:81], off offset:128
	global_load_dwordx2 v[88:89], v[80:81], off offset:2176
	v_add_co_u32_e32 v90, vcc, s21, v80
	s_waitcnt vmcnt(0) lgkmcnt(0)
	v_cvt_f32_ubyte1_e32 v105, v84
	v_addc_co_u32_e32 v91, vcc, 0, v81, vcc
	global_load_dwordx2 v[92:93], v[90:91], off
	global_load_dwordx2 v[94:95], v[90:91], off offset:2048
	global_load_dwordx2 v[182:183], v[90:91], off offset:128
	s_nop 0
	global_load_dwordx2 v[90:91], v[90:91], off offset:2176
	v_cvt_f32_ubyte0_e32 v96, v86
	v_cvt_f32_ubyte1_e32 v97, v86
	v_cvt_f32_ubyte2_e32 v98, v86
	v_cvt_f32_ubyte3_e32 v99, v86
	v_cvt_f32_ubyte0_e32 v100, v87
	v_cvt_f32_ubyte1_e32 v101, v87
	v_cvt_f32_ubyte2_e32 v102, v87
	v_cvt_f32_ubyte3_e32 v103, v87
	v_rcp_iflag_f32_e32 v86, v96
	v_rcp_iflag_f32_e32 v87, v97
	v_rcp_iflag_f32_e32 v96, v100
	v_rcp_iflag_f32_e32 v97, v101
	v_rcp_iflag_f32_e32 v98, v98
	v_rcp_iflag_f32_e32 v100, v102
	v_rcp_iflag_f32_e32 v99, v99
	v_rcp_iflag_f32_e32 v101, v103
	v_cvt_f32_ubyte0_e32 v104, v84
	v_pk_mul_f32 v[86:87], v[86:87], v[104:105]
	v_cvt_f32_ubyte3_e32 v103, v84
	v_cvt_f32_ubyte2_e32 v102, v84
	v_pk_mul_f32 v[108:109], v[76:77], v[86:87]
	v_cvt_f32_ubyte3_e32 v77, v85
	v_cvt_f32_ubyte2_e32 v76, v85
	v_pk_mul_f32 v[98:99], v[98:99], v[102:103]
	v_pk_mul_f32 v[76:77], v[100:101], v[76:77]
	v_pk_mul_f32 v[110:111], v[78:79], v[98:99]
	v_cvt_f32_ubyte1_e32 v79, v85
	v_cvt_f32_ubyte0_e32 v78, v85
	v_pk_mul_f32 v[106:107], v[74:75], v[76:77]
	v_cvt_f32_ubyte2_e32 v76, v88
	v_cvt_f32_ubyte3_e32 v77, v88
	v_pk_mul_f32 v[78:79], v[96:97], v[78:79]
	v_rcp_iflag_f32_e32 v76, v76
	v_rcp_iflag_f32_e32 v77, v77
	v_pk_mul_f32 v[104:105], v[72:73], v[78:79]
	v_cvt_f32_ubyte0_e32 v72, v88
	v_cvt_f32_ubyte1_e32 v73, v88
	v_cvt_f32_ubyte0_e32 v74, v89
	v_cvt_f32_ubyte1_e32 v75, v89
	v_cvt_f32_ubyte2_e32 v78, v89
	v_cvt_f32_ubyte3_e32 v79, v89
	v_rcp_iflag_f32_e32 v72, v72
	v_rcp_iflag_f32_e32 v74, v74
	v_rcp_iflag_f32_e32 v73, v73
	v_rcp_iflag_f32_e32 v75, v75
	v_rcp_iflag_f32_e32 v84, v78
	v_rcp_iflag_f32_e32 v85, v79
	v_cvt_f32_ubyte3_e32 v79, v82
	v_cvt_f32_ubyte2_e32 v78, v82
	v_pk_mul_f32 v[76:77], v[76:77], v[78:79]
	v_cvt_f32_ubyte1_e32 v87, v82
	v_cvt_f32_ubyte0_e32 v86, v82
	v_pk_mul_f32 v[78:79], v[70:71], v[76:77]
	v_cvt_f32_ubyte1_e32 v71, v83
	v_cvt_f32_ubyte0_e32 v70, v83
	v_pk_mul_f32 v[72:73], v[72:73], v[86:87]
	v_pk_mul_f32 v[70:71], v[74:75], v[70:71]
	v_pk_mul_f32 v[76:77], v[68:69], v[72:73]
	v_cvt_f32_ubyte3_e32 v69, v83
	v_cvt_f32_ubyte2_e32 v68, v83
	v_pk_mul_f32 v[72:73], v[56:57], v[70:71]
	v_pk_mul_f32 v[68:69], v[84:85], v[68:69]
	s_waitcnt vmcnt(0) lgkmcnt(0)
;     DI void mid(AccT& acc, const Unit& u, int seg, int wr, int wc, int fr, int fq) const {
;         const int row0 = u.pm * BM + wr * 64 + fr, col0 = u.pn * BM + wc * 32 + 8 * fq;
;         const unsigned char* pa = (const unsigned char*)G + (size_t)row0 * NGATE + seg * 2048 + col0;
; #pragma unroll
;         for (int ai = 0; ai < 2; ++ai) {
; #pragma unroll
;             for (int mh = 0; mh < 2; ++mh) {
;                 u32x2 ra[2][2], rb[2][2];
; #pragma unroll
;                 for (int mm = 0; mm < 2; ++mm)
; #pragma unroll
;                     for (int bj = 0; bj < 2; ++bj) { const unsigned char* p = pa + (size_t)(mm * 16) * NGATE + bj * HALF; ra[mm][bj] = *(const u32x2*)p; rb[mm][bj] = *(const u32x2*)(p + 2048); }
; #pragma unroll
;                 for (int mm = 0; mm < 2; ++mm)
; #pragma unroll
;                     for (int bj = 0; bj < 2; ++bj) {
;                         float ga[8], gb[8];
;                         unpack_gate8(ra[mm][bj], ga); unpack_gate8(rb[mm][bj], gb);
;                         const int m = 2 * mh + mm;
; #pragma unroll
;                         for (int j = 0; j < 4; ++j) { const float r0 = ga[j] * __builtin_amdgcn_rcpf(gb[j]), r1 = ga[4 + j] * __builtin_amdgcn_rcpf(gb[4 + j]);
;                             acc[ai][bj][m][0][j] *= r0; acc[ai][bj][m][1][j] *= r1; } }
;                 pa += (size_t)(mh == 1 ? 96 : 32) * NGATE;
;                 asm volatile("" : "+v"(pa));
;             } }
	v_cvt_f32_ubyte1_e32 v85, v92
	v_cvt_f32_ubyte0_e32 v56, v94
	v_cvt_f32_ubyte1_e32 v57, v94
	v_rcp_iflag_f32_e32 v56, v56
	v_rcp_iflag_f32_e32 v57, v57
	v_pk_mul_f32 v[74:75], v[58:59], v[68:69]
	v_cvt_f32_ubyte0_e32 v58, v95
	v_cvt_f32_ubyte1_e32 v59, v95
	v_cvt_f32_ubyte2_e32 v70, v95
	v_cvt_f32_ubyte3_e32 v71, v95
	v_rcp_iflag_f32_e32 v58, v58
	v_rcp_iflag_f32_e32 v59, v59
	v_rcp_iflag_f32_e32 v70, v70
	v_rcp_iflag_f32_e32 v71, v71
	v_cvt_f32_ubyte0_e32 v84, v92
	v_pk_mul_f32 v[56:57], v[56:57], v[84:85]
	v_cvt_f32_ubyte2_e32 v68, v94
	v_cvt_f32_ubyte3_e32 v69, v94
	v_pk_mul_f32 v[100:101], v[64:65], v[56:57]
	v_cvt_f32_ubyte3_e32 v57, v93
	v_cvt_f32_ubyte2_e32 v56, v93
	v_cvt_f32_ubyte1_e32 v65, v93
	v_cvt_f32_ubyte0_e32 v64, v93
	v_rcp_iflag_f32_e32 v68, v68
	v_rcp_iflag_f32_e32 v69, v69
	v_pk_mul_f32 v[58:59], v[58:59], v[64:65]
	v_pk_mul_f32 v[56:57], v[70:71], v[56:57]
	v_pk_mul_f32 v[96:97], v[60:61], v[58:59]
	v_pk_mul_f32 v[98:99], v[62:63], v[56:57]
	v_cvt_f32_ubyte0_e32 v56, v90
	v_cvt_f32_ubyte1_e32 v57, v90
	v_cvt_f32_ubyte2_e32 v60, v90
	v_cvt_f32_ubyte3_e32 v61, v90
	v_rcp_iflag_f32_e32 v56, v56
	v_rcp_iflag_f32_e32 v57, v57
	v_rcp_iflag_f32_e32 v60, v60
	v_rcp_iflag_f32_e32 v61, v61
	v_cvt_f32_ubyte3_e32 v83, v92
	v_cvt_f32_ubyte2_e32 v82, v92
	v_cvt_f32_ubyte0_e32 v58, v91
	v_cvt_f32_ubyte1_e32 v59, v91
	v_cvt_f32_ubyte2_e32 v62, v91
	v_cvt_f32_ubyte3_e32 v63, v91
	v_pk_mul_f32 v[68:69], v[68:69], v[82:83]
	v_rcp_iflag_f32_e32 v58, v58
	v_rcp_iflag_f32_e32 v59, v59
	v_rcp_iflag_f32_e32 v62, v62
	v_rcp_iflag_f32_e32 v63, v63
	v_pk_mul_f32 v[102:103], v[66:67], v[68:69]
	v_cvt_f32_ubyte3_e32 v65, v182
	v_cvt_f32_ubyte2_e32 v64, v182
	v_cvt_f32_ubyte1_e32 v67, v182
	v_cvt_f32_ubyte0_e32 v66, v182
	v_pk_mul_f32 v[56:57], v[56:57], v[66:67]
	v_pk_mul_f32 v[60:61], v[60:61], v[64:65]
	v_pk_mul_f32 v[68:69], v[52:53], v[56:57]
	v_pk_mul_f32 v[70:71], v[54:55], v[60:61]
	v_cvt_f32_ubyte3_e32 v53, v183
	v_cvt_f32_ubyte2_e32 v52, v183
	v_cvt_f32_ubyte1_e32 v55, v183
	v_cvt_f32_ubyte0_e32 v54, v183
	v_lshl_add_u64 v[182:183], v[80:81], 0, s[24:25]
	v_pk_mul_f32 v[54:55], v[58:59], v[54:55]
	v_pk_mul_f32 v[52:53], v[62:63], v[52:53]
	v_pk_mul_f32 v[64:65], v[48:49], v[54:55]
	v_pk_mul_f32 v[66:67], v[50:51], v[52:53]
	global_load_dwordx2 v[50:51], v[182:183], off
	global_load_dwordx2 v[52:53], v[182:183], off offset:2048
	global_load_dwordx2 v[48:49], v[182:183], off offset:128
	global_load_dwordx2 v[54:55], v[182:183], off offset:2176
	v_add_co_u32_e32 v56, vcc, s21, v182
	s_waitcnt vmcnt(0) lgkmcnt(0)
	v_cvt_f32_ubyte1_e32 v85, v50
	v_addc_co_u32_e32 v57, vcc, 0, v183, vcc
	global_load_dwordx2 v[80:81], v[56:57], off
	global_load_dwordx2 v[82:83], v[56:57], off offset:2048
	global_load_dwordx2 v[184:185], v[56:57], off offset:128
	global_load_dwordx2 v[214:215], v[56:57], off offset:2176
	v_cvt_f32_ubyte0_e32 v56, v52
	v_cvt_f32_ubyte1_e32 v57, v52
	v_cvt_f32_ubyte2_e32 v58, v52
	v_cvt_f32_ubyte3_e32 v59, v52
	v_cvt_f32_ubyte0_e32 v60, v53
	v_cvt_f32_ubyte1_e32 v61, v53
	v_cvt_f32_ubyte2_e32 v62, v53
	v_cvt_f32_ubyte3_e32 v63, v53
	v_rcp_iflag_f32_e32 v52, v56
	v_rcp_iflag_f32_e32 v53, v57
	v_rcp_iflag_f32_e32 v58, v58
	v_rcp_iflag_f32_e32 v59, v59
	v_rcp_iflag_f32_e32 v56, v60
	v_rcp_iflag_f32_e32 v57, v61
	v_rcp_iflag_f32_e32 v60, v62
	v_rcp_iflag_f32_e32 v61, v63
	v_cvt_f32_ubyte3_e32 v63, v50
	v_cvt_f32_ubyte2_e32 v62, v50
	v_cvt_f32_ubyte0_e32 v84, v50
	v_pk_mul_f32 v[52:53], v[52:53], v[84:85]
	v_pk_mul_f32 v[58:59], v[58:59], v[62:63]
	v_pk_mul_f32 v[92:93], v[28:29], v[52:53]
	v_pk_mul_f32 v[94:95], v[30:31], v[58:59]
	v_cvt_f32_ubyte3_e32 v29, v51
	v_cvt_f32_ubyte2_e32 v28, v51
	v_cvt_f32_ubyte1_e32 v31, v51
	v_cvt_f32_ubyte0_e32 v30, v51
	v_pk_mul_f32 v[30:31], v[56:57], v[30:31]
	v_pk_mul_f32 v[28:29], v[60:61], v[28:29]
	v_pk_mul_f32 v[88:89], v[24:25], v[30:31]
	v_pk_mul_f32 v[90:91], v[26:27], v[28:29]
	v_cvt_f32_ubyte0_e32 v24, v54
	v_cvt_f32_ubyte1_e32 v25, v54
	v_cvt_f32_ubyte2_e32 v28, v54
	v_cvt_f32_ubyte3_e32 v29, v54
	v_rcp_iflag_f32_e32 v24, v24
	v_rcp_iflag_f32_e32 v25, v25
	v_rcp_iflag_f32_e32 v28, v28
	v_rcp_iflag_f32_e32 v29, v29
	v_cvt_f32_ubyte0_e32 v26, v55
	v_cvt_f32_ubyte1_e32 v27, v55
	v_cvt_f32_ubyte2_e32 v30, v55
	v_cvt_f32_ubyte3_e32 v31, v55
	v_rcp_iflag_f32_e32 v26, v26
	v_rcp_iflag_f32_e32 v27, v27
	v_rcp_iflag_f32_e32 v30, v30
	v_rcp_iflag_f32_e32 v31, v31
	v_cvt_f32_ubyte3_e32 v51, v48
	v_cvt_f32_ubyte2_e32 v50, v48
	v_cvt_f32_ubyte1_e32 v53, v48
	v_cvt_f32_ubyte0_e32 v52, v48
	v_pk_mul_f32 v[24:25], v[24:25], v[52:53]
	v_pk_mul_f32 v[28:29], v[28:29], v[50:51]
	v_pk_mul_f32 v[60:61], v[20:21], v[24:25]
	v_pk_mul_f32 v[62:63], v[22:23], v[28:29]
	v_cvt_f32_ubyte3_e32 v21, v49
	v_cvt_f32_ubyte2_e32 v20, v49
	v_cvt_f32_ubyte1_e32 v23, v49
	v_cvt_f32_ubyte0_e32 v22, v49
	v_pk_mul_f32 v[22:23], v[26:27], v[22:23]
	v_pk_mul_f32 v[20:21], v[30:31], v[20:21]
	v_pk_mul_f32 v[56:57], v[16:17], v[22:23]
	v_pk_mul_f32 v[58:59], v[18:19], v[20:21]
	s_waitcnt vmcnt(0) lgkmcnt(0)
;     DI void mid(AccT& acc, const Unit& u, int seg, int wr, int wc, int fr, int fq) const {
;     ...
;                 for (int mm = 0; mm < 2; ++mm)
; #pragma unroll
;                     for (int bj = 0; bj < 2; ++bj) { const unsigned char* p = pa + (size_t)(mm * 16) * NGATE + bj * HALF; ra[mm][bj] = *(const u32x2*)p; rb[mm][bj] = *(const u32x2*)(p + 2048); }
; #pragma unroll
;                 for (int mm = 0; mm < 2; ++mm)
; #pragma unroll
;                     for (int bj = 0; bj < 2; ++bj) {
;                         float ga[8], gb[8];
;                         unpack_gate8(ra[mm][bj], ga); unpack_gate8(rb[mm][bj], gb);
;                         const int m = 2 * mh + mm;
; #pragma unroll
;                         for (int j = 0; j < 4; ++j) { const float r0 = ga[j] * __builtin_amdgcn_rcpf(gb[j]), r1 = ga[4 + j] * __builtin_amdgcn_rcpf(gb[4 + j]);
;                             acc[ai][bj][m][0][j] *= r0; acc[ai][bj][m][1][j] *= r1; } }
	v_cvt_f32_ubyte3_e32 v25, v80
	v_cvt_f32_ubyte0_e32 v16, v82
	v_cvt_f32_ubyte1_e32 v17, v82
	v_cvt_f32_ubyte2_e32 v20, v82
	v_cvt_f32_ubyte3_e32 v21, v82
	v_rcp_iflag_f32_e32 v16, v16
	v_rcp_iflag_f32_e32 v17, v17
	v_rcp_iflag_f32_e32 v20, v20
	v_rcp_iflag_f32_e32 v21, v21
	v_cvt_f32_ubyte0_e32 v18, v83
	v_cvt_f32_ubyte1_e32 v19, v83
	v_cvt_f32_ubyte2_e32 v22, v83
	v_cvt_f32_ubyte3_e32 v23, v83
	v_rcp_iflag_f32_e32 v18, v18
	v_rcp_iflag_f32_e32 v19, v19
	v_rcp_iflag_f32_e32 v22, v22
	v_rcp_iflag_f32_e32 v23, v23
	v_cvt_f32_ubyte2_e32 v24, v80
	v_cvt_f32_ubyte1_e32 v27, v80
	v_cvt_f32_ubyte0_e32 v26, v80
	v_pk_mul_f32 v[16:17], v[16:17], v[26:27]
	v_pk_mul_f32 v[20:21], v[20:21], v[24:25]
	v_pk_mul_f32 v[84:85], v[12:13], v[16:17]
	v_pk_mul_f32 v[86:87], v[14:15], v[20:21]
	v_cvt_f32_ubyte3_e32 v13, v81
	v_cvt_f32_ubyte2_e32 v12, v81
	v_cvt_f32_ubyte1_e32 v15, v81
	v_cvt_f32_ubyte0_e32 v14, v81
	v_pk_mul_f32 v[14:15], v[18:19], v[14:15]
	v_pk_mul_f32 v[12:13], v[22:23], v[12:13]
	v_pk_mul_f32 v[80:81], v[8:9], v[14:15]
	v_pk_mul_f32 v[82:83], v[10:11], v[12:13]
	v_cvt_f32_ubyte0_e32 v8, v214
	v_cvt_f32_ubyte1_e32 v9, v214
	v_cvt_f32_ubyte2_e32 v12, v214
	v_cvt_f32_ubyte3_e32 v13, v214
	v_rcp_iflag_f32_e32 v8, v8
	v_rcp_iflag_f32_e32 v9, v9
	v_rcp_iflag_f32_e32 v12, v12
	v_rcp_iflag_f32_e32 v13, v13
	v_cvt_f32_ubyte0_e32 v10, v215
	v_cvt_f32_ubyte1_e32 v11, v215
	v_cvt_f32_ubyte2_e32 v14, v215
	v_cvt_f32_ubyte3_e32 v15, v215
	v_rcp_iflag_f32_e32 v10, v10
	v_rcp_iflag_f32_e32 v11, v11
	v_rcp_iflag_f32_e32 v14, v14
	v_rcp_iflag_f32_e32 v15, v15
	v_cvt_f32_ubyte3_e32 v17, v184
	v_cvt_f32_ubyte2_e32 v16, v184
	v_cvt_f32_ubyte1_e32 v19, v184
	v_cvt_f32_ubyte0_e32 v18, v184
	v_pk_mul_f32 v[8:9], v[8:9], v[18:19]
	v_pk_mul_f32 v[12:13], v[12:13], v[16:17]
	v_pk_mul_f32 v[52:53], v[4:5], v[8:9]
	v_pk_mul_f32 v[54:55], v[6:7], v[12:13]
	v_cvt_f32_ubyte3_e32 v5, v185
	v_cvt_f32_ubyte2_e32 v4, v185
	v_cvt_f32_ubyte1_e32 v7, v185
	v_cvt_f32_ubyte0_e32 v6, v185
	v_pk_mul_f32 v[6:7], v[10:11], v[6:7]
	v_pk_mul_f32 v[4:5], v[14:15], v[4:5]
	v_pk_mul_f32 v[48:49], v[0:1], v[6:7]
	v_pk_mul_f32 v[50:51], v[2:3], v[4:5]
	v_lshl_add_u64 v[0:1], v[182:183], 0, s[26:27]
.LBB0_1321:
	s_add_u32 s50, s16, s10
	ds_read_b128 v[0:3], v209
	ds_read_b128 v[4:7], v209 offset:1024
	ds_read_b128 v[8:11], v209 offset:2048
	ds_read_b128 v[12:15], v209 offset:3072
	s_addc_u32 s51, s18, s11
	s_add_u32 s12, s50, 0x15d00100
	s_addc_u32 s13, s51, 0
	s_add_u32 s19, s2, s10
	s_addc_u32 s52, s3, s11
	s_cmpk_eq_i32 s10, 0x300
	s_cselect_b32 s15, s7, s13
	s_cselect_b32 s14, s6, s12
	s_cselect_b32 s13, s9, s52
	s_cselect_b32 s12, s8, s19
	v_add_u32_e32 v160, v170, v204
	v_lshl_add_u64 v[226:227], s[50:51], 0, v[160:161]
	s_mov_b32 m0, s17
	v_lshl_add_u64 v[226:227], v[226:227], 0, s[90:91]
	v_add_u32_e32 v242, v172, v205
	v_mov_b32_e32 v243, v161
	ds_read_b128 v[16:19], v203
	ds_read_b128 v[20:23], v203 offset:1024
	ds_read_b128 v[24:27], v203 offset:2048
	ds_read_b128 v[28:31], v203 offset:3072
	ds_read_b128 v[182:185], v203 offset:4096
	ds_read_b128 v[214:217], v203 offset:5120
	ds_read_b128 v[218:221], v203 offset:6144
	ds_read_b128 v[222:225], v203 offset:7168
	global_load_lds_dwordx4 v[226:227], off
	v_lshl_add_u64 v[226:227], s[50:51], 0, v[242:243]
	v_lshl_add_u64 v[226:227], v[226:227], 0, s[90:91]
	s_mov_b32 m0, s86
	s_nop 0
	global_load_lds_dwordx4 v[226:227], off
	s_waitcnt lgkmcnt(8)
	s_barrier
	s_waitcnt lgkmcnt(0)
	s_setprio 1
	s_waitcnt lgkmcnt(0)
	v_mfma_f32_16x16x32_bf16 v[140:143], v[0:3], v[16:19], v[140:143]
	v_mfma_f32_16x16x32_bf16 v[136:139], v[8:11], v[16:19], v[136:139]
	v_mfma_f32_16x16x32_bf16 v[132:135], v[0:3], v[24:27], v[132:135]
	v_mfma_f32_16x16x32_bf16 v[128:131], v[8:11], v[24:27], v[128:131]
	v_mfma_f32_16x16x32_bf16 v[156:159], v[0:3], v[182:185], v[156:159]
	v_mfma_f32_16x16x32_bf16 v[152:155], v[8:11], v[182:185], v[152:155]
	v_mfma_f32_16x16x32_bf16 v[148:151], v[0:3], v[218:221], v[148:151]
	v_mfma_f32_16x16x32_bf16 v[144:147], v[8:11], v[218:221], v[144:147]
	v_mfma_f32_16x16x32_bf16 v[140:143], v[4:7], v[20:23], v[140:143]
	v_mfma_f32_16x16x32_bf16 v[136:139], v[12:15], v[20:23], v[136:139]
	v_mfma_f32_16x16x32_bf16 v[132:135], v[4:7], v[28:31], v[132:135]
	v_mfma_f32_16x16x32_bf16 v[128:131], v[12:15], v[28:31], v[128:131]
	v_mfma_f32_16x16x32_bf16 v[156:159], v[4:7], v[214:217], v[156:159]
	v_mfma_f32_16x16x32_bf16 v[152:155], v[12:15], v[214:217], v[152:155]
	v_mfma_f32_16x16x32_bf16 v[148:151], v[4:7], v[222:225], v[148:151]
	v_mfma_f32_16x16x32_bf16 v[144:147], v[12:15], v[222:225], v[144:147]
	s_setprio 0
	s_barrier
	s_mov_b32 m0, s87
	v_add_u32_e32 v246, v170, v206
	ds_read_b128 v[226:229], v210
	ds_read_b128 v[230:233], v210 offset:1024
	ds_read_b128 v[234:237], v210 offset:2048
	ds_read_b128 v[238:241], v210 offset:3072
	global_load_lds_dwordx4 v246, s[12:13]
	v_add_u32_e32 v248, v172, v207
	s_mov_b32 m0, s36
	v_mov_b32_e32 v247, v161
	global_load_lds_dwordx4 v248, s[12:13]
	s_barrier
	s_waitcnt lgkmcnt(0)
	v_mov_b32_e32 v249, v161
	v_lshl_add_u64 v[250:251], s[12:13], 0, v[246:247]
	v_lshl_add_u64 v[166:167], s[12:13], 0, v[248:249]
	s_setprio 1
	s_waitcnt lgkmcnt(0)
	v_mfma_f32_16x16x32_bf16 v[44:47], v[226:229], v[16:19], v[44:47]
	v_mfma_f32_16x16x32_bf16 v[16:19], v[234:237], v[16:19], v[40:43]
	v_mfma_f32_16x16x32_bf16 v[44:47], v[230:233], v[20:23], v[44:47]
	v_mfma_f32_16x16x32_bf16 v[16:19], v[238:241], v[20:23], v[16:19]
	v_mfma_f32_16x16x32_bf16 v[20:23], v[226:229], v[24:27], v[36:39]
	v_mfma_f32_16x16x32_bf16 v[24:27], v[234:237], v[24:27], v[32:35]
	v_mfma_f32_16x16x32_bf16 v[32:35], v[234:237], v[182:185], v[120:123]
	v_mfma_f32_16x16x32_bf16 v[120:123], v[238:241], v[214:217], v[32:35]
	v_mfma_f32_16x16x32_bf16 v[32:35], v[226:229], v[218:221], v[116:119]
	v_mfma_f32_16x16x32_bf16 v[116:119], v[230:233], v[222:225], v[32:35]
	v_mfma_f32_16x16x32_bf16 v[32:35], v[234:237], v[218:221], v[112:115]
	v_mfma_f32_16x16x32_bf16 v[20:23], v[230:233], v[28:31], v[20:23]
	v_mfma_f32_16x16x32_bf16 v[24:27], v[238:241], v[28:31], v[24:27]
	v_mfma_f32_16x16x32_bf16 v[28:31], v[226:229], v[182:185], v[124:127]
	v_mfma_f32_16x16x32_bf16 v[112:115], v[238:241], v[222:225], v[32:35]
	v_mfma_f32_16x16x32_bf16 v[28:31], v[230:233], v[214:217], v[28:31]
	s_setprio 0
	s_mov_b32 m0, s60
	s_barrier
	ds_read_b128 v[32:35], v203 offset:16384
	ds_read_b128 v[36:39], v203 offset:17408
	ds_read_b128 v[40:43], v203 offset:18432
	ds_read_b128 v[124:127], v203 offset:19456
	ds_read_b128 v[182:185], v203 offset:20480
	ds_read_b128 v[214:217], v203 offset:21504
	ds_read_b128 v[218:221], v203 offset:22528
	ds_read_b128 v[222:225], v203 offset:23552
	global_load_lds_dwordx4 v160, s[14:15]
	s_mov_b32 m0, s61
	v_lshl_add_u64 v[168:169], s[14:15], 0, v[160:161]
	global_load_lds_dwordx4 v242, s[14:15]
	s_barrier
	s_waitcnt lgkmcnt(0)
	v_lshl_add_u64 v[190:191], s[14:15], 0, v[242:243]
	s_setprio 1
	s_waitcnt lgkmcnt(0)
	v_mfma_f32_16x16x32_bf16 v[108:111], v[0:3], v[32:35], v[108:111]
	v_mfma_f32_16x16x32_bf16 v[104:107], v[8:11], v[32:35], v[104:107]
	v_mfma_f32_16x16x32_bf16 v[100:103], v[0:3], v[40:43], v[100:103]
	v_mfma_f32_16x16x32_bf16 v[96:99], v[8:11], v[40:43], v[96:99]
	v_mfma_f32_16x16x32_bf16 v[92:95], v[0:3], v[182:185], v[92:95]
	v_mfma_f32_16x16x32_bf16 v[88:91], v[8:11], v[182:185], v[88:91]
	v_mfma_f32_16x16x32_bf16 v[0:3], v[0:3], v[218:221], v[84:87]
	v_mfma_f32_16x16x32_bf16 v[108:111], v[4:7], v[36:39], v[108:111]
	v_mfma_f32_16x16x32_bf16 v[104:107], v[12:15], v[36:39], v[104:107]
	v_mfma_f32_16x16x32_bf16 v[100:103], v[4:7], v[124:127], v[100:103]
	v_mfma_f32_16x16x32_bf16 v[96:99], v[12:15], v[124:127], v[96:99]
	v_mfma_f32_16x16x32_bf16 v[92:95], v[4:7], v[214:217], v[92:95]
	v_mfma_f32_16x16x32_bf16 v[88:91], v[12:15], v[214:217], v[88:91]
	v_mfma_f32_16x16x32_bf16 v[0:3], v[4:7], v[222:225], v[0:3]
	v_mfma_f32_16x16x32_bf16 v[4:7], v[8:11], v[218:221], v[80:83]
	v_mfma_f32_16x16x32_bf16 v[4:7], v[12:15], v[222:225], v[4:7]
	s_setprio 0
	s_barrier
	s_add_u32 s50, s12, 0x20000
	s_addc_u32 s51, s13, 0
	s_mov_b32 m0, s37
	s_nop 0
	global_load_lds_dwordx4 v246, s[50:51]
	s_mov_b32 m0, s70
	s_nop 0
	global_load_lds_dwordx4 v248, s[50:51]
	s_waitcnt vmcnt(6)
	s_barrier
	s_setprio 1
	v_mfma_f32_16x16x32_bf16 v[8:11], v[226:229], v[32:35], v[76:79]
	v_mfma_f32_16x16x32_bf16 v[12:15], v[234:237], v[32:35], v[72:75]
	v_mfma_f32_16x16x32_bf16 v[32:35], v[226:229], v[40:43], v[68:71]
	v_mfma_f32_16x16x32_bf16 v[68:71], v[230:233], v[124:127], v[32:35]
	v_mfma_f32_16x16x32_bf16 v[32:35], v[234:237], v[40:43], v[64:67]
	v_mfma_f32_16x16x32_bf16 v[64:67], v[238:241], v[124:127], v[32:35]
	v_mfma_f32_16x16x32_bf16 v[32:35], v[226:229], v[182:185], v[60:63]
	v_mfma_f32_16x16x32_bf16 v[60:63], v[230:233], v[214:217], v[32:35]
	v_mfma_f32_16x16x32_bf16 v[32:35], v[234:237], v[182:185], v[56:59]
	v_mfma_f32_16x16x32_bf16 v[56:59], v[238:241], v[214:217], v[32:35]
	v_mfma_f32_16x16x32_bf16 v[32:35], v[226:229], v[218:221], v[52:55]
	v_mfma_f32_16x16x32_bf16 v[52:55], v[230:233], v[222:225], v[32:35]
	v_mfma_f32_16x16x32_bf16 v[32:35], v[234:237], v[218:221], v[48:51]
	v_mfma_f32_16x16x32_bf16 v[48:51], v[238:241], v[222:225], v[32:35]
	v_mfma_f32_16x16x32_bf16 v[8:11], v[230:233], v[36:39], v[8:11]
	v_mfma_f32_16x16x32_bf16 v[12:15], v[238:241], v[36:39], v[12:15]
	s_setprio 0
	s_barrier
	ds_read_b128 v[72:75], v211
	ds_read_b128 v[76:79], v211 offset:1024
	ds_read_b128 v[80:83], v211 offset:2048
	ds_read_b128 v[182:185], v211 offset:3072
	s_add_u32 s14, s14, 0x20000
	s_addc_u32 s15, s15, 0
	s_mov_b32 m0, s62
	ds_read_b128 v[32:35], v203 offset:32768
	ds_read_b128 v[36:39], v203 offset:33792
	ds_read_b128 v[84:87], v203 offset:34816
	ds_read_b128 v[124:127], v203 offset:35840
	ds_read_b128 v[214:217], v203 offset:36864
	ds_read_b128 v[218:221], v203 offset:37888
	ds_read_b128 v[222:225], v203 offset:38912
	ds_read_b128 v[226:229], v203 offset:39936
	global_load_lds_dwordx4 v160, s[14:15]
	s_mov_b32 m0, s63
	s_nop 0
	global_load_lds_dwordx4 v242, s[14:15]
	s_waitcnt lgkmcnt(8)
	s_barrier
	s_waitcnt lgkmcnt(0)
	s_setprio 1
	s_waitcnt lgkmcnt(0)
	v_mfma_f32_16x16x32_bf16 v[40:43], v[72:75], v[32:35], v[140:143]
	v_mfma_f32_16x16x32_bf16 v[140:143], v[76:79], v[36:39], v[40:43]
	v_mfma_f32_16x16x32_bf16 v[40:43], v[80:83], v[32:35], v[136:139]
	v_mfma_f32_16x16x32_bf16 v[136:139], v[182:185], v[36:39], v[40:43]
	v_mfma_f32_16x16x32_bf16 v[40:43], v[72:75], v[84:87], v[132:135]
	v_mfma_f32_16x16x32_bf16 v[132:135], v[76:79], v[124:127], v[40:43]
	v_mfma_f32_16x16x32_bf16 v[40:43], v[80:83], v[84:87], v[128:131]
	v_mfma_f32_16x16x32_bf16 v[128:131], v[182:185], v[124:127], v[40:43]
	v_mfma_f32_16x16x32_bf16 v[40:43], v[72:75], v[214:217], v[156:159]
	v_mfma_f32_16x16x32_bf16 v[156:159], v[76:79], v[218:221], v[40:43]
	v_mfma_f32_16x16x32_bf16 v[40:43], v[80:83], v[214:217], v[152:155]
	v_mfma_f32_16x16x32_bf16 v[152:155], v[182:185], v[218:221], v[40:43]
	v_mfma_f32_16x16x32_bf16 v[40:43], v[72:75], v[222:225], v[148:151]
	v_mfma_f32_16x16x32_bf16 v[148:151], v[76:79], v[226:229], v[40:43]
	v_mfma_f32_16x16x32_bf16 v[40:43], v[80:83], v[222:225], v[144:147]
	v_mfma_f32_16x16x32_bf16 v[144:147], v[182:185], v[226:229], v[40:43]
	s_setprio 0
	s_barrier
	s_mov_b32 m0, s54
	s_nop 3
	v_lshl_add_u64 v[40:41], v[250:251], 0, s[78:79]
	ds_read_b128 v[230:233], v212
	ds_read_b128 v[234:237], v212 offset:1024
	ds_read_b128 v[238:241], v212 offset:2048
	ds_read_b128 v[242:245], v212 offset:3072
	global_load_lds_dwordx4 v[40:41], off
	v_lshl_add_u64 v[40:41], v[166:167], 0, s[78:79]
	s_mov_b32 m0, s55
	s_nop 0
	global_load_lds_dwordx4 v[40:41], off
	s_barrier
	s_waitcnt lgkmcnt(0)
	s_setprio 1
	s_waitcnt lgkmcnt(0)
	v_mfma_f32_16x16x32_bf16 v[40:43], v[230:233], v[32:35], v[44:47]
	v_mfma_f32_16x16x32_bf16 v[16:19], v[238:241], v[32:35], v[16:19]
	v_mfma_f32_16x16x32_bf16 v[44:47], v[234:237], v[36:39], v[40:43]
	v_mfma_f32_16x16x32_bf16 v[40:43], v[242:245], v[36:39], v[16:19]
	v_mfma_f32_16x16x32_bf16 v[16:19], v[230:233], v[84:87], v[20:23]
	v_mfma_f32_16x16x32_bf16 v[36:39], v[234:237], v[124:127], v[16:19]
	v_mfma_f32_16x16x32_bf16 v[16:19], v[238:241], v[84:87], v[24:27]
	v_mfma_f32_16x16x32_bf16 v[32:35], v[242:245], v[124:127], v[16:19]
	v_mfma_f32_16x16x32_bf16 v[16:19], v[230:233], v[214:217], v[28:31]
	v_mfma_f32_16x16x32_bf16 v[124:127], v[234:237], v[218:221], v[16:19]
	v_mfma_f32_16x16x32_bf16 v[16:19], v[238:241], v[214:217], v[120:123]
	v_mfma_f32_16x16x32_bf16 v[120:123], v[242:245], v[218:221], v[16:19]
	v_mfma_f32_16x16x32_bf16 v[16:19], v[230:233], v[222:225], v[116:119]
	v_mfma_f32_16x16x32_bf16 v[116:119], v[234:237], v[226:229], v[16:19]
	v_mfma_f32_16x16x32_bf16 v[16:19], v[238:241], v[222:225], v[112:115]
	v_mfma_f32_16x16x32_bf16 v[112:115], v[242:245], v[226:229], v[16:19]
	s_setprio 0
	s_mov_b32 m0, s74
	v_lshl_add_u64 v[84:85], v[168:169], 0, s[78:79]
	s_barrier
	s_nop 2
	ds_read_b128 v[16:19], v203 offset:49152
	ds_read_b128 v[20:23], v203 offset:50176
	ds_read_b128 v[24:27], v203 offset:51200
	ds_read_b128 v[28:31], v203 offset:52224
	ds_read_b128 v[214:217], v203 offset:53248
	ds_read_b128 v[218:221], v203 offset:54272
	ds_read_b128 v[222:225], v203 offset:55296
	ds_read_b128 v[226:229], v203 offset:56320
	global_load_lds_dwordx4 v[84:85], off
	v_lshl_add_u64 v[84:85], v[190:191], 0, s[78:79]
	s_mov_b32 m0, s75
	s_nop 0
	global_load_lds_dwordx4 v[84:85], off
	s_barrier
	s_waitcnt lgkmcnt(0)
	s_setprio 1
	s_waitcnt lgkmcnt(0)
	v_mfma_f32_16x16x32_bf16 v[84:87], v[72:75], v[16:19], v[108:111]
	v_mfma_f32_16x16x32_bf16 v[108:111], v[76:79], v[20:23], v[84:87]
	v_mfma_f32_16x16x32_bf16 v[84:87], v[80:83], v[16:19], v[104:107]
	v_mfma_f32_16x16x32_bf16 v[104:107], v[182:185], v[20:23], v[84:87]
	v_mfma_f32_16x16x32_bf16 v[84:87], v[72:75], v[24:27], v[100:103]
	v_mfma_f32_16x16x32_bf16 v[100:103], v[76:79], v[28:31], v[84:87]
	v_mfma_f32_16x16x32_bf16 v[84:87], v[80:83], v[24:27], v[96:99]
	v_mfma_f32_16x16x32_bf16 v[96:99], v[182:185], v[28:31], v[84:87]
	v_mfma_f32_16x16x32_bf16 v[84:87], v[72:75], v[214:217], v[92:95]
	v_mfma_f32_16x16x32_bf16 v[92:95], v[76:79], v[218:221], v[84:87]
	v_mfma_f32_16x16x32_bf16 v[84:87], v[80:83], v[214:217], v[88:91]
	v_mfma_f32_16x16x32_bf16 v[0:3], v[72:75], v[222:225], v[0:3]
	v_mfma_f32_16x16x32_bf16 v[88:91], v[182:185], v[218:221], v[84:87]
	v_mfma_f32_16x16x32_bf16 v[84:87], v[76:79], v[226:229], v[0:3]
	v_mfma_f32_16x16x32_bf16 v[0:3], v[80:83], v[222:225], v[4:7]
	v_mfma_f32_16x16x32_bf16 v[80:83], v[182:185], v[226:229], v[0:3]
	s_setprio 0
	s_barrier
	s_add_u32 s12, s12, 0x20080
	s_addc_u32 s13, s13, 0
	s_mov_b32 m0, s22
	s_nop 0
	global_load_lds_dwordx4 v246, s[12:13]
	s_mov_b32 m0, s23
	s_nop 0
	global_load_lds_dwordx4 v248, s[12:13]
	s_waitcnt vmcnt(6)
	s_barrier
	s_setprio 1
	v_mfma_f32_16x16x32_bf16 v[0:3], v[230:233], v[16:19], v[8:11]
	v_mfma_f32_16x16x32_bf16 v[76:79], v[234:237], v[20:23], v[0:3]
	v_mfma_f32_16x16x32_bf16 v[0:3], v[238:241], v[16:19], v[12:15]
	v_mfma_f32_16x16x32_bf16 v[72:75], v[242:245], v[20:23], v[0:3]
	v_mfma_f32_16x16x32_bf16 v[0:3], v[230:233], v[24:27], v[68:71]
	v_mfma_f32_16x16x32_bf16 v[68:71], v[234:237], v[28:31], v[0:3]
	v_mfma_f32_16x16x32_bf16 v[0:3], v[238:241], v[24:27], v[64:67]
	v_mfma_f32_16x16x32_bf16 v[64:67], v[242:245], v[28:31], v[0:3]
	v_mfma_f32_16x16x32_bf16 v[0:3], v[230:233], v[214:217], v[60:63]
	v_mfma_f32_16x16x32_bf16 v[60:63], v[234:237], v[218:221], v[0:3]
	v_mfma_f32_16x16x32_bf16 v[0:3], v[238:241], v[214:217], v[56:59]
	v_mfma_f32_16x16x32_bf16 v[56:59], v[242:245], v[218:221], v[0:3]
	v_mfma_f32_16x16x32_bf16 v[0:3], v[230:233], v[222:225], v[52:55]
	v_mfma_f32_16x16x32_bf16 v[52:55], v[234:237], v[226:229], v[0:3]
	v_mfma_f32_16x16x32_bf16 v[0:3], v[238:241], v[222:225], v[48:51]
	v_mfma_f32_16x16x32_bf16 v[48:51], v[242:245], v[226:229], v[0:3]
	s_setprio 0
	s_add_i32 s5, s5, 2
	s_add_u32 s10, s10, 0x100
	s_addc_u32 s11, s11, 0
	s_cmp_gt_u32 s5, 5
	s_barrier
;     DI void mid(AccT& acc, const Unit& u, int seg, int wr, int wc, int fr, int fq) const {
;         const int row0 = u.pm * BM + wr * 64 + fr, col0 = u.pn * BM + wc * 32 + 8 * fq;
;         const unsigned char* pa = (const unsigned char*)G + (size_t)row0 * NGATE + seg * 2048 + col0;
; #pragma unroll
;         for (int ai = 0; ai < 2; ++ai) {
; #pragma unroll
;             for (int mh = 0; mh < 2; ++mh) {
;                 u32x2 ra[2][2], rb[2][2];
; #pragma unroll
;                 for (int mm = 0; mm < 2; ++mm)
; #pragma unroll
;                     for (int bj = 0; bj < 2; ++bj) { const unsigned char* p = pa + (size_t)(mm * 16) * NGATE + bj * HALF; ra[mm][bj] = *(const u32x2*)p; rb[mm][bj] = *(const u32x2*)(p + 2048); }
; #pragma unroll
;                 for (int mm = 0; mm < 2; ++mm)
; #pragma unroll
;                     for (int bj = 0; bj < 2; ++bj) {
;                         float ga[8], gb[8];
;                         unpack_gate8(ra[mm][bj], ga); unpack_gate8(rb[mm][bj], gb);
;                         const int m = 2 * mh + mm;
; #pragma unroll
;                         for (int j = 0; j < 4; ++j) { const float r0 = ga[j] * __builtin_amdgcn_rcpf(gb[j]), r1 = ga[4 + j] * __builtin_amdgcn_rcpf(gb[4 + j]);
;                             acc[ai][bj][m][0][j] *= r0; acc[ai][bj][m][1][j] *= r1; } }
	s_cbranch_scc0 .LBB0_1321
	global_load_dwordx2 v[0:1], v[174:175], off offset:2048
	global_load_dwordx2 v[2:3], v[180:181], off offset:2048
	global_load_dwordx2 v[4:5], v[174:175], off offset:2176
	global_load_dwordx2 v[6:7], v[180:181], off offset:2176
	v_add_co_u32_e32 v8, vcc, 0x18000, v180
	s_add_u32 s5, s77, s48
	s_nop 0
	v_addc_co_u32_e32 v9, vcc, 0, v181, vcc
	global_load_dwordx2 v[10:11], v[8:9], off
	global_load_dwordx2 v[12:13], v[8:9], off offset:2048
	global_load_dwordx2 v[182:183], v[8:9], off offset:128
	global_load_dwordx2 v[184:185], v[8:9], off offset:2176
	s_addc_u32 s10, s82, s49
	s_mov_b32 s11, -2
	s_mov_b64 s[6:7], 0
	s_movk_i32 s57, 0x2000
	s_waitcnt vmcnt(0) lgkmcnt(0)
	v_cvt_f32_ubyte1_e32 v21, v0
	v_cvt_f32_ubyte2_e32 v14, v2
	v_cvt_f32_ubyte3_e32 v15, v2
	v_cvt_f32_ubyte0_e32 v8, v2
	v_cvt_f32_ubyte1_e32 v9, v2
	v_rcp_iflag_f32_e32 v14, v14
	v_rcp_iflag_f32_e32 v15, v15
	v_cvt_f32_ubyte0_e32 v16, v3
	v_cvt_f32_ubyte1_e32 v17, v3
	v_cvt_f32_ubyte2_e32 v18, v3
	v_cvt_f32_ubyte3_e32 v19, v3
	v_rcp_iflag_f32_e32 v2, v8
	v_rcp_iflag_f32_e32 v3, v9
	v_rcp_iflag_f32_e32 v8, v16
	v_rcp_iflag_f32_e32 v9, v17
	v_rcp_iflag_f32_e32 v16, v18
	v_rcp_iflag_f32_e32 v17, v19
	v_cvt_f32_ubyte3_e32 v19, v0
	v_cvt_f32_ubyte2_e32 v18, v0
	v_cvt_f32_ubyte0_e32 v20, v0
	v_pk_mul_f32 v[14:15], v[14:15], v[18:19]
	v_pk_mul_f32 v[2:3], v[2:3], v[20:21]
	v_pk_mul_f32 v[30:31], v[142:143], v[14:15]
	v_cvt_f32_ubyte1_e32 v15, v1
	v_cvt_f32_ubyte0_e32 v14, v1
	v_pk_mul_f32 v[28:29], v[140:141], v[2:3]
	v_cvt_f32_ubyte3_e32 v3, v1
	v_cvt_f32_ubyte2_e32 v2, v1
	v_pk_mul_f32 v[0:1], v[8:9], v[14:15]
	v_pk_mul_f32 v[2:3], v[16:17], v[2:3]
	v_pk_mul_f32 v[24:25], v[136:137], v[0:1]
	v_cvt_f32_ubyte0_e32 v0, v6
	v_cvt_f32_ubyte1_e32 v1, v6
	v_rcp_iflag_f32_e32 v0, v0
	v_rcp_iflag_f32_e32 v1, v1
	v_cvt_f32_ubyte2_e32 v8, v6
	v_cvt_f32_ubyte3_e32 v9, v6
	v_cvt_f32_ubyte2_e32 v14, v7
	v_cvt_f32_ubyte3_e32 v15, v7
	v_pk_mul_f32 v[26:27], v[138:139], v[2:3]
	v_cvt_f32_ubyte0_e32 v2, v7
	v_cvt_f32_ubyte1_e32 v3, v7
	v_rcp_iflag_f32_e32 v6, v8
	v_rcp_iflag_f32_e32 v8, v14
	v_rcp_iflag_f32_e32 v7, v9
	v_rcp_iflag_f32_e32 v9, v15
	v_cvt_f32_ubyte1_e32 v17, v4
	v_cvt_f32_ubyte0_e32 v16, v4
	v_pk_mul_f32 v[0:1], v[0:1], v[16:17]
	v_rcp_iflag_f32_e32 v2, v2
	v_rcp_iflag_f32_e32 v3, v3
	v_pk_mul_f32 v[20:21], v[44:45], v[0:1]
	v_cvt_f32_ubyte3_e32 v1, v5
	v_cvt_f32_ubyte2_e32 v0, v5
	v_cvt_f32_ubyte3_e32 v15, v4
	v_cvt_f32_ubyte2_e32 v14, v4
	v_pk_mul_f32 v[0:1], v[8:9], v[0:1]
	v_pk_mul_f32 v[6:7], v[6:7], v[14:15]
	v_pk_mul_f32 v[18:19], v[42:43], v[0:1]
	v_cvt_f32_ubyte0_e32 v0, v12
	v_cvt_f32_ubyte1_e32 v1, v12
	v_pk_mul_f32 v[22:23], v[46:47], v[6:7]
	v_cvt_f32_ubyte1_e32 v7, v5
	v_cvt_f32_ubyte0_e32 v6, v5
	v_cvt_f32_ubyte2_e32 v4, v12
	v_cvt_f32_ubyte3_e32 v5, v12
	v_rcp_iflag_f32_e32 v0, v0
	v_rcp_iflag_f32_e32 v1, v1
	v_pk_mul_f32 v[2:3], v[2:3], v[6:7]
	v_cvt_f32_ubyte2_e32 v6, v13
	v_cvt_f32_ubyte3_e32 v7, v13
	v_rcp_iflag_f32_e32 v4, v4
	v_rcp_iflag_f32_e32 v5, v5
	v_pk_mul_f32 v[16:17], v[40:41], v[2:3]
	v_cvt_f32_ubyte0_e32 v2, v13
	v_cvt_f32_ubyte1_e32 v3, v13
	v_rcp_iflag_f32_e32 v6, v6
	v_rcp_iflag_f32_e32 v7, v7
	v_rcp_iflag_f32_e32 v2, v2
	v_rcp_iflag_f32_e32 v3, v3
	v_cvt_f32_ubyte1_e32 v13, v10
	v_cvt_f32_ubyte0_e32 v12, v10
	v_cvt_f32_ubyte3_e32 v9, v10
	v_cvt_f32_ubyte2_e32 v8, v10
	v_pk_mul_f32 v[0:1], v[0:1], v[12:13]
	v_pk_mul_f32 v[4:5], v[4:5], v[8:9]
	v_pk_mul_f32 v[12:13], v[132:133], v[0:1]
	v_cvt_f32_ubyte3_e32 v1, v11
	v_cvt_f32_ubyte2_e32 v0, v11
	v_pk_mul_f32 v[14:15], v[134:135], v[4:5]
	v_cvt_f32_ubyte1_e32 v5, v11
	v_cvt_f32_ubyte0_e32 v4, v11
	v_pk_mul_f32 v[0:1], v[6:7], v[0:1]
	v_pk_mul_f32 v[2:3], v[2:3], v[4:5]
	v_pk_mul_f32 v[10:11], v[130:131], v[0:1]
	v_cvt_f32_ubyte0_e32 v0, v184
	v_cvt_f32_ubyte1_e32 v1, v184
	v_cvt_f32_ubyte2_e32 v4, v184
	v_cvt_f32_ubyte3_e32 v5, v184
	v_rcp_iflag_f32_e32 v0, v0
	v_rcp_iflag_f32_e32 v1, v1
	v_rcp_iflag_f32_e32 v4, v4
	v_rcp_iflag_f32_e32 v5, v5
	v_pk_mul_f32 v[8:9], v[128:129], v[2:3]
	v_cvt_f32_ubyte0_e32 v2, v185
	v_cvt_f32_ubyte1_e32 v3, v185
	v_cvt_f32_ubyte2_e32 v6, v185
	v_cvt_f32_ubyte3_e32 v7, v185
	v_rcp_iflag_f32_e32 v2, v2
	v_rcp_iflag_f32_e32 v3, v3
	v_rcp_iflag_f32_e32 v40, v6
	v_rcp_iflag_f32_e32 v41, v7
	v_cvt_f32_ubyte3_e32 v7, v182
	v_cvt_f32_ubyte2_e32 v6, v182
	v_cvt_f32_ubyte1_e32 v43, v182
	v_cvt_f32_ubyte0_e32 v42, v182
	v_pk_mul_f32 v[0:1], v[0:1], v[42:43]
	v_pk_mul_f32 v[4:5], v[4:5], v[6:7]
	v_lshl_add_u64 v[136:137], v[180:181], 0, s[24:25]
	v_pk_mul_f32 v[6:7], v[38:39], v[4:5]
	v_pk_mul_f32 v[4:5], v[36:37], v[0:1]
	v_cvt_f32_ubyte3_e32 v1, v183
	v_cvt_f32_ubyte2_e32 v0, v183
	v_cvt_f32_ubyte1_e32 v37, v183
	v_cvt_f32_ubyte0_e32 v36, v183
	v_pk_mul_f32 v[36:37], v[2:3], v[36:37]
	v_pk_mul_f32 v[0:1], v[40:41], v[0:1]
	s_nop 0
	v_pk_mul_f32 v[2:3], v[34:35], v[0:1]
	v_pk_mul_f32 v[0:1], v[32:33], v[36:37]
	global_load_dwordx2 v[34:35], v[136:137], off
	global_load_dwordx2 v[36:37], v[136:137], off offset:2048
	global_load_dwordx2 v[32:33], v[136:137], off offset:128
	global_load_dwordx2 v[38:39], v[136:137], off offset:2176
	v_add_co_u32_e32 v40, vcc, s21, v136
	s_waitcnt vmcnt(0) lgkmcnt(0)
;     DI void mid(AccT& acc, const Unit& u, int seg, int wr, int wc, int fr, int fq) const {
;         const int row0 = u.pm * BM + wr * 64 + fr, col0 = u.pn * BM + wc * 32 + 8 * fq;
;         const unsigned char* pa = (const unsigned char*)G + (size_t)row0 * NGATE + seg * 2048 + col0;
; #pragma unroll
;         for (int ai = 0; ai < 2; ++ai) {
; #pragma unroll
;             for (int mh = 0; mh < 2; ++mh) {
;                 u32x2 ra[2][2], rb[2][2];
; #pragma unroll
;                 for (int mm = 0; mm < 2; ++mm)
; #pragma unroll
;                     for (int bj = 0; bj < 2; ++bj) { const unsigned char* p = pa + (size_t)(mm * 16) * NGATE + bj * HALF; ra[mm][bj] = *(const u32x2*)p; rb[mm][bj] = *(const u32x2*)(p + 2048); }
; #pragma unroll
;                 for (int mm = 0; mm < 2; ++mm)
; #pragma unroll
;                     for (int bj = 0; bj < 2; ++bj) {
;                         float ga[8], gb[8];
;                         unpack_gate8(ra[mm][bj], ga); unpack_gate8(rb[mm][bj], gb);
;                         const int m = 2 * mh + mm;
; #pragma unroll
;                         for (int j = 0; j < 4; ++j) { const float r0 = ga[j] * __builtin_amdgcn_rcpf(gb[j]), r1 = ga[4 + j] * __builtin_amdgcn_rcpf(gb[4 + j]);
;                             acc[ai][bj][m][0][j] *= r0; acc[ai][bj][m][1][j] *= r1; } }
;                 pa += (size_t)(mh == 1 ? 96 : 32) * NGATE;
;                 asm volatile("" : "+v"(pa));
;             } }
	v_cvt_f32_ubyte1_e32 v133, v34
	v_addc_co_u32_e32 v41, vcc, 0, v137, vcc
	global_load_dwordx2 v[42:43], v[40:41], off
	global_load_dwordx2 v[44:45], v[40:41], off offset:2048
	global_load_dwordx2 v[138:139], v[40:41], off offset:128
	global_load_dwordx2 v[140:141], v[40:41], off offset:2176
	v_cvt_f32_ubyte0_e32 v40, v36
	v_cvt_f32_ubyte1_e32 v41, v36
	v_cvt_f32_ubyte2_e32 v46, v36
	v_cvt_f32_ubyte3_e32 v47, v36
	v_cvt_f32_ubyte0_e32 v128, v37
	v_cvt_f32_ubyte1_e32 v129, v37
	v_cvt_f32_ubyte2_e32 v130, v37
	v_cvt_f32_ubyte3_e32 v131, v37
	v_rcp_iflag_f32_e32 v36, v40
	v_rcp_iflag_f32_e32 v37, v41
	v_rcp_iflag_f32_e32 v46, v46
	v_rcp_iflag_f32_e32 v47, v47
	v_rcp_iflag_f32_e32 v40, v128
	v_rcp_iflag_f32_e32 v41, v129
	v_rcp_iflag_f32_e32 v128, v130
	v_rcp_iflag_f32_e32 v129, v131
	v_cvt_f32_ubyte3_e32 v131, v34
	v_cvt_f32_ubyte2_e32 v130, v34
	v_cvt_f32_ubyte0_e32 v132, v34
	v_pk_mul_f32 v[36:37], v[36:37], v[132:133]
	v_pk_mul_f32 v[46:47], v[46:47], v[130:131]
	v_pk_mul_f32 v[132:133], v[156:157], v[36:37]
	v_pk_mul_f32 v[134:135], v[158:159], v[46:47]
	v_cvt_f32_ubyte3_e32 v37, v35
	v_cvt_f32_ubyte2_e32 v36, v35
	v_cvt_f32_ubyte1_e32 v47, v35
	v_cvt_f32_ubyte0_e32 v46, v35
	v_pk_mul_f32 v[34:35], v[40:41], v[46:47]
	v_pk_mul_f32 v[36:37], v[128:129], v[36:37]
	v_cvt_f32_ubyte2_e32 v40, v38
	v_cvt_f32_ubyte3_e32 v41, v38
	v_pk_mul_f32 v[130:131], v[154:155], v[36:37]
	v_pk_mul_f32 v[128:129], v[152:153], v[34:35]
	v_cvt_f32_ubyte0_e32 v34, v38
	v_cvt_f32_ubyte1_e32 v35, v38
	v_cvt_f32_ubyte0_e32 v36, v39
	v_cvt_f32_ubyte1_e32 v37, v39
	v_cvt_f32_ubyte2_e32 v46, v39
	v_cvt_f32_ubyte3_e32 v47, v39
	v_rcp_iflag_f32_e32 v38, v40
	v_rcp_iflag_f32_e32 v39, v41
	v_rcp_iflag_f32_e32 v34, v34
	v_rcp_iflag_f32_e32 v35, v35
	v_rcp_iflag_f32_e32 v36, v36
	v_rcp_iflag_f32_e32 v37, v37
	v_rcp_iflag_f32_e32 v40, v46
	v_rcp_iflag_f32_e32 v41, v47
	v_cvt_f32_ubyte3_e32 v47, v32
	v_cvt_f32_ubyte2_e32 v46, v32
	v_cvt_f32_ubyte1_e32 v143, v32
	v_cvt_f32_ubyte0_e32 v142, v32
	v_pk_mul_f32 v[38:39], v[38:39], v[46:47]
	v_pk_mul_f32 v[34:35], v[34:35], v[142:143]
	v_pk_mul_f32 v[126:127], v[126:127], v[38:39]
	v_cvt_f32_ubyte1_e32 v39, v33
	v_cvt_f32_ubyte0_e32 v38, v33
	v_pk_mul_f32 v[124:125], v[124:125], v[34:35]
	v_cvt_f32_ubyte3_e32 v35, v33
	v_cvt_f32_ubyte2_e32 v34, v33
	v_pk_mul_f32 v[32:33], v[36:37], v[38:39]
	v_pk_mul_f32 v[34:35], v[40:41], v[34:35]
	v_pk_mul_f32 v[120:121], v[120:121], v[32:33]
	v_pk_mul_f32 v[122:123], v[122:123], v[34:35]
	s_waitcnt vmcnt(0) lgkmcnt(0)
	v_cvt_f32_ubyte3_e32 v41, v42
	v_cvt_f32_ubyte0_e32 v32, v44
	v_cvt_f32_ubyte1_e32 v33, v44
	v_cvt_f32_ubyte2_e32 v36, v44
	v_cvt_f32_ubyte3_e32 v37, v44
	v_rcp_iflag_f32_e32 v32, v32
	v_rcp_iflag_f32_e32 v33, v33
	v_cvt_f32_ubyte2_e32 v38, v45
	v_cvt_f32_ubyte3_e32 v39, v45
	v_rcp_iflag_f32_e32 v36, v36
	v_rcp_iflag_f32_e32 v37, v37
	v_cvt_f32_ubyte0_e32 v34, v45
	v_cvt_f32_ubyte1_e32 v35, v45
	v_rcp_iflag_f32_e32 v38, v38
	v_rcp_iflag_f32_e32 v39, v39
	v_rcp_iflag_f32_e32 v34, v34
	v_rcp_iflag_f32_e32 v35, v35
	v_cvt_f32_ubyte1_e32 v45, v42
	v_cvt_f32_ubyte0_e32 v44, v42
	v_cvt_f32_ubyte2_e32 v40, v42
	v_pk_mul_f32 v[32:33], v[32:33], v[44:45]
	v_pk_mul_f32 v[36:37], v[36:37], v[40:41]
	v_pk_mul_f32 v[44:45], v[148:149], v[32:33]
	v_cvt_f32_ubyte3_e32 v33, v43
	v_cvt_f32_ubyte2_e32 v32, v43
	v_pk_mul_f32 v[46:47], v[150:151], v[36:37]
	v_cvt_f32_ubyte1_e32 v37, v43
	v_cvt_f32_ubyte0_e32 v36, v43
	v_pk_mul_f32 v[32:33], v[38:39], v[32:33]
	v_pk_mul_f32 v[34:35], v[34:35], v[36:37]
	v_pk_mul_f32 v[42:43], v[146:147], v[32:33]
	v_cvt_f32_ubyte0_e32 v32, v140
	v_cvt_f32_ubyte1_e32 v33, v140
	v_cvt_f32_ubyte2_e32 v36, v140
	v_cvt_f32_ubyte3_e32 v37, v140
	v_rcp_iflag_f32_e32 v32, v32
	v_rcp_iflag_f32_e32 v33, v33
	v_rcp_iflag_f32_e32 v36, v36
	v_rcp_iflag_f32_e32 v37, v37
	v_pk_mul_f32 v[40:41], v[144:145], v[34:35]
	v_cvt_f32_ubyte0_e32 v34, v141
	v_cvt_f32_ubyte1_e32 v35, v141
	v_cvt_f32_ubyte2_e32 v38, v141
	v_cvt_f32_ubyte3_e32 v39, v141
	v_rcp_iflag_f32_e32 v34, v34
	v_rcp_iflag_f32_e32 v35, v35
	v_rcp_iflag_f32_e32 v140, v38
	v_rcp_iflag_f32_e32 v141, v39
	v_cvt_f32_ubyte3_e32 v39, v138
	v_cvt_f32_ubyte2_e32 v38, v138
	v_cvt_f32_ubyte1_e32 v143, v138
	v_cvt_f32_ubyte0_e32 v142, v138
	v_pk_mul_f32 v[32:33], v[32:33], v[142:143]
	v_pk_mul_f32 v[36:37], v[36:37], v[38:39]
	s_nop 0
	v_pk_mul_f32 v[38:39], v[118:119], v[36:37]
	v_pk_mul_f32 v[36:37], v[116:117], v[32:33]
	v_cvt_f32_ubyte3_e32 v33, v139
	v_cvt_f32_ubyte2_e32 v32, v139
	v_cvt_f32_ubyte1_e32 v117, v139
	v_cvt_f32_ubyte0_e32 v116, v139
	v_pk_mul_f32 v[116:117], v[34:35], v[116:117]
	v_pk_mul_f32 v[32:33], v[140:141], v[32:33]
	s_nop 0
	v_pk_mul_f32 v[34:35], v[114:115], v[32:33]
	v_pk_mul_f32 v[32:33], v[112:113], v[116:117]
	v_lshl_add_u64 v[116:117], v[136:137], 0, s[26:27]
	global_load_dwordx2 v[114:115], v[116:117], off
	global_load_dwordx2 v[118:119], v[116:117], off offset:2048
	global_load_dwordx2 v[112:113], v[116:117], off offset:128
	global_load_dwordx2 v[136:137], v[116:117], off offset:2176
	v_add_co_u32_e32 v138, vcc, s21, v116
	s_waitcnt vmcnt(0) lgkmcnt(0)
;     DI void mid(AccT& acc, const Unit& u, int seg, int wr, int wc, int fr, int fq) const {
;         const int row0 = u.pm * BM + wr * 64 + fr, col0 = u.pn * BM + wc * 32 + 8 * fq;
;         const unsigned char* pa = (const unsigned char*)G + (size_t)row0 * NGATE + seg * 2048 + col0;
; #pragma unroll
;         for (int ai = 0; ai < 2; ++ai) {
; #pragma unroll
;             for (int mh = 0; mh < 2; ++mh) {
;                 u32x2 ra[2][2], rb[2][2];
; #pragma unroll
;                 for (int mm = 0; mm < 2; ++mm)
; #pragma unroll
;                     for (int bj = 0; bj < 2; ++bj) { const unsigned char* p = pa + (size_t)(mm * 16) * NGATE + bj * HALF; ra[mm][bj] = *(const u32x2*)p; rb[mm][bj] = *(const u32x2*)(p + 2048); }
; #pragma unroll
;                 for (int mm = 0; mm < 2; ++mm)
; #pragma unroll
;                     for (int bj = 0; bj < 2; ++bj) {
;                         float ga[8], gb[8];
;                         unpack_gate8(ra[mm][bj], ga); unpack_gate8(rb[mm][bj], gb);
;                         const int m = 2 * mh + mm;
; #pragma unroll
;                         for (int j = 0; j < 4; ++j) { const float r0 = ga[j] * __builtin_amdgcn_rcpf(gb[j]), r1 = ga[4 + j] * __builtin_amdgcn_rcpf(gb[4 + j]);
;                             acc[ai][bj][m][0][j] *= r0; acc[ai][bj][m][1][j] *= r1; } }
;                 pa += (size_t)(mh == 1 ? 96 : 32) * NGATE;
;                 asm volatile("" : "+v"(pa));
;             } }
	v_cvt_f32_ubyte1_e32 v155, v114
	v_addc_co_u32_e32 v139, vcc, 0, v117, vcc
	global_load_dwordx2 v[140:141], v[138:139], off
	global_load_dwordx2 v[142:143], v[138:139], off offset:2048
	global_load_dwordx2 v[144:145], v[138:139], off offset:128
	s_nop 0
	global_load_dwordx2 v[138:139], v[138:139], off offset:2176
	v_cvt_f32_ubyte0_e32 v146, v118
	v_cvt_f32_ubyte1_e32 v147, v118
	v_cvt_f32_ubyte2_e32 v148, v118
	v_cvt_f32_ubyte3_e32 v149, v118
	v_cvt_f32_ubyte0_e32 v150, v119
	v_cvt_f32_ubyte1_e32 v151, v119
	v_cvt_f32_ubyte2_e32 v152, v119
	v_cvt_f32_ubyte3_e32 v153, v119
	v_rcp_iflag_f32_e32 v118, v146
	v_rcp_iflag_f32_e32 v119, v147
	v_rcp_iflag_f32_e32 v148, v148
	v_rcp_iflag_f32_e32 v149, v149
	v_rcp_iflag_f32_e32 v146, v150
	v_rcp_iflag_f32_e32 v147, v151
	v_rcp_iflag_f32_e32 v150, v152
	v_rcp_iflag_f32_e32 v151, v153
	v_cvt_f32_ubyte3_e32 v153, v114
	v_cvt_f32_ubyte2_e32 v152, v114
	v_cvt_f32_ubyte0_e32 v154, v114
	v_pk_mul_f32 v[118:119], v[118:119], v[154:155]
	v_pk_mul_f32 v[148:149], v[148:149], v[152:153]
	v_pk_mul_f32 v[108:109], v[108:109], v[118:119]
	v_pk_mul_f32 v[110:111], v[110:111], v[148:149]
	v_cvt_f32_ubyte3_e32 v119, v115
	v_cvt_f32_ubyte2_e32 v118, v115
	v_cvt_f32_ubyte1_e32 v149, v115
	v_cvt_f32_ubyte0_e32 v148, v115
	v_pk_mul_f32 v[114:115], v[146:147], v[148:149]
	v_pk_mul_f32 v[118:119], v[150:151], v[118:119]
	v_cvt_f32_ubyte2_e32 v146, v136
	v_cvt_f32_ubyte3_e32 v147, v136
	v_pk_mul_f32 v[106:107], v[106:107], v[118:119]
	v_pk_mul_f32 v[104:105], v[104:105], v[114:115]
	v_cvt_f32_ubyte0_e32 v114, v136
	v_cvt_f32_ubyte1_e32 v115, v136
	v_cvt_f32_ubyte0_e32 v118, v137
	v_cvt_f32_ubyte1_e32 v119, v137
	v_cvt_f32_ubyte2_e32 v148, v137
	v_cvt_f32_ubyte3_e32 v149, v137
	v_rcp_iflag_f32_e32 v136, v146
	v_rcp_iflag_f32_e32 v137, v147
	v_rcp_iflag_f32_e32 v114, v114
	v_rcp_iflag_f32_e32 v115, v115
	v_rcp_iflag_f32_e32 v118, v118
	v_rcp_iflag_f32_e32 v119, v119
	v_rcp_iflag_f32_e32 v146, v148
	v_rcp_iflag_f32_e32 v147, v149
	v_cvt_f32_ubyte3_e32 v149, v112
	v_cvt_f32_ubyte2_e32 v148, v112
	v_cvt_f32_ubyte1_e32 v151, v112
	v_cvt_f32_ubyte0_e32 v150, v112
	v_pk_mul_f32 v[136:137], v[136:137], v[148:149]
	v_pk_mul_f32 v[114:115], v[114:115], v[150:151]
	v_pk_mul_f32 v[78:79], v[78:79], v[136:137]
	v_cvt_f32_ubyte1_e32 v137, v113
	v_cvt_f32_ubyte0_e32 v136, v113
	v_pk_mul_f32 v[76:77], v[76:77], v[114:115]
	v_cvt_f32_ubyte3_e32 v115, v113
	v_cvt_f32_ubyte2_e32 v114, v113
	v_pk_mul_f32 v[112:113], v[118:119], v[136:137]
	v_pk_mul_f32 v[114:115], v[146:147], v[114:115]
	v_pk_mul_f32 v[112:113], v[72:73], v[112:113]
	v_pk_mul_f32 v[114:115], v[74:75], v[114:115]
	s_waitcnt vmcnt(0) lgkmcnt(0)
	v_cvt_f32_ubyte1_e32 v147, v140
	v_cvt_f32_ubyte0_e32 v72, v142
	v_cvt_f32_ubyte1_e32 v73, v142
	v_cvt_f32_ubyte2_e32 v118, v142
	v_cvt_f32_ubyte3_e32 v119, v142
	v_rcp_iflag_f32_e32 v72, v72
	v_rcp_iflag_f32_e32 v73, v73
	v_rcp_iflag_f32_e32 v118, v118
	v_rcp_iflag_f32_e32 v119, v119
	v_cvt_f32_ubyte0_e32 v74, v143
	v_cvt_f32_ubyte1_e32 v75, v143
	v_cvt_f32_ubyte2_e32 v136, v143
	v_cvt_f32_ubyte3_e32 v137, v143
	v_rcp_iflag_f32_e32 v74, v74
	v_rcp_iflag_f32_e32 v75, v75
	v_rcp_iflag_f32_e32 v136, v136
	v_rcp_iflag_f32_e32 v137, v137
	v_cvt_f32_ubyte3_e32 v143, v140
	v_cvt_f32_ubyte2_e32 v142, v140
	v_cvt_f32_ubyte0_e32 v146, v140
	v_pk_mul_f32 v[72:73], v[72:73], v[146:147]
	v_pk_mul_f32 v[118:119], v[118:119], v[142:143]
	v_pk_mul_f32 v[100:101], v[100:101], v[72:73]
	v_pk_mul_f32 v[102:103], v[102:103], v[118:119]
	v_cvt_f32_ubyte3_e32 v73, v141
	v_cvt_f32_ubyte2_e32 v72, v141
	v_cvt_f32_ubyte1_e32 v119, v141
	v_cvt_f32_ubyte0_e32 v118, v141
	v_pk_mul_f32 v[118:119], v[74:75], v[118:119]
	v_pk_mul_f32 v[72:73], v[136:137], v[72:73]
	v_cvt_f32_ubyte2_e32 v136, v139
	v_pk_mul_f32 v[74:75], v[98:99], v[72:73]
	v_pk_mul_f32 v[72:73], v[96:97], v[118:119]
	v_cvt_f32_ubyte0_e32 v96, v138
	v_cvt_f32_ubyte1_e32 v97, v138
	v_rcp_iflag_f32_e32 v96, v96
	v_rcp_iflag_f32_e32 v97, v97
	v_cvt_f32_ubyte2_e32 v118, v138
	v_cvt_f32_ubyte3_e32 v119, v138
	v_cvt_f32_ubyte3_e32 v137, v139
	v_rcp_iflag_f32_e32 v118, v118
	v_rcp_iflag_f32_e32 v136, v136
	v_rcp_iflag_f32_e32 v119, v119
	v_rcp_iflag_f32_e32 v137, v137
	v_cvt_f32_ubyte0_e32 v98, v139
	v_cvt_f32_ubyte1_e32 v99, v139
	v_cvt_f32_ubyte1_e32 v141, v144
	v_cvt_f32_ubyte0_e32 v140, v144
	v_rcp_iflag_f32_e32 v98, v98
	v_rcp_iflag_f32_e32 v99, v99
	v_pk_mul_f32 v[96:97], v[96:97], v[140:141]
	v_cvt_f32_ubyte3_e32 v139, v144
	v_cvt_f32_ubyte2_e32 v138, v144
	v_pk_mul_f32 v[68:69], v[68:69], v[96:97]
	v_cvt_f32_ubyte3_e32 v97, v145
	v_cvt_f32_ubyte2_e32 v96, v145
	v_pk_mul_f32 v[118:119], v[118:119], v[138:139]
	v_pk_mul_f32 v[96:97], v[136:137], v[96:97]
	v_pk_mul_f32 v[70:71], v[70:71], v[118:119]
	v_cvt_f32_ubyte1_e32 v119, v145
	v_cvt_f32_ubyte0_e32 v118, v145
	v_pk_mul_f32 v[66:67], v[66:67], v[96:97]
	v_lshl_add_u64 v[96:97], v[116:117], 0, s[24:25]
	v_pk_mul_f32 v[98:99], v[98:99], v[118:119]
	s_nop 0
	v_pk_mul_f32 v[64:65], v[64:65], v[98:99]
	global_load_dwordx2 v[116:117], v[96:97], off
	global_load_dwordx2 v[118:119], v[96:97], off offset:2048
	global_load_dwordx2 v[98:99], v[96:97], off offset:128
	global_load_dwordx2 v[138:139], v[96:97], off offset:2176
	v_add_co_u32_e32 v140, vcc, s21, v96
	s_waitcnt vmcnt(0) lgkmcnt(0)
;     DI void mid(AccT& acc, const Unit& u, int seg, int wr, int wc, int fr, int fq) const {
;         const int row0 = u.pm * BM + wr * 64 + fr, col0 = u.pn * BM + wc * 32 + 8 * fq;
;         const unsigned char* pa = (const unsigned char*)G + (size_t)row0 * NGATE + seg * 2048 + col0;
; #pragma unroll
;         for (int ai = 0; ai < 2; ++ai) {
; #pragma unroll
;             for (int mh = 0; mh < 2; ++mh) {
;                 u32x2 ra[2][2], rb[2][2];
; #pragma unroll
;                 for (int mm = 0; mm < 2; ++mm)
; #pragma unroll
;                     for (int bj = 0; bj < 2; ++bj) { const unsigned char* p = pa + (size_t)(mm * 16) * NGATE + bj * HALF; ra[mm][bj] = *(const u32x2*)p; rb[mm][bj] = *(const u32x2*)(p + 2048); }
; #pragma unroll
;                 for (int mm = 0; mm < 2; ++mm)
; #pragma unroll
;                     for (int bj = 0; bj < 2; ++bj) {
;                         float ga[8], gb[8];
;                         unpack_gate8(ra[mm][bj], ga); unpack_gate8(rb[mm][bj], gb);
;                         const int m = 2 * mh + mm;
; #pragma unroll
;                         for (int j = 0; j < 4; ++j) { const float r0 = ga[j] * __builtin_amdgcn_rcpf(gb[j]), r1 = ga[4 + j] * __builtin_amdgcn_rcpf(gb[4 + j]);
;                             acc[ai][bj][m][0][j] *= r0; acc[ai][bj][m][1][j] *= r1; } }
;                 pa += (size_t)(mh == 1 ? 96 : 32) * NGATE;
;                 asm volatile("" : "+v"(pa));
;             } }
	v_cvt_f32_ubyte1_e32 v155, v116
	v_addc_co_u32_e32 v141, vcc, 0, v97, vcc
	global_load_dwordx2 v[142:143], v[140:141], off
	global_load_dwordx2 v[144:145], v[140:141], off offset:2048
	global_load_dwordx2 v[136:137], v[140:141], off offset:128
	s_nop 0
	global_load_dwordx2 v[140:141], v[140:141], off offset:2176
	v_cvt_f32_ubyte0_e32 v146, v118
	v_cvt_f32_ubyte1_e32 v147, v118
	v_cvt_f32_ubyte2_e32 v148, v118
	v_cvt_f32_ubyte3_e32 v149, v118
	v_cvt_f32_ubyte0_e32 v150, v119
	v_cvt_f32_ubyte1_e32 v151, v119
	v_cvt_f32_ubyte2_e32 v152, v119
	v_cvt_f32_ubyte3_e32 v153, v119
	v_rcp_iflag_f32_e32 v118, v146
	v_rcp_iflag_f32_e32 v119, v147
	v_rcp_iflag_f32_e32 v148, v148
	v_rcp_iflag_f32_e32 v149, v149
	v_rcp_iflag_f32_e32 v146, v150
	v_rcp_iflag_f32_e32 v147, v151
	v_rcp_iflag_f32_e32 v150, v152
	v_rcp_iflag_f32_e32 v151, v153
	v_cvt_f32_ubyte3_e32 v153, v116
	v_cvt_f32_ubyte2_e32 v152, v116
	v_cvt_f32_ubyte0_e32 v154, v116
	v_pk_mul_f32 v[118:119], v[118:119], v[154:155]
	v_pk_mul_f32 v[148:149], v[148:149], v[152:153]
	v_pk_mul_f32 v[92:93], v[92:93], v[118:119]
	v_pk_mul_f32 v[94:95], v[94:95], v[148:149]
	v_cvt_f32_ubyte3_e32 v119, v117
	v_cvt_f32_ubyte2_e32 v118, v117
	v_cvt_f32_ubyte1_e32 v149, v117
	v_cvt_f32_ubyte0_e32 v148, v117
	v_pk_mul_f32 v[116:117], v[146:147], v[148:149]
	v_pk_mul_f32 v[118:119], v[150:151], v[118:119]
	v_cvt_f32_ubyte2_e32 v146, v138
	v_cvt_f32_ubyte3_e32 v147, v138
	v_pk_mul_f32 v[90:91], v[90:91], v[118:119]
	v_pk_mul_f32 v[88:89], v[88:89], v[116:117]
	v_cvt_f32_ubyte0_e32 v116, v138
	v_cvt_f32_ubyte1_e32 v117, v138
	v_cvt_f32_ubyte0_e32 v118, v139
	v_cvt_f32_ubyte1_e32 v119, v139
	v_cvt_f32_ubyte2_e32 v148, v139
	v_cvt_f32_ubyte3_e32 v149, v139
	v_rcp_iflag_f32_e32 v138, v146
	v_rcp_iflag_f32_e32 v139, v147
	v_rcp_iflag_f32_e32 v116, v116
	v_rcp_iflag_f32_e32 v117, v117
	v_rcp_iflag_f32_e32 v118, v118
	v_rcp_iflag_f32_e32 v119, v119
	v_rcp_iflag_f32_e32 v146, v148
	v_rcp_iflag_f32_e32 v147, v149
	v_cvt_f32_ubyte3_e32 v149, v98
	v_cvt_f32_ubyte2_e32 v148, v98
	v_cvt_f32_ubyte1_e32 v151, v98
	v_cvt_f32_ubyte0_e32 v150, v98
	v_pk_mul_f32 v[138:139], v[138:139], v[148:149]
	v_pk_mul_f32 v[116:117], v[116:117], v[150:151]
	v_pk_mul_f32 v[62:63], v[62:63], v[138:139]
	v_cvt_f32_ubyte1_e32 v139, v99
	v_cvt_f32_ubyte0_e32 v138, v99
	v_pk_mul_f32 v[60:61], v[60:61], v[116:117]
	v_cvt_f32_ubyte3_e32 v117, v99
	v_cvt_f32_ubyte2_e32 v116, v99
	v_pk_mul_f32 v[98:99], v[118:119], v[138:139]
	v_pk_mul_f32 v[116:117], v[146:147], v[116:117]
	v_pk_mul_f32 v[56:57], v[56:57], v[98:99]
	v_pk_mul_f32 v[58:59], v[58:59], v[116:117]
	v_lshl_add_u64 v[96:97], v[96:97], 0, s[26:27]
	s_waitcnt vmcnt(0) lgkmcnt(0)
	v_cvt_f32_ubyte1_e32 v147, v142
	v_cvt_f32_ubyte0_e32 v98, v144
	v_cvt_f32_ubyte1_e32 v99, v144
	v_cvt_f32_ubyte2_e32 v118, v144
	v_cvt_f32_ubyte3_e32 v119, v144
	v_rcp_iflag_f32_e32 v98, v98
	v_rcp_iflag_f32_e32 v99, v99
	v_cvt_f32_ubyte2_e32 v138, v145
	v_cvt_f32_ubyte3_e32 v139, v145
	v_rcp_iflag_f32_e32 v118, v118
	v_rcp_iflag_f32_e32 v119, v119
	v_cvt_f32_ubyte0_e32 v116, v145
	v_cvt_f32_ubyte1_e32 v117, v145
	v_rcp_iflag_f32_e32 v138, v138
	v_rcp_iflag_f32_e32 v139, v139
	v_rcp_iflag_f32_e32 v116, v116
	v_rcp_iflag_f32_e32 v117, v117
	v_cvt_f32_ubyte0_e32 v146, v142
	v_cvt_f32_ubyte3_e32 v145, v142
	v_cvt_f32_ubyte2_e32 v144, v142
	v_pk_mul_f32 v[98:99], v[98:99], v[146:147]
	v_pk_mul_f32 v[118:119], v[118:119], v[144:145]
	v_pk_mul_f32 v[84:85], v[84:85], v[98:99]
	v_cvt_f32_ubyte3_e32 v99, v143
	v_cvt_f32_ubyte2_e32 v98, v143
	v_pk_mul_f32 v[86:87], v[86:87], v[118:119]
	v_cvt_f32_ubyte1_e32 v119, v143
	v_cvt_f32_ubyte0_e32 v118, v143
	v_pk_mul_f32 v[98:99], v[138:139], v[98:99]
	v_pk_mul_f32 v[116:117], v[116:117], v[118:119]
	v_pk_mul_f32 v[82:83], v[82:83], v[98:99]
	v_cvt_f32_ubyte0_e32 v98, v140
	v_cvt_f32_ubyte1_e32 v99, v140
	v_cvt_f32_ubyte2_e32 v118, v140
	v_cvt_f32_ubyte3_e32 v119, v140
	v_rcp_iflag_f32_e32 v98, v98
	v_rcp_iflag_f32_e32 v99, v99
	v_rcp_iflag_f32_e32 v118, v118
	v_rcp_iflag_f32_e32 v119, v119
	v_pk_mul_f32 v[80:81], v[80:81], v[116:117]
	v_cvt_f32_ubyte0_e32 v116, v141
	v_cvt_f32_ubyte1_e32 v117, v141
	v_cvt_f32_ubyte2_e32 v138, v141
	v_cvt_f32_ubyte3_e32 v139, v141
	v_rcp_iflag_f32_e32 v116, v116
	v_rcp_iflag_f32_e32 v117, v117
	v_rcp_iflag_f32_e32 v138, v138
	v_rcp_iflag_f32_e32 v139, v139
	v_cvt_f32_ubyte3_e32 v141, v136
	v_cvt_f32_ubyte2_e32 v140, v136
	v_cvt_f32_ubyte1_e32 v143, v136
	v_cvt_f32_ubyte0_e32 v142, v136
	v_pk_mul_f32 v[98:99], v[98:99], v[142:143]
	v_pk_mul_f32 v[118:119], v[118:119], v[140:141]
	v_pk_mul_f32 v[52:53], v[52:53], v[98:99]
	v_pk_mul_f32 v[54:55], v[54:55], v[118:119]
	v_cvt_f32_ubyte3_e32 v99, v137
	v_cvt_f32_ubyte2_e32 v98, v137
	v_cvt_f32_ubyte1_e32 v119, v137
	v_cvt_f32_ubyte0_e32 v118, v137
	v_pk_mul_f32 v[116:117], v[116:117], v[118:119]
	v_pk_mul_f32 v[98:99], v[138:139], v[98:99]
	v_pk_mul_f32 v[48:49], v[48:49], v[116:117]
	v_pk_mul_f32 v[50:51], v[50:51], v[98:99]
.LBB0_1323:
	s_add_u32 s12, s16, s6
	s_addc_u32 s13, s18, s7
	ds_read_b128 v[96:99], v209
	ds_read_b128 v[116:119], v209 offset:1024
	ds_read_b128 v[136:139], v209 offset:2048
	ds_read_b128 v[140:143], v209 offset:3072
	s_add_u32 s2, s12, 0x16d00100
	s_addc_u32 s3, s13, 0
	s_add_u32 s14, s5, s6
	s_addc_u32 s15, s10, s7
	s_cmpk_eq_i32 s6, 0x300
	s_cselect_b32 s19, s1, 0x200
	s_cselect_b32 s9, s41, s3
	s_cselect_b32 s8, s40, s2
	s_cselect_b32 s2, s34, s14
	s_cselect_b32 s3, s35, s15
	s_lshl_b32 s14, s19, 8
	v_add_u32_e32 v160, v170, v204
	v_lshl_add_u64 v[166:167], s[12:13], 0, v[160:161]
	s_mov_b32 m0, s17
	v_lshl_add_u64 v[166:167], v[166:167], 0, s[92:93]
	v_add_u32_e32 v160, v172, v205
	ds_read_b128 v[144:147], v203
	ds_read_b128 v[148:151], v203 offset:1024
	ds_read_b128 v[152:155], v203 offset:2048
	ds_read_b128 v[156:159], v203 offset:3072
	ds_read_b128 v[180:183], v203 offset:4096
	ds_read_b128 v[214:217], v203 offset:5120
	ds_read_b128 v[218:221], v203 offset:6144
	ds_read_b128 v[222:225], v203 offset:7168
	global_load_lds_dwordx4 v[166:167], off
	v_lshl_add_u64 v[166:167], s[12:13], 0, v[160:161]
	v_lshl_add_u64 v[166:167], v[166:167], 0, s[92:93]
	s_mov_b32 m0, s86
	s_nop 0
	global_load_lds_dwordx4 v[166:167], off
	s_waitcnt lgkmcnt(8)
	s_barrier
	s_waitcnt lgkmcnt(0)
	s_setprio 1
	s_waitcnt lgkmcnt(0)
	v_mfma_f32_16x16x32_bf16 v[28:31], v[96:99], v[144:147], v[28:31]
	v_mfma_f32_16x16x32_bf16 v[24:27], v[136:139], v[144:147], v[24:27]
	v_mfma_f32_16x16x32_bf16 v[12:15], v[96:99], v[152:155], v[12:15]
	v_mfma_f32_16x16x32_bf16 v[8:11], v[136:139], v[152:155], v[8:11]
	v_mfma_f32_16x16x32_bf16 v[132:135], v[96:99], v[180:183], v[132:135]
	v_mfma_f32_16x16x32_bf16 v[128:131], v[136:139], v[180:183], v[128:131]
	v_mfma_f32_16x16x32_bf16 v[44:47], v[96:99], v[218:221], v[44:47]
	v_mfma_f32_16x16x32_bf16 v[40:43], v[136:139], v[218:221], v[40:43]
	v_mfma_f32_16x16x32_bf16 v[28:31], v[116:119], v[148:151], v[28:31]
	v_mfma_f32_16x16x32_bf16 v[24:27], v[140:143], v[148:151], v[24:27]
	v_mfma_f32_16x16x32_bf16 v[12:15], v[116:119], v[156:159], v[12:15]
	v_mfma_f32_16x16x32_bf16 v[8:11], v[140:143], v[156:159], v[8:11]
	v_mfma_f32_16x16x32_bf16 v[132:135], v[116:119], v[214:217], v[132:135]
	v_mfma_f32_16x16x32_bf16 v[128:131], v[140:143], v[214:217], v[128:131]
	v_mfma_f32_16x16x32_bf16 v[44:47], v[116:119], v[222:225], v[44:47]
	v_mfma_f32_16x16x32_bf16 v[40:43], v[140:143], v[222:225], v[40:43]
	s_setprio 0
	s_barrier
	s_mov_b32 m0, s87
	v_mad_u64_u32 v[166:167], s[12:13], s19, v199, v[170:171]
	ds_read_b128 v[226:229], v210
	ds_read_b128 v[230:233], v210 offset:1024
	ds_read_b128 v[234:237], v210 offset:2048
	ds_read_b128 v[238:241], v210 offset:3072
	global_load_lds_dwordx4 v166, s[2:3]
	v_mad_u64_u32 v[168:169], s[12:13], s19, v200, v[172:173]
	s_mov_b32 m0, s36
	v_mov_b32_e32 v167, v161
	global_load_lds_dwordx4 v168, s[2:3]
	s_barrier
	s_waitcnt lgkmcnt(0)
	v_mov_b32_e32 v169, v161
	v_lshl_add_u64 v[184:185], s[2:3], 0, v[166:167]
	v_lshl_add_u64 v[190:191], s[2:3], 0, v[168:169]
	s_setprio 1
	s_waitcnt lgkmcnt(0)
	v_mfma_f32_16x16x32_bf16 v[20:23], v[226:229], v[144:147], v[20:23]
	v_mfma_f32_16x16x32_bf16 v[16:19], v[234:237], v[144:147], v[16:19]
	v_mfma_f32_16x16x32_bf16 v[4:7], v[226:229], v[152:155], v[4:7]
	v_mfma_f32_16x16x32_bf16 v[0:3], v[234:237], v[152:155], v[0:3]
	v_mfma_f32_16x16x32_bf16 v[124:127], v[226:229], v[180:183], v[124:127]
	v_mfma_f32_16x16x32_bf16 v[120:123], v[234:237], v[180:183], v[120:123]
	v_mfma_f32_16x16x32_bf16 v[36:39], v[226:229], v[218:221], v[36:39]
	v_mfma_f32_16x16x32_bf16 v[32:35], v[234:237], v[218:221], v[32:35]
	v_mfma_f32_16x16x32_bf16 v[20:23], v[230:233], v[148:151], v[20:23]
	v_mfma_f32_16x16x32_bf16 v[16:19], v[238:241], v[148:151], v[16:19]
	v_mfma_f32_16x16x32_bf16 v[4:7], v[230:233], v[156:159], v[4:7]
	v_mfma_f32_16x16x32_bf16 v[0:3], v[238:241], v[156:159], v[0:3]
	v_mfma_f32_16x16x32_bf16 v[124:127], v[230:233], v[214:217], v[124:127]
	v_mfma_f32_16x16x32_bf16 v[120:123], v[238:241], v[214:217], v[120:123]
	v_mfma_f32_16x16x32_bf16 v[36:39], v[230:233], v[222:225], v[36:39]
	v_mfma_f32_16x16x32_bf16 v[32:35], v[238:241], v[222:225], v[32:35]
	s_setprio 0
	s_mov_b32 m0, s60
	v_mad_u64_u32 v[242:243], s[12:13], s19, v171, v[170:171]
	s_barrier
	ds_read_b128 v[144:147], v203 offset:16384
	ds_read_b128 v[148:151], v203 offset:17408
	ds_read_b128 v[152:155], v203 offset:18432
	ds_read_b128 v[156:159], v203 offset:19456
	ds_read_b128 v[180:183], v203 offset:20480
	ds_read_b128 v[214:217], v203 offset:21504
	ds_read_b128 v[218:221], v203 offset:22528
	ds_read_b128 v[222:225], v203 offset:23552
	global_load_lds_dwordx4 v242, s[8:9]
	v_mad_u64_u32 v[244:245], s[12:13], s19, v173, v[172:173]
	s_mov_b32 m0, s61
	v_mov_b32_e32 v243, v161
	global_load_lds_dwordx4 v244, s[8:9]
	s_barrier
	s_waitcnt lgkmcnt(0)
	v_mov_b32_e32 v245, v161
	v_lshl_add_u64 v[246:247], s[8:9], 0, v[242:243]
	v_lshl_add_u64 v[248:249], s[8:9], 0, v[244:245]
	s_setprio 1
	s_waitcnt lgkmcnt(0)
	v_mfma_f32_16x16x32_bf16 v[108:111], v[96:99], v[144:147], v[108:111]
	v_mfma_f32_16x16x32_bf16 v[104:107], v[136:139], v[144:147], v[104:107]
	v_mfma_f32_16x16x32_bf16 v[100:103], v[96:99], v[152:155], v[100:103]
	v_mfma_f32_16x16x32_bf16 v[72:75], v[136:139], v[152:155], v[72:75]
	v_mfma_f32_16x16x32_bf16 v[92:95], v[96:99], v[180:183], v[92:95]
	v_mfma_f32_16x16x32_bf16 v[88:91], v[136:139], v[180:183], v[88:91]
	v_mfma_f32_16x16x32_bf16 v[84:87], v[96:99], v[218:221], v[84:87]
	v_mfma_f32_16x16x32_bf16 v[80:83], v[136:139], v[218:221], v[80:83]
	v_mfma_f32_16x16x32_bf16 v[108:111], v[116:119], v[148:151], v[108:111]
	v_mfma_f32_16x16x32_bf16 v[104:107], v[140:143], v[148:151], v[104:107]
	v_mfma_f32_16x16x32_bf16 v[100:103], v[116:119], v[156:159], v[100:103]
	v_mfma_f32_16x16x32_bf16 v[72:75], v[140:143], v[156:159], v[72:75]
	v_mfma_f32_16x16x32_bf16 v[92:95], v[116:119], v[214:217], v[92:95]
	v_mfma_f32_16x16x32_bf16 v[88:91], v[140:143], v[214:217], v[88:91]
	v_mfma_f32_16x16x32_bf16 v[84:87], v[116:119], v[222:225], v[84:87]
	v_mfma_f32_16x16x32_bf16 v[80:83], v[140:143], v[222:225], v[80:83]
	s_setprio 0
	s_barrier
	s_add_u32 s2, s2, s14
	s_mov_b32 m0, s37
	s_addc_u32 s3, s3, 0
	global_load_lds_dwordx4 v166, s[2:3]
	s_mov_b32 m0, s70
	v_lshl_add_u64 v[166:167], s[2:3], 0, v[166:167]
	global_load_lds_dwordx4 v168, s[2:3]
	s_waitcnt vmcnt(6)
	v_lshl_add_u64 v[168:169], s[2:3], 0, v[168:169]
	s_barrier
	s_setprio 1
	v_mfma_f32_16x16x32_bf16 v[76:79], v[226:229], v[144:147], v[76:79]
	v_mfma_f32_16x16x32_bf16 v[68:71], v[226:229], v[152:155], v[68:71]
	v_mfma_f32_16x16x32_bf16 v[64:67], v[234:237], v[152:155], v[64:67]
	v_mfma_f32_16x16x32_bf16 v[60:63], v[226:229], v[180:183], v[60:63]
	v_mfma_f32_16x16x32_bf16 v[56:59], v[234:237], v[180:183], v[56:59]
	v_mfma_f32_16x16x32_bf16 v[52:55], v[226:229], v[218:221], v[52:55]
	v_mfma_f32_16x16x32_bf16 v[48:51], v[234:237], v[218:221], v[48:51]
	v_mfma_f32_16x16x32_bf16 v[76:79], v[230:233], v[148:151], v[76:79]
	v_mfma_f32_16x16x32_bf16 v[96:99], v[234:237], v[144:147], v[112:115]
	v_mfma_f32_16x16x32_bf16 v[68:71], v[230:233], v[156:159], v[68:71]
	v_mfma_f32_16x16x32_bf16 v[64:67], v[238:241], v[156:159], v[64:67]
	v_mfma_f32_16x16x32_bf16 v[60:63], v[230:233], v[214:217], v[60:63]
	v_mfma_f32_16x16x32_bf16 v[56:59], v[238:241], v[214:217], v[56:59]
	v_mfma_f32_16x16x32_bf16 v[52:55], v[230:233], v[222:225], v[52:55]
	v_mfma_f32_16x16x32_bf16 v[48:51], v[238:241], v[222:225], v[48:51]
	v_mfma_f32_16x16x32_bf16 v[96:99], v[238:241], v[148:151], v[96:99]
	s_setprio 0
	s_barrier
	ds_read_b128 v[112:115], v211
	ds_read_b128 v[116:119], v211 offset:1024
	ds_read_b128 v[136:139], v211 offset:2048
	ds_read_b128 v[140:143], v211 offset:3072
	s_add_u32 s2, s8, s14
	s_addc_u32 s3, s9, 0
	s_mov_b32 m0, s62
	ds_read_b128 v[144:147], v203 offset:32768
	ds_read_b128 v[148:151], v203 offset:33792
	ds_read_b128 v[152:155], v203 offset:34816
	ds_read_b128 v[156:159], v203 offset:35840
	ds_read_b128 v[180:183], v203 offset:36864
	ds_read_b128 v[214:217], v203 offset:37888
	ds_read_b128 v[218:221], v203 offset:38912
	ds_read_b128 v[222:225], v203 offset:39936
	global_load_lds_dwordx4 v242, s[2:3]
	s_mov_b32 m0, s63
	s_nop 0
	global_load_lds_dwordx4 v244, s[2:3]
	s_waitcnt lgkmcnt(8)
	s_barrier
	s_waitcnt lgkmcnt(0)
	s_setprio 1
	s_waitcnt lgkmcnt(0)
	v_mfma_f32_16x16x32_bf16 v[28:31], v[112:115], v[144:147], v[28:31]
	v_mfma_f32_16x16x32_bf16 v[24:27], v[136:139], v[144:147], v[24:27]
	v_mfma_f32_16x16x32_bf16 v[12:15], v[112:115], v[152:155], v[12:15]
	v_mfma_f32_16x16x32_bf16 v[8:11], v[136:139], v[152:155], v[8:11]
	v_mfma_f32_16x16x32_bf16 v[132:135], v[112:115], v[180:183], v[132:135]
	v_mfma_f32_16x16x32_bf16 v[128:131], v[136:139], v[180:183], v[128:131]
	v_mfma_f32_16x16x32_bf16 v[44:47], v[112:115], v[218:221], v[44:47]
	v_mfma_f32_16x16x32_bf16 v[40:43], v[136:139], v[218:221], v[40:43]
	v_mfma_f32_16x16x32_bf16 v[28:31], v[116:119], v[148:151], v[28:31]
	v_mfma_f32_16x16x32_bf16 v[24:27], v[140:143], v[148:151], v[24:27]
	v_mfma_f32_16x16x32_bf16 v[12:15], v[116:119], v[156:159], v[12:15]
	v_mfma_f32_16x16x32_bf16 v[8:11], v[140:143], v[156:159], v[8:11]
	v_mfma_f32_16x16x32_bf16 v[132:135], v[116:119], v[214:217], v[132:135]
	v_mfma_f32_16x16x32_bf16 v[128:131], v[140:143], v[214:217], v[128:131]
	v_mfma_f32_16x16x32_bf16 v[44:47], v[116:119], v[222:225], v[44:47]
	v_mfma_f32_16x16x32_bf16 v[40:43], v[140:143], v[222:225], v[40:43]
	s_setprio 0
	s_barrier
	s_mov_b32 m0, s54
	v_lshl_add_u64 v[184:185], v[184:185], 0, s[78:79]
	ds_read_b128 v[226:229], v212
	ds_read_b128 v[230:233], v212 offset:1024
	ds_read_b128 v[234:237], v212 offset:2048
	ds_read_b128 v[238:241], v212 offset:3072
	global_load_lds_dwordx4 v[184:185], off
	v_lshl_add_u64 v[184:185], v[190:191], 0, s[78:79]
	s_mov_b32 m0, s55
	s_nop 0
	global_load_lds_dwordx4 v[184:185], off
	s_barrier
	s_waitcnt lgkmcnt(0)
	s_setprio 1
	s_waitcnt lgkmcnt(0)
	v_mfma_f32_16x16x32_bf16 v[20:23], v[226:229], v[144:147], v[20:23]
	v_mfma_f32_16x16x32_bf16 v[16:19], v[234:237], v[144:147], v[16:19]
	v_mfma_f32_16x16x32_bf16 v[4:7], v[226:229], v[152:155], v[4:7]
	v_mfma_f32_16x16x32_bf16 v[0:3], v[234:237], v[152:155], v[0:3]
	v_mfma_f32_16x16x32_bf16 v[124:127], v[226:229], v[180:183], v[124:127]
	v_mfma_f32_16x16x32_bf16 v[120:123], v[234:237], v[180:183], v[120:123]
	v_mfma_f32_16x16x32_bf16 v[36:39], v[226:229], v[218:221], v[36:39]
	v_mfma_f32_16x16x32_bf16 v[32:35], v[234:237], v[218:221], v[32:35]
	v_mfma_f32_16x16x32_bf16 v[20:23], v[230:233], v[148:151], v[20:23]
	v_mfma_f32_16x16x32_bf16 v[16:19], v[238:241], v[148:151], v[16:19]
	v_mfma_f32_16x16x32_bf16 v[4:7], v[230:233], v[156:159], v[4:7]
	v_mfma_f32_16x16x32_bf16 v[0:3], v[238:241], v[156:159], v[0:3]
	v_mfma_f32_16x16x32_bf16 v[124:127], v[230:233], v[214:217], v[124:127]
	v_mfma_f32_16x16x32_bf16 v[120:123], v[238:241], v[214:217], v[120:123]
	v_mfma_f32_16x16x32_bf16 v[36:39], v[230:233], v[222:225], v[36:39]
	v_mfma_f32_16x16x32_bf16 v[32:35], v[238:241], v[222:225], v[32:35]
	s_setprio 0
	s_mov_b32 m0, s74
	v_lshl_add_u64 v[184:185], v[246:247], 0, s[78:79]
	s_barrier
	ds_read_b128 v[144:147], v203 offset:49152
	ds_read_b128 v[148:151], v203 offset:50176
	ds_read_b128 v[152:155], v203 offset:51200
	ds_read_b128 v[156:159], v203 offset:52224
	ds_read_b128 v[180:183], v203 offset:53248
	ds_read_b128 v[214:217], v203 offset:54272
	ds_read_b128 v[218:221], v203 offset:55296
	ds_read_b128 v[222:225], v203 offset:56320
	global_load_lds_dwordx4 v[184:185], off
	v_lshl_add_u64 v[184:185], v[248:249], 0, s[78:79]
	s_mov_b32 m0, s75
	s_nop 0
	global_load_lds_dwordx4 v[184:185], off
	s_barrier
; DI u32x4 pack8(const float* v) { u32x4 w; w.x = pk2(v[0], v[1]); w.y = pk2(v[2], v[3]); w.z = pk2(v[4], v[5]); w.w = pk2(v[6], v[7]); return w; }
;     DI void fin(const AccT& acc, const Unit& u, int wr, int wc, int fr, int fq) const {
;         const int row0 = u.pm * BM + wr * 64 + fr, col0 = u.pn * BM + wc * 32 + 8 * fq;
;         const unsigned char* pg = (const unsigned char*)G + (size_t)row0 * NGATE + 4096 + col0;
;         bf16_t* pm_ = Mg + (size_t)row0 * D_ + col0;
;         f32x4 bv[2][2];
; #pragma unroll
;         for (int bj = 0; bj < 2; ++bj)
; #pragma unroll
;             for (int n = 0; n < 2; ++n) bv[bj][n] = *(const f32x4*)(bias + col0 + bj * HALF + 4 * n);
; #pragma unroll
;         for (int ai = 0; ai < 2; ++ai) {
; #pragma unroll
;             for (int mh = 0; mh < 2; ++mh) {
;                 u32x2 rg[2][2];
; #pragma unroll
;                 for (int mm = 0; mm < 2; ++mm)
; #pragma unroll
;                     for (int bj = 0; bj < 2; ++bj) rg[mm][bj] = *(const u32x2*)(pg + (size_t)(mm * 16) * NGATE + bj * HALF);
; #pragma unroll
;                 for (int mm = 0; mm < 2; ++mm)
; #pragma unroll
;                     for (int bj = 0; bj < 2; ++bj) {
;                         const int m = 2 * mh + mm;
;                         float gv[8], o[8];
;                         unpack_gate8(rg[mm][bj], gv);
;                         const f32x4 v0 = acc[ai][bj][m][0] + bv[bj][0], v1 = acc[ai][bj][m][1] + bv[bj][1];
; #pragma unroll
;                         for (int j = 0; j < 4; ++j) { o[j] = gv[j] * (1.f / 255.f) * v0[j]; o[4 + j] = gv[4 + j] * (1.f / 255.f) * v1[j]; }
;                         *(u32x4*)(pm_ + (size_t)(mm * 16) * D_ + bj * HALF) = pack8(o); }
;                 pg += (size_t)(mh == 1 ? 96 : 32) * NGATE; pm_ += (size_t)(mh == 1 ? 96 : 32) * D_;
;                 asm volatile("" : "+v"(pg), "+v"(pm_));
;             } }
	s_waitcnt lgkmcnt(0)
	s_setprio 1
	s_waitcnt lgkmcnt(0)
	v_mfma_f32_16x16x32_bf16 v[108:111], v[112:115], v[144:147], v[108:111]
	v_mfma_f32_16x16x32_bf16 v[104:107], v[136:139], v[144:147], v[104:107]
	v_mfma_f32_16x16x32_bf16 v[100:103], v[112:115], v[152:155], v[100:103]
	v_mfma_f32_16x16x32_bf16 v[72:75], v[136:139], v[152:155], v[72:75]
	v_mfma_f32_16x16x32_bf16 v[92:95], v[112:115], v[180:183], v[92:95]
	v_mfma_f32_16x16x32_bf16 v[88:91], v[136:139], v[180:183], v[88:91]
	v_mfma_f32_16x16x32_bf16 v[84:87], v[112:115], v[218:221], v[84:87]
	v_mfma_f32_16x16x32_bf16 v[80:83], v[136:139], v[218:221], v[80:83]
	v_mfma_f32_16x16x32_bf16 v[108:111], v[116:119], v[148:151], v[108:111]
	v_mfma_f32_16x16x32_bf16 v[104:107], v[140:143], v[148:151], v[104:107]
	v_mfma_f32_16x16x32_bf16 v[100:103], v[116:119], v[156:159], v[100:103]
	v_mfma_f32_16x16x32_bf16 v[72:75], v[140:143], v[156:159], v[72:75]
	v_mfma_f32_16x16x32_bf16 v[92:95], v[116:119], v[214:217], v[92:95]
	v_mfma_f32_16x16x32_bf16 v[88:91], v[140:143], v[214:217], v[88:91]
	v_mfma_f32_16x16x32_bf16 v[84:87], v[116:119], v[222:225], v[84:87]
	v_mfma_f32_16x16x32_bf16 v[80:83], v[140:143], v[222:225], v[80:83]
	s_setprio 0
	s_barrier
	s_mov_b32 m0, s22
	v_lshl_add_u64 v[112:113], v[166:167], 0, s[78:79]
	global_load_lds_dwordx4 v[112:113], off
	v_lshl_add_u64 v[112:113], v[168:169], 0, s[78:79]
	s_mov_b32 m0, s23
	s_nop 0
	global_load_lds_dwordx4 v[112:113], off
	s_waitcnt vmcnt(6)
	s_barrier
	s_setprio 1
	v_mfma_f32_16x16x32_bf16 v[76:79], v[226:229], v[144:147], v[76:79]
	v_mfma_f32_16x16x32_bf16 v[96:99], v[234:237], v[144:147], v[96:99]
	v_mfma_f32_16x16x32_bf16 v[68:71], v[226:229], v[152:155], v[68:71]
	v_mfma_f32_16x16x32_bf16 v[64:67], v[234:237], v[152:155], v[64:67]
	v_mfma_f32_16x16x32_bf16 v[60:63], v[226:229], v[180:183], v[60:63]
	v_mfma_f32_16x16x32_bf16 v[56:59], v[234:237], v[180:183], v[56:59]
	v_mfma_f32_16x16x32_bf16 v[52:55], v[226:229], v[218:221], v[52:55]
	v_mfma_f32_16x16x32_bf16 v[48:51], v[234:237], v[218:221], v[48:51]
	v_mfma_f32_16x16x32_bf16 v[76:79], v[230:233], v[148:151], v[76:79]
	v_mfma_f32_16x16x32_bf16 v[112:115], v[238:241], v[148:151], v[96:99]
	v_mfma_f32_16x16x32_bf16 v[68:71], v[230:233], v[156:159], v[68:71]
	v_mfma_f32_16x16x32_bf16 v[64:67], v[238:241], v[156:159], v[64:67]
	v_mfma_f32_16x16x32_bf16 v[60:63], v[230:233], v[214:217], v[60:63]
	v_mfma_f32_16x16x32_bf16 v[56:59], v[238:241], v[214:217], v[56:59]
	v_mfma_f32_16x16x32_bf16 v[52:55], v[230:233], v[222:225], v[52:55]
	v_mfma_f32_16x16x32_bf16 v[48:51], v[238:241], v[222:225], v[48:51]
	s_setprio 0
	s_add_i32 s11, s11, 2
	s_add_u32 s6, s6, 0x100
	s_addc_u32 s7, s7, 0
	s_cmp_gt_u32 s11, 5
	s_barrier
	s_cbranch_scc0 .LBB0_1323
	v_add_co_u32_e32 v148, vcc, 0x1000, v174
	v_lshlrev_b64 v[96:97], 12, v[178:179]
	v_lshl_add_u64 v[116:117], v[176:177], 2, s[46:47]
	s_mov_b64 s[2:3], 0x1000
	v_addc_co_u32_e32 v149, vcc, 0, v175, vcc
	v_lshl_add_u64 v[144:145], s[42:43], 0, v[96:97]
	global_load_dwordx4 v[136:139], v[116:117], off offset:16
	global_load_dwordx4 v[140:143], v[116:117], off
	global_load_dwordx4 v[96:99], v[116:117], off offset:528
	s_nop 0
	global_load_dwordx4 v[116:119], v[116:117], off offset:512
	v_lshl_add_u64 v[146:147], v[174:175], 0, s[2:3]
	global_load_dwordx2 v[150:151], v[148:149], off
	global_load_dwordx2 v[152:153], v[146:147], off offset:128
	v_add_co_u32_e32 v146, vcc, 0x19000, v174
	v_lshl_add_u64 v[144:145], v[176:177], 1, v[144:145]
	s_nop 0
	v_addc_co_u32_e32 v147, vcc, 0, v175, vcc
	global_load_dwordx2 v[148:149], v[146:147], off
	s_nop 0
	global_load_dwordx2 v[146:147], v[146:147], off offset:128
	s_mov_b64 s[2:3], 0x31000
	s_mov_b64 s[6:7], 0x60000
	s_mov_b64 s[50:51], s[40:41]
	s_mov_b64 s[52:53], s[34:35]
	s_mov_b32 s12, s1
	s_mov_b32 s5, s4
	s_mov_b32 s14, s56
	s_mov_b32 s16, s0
	v_readlane_b32 s86, v254, 59
	v_readlane_b32 s87, v255, 21
	s_waitcnt vmcnt(0)
	v_pk_add_f32 v[24:25], v[24:25], v[136:137]
	v_pk_add_f32 v[28:29], v[28:29], v[140:141]
	v_pk_add_f32 v[30:31], v[30:31], v[142:143]
	v_pk_add_f32 v[26:27], v[26:27], v[138:139]
	s_waitcnt lgkmcnt(0)
	v_cvt_f32_ubyte1_e32 v155, v150
	v_cvt_f32_ubyte0_e32 v154, v150
	v_pk_mul_f32 v[154:155], v[154:155], s[28:29] op_sel_hi:[1,0]
	v_pk_add_f32 v[20:21], v[20:21], v[116:117]
	v_pk_mul_f32 v[28:29], v[28:29], v[154:155]
	v_cvt_f32_ubyte1_e32 v155, v151
	v_cvt_f32_ubyte0_e32 v154, v151
	v_pk_mul_f32 v[154:155], v[154:155], s[28:29] op_sel_hi:[1,0]
	v_pk_add_f32 v[16:17], v[16:17], v[96:97]
	v_pk_mul_f32 v[154:155], v[24:25], v[154:155]
	v_cvt_f32_ubyte3_e32 v25, v150
	v_cvt_f32_ubyte2_e32 v24, v150
	v_pk_mul_f32 v[24:25], v[24:25], s[28:29] op_sel_hi:[1,0]
	v_pk_add_f32 v[22:23], v[22:23], v[118:119]
	v_pk_mul_f32 v[30:31], v[30:31], v[24:25]
	v_cvt_f32_ubyte3_e32 v25, v151
	v_cvt_f32_ubyte2_e32 v24, v151
	v_pk_mul_f32 v[24:25], v[24:25], s[28:29] op_sel_hi:[1,0]
	v_pk_add_f32 v[18:19], v[18:19], v[98:99]
	v_pk_mul_f32 v[150:151], v[26:27], v[24:25]
	v_cvt_pk_bf16_f32 v24, v28, v29
	v_cvt_pk_bf16_f32 v25, v30, v31
	v_cvt_pk_bf16_f32 v26, v154, v155
	v_cvt_pk_bf16_f32 v27, v150, v151
	global_store_dwordx4 v[144:145], v[24:27], off
	v_pk_add_f32 v[12:13], v[12:13], v[140:141]
	v_pk_add_f32 v[8:9], v[8:9], v[136:137]
	v_cvt_f32_ubyte1_e32 v25, v152
	v_cvt_f32_ubyte0_e32 v24, v152
	v_pk_mul_f32 v[24:25], v[24:25], s[28:29] op_sel_hi:[1,0]
	v_pk_add_f32 v[14:15], v[14:15], v[142:143]
	v_pk_mul_f32 v[20:21], v[20:21], v[24:25]
	v_cvt_f32_ubyte1_e32 v25, v153
	v_cvt_f32_ubyte0_e32 v24, v153
	v_pk_mul_f32 v[24:25], v[24:25], s[28:29] op_sel_hi:[1,0]
	v_pk_add_f32 v[10:11], v[10:11], v[138:139]
; DI u32x4 pack8(const float* v) { u32x4 w; w.x = pk2(v[0], v[1]); w.y = pk2(v[2], v[3]); w.z = pk2(v[4], v[5]); w.w = pk2(v[6], v[7]); return w; }
;     DI void fin(const AccT& acc, const Unit& u, int wr, int wc, int fr, int fq) const {
;     ...
;                     for (int bj = 0; bj < 2; ++bj) rg[mm][bj] = *(const u32x2*)(pg + (size_t)(mm * 16) * NGATE + bj * HALF);
; #pragma unroll
;                 for (int mm = 0; mm < 2; ++mm)
; #pragma unroll
;                     for (int bj = 0; bj < 2; ++bj) {
;                         const int m = 2 * mh + mm;
;                         float gv[8], o[8];
;                         unpack_gate8(rg[mm][bj], gv);
;                         const f32x4 v0 = acc[ai][bj][m][0] + bv[bj][0], v1 = acc[ai][bj][m][1] + bv[bj][1];
; #pragma unroll
;                         for (int j = 0; j < 4; ++j) { o[j] = gv[j] * (1.f / 255.f) * v0[j]; o[4 + j] = gv[4 + j] * (1.f / 255.f) * v1[j]; }
;                         *(u32x4*)(pm_ + (size_t)(mm * 16) * D_ + bj * HALF) = pack8(o); }
;                 pg += (size_t)(mh == 1 ? 96 : 32) * NGATE; pm_ += (size_t)(mh == 1 ? 96 : 32) * D_;
;                 asm volatile("" : "+v"(pg), "+v"(pm_));
;             } }
	v_pk_mul_f32 v[24:25], v[16:17], v[24:25]
	v_cvt_f32_ubyte3_e32 v17, v152
	v_cvt_f32_ubyte2_e32 v16, v152
	v_pk_mul_f32 v[16:17], v[16:17], s[28:29] op_sel_hi:[1,0]
	v_pk_add_f32 v[4:5], v[4:5], v[116:117]
	v_pk_mul_f32 v[22:23], v[22:23], v[16:17]
	v_cvt_f32_ubyte3_e32 v17, v153
	v_cvt_f32_ubyte2_e32 v16, v153
	v_pk_mul_f32 v[16:17], v[16:17], s[28:29] op_sel_hi:[1,0]
	v_pk_add_f32 v[0:1], v[0:1], v[96:97]
	v_pk_mul_f32 v[26:27], v[18:19], v[16:17]
	v_cvt_pk_bf16_f32 v16, v20, v21
	v_cvt_pk_bf16_f32 v17, v22, v23
	v_cvt_pk_bf16_f32 v18, v24, v25
	v_cvt_pk_bf16_f32 v19, v26, v27
	global_store_dwordx4 v[144:145], v[16:19], off offset:256
	v_pk_add_f32 v[6:7], v[6:7], v[118:119]
	v_pk_add_f32 v[2:3], v[2:3], v[98:99]
	v_cvt_f32_ubyte1_e32 v17, v148
	v_cvt_f32_ubyte0_e32 v16, v148
	v_pk_mul_f32 v[16:17], v[16:17], s[28:29] op_sel_hi:[1,0]
	v_pk_add_f32 v[20:21], v[128:129], v[136:137]
	v_pk_mul_f32 v[12:13], v[12:13], v[16:17]
	v_cvt_f32_ubyte1_e32 v17, v149
	v_cvt_f32_ubyte0_e32 v16, v149
	v_pk_mul_f32 v[16:17], v[16:17], s[28:29] op_sel_hi:[1,0]
	s_nop 0
	v_pk_mul_f32 v[16:17], v[8:9], v[16:17]
	v_cvt_f32_ubyte3_e32 v9, v148
	v_cvt_f32_ubyte2_e32 v8, v148
	v_pk_mul_f32 v[8:9], v[8:9], s[28:29] op_sel_hi:[1,0]
	s_nop 0
	v_pk_mul_f32 v[14:15], v[14:15], v[8:9]
	v_cvt_f32_ubyte3_e32 v9, v149
	v_cvt_f32_ubyte2_e32 v8, v149
	v_pk_mul_f32 v[8:9], v[8:9], s[28:29] op_sel_hi:[1,0]
	s_nop 0
	v_pk_mul_f32 v[18:19], v[10:11], v[8:9]
	v_cvt_pk_bf16_f32 v8, v12, v13
	v_add_co_u32_e32 v12, vcc, s20, v144
	v_cvt_pk_bf16_f32 v9, v14, v15
	v_cvt_pk_bf16_f32 v10, v16, v17
	v_cvt_pk_bf16_f32 v11, v18, v19
	v_addc_co_u32_e32 v13, vcc, 0, v145, vcc
	global_store_dwordx4 v[12:13], v[8:11], off
	v_pk_add_f32 v[16:17], v[132:133], v[140:141]
	v_pk_add_f32 v[14:15], v[134:135], v[142:143]
	v_cvt_f32_ubyte1_e32 v9, v146
	v_cvt_f32_ubyte0_e32 v8, v146
	v_pk_mul_f32 v[8:9], v[8:9], s[28:29] op_sel_hi:[1,0]
	v_pk_add_f32 v[18:19], v[130:131], v[138:139]
	v_pk_mul_f32 v[4:5], v[4:5], v[8:9]
	v_cvt_f32_ubyte1_e32 v9, v147
	v_cvt_f32_ubyte0_e32 v8, v147
	v_pk_mul_f32 v[8:9], v[8:9], s[28:29] op_sel_hi:[1,0]
	s_nop 0
	v_pk_mul_f32 v[8:9], v[0:1], v[8:9]
	v_cvt_f32_ubyte3_e32 v1, v146
	v_cvt_f32_ubyte2_e32 v0, v146
	v_pk_mul_f32 v[0:1], v[0:1], s[28:29] op_sel_hi:[1,0]
	s_nop 0
	v_pk_mul_f32 v[6:7], v[6:7], v[0:1]
	v_cvt_f32_ubyte3_e32 v1, v147
	v_cvt_f32_ubyte2_e32 v0, v147
	v_pk_mul_f32 v[0:1], v[0:1], s[28:29] op_sel_hi:[1,0]
	s_nop 0
	v_pk_mul_f32 v[10:11], v[2:3], v[0:1]
	v_cvt_pk_bf16_f32 v0, v4, v5
	v_cvt_pk_bf16_f32 v1, v6, v7
	v_cvt_pk_bf16_f32 v2, v8, v9
	v_cvt_pk_bf16_f32 v3, v10, v11
	global_store_dwordx4 v[12:13], v[0:3], off offset:256
	s_nop 1
	v_lshl_add_u64 v[0:1], v[174:175], 0, s[2:3]
	s_mov_b64 s[2:3], 0x20000
	v_lshl_add_u64 v[2:3], v[144:145], 0, s[2:3]
	global_load_dwordx2 v[10:11], v[0:1], off
	global_load_dwordx2 v[8:9], v[0:1], off offset:128
	v_add_co_u32_e32 v4, vcc, s21, v0
	s_waitcnt vmcnt(0) lgkmcnt(0)
	v_cvt_f32_ubyte1_e32 v13, v10
	v_addc_co_u32_e32 v5, vcc, 0, v1, vcc
	global_load_dwordx2 v[6:7], v[4:5], off
	s_nop 0
	global_load_dwordx2 v[4:5], v[4:5], off offset:128
	v_cvt_f32_ubyte0_e32 v12, v10
	v_pk_mul_f32 v[12:13], v[12:13], s[28:29] op_sel_hi:[1,0]
	s_nop 0
	v_pk_mul_f32 v[12:13], v[16:17], v[12:13]
	v_cvt_f32_ubyte1_e32 v17, v11
	v_cvt_f32_ubyte0_e32 v16, v11
	v_pk_mul_f32 v[16:17], v[16:17], s[28:29] op_sel_hi:[1,0]
	s_nop 0
	v_pk_mul_f32 v[16:17], v[20:21], v[16:17]
	v_cvt_f32_ubyte3_e32 v21, v10
	v_cvt_f32_ubyte2_e32 v20, v10
	v_pk_mul_f32 v[20:21], v[20:21], s[28:29] op_sel_hi:[1,0]
	s_nop 0
	v_pk_mul_f32 v[14:15], v[14:15], v[20:21]
	v_cvt_f32_ubyte3_e32 v21, v11
	v_cvt_f32_ubyte2_e32 v20, v11
	v_pk_mul_f32 v[10:11], v[20:21], s[28:29] op_sel_hi:[1,0]
	v_pk_add_f32 v[20:21], v[104:105], v[136:137]
	v_pk_mul_f32 v[18:19], v[18:19], v[10:11]
	v_cvt_pk_bf16_f32 v10, v12, v13
	v_cvt_pk_bf16_f32 v11, v14, v15
	v_cvt_pk_bf16_f32 v12, v16, v17
	v_cvt_pk_bf16_f32 v13, v18, v19
	global_store_dwordx4 v[2:3], v[10:13], off
	v_pk_add_f32 v[14:15], v[124:125], v[116:117]
	v_pk_add_f32 v[18:19], v[120:121], v[96:97]
	v_cvt_f32_ubyte1_e32 v11, v8
	v_cvt_f32_ubyte0_e32 v10, v8
	v_pk_mul_f32 v[10:11], v[10:11], s[28:29] op_sel_hi:[1,0]
	v_pk_add_f32 v[12:13], v[126:127], v[118:119]
	v_pk_mul_f32 v[10:11], v[14:15], v[10:11]
	v_cvt_f32_ubyte1_e32 v15, v9
	v_cvt_f32_ubyte0_e32 v14, v9
	v_pk_mul_f32 v[14:15], v[14:15], s[28:29] op_sel_hi:[1,0]
	v_pk_add_f32 v[16:17], v[122:123], v[98:99]
	v_pk_mul_f32 v[14:15], v[18:19], v[14:15]
	v_cvt_f32_ubyte3_e32 v19, v8
	v_cvt_f32_ubyte2_e32 v18, v8
	v_pk_mul_f32 v[18:19], v[18:19], s[28:29] op_sel_hi:[1,0]
	s_nop 0
	v_pk_mul_f32 v[12:13], v[12:13], v[18:19]
	v_cvt_f32_ubyte3_e32 v19, v9
	v_cvt_f32_ubyte2_e32 v18, v9
	v_pk_mul_f32 v[8:9], v[18:19], s[28:29] op_sel_hi:[1,0]
	v_pk_add_f32 v[18:19], v[106:107], v[138:139]
	v_pk_mul_f32 v[16:17], v[16:17], v[8:9]
	v_cvt_pk_bf16_f32 v8, v10, v11
	v_cvt_pk_bf16_f32 v9, v12, v13
	v_cvt_pk_bf16_f32 v10, v14, v15
	v_cvt_pk_bf16_f32 v11, v16, v17
	global_store_dwordx4 v[2:3], v[8:11], off offset:256
	v_pk_add_f32 v[12:13], v[44:45], v[140:141]
	v_pk_add_f32 v[16:17], v[40:41], v[136:137]
	v_pk_add_f32 v[10:11], v[46:47], v[142:143]
	v_pk_add_f32 v[14:15], v[42:43], v[138:139]
	s_waitcnt vmcnt(0) lgkmcnt(0)
; DI u32x4 pack8(const float* v) { u32x4 w; w.x = pk2(v[0], v[1]); w.y = pk2(v[2], v[3]); w.z = pk2(v[4], v[5]); w.w = pk2(v[6], v[7]); return w; }
;     DI void fin(const AccT& acc, const Unit& u, int wr, int wc, int fr, int fq) const {
;         const int row0 = u.pm * BM + wr * 64 + fr, col0 = u.pn * BM + wc * 32 + 8 * fq;
;         const unsigned char* pg = (const unsigned char*)G + (size_t)row0 * NGATE + 4096 + col0;
;         bf16_t* pm_ = Mg + (size_t)row0 * D_ + col0;
;         f32x4 bv[2][2];
; #pragma unroll
;         for (int bj = 0; bj < 2; ++bj)
; #pragma unroll
;             for (int n = 0; n < 2; ++n) bv[bj][n] = *(const f32x4*)(bias + col0 + bj * HALF + 4 * n);
; #pragma unroll
;         for (int ai = 0; ai < 2; ++ai) {
; #pragma unroll
;             for (int mh = 0; mh < 2; ++mh) {
;                 u32x2 rg[2][2];
; #pragma unroll
;                 for (int mm = 0; mm < 2; ++mm)
; #pragma unroll
;                     for (int bj = 0; bj < 2; ++bj) rg[mm][bj] = *(const u32x2*)(pg + (size_t)(mm * 16) * NGATE + bj * HALF);
; #pragma unroll
;                 for (int mm = 0; mm < 2; ++mm)
; #pragma unroll
;                     for (int bj = 0; bj < 2; ++bj) {
;                         const int m = 2 * mh + mm;
;                         float gv[8], o[8];
;                         unpack_gate8(rg[mm][bj], gv);
;                         const f32x4 v0 = acc[ai][bj][m][0] + bv[bj][0], v1 = acc[ai][bj][m][1] + bv[bj][1];
; #pragma unroll
;                         for (int j = 0; j < 4; ++j) { o[j] = gv[j] * (1.f / 255.f) * v0[j]; o[4 + j] = gv[4 + j] * (1.f / 255.f) * v1[j]; }
;                         *(u32x4*)(pm_ + (size_t)(mm * 16) * D_ + bj * HALF) = pack8(o); }
;                 pg += (size_t)(mh == 1 ? 96 : 32) * NGATE; pm_ += (size_t)(mh == 1 ? 96 : 32) * D_;
;                 asm volatile("" : "+v"(pg), "+v"(pm_));
;             } }
	v_cvt_f32_ubyte1_e32 v9, v6
	v_cvt_f32_ubyte0_e32 v8, v6
	v_pk_mul_f32 v[8:9], v[8:9], s[28:29] op_sel_hi:[1,0]
	s_nop 0
	v_pk_mul_f32 v[8:9], v[12:13], v[8:9]
	v_cvt_f32_ubyte1_e32 v13, v7
	v_cvt_f32_ubyte0_e32 v12, v7
	v_pk_mul_f32 v[12:13], v[12:13], s[28:29] op_sel_hi:[1,0]
	s_nop 0
	v_pk_mul_f32 v[12:13], v[16:17], v[12:13]
	v_cvt_f32_ubyte3_e32 v17, v6
	v_cvt_f32_ubyte2_e32 v16, v6
	v_pk_mul_f32 v[16:17], v[16:17], s[28:29] op_sel_hi:[1,0]
	s_nop 0
	v_pk_mul_f32 v[10:11], v[10:11], v[16:17]
	v_cvt_f32_ubyte3_e32 v17, v7
	v_cvt_f32_ubyte2_e32 v16, v7
	v_pk_mul_f32 v[6:7], v[16:17], s[28:29] op_sel_hi:[1,0]
	v_pk_add_f32 v[16:17], v[32:33], v[96:97]
	v_pk_mul_f32 v[14:15], v[14:15], v[6:7]
	v_cvt_pk_bf16_f32 v7, v10, v11
	v_add_co_u32_e32 v10, vcc, s20, v2
	v_cvt_pk_bf16_f32 v6, v8, v9
	v_cvt_pk_bf16_f32 v8, v12, v13
	v_cvt_pk_bf16_f32 v9, v14, v15
	v_addc_co_u32_e32 v11, vcc, 0, v3, vcc
	global_store_dwordx4 v[10:11], v[6:9], off
	v_pk_add_f32 v[12:13], v[36:37], v[116:117]
	v_pk_add_f32 v[14:15], v[34:35], v[98:99]
	v_cvt_f32_ubyte1_e32 v7, v4
	v_cvt_f32_ubyte0_e32 v6, v4
	v_pk_mul_f32 v[6:7], v[6:7], s[28:29] op_sel_hi:[1,0]
	v_pk_add_f32 v[8:9], v[38:39], v[118:119]
	v_pk_mul_f32 v[6:7], v[12:13], v[6:7]
	v_cvt_f32_ubyte1_e32 v13, v5
	v_cvt_f32_ubyte0_e32 v12, v5
	v_pk_mul_f32 v[12:13], v[12:13], s[28:29] op_sel_hi:[1,0]
	s_nop 0
	v_pk_mul_f32 v[12:13], v[16:17], v[12:13]
	v_cvt_f32_ubyte3_e32 v17, v4
	v_cvt_f32_ubyte2_e32 v16, v4
	v_pk_mul_f32 v[16:17], v[16:17], s[28:29] op_sel_hi:[1,0]
	s_nop 0
	v_pk_mul_f32 v[8:9], v[8:9], v[16:17]
	v_cvt_f32_ubyte3_e32 v17, v5
	v_cvt_f32_ubyte2_e32 v16, v5
	v_pk_mul_f32 v[4:5], v[16:17], s[28:29] op_sel_hi:[1,0]
	v_pk_add_f32 v[16:17], v[108:109], v[140:141]
	v_pk_mul_f32 v[14:15], v[14:15], v[4:5]
	v_cvt_pk_bf16_f32 v4, v6, v7
	v_cvt_pk_bf16_f32 v5, v8, v9
	v_cvt_pk_bf16_f32 v6, v12, v13
	v_cvt_pk_bf16_f32 v7, v14, v15
	global_store_dwordx4 v[10:11], v[4:7], off offset:256
	v_pk_add_f32 v[14:15], v[110:111], v[142:143]
	s_nop 0
	v_lshl_add_u64 v[4:5], v[0:1], 0, s[26:27]
	v_lshl_add_u64 v[6:7], v[2:3], 0, s[6:7]
	global_load_dwordx2 v[0:1], v[4:5], off
	global_load_dwordx2 v[8:9], v[4:5], off offset:128
	v_add_co_u32_e32 v2, vcc, s21, v4
	s_nop 1
	v_addc_co_u32_e32 v3, vcc, 0, v5, vcc
	global_load_dwordx2 v[10:11], v[2:3], off
	global_load_dwordx2 v[12:13], v[2:3], off offset:128
	v_lshl_add_u64 v[4:5], v[4:5], 0, s[24:25]
	s_waitcnt vmcnt(0) lgkmcnt(0)
	v_cvt_f32_ubyte1_e32 v3, v0
	v_cvt_f32_ubyte0_e32 v2, v0
	v_pk_mul_f32 v[2:3], v[2:3], s[28:29] op_sel_hi:[1,0]
	s_nop 0
	v_pk_mul_f32 v[2:3], v[16:17], v[2:3]
	v_cvt_f32_ubyte1_e32 v17, v1
	v_cvt_f32_ubyte0_e32 v16, v1
	v_pk_mul_f32 v[16:17], v[16:17], s[28:29] op_sel_hi:[1,0]
	s_nop 0
	v_pk_mul_f32 v[16:17], v[20:21], v[16:17]
	v_cvt_f32_ubyte3_e32 v21, v0
	v_cvt_f32_ubyte2_e32 v20, v0
	v_pk_mul_f32 v[20:21], v[20:21], s[28:29] op_sel_hi:[1,0]
	s_nop 0
	v_pk_mul_f32 v[14:15], v[14:15], v[20:21]
	v_cvt_f32_ubyte3_e32 v21, v1
	v_cvt_f32_ubyte2_e32 v20, v1
	v_pk_mul_f32 v[0:1], v[20:21], s[28:29] op_sel_hi:[1,0]
	v_pk_add_f32 v[20:21], v[88:89], v[136:137]
	v_pk_mul_f32 v[18:19], v[18:19], v[0:1]
	v_cvt_pk_bf16_f32 v0, v2, v3
	v_cvt_pk_bf16_f32 v1, v14, v15
	v_cvt_pk_bf16_f32 v2, v16, v17
	v_cvt_pk_bf16_f32 v3, v18, v19
	global_store_dwordx4 v[6:7], v[0:3], off
	v_pk_add_f32 v[14:15], v[76:77], v[116:117]
	v_pk_add_f32 v[18:19], v[112:113], v[96:97]
	v_cvt_f32_ubyte1_e32 v1, v8
	v_cvt_f32_ubyte0_e32 v0, v8
	v_pk_mul_f32 v[0:1], v[0:1], s[28:29] op_sel_hi:[1,0]
	v_pk_add_f32 v[2:3], v[78:79], v[118:119]
	v_pk_mul_f32 v[0:1], v[14:15], v[0:1]
	v_cvt_f32_ubyte1_e32 v15, v9
	v_cvt_f32_ubyte0_e32 v14, v9
	v_pk_mul_f32 v[14:15], v[14:15], s[28:29] op_sel_hi:[1,0]
	v_pk_add_f32 v[16:17], v[114:115], v[98:99]
	v_pk_mul_f32 v[14:15], v[18:19], v[14:15]
	v_cvt_f32_ubyte3_e32 v19, v8
	v_cvt_f32_ubyte2_e32 v18, v8
	v_pk_mul_f32 v[18:19], v[18:19], s[28:29] op_sel_hi:[1,0]
	v_cvt_pk_bf16_f32 v0, v0, v1
	v_pk_mul_f32 v[2:3], v[2:3], v[18:19]
	v_cvt_f32_ubyte3_e32 v19, v9
	v_cvt_f32_ubyte2_e32 v18, v9
	v_pk_mul_f32 v[8:9], v[18:19], s[28:29] op_sel_hi:[1,0]
	v_cvt_pk_bf16_f32 v1, v2, v3
	v_pk_mul_f32 v[8:9], v[16:17], v[8:9]
	v_cvt_pk_bf16_f32 v2, v14, v15
	v_cvt_pk_bf16_f32 v3, v8, v9
	global_store_dwordx4 v[6:7], v[0:3], off offset:256
	v_pk_add_f32 v[8:9], v[100:101], v[140:141]
	v_pk_add_f32 v[16:17], v[72:73], v[136:137]
	v_cvt_f32_ubyte1_e32 v1, v10
	v_cvt_f32_ubyte0_e32 v0, v10
	v_pk_mul_f32 v[0:1], v[0:1], s[28:29] op_sel_hi:[1,0]
	v_pk_add_f32 v[2:3], v[102:103], v[142:143]
	v_pk_mul_f32 v[0:1], v[8:9], v[0:1]
	v_cvt_f32_ubyte1_e32 v9, v11
	v_cvt_f32_ubyte0_e32 v8, v11
	v_pk_mul_f32 v[8:9], v[8:9], s[28:29] op_sel_hi:[1,0]
	v_pk_add_f32 v[14:15], v[74:75], v[138:139]
	v_pk_mul_f32 v[8:9], v[16:17], v[8:9]
	v_cvt_f32_ubyte3_e32 v17, v10
	v_cvt_f32_ubyte2_e32 v16, v10
	v_pk_mul_f32 v[16:17], v[16:17], s[28:29] op_sel_hi:[1,0]
	v_cvt_pk_bf16_f32 v0, v0, v1
	v_pk_mul_f32 v[2:3], v[2:3], v[16:17]
	v_cvt_f32_ubyte3_e32 v17, v11
	v_cvt_f32_ubyte2_e32 v16, v11
	v_pk_mul_f32 v[10:11], v[16:17], s[28:29] op_sel_hi:[1,0]
	v_cvt_pk_bf16_f32 v1, v2, v3
	v_pk_mul_f32 v[10:11], v[14:15], v[10:11]
	v_cvt_pk_bf16_f32 v2, v8, v9
	v_add_co_u32_e32 v8, vcc, s20, v6
	v_cvt_pk_bf16_f32 v3, v10, v11
	s_nop 0
	v_addc_co_u32_e32 v9, vcc, 0, v7, vcc
	global_store_dwordx4 v[8:9], v[0:3], off
	v_pk_add_f32 v[10:11], v[68:69], v[116:117]
	v_pk_add_f32 v[16:17], v[64:65], v[96:97]
	v_cvt_f32_ubyte1_e32 v1, v12
	v_cvt_f32_ubyte0_e32 v0, v12
	v_pk_mul_f32 v[0:1], v[0:1], s[28:29] op_sel_hi:[1,0]
	v_pk_add_f32 v[2:3], v[70:71], v[118:119]
	v_pk_mul_f32 v[0:1], v[10:11], v[0:1]
	v_cvt_f32_ubyte1_e32 v11, v13
	v_cvt_f32_ubyte0_e32 v10, v13
	v_pk_mul_f32 v[10:11], v[10:11], s[28:29] op_sel_hi:[1,0]
	v_pk_add_f32 v[14:15], v[66:67], v[98:99]
	v_pk_mul_f32 v[10:11], v[16:17], v[10:11]
	v_cvt_f32_ubyte3_e32 v17, v12
	v_cvt_f32_ubyte2_e32 v16, v12
	v_pk_mul_f32 v[16:17], v[16:17], s[28:29] op_sel_hi:[1,0]
	v_cvt_pk_bf16_f32 v0, v0, v1
	v_pk_mul_f32 v[2:3], v[2:3], v[16:17]
	v_cvt_f32_ubyte3_e32 v17, v13
	v_cvt_f32_ubyte2_e32 v16, v13
	v_pk_mul_f32 v[12:13], v[16:17], s[28:29] op_sel_hi:[1,0]
	v_cvt_pk_bf16_f32 v1, v2, v3
	v_pk_mul_f32 v[12:13], v[14:15], v[12:13]
	v_cvt_pk_bf16_f32 v2, v10, v11
	v_cvt_pk_bf16_f32 v3, v12, v13
	v_lshl_add_u64 v[6:7], v[6:7], 0, s[2:3]
	global_store_dwordx4 v[8:9], v[0:3], off offset:256
	global_load_dwordx2 v[0:1], v[4:5], off
	global_load_dwordx2 v[8:9], v[4:5], off offset:128
	v_add_co_u32_e32 v2, vcc, s21, v4
	v_pk_add_f32 v[16:17], v[92:93], v[140:141]
	s_nop 0
	v_addc_co_u32_e32 v3, vcc, 0, v5, vcc
	global_load_dwordx2 v[10:11], v[2:3], off
	global_load_dwordx2 v[12:13], v[2:3], off offset:128
	v_pk_add_f32 v[14:15], v[94:95], v[142:143]
	v_pk_add_f32 v[18:19], v[90:91], v[138:139]
	s_waitcnt vmcnt(0) lgkmcnt(0)
; template <class Epi, class Sched>
; DI void merge_phase(LAS unsigned char* lds, const bf16_t* a0, const bf16_t* a1, const bf16_t* a2, const bf16_t* b0, const bf16_t* b1, const bf16_t* b2, const Sched& S, const Epi& E) {
;     ...
;     for (int ui = 0;; ++ui) {
;         Seg s1, s2; merge_seg(a0, a1, a2, b0, b1, b2, cu.pm, cu.pn, 1, s1); merge_seg(a0, a1, a2, b0, b1, b2, cu.pm, cu.pn, 2, s2);
;         const bool has_next = S.next(ui + 1, nu);
;         if (has_next) merge_seg(a0, a1, a2, b0, b1, b2, nu.pm, nu.pn, 0, nxt); else nxt = s2;
;         MRG_KLOOP(cur, s1);
;         E.mid(acc, cu, 0, wr, wc, fr, fq);
;         MRG_KLOOP(s1, s2);
;         E.mid(acc, cu, 1, wr, wc, fr, fq);
;         MRG_KLOOP(s2, nxt);
;         E.fin(acc, cu, wr, wc, fr, fq);
; #pragma unroll
;         for (int a = 0; a < 2; ++a)
; #pragma unroll
;             for (int b = 0; b < 2; ++b)
; #pragma unroll
;                 for (int m = 0; m < 4; ++m)
; #pragma unroll
;                     for (int n = 0; n < 2; ++n) acc[a][b][m][n] = (f32x4){0.f, 0.f, 0.f, 0.f};
;         if (!has_next) break;
;         cur = nxt; cu = nu;
;     }
;     ...
;     PG8_WAIT_V(0);
;     if (wr == 0) PG8_BAR;
;     PG8_BAR;
;     DI void fin(const AccT& acc, const Unit& u, int wr, int wc, int fr, int fq) const {
;     ...
;             for (int mh = 0; mh < 2; ++mh) {
;                 u32x2 rg[2][2];
; #pragma unroll
;                 for (int mm = 0; mm < 2; ++mm)
; #pragma unroll
;                     for (int bj = 0; bj < 2; ++bj) rg[mm][bj] = *(const u32x2*)(pg + (size_t)(mm * 16) * NGATE + bj * HALF);
; #pragma unroll
;                 for (int mm = 0; mm < 2; ++mm)
; #pragma unroll
;                     for (int bj = 0; bj < 2; ++bj) {
;                         const int m = 2 * mh + mm;
;                         float gv[8], o[8];
;                         unpack_gate8(rg[mm][bj], gv);
;                         const f32x4 v0 = acc[ai][bj][m][0] + bv[bj][0], v1 = acc[ai][bj][m][1] + bv[bj][1];
; #pragma unroll
;                         for (int j = 0; j < 4; ++j) { o[j] = gv[j] * (1.f / 255.f) * v0[j]; o[4 + j] = gv[4 + j] * (1.f / 255.f) * v1[j]; }
;                         *(u32x4*)(pm_ + (size_t)(mm * 16) * D_ + bj * HALF) = pack8(o); }
;                 pg += (size_t)(mh == 1 ? 96 : 32) * NGATE; pm_ += (size_t)(mh == 1 ? 96 : 32) * D_;
;                 asm volatile("" : "+v"(pg), "+v"(pm_));
;             } }
	v_cvt_f32_ubyte1_e32 v3, v0
	v_cvt_f32_ubyte0_e32 v2, v0
	v_pk_mul_f32 v[2:3], v[2:3], s[28:29] op_sel_hi:[1,0]
	s_nop 0
	v_pk_mul_f32 v[2:3], v[16:17], v[2:3]
	v_cvt_f32_ubyte1_e32 v17, v1
	v_cvt_f32_ubyte0_e32 v16, v1
	v_pk_mul_f32 v[16:17], v[16:17], s[28:29] op_sel_hi:[1,0]
	s_nop 0
	v_pk_mul_f32 v[16:17], v[20:21], v[16:17]
	v_cvt_f32_ubyte3_e32 v21, v0
	v_cvt_f32_ubyte2_e32 v20, v0
	v_pk_mul_f32 v[20:21], v[20:21], s[28:29] op_sel_hi:[1,0]
	s_nop 0
	v_pk_mul_f32 v[14:15], v[14:15], v[20:21]
	v_cvt_f32_ubyte3_e32 v21, v1
	v_cvt_f32_ubyte2_e32 v20, v1
	v_pk_mul_f32 v[0:1], v[20:21], s[28:29] op_sel_hi:[1,0]
	s_nop 0
	v_pk_mul_f32 v[18:19], v[18:19], v[0:1]
	v_cvt_pk_bf16_f32 v0, v2, v3
	v_cvt_pk_bf16_f32 v1, v14, v15
	v_cvt_pk_bf16_f32 v2, v16, v17
	v_cvt_pk_bf16_f32 v3, v18, v19
	global_store_dwordx4 v[6:7], v[0:3], off
	v_pk_add_f32 v[14:15], v[60:61], v[116:117]
	v_pk_add_f32 v[18:19], v[56:57], v[96:97]
	v_cvt_f32_ubyte1_e32 v1, v8
	v_cvt_f32_ubyte0_e32 v0, v8
	v_pk_mul_f32 v[0:1], v[0:1], s[28:29] op_sel_hi:[1,0]
	v_pk_add_f32 v[2:3], v[62:63], v[118:119]
	v_pk_mul_f32 v[0:1], v[14:15], v[0:1]
	v_cvt_f32_ubyte1_e32 v15, v9
	v_cvt_f32_ubyte0_e32 v14, v9
	v_pk_mul_f32 v[14:15], v[14:15], s[28:29] op_sel_hi:[1,0]
	v_pk_add_f32 v[16:17], v[58:59], v[98:99]
	v_pk_mul_f32 v[14:15], v[18:19], v[14:15]
	v_cvt_f32_ubyte3_e32 v19, v8
	v_cvt_f32_ubyte2_e32 v18, v8
	v_pk_mul_f32 v[18:19], v[18:19], s[28:29] op_sel_hi:[1,0]
	v_cvt_pk_bf16_f32 v0, v0, v1
	v_pk_mul_f32 v[2:3], v[2:3], v[18:19]
	v_cvt_f32_ubyte3_e32 v19, v9
	v_cvt_f32_ubyte2_e32 v18, v9
	v_pk_mul_f32 v[8:9], v[18:19], s[28:29] op_sel_hi:[1,0]
	v_cvt_pk_bf16_f32 v1, v2, v3
	v_pk_mul_f32 v[8:9], v[16:17], v[8:9]
	v_cvt_pk_bf16_f32 v2, v14, v15
	v_cvt_pk_bf16_f32 v3, v8, v9
	global_store_dwordx4 v[6:7], v[0:3], off offset:256
	v_pk_add_f32 v[8:9], v[84:85], v[140:141]
	v_pk_add_f32 v[16:17], v[80:81], v[136:137]
	v_cvt_f32_ubyte1_e32 v1, v10
	v_cvt_f32_ubyte0_e32 v0, v10
	v_pk_mul_f32 v[0:1], v[0:1], s[28:29] op_sel_hi:[1,0]
	v_pk_add_f32 v[2:3], v[86:87], v[142:143]
	v_pk_mul_f32 v[0:1], v[8:9], v[0:1]
	v_cvt_f32_ubyte1_e32 v9, v11
	v_cvt_f32_ubyte0_e32 v8, v11
	v_pk_mul_f32 v[8:9], v[8:9], s[28:29] op_sel_hi:[1,0]
	v_pk_add_f32 v[14:15], v[82:83], v[138:139]
	v_pk_mul_f32 v[8:9], v[16:17], v[8:9]
	v_cvt_f32_ubyte3_e32 v17, v10
	v_cvt_f32_ubyte2_e32 v16, v10
	v_pk_mul_f32 v[16:17], v[16:17], s[28:29] op_sel_hi:[1,0]
	v_cvt_pk_bf16_f32 v0, v0, v1
	v_pk_mul_f32 v[2:3], v[2:3], v[16:17]
	v_cvt_f32_ubyte3_e32 v17, v11
	v_cvt_f32_ubyte2_e32 v16, v11
	v_pk_mul_f32 v[10:11], v[16:17], s[28:29] op_sel_hi:[1,0]
	v_cvt_pk_bf16_f32 v1, v2, v3
	v_pk_mul_f32 v[10:11], v[14:15], v[10:11]
	v_cvt_pk_bf16_f32 v2, v8, v9
	v_add_co_u32_e32 v8, vcc, s20, v6
	v_cvt_pk_bf16_f32 v3, v10, v11
	s_nop 0
	v_addc_co_u32_e32 v9, vcc, 0, v7, vcc
	global_store_dwordx4 v[8:9], v[0:3], off
	v_pk_add_f32 v[10:11], v[52:53], v[116:117]
	v_pk_add_f32 v[16:17], v[48:49], v[96:97]
	v_cvt_f32_ubyte1_e32 v1, v12
	v_cvt_f32_ubyte0_e32 v0, v12
	v_pk_mul_f32 v[0:1], v[0:1], s[28:29] op_sel_hi:[1,0]
	v_pk_add_f32 v[2:3], v[54:55], v[118:119]
	v_pk_mul_f32 v[0:1], v[10:11], v[0:1]
	v_cvt_f32_ubyte1_e32 v11, v13
	v_cvt_f32_ubyte0_e32 v10, v13
	v_pk_mul_f32 v[10:11], v[10:11], s[28:29] op_sel_hi:[1,0]
	v_pk_add_f32 v[14:15], v[50:51], v[98:99]
	v_pk_mul_f32 v[10:11], v[16:17], v[10:11]
	v_cvt_f32_ubyte3_e32 v17, v12
	v_cvt_f32_ubyte2_e32 v16, v12
	v_pk_mul_f32 v[16:17], v[16:17], s[28:29] op_sel_hi:[1,0]
	v_cvt_pk_bf16_f32 v0, v0, v1
	v_pk_mul_f32 v[2:3], v[2:3], v[16:17]
	v_cvt_f32_ubyte3_e32 v17, v13
	v_cvt_f32_ubyte2_e32 v16, v13
	v_pk_mul_f32 v[12:13], v[16:17], s[28:29] op_sel_hi:[1,0]
	v_cvt_pk_bf16_f32 v1, v2, v3
	v_pk_mul_f32 v[12:13], v[14:15], v[12:13]
	v_cvt_pk_bf16_f32 v2, v10, v11
	v_cvt_pk_bf16_f32 v3, v12, v13
	global_store_dwordx4 v[8:9], v[0:3], off offset:256
	s_and_b64 vcc, exec, s[38:39]
	s_nop 0
	v_lshl_add_u64 v[0:1], v[4:5], 0, s[26:27]
	v_lshl_add_u64 v[2:3], v[6:7], 0, s[6:7]
	s_cbranch_vccz .LBB0_1309
	s_waitcnt vmcnt(0)
	v_readlane_b32 s0, v255, 27
	v_readlane_b32 s76, v255, 9
	v_readlane_b32 s68, v255, 11
	v_readlane_b32 s72, v255, 13
	v_readlane_b32 s74, v255, 15
	v_readlane_b32 s12, v252, 50
	s_cmpk_gt_u32 s0, 0xff
	v_readlane_b32 s82, v255, 7
	v_readlane_b32 s77, v255, 10
	v_readlane_b32 s69, v255, 12
	v_readlane_b32 s73, v255, 14
	v_readlane_b32 s75, v255, 16
	v_readlane_b32 s13, v252, 51
	v_readlane_b32 s14, v255, 24
	v_readlane_b32 s83, v255, 8
	s_cbranch_scc1 .LBB0_1327
	s_barrier

; DI unsigned pk2(float lo, float hi) { f32x2 v = {lo, hi}; bf16x2_t b = __builtin_convertvector(v, bf16x2_t); return __builtin_bit_cast(unsigned, b); }
; DI void rms_row_to_bf16(const float* xrow, const float* g, bf16_t* orow, int lane) {
;     const f32x4* xr = (const f32x4*)xrow + lane; const f32x4* gr = (const f32x4*)g + lane;
;     f32x4 v[8]; float s = 0.f;
; #pragma unroll
;     for (int j = 0; j < 8; ++j) { v[j] = xr[64 * j]; s += (v[j].x * v[j].x + v[j].y * v[j].y) + (v[j].z * v[j].z + v[j].w * v[j].w); }
;     const float rs = rsqrtf(wave_sum(s) * (1.f / D_) + EPS_);
;     u32x2* o8 = (u32x2*)orow + lane;
; #pragma unroll
;     for (int j = 0; j < 8; ++j) { const f32x4 gg = gr[64 * j]; u32x2 w; w.x = pk2(v[j].x * rs * gg.x, v[j].y * rs * gg.y); w.y = pk2(v[j].z * rs * gg.z, v[j].w * rs * gg.w); o8[64 * j] = w; }
; }
; __global__ void __launch_bounds__(512, 2) fwd_megakernel(Args args) {
;     ...
;         for (int m = gw; m < T_; m += 4 * NGW) {
;             if (m + 3 * NGW < T_) rms_rows4_to_bf16(out + (size_t)m * D_, (size_t)NGW * D_, norm2_g, A + (size_t)m * D_, (size_t)NGW * D_, lane);
;             else for (int mm = m; mm < T_; mm += NGW) rms_row_to_bf16(out + (size_t)mm * D_, norm2_g, A + (size_t)mm * D_, lane);
;         } }
.LBB0_1453:
	v_add_co_u32_e32 v0, vcc, 0xfffff000, v36
	s_add_i32 s1, s1, s96
	s_nop 0
	v_addc_co_u32_e32 v1, vcc, -1, v37, vcc
	global_load_dwordx4 v[12:15], v[0:1], off offset:-3072
	global_load_dwordx4 v[8:11], v[0:1], off offset:-2048
	s_cmpk_lt_i32 s1, 0x4000
	s_waitcnt vmcnt(0)
	v_mov_b32_e32 v4, v13
	v_mov_b32_e32 v5, v9
	v_mov_b32_e32 v2, v12
	v_mov_b32_e32 v3, v8
	v_pk_mul_f32 v[4:5], v[4:5], v[4:5]
	v_mov_b32_e32 v6, v15
	v_mov_b32_e32 v7, v11
	v_pk_fma_f32 v[2:3], v[2:3], v[2:3], v[4:5]
	v_mov_b32_e32 v4, v14
	v_mov_b32_e32 v5, v10
	v_pk_mul_f32 v[6:7], v[6:7], v[6:7]
	s_nop 0
	v_pk_fma_f32 v[4:5], v[4:5], v[4:5], v[6:7]
	s_nop 0
	v_pk_add_f32 v[20:21], v[2:3], v[4:5]
	global_load_dwordx4 v[4:7], v[0:1], off offset:-1024
	v_pk_add_f32 v[20:21], v[20:21], v[20:21] op_sel:[0,1] op_sel_hi:[1,0]
	s_waitcnt vmcnt(0)
	v_pk_mul_f32 v[0:1], v[6:7], v[6:7]
	v_pk_mul_f32 v[2:3], v[4:5], v[4:5]
	s_nop 0
	v_pk_mov_b32 v[16:17], v[2:3], v[0:1] op_sel:[1,0]
	v_mov_b32_e32 v3, v1
	v_pk_add_f32 v[22:23], v[16:17], v[2:3]
	global_load_dwordx4 v[0:3], v[36:37], off offset:-4096
	global_load_dwordx4 v[16:19], v[36:37], off offset:-3072
	v_pk_add_f32 v[22:23], v[22:23], v[22:23] op_sel:[0,1] op_sel_hi:[1,0]
	s_waitcnt vmcnt(0)
	v_mul_f32_e32 v24, v16, v16
	v_mul_f32_e32 v25, v17, v17
	v_mov_b32_e32 v21, v24
	v_mov_b32_e32 v23, v25
	v_pk_add_f32 v[20:21], v[20:21], v[22:23]
	v_mul_f32_e32 v22, v1, v1
	v_mul_f32_e32 v24, v3, v3
	v_mul_f32_e32 v26, v18, v18
	v_mul_f32_e32 v27, v19, v19
	v_pk_fma_f32 v[22:23], v[0:1], v[0:1], v[22:23] op_sel_hi:[1,1,0]
	v_pk_fma_f32 v[24:25], v[2:3], v[2:3], v[24:25] op_sel_hi:[1,1,0]
	v_mov_b32_e32 v23, v26
	v_mov_b32_e32 v25, v27
	v_pk_add_f32 v[22:23], v[22:23], v[24:25]
	s_nop 0
	v_pk_add_f32 v[32:33], v[20:21], v[22:23]
	global_load_dwordx4 v[20:23], v[36:37], off offset:-2048
	v_pk_add_f32 v[32:33], v[32:33], v[32:33] op_sel:[0,1] op_sel_hi:[1,0]
	s_waitcnt vmcnt(0)
	v_pk_mul_f32 v[24:25], v[22:23], v[22:23]
	v_pk_mul_f32 v[26:27], v[20:21], v[20:21]
	s_nop 0
	v_pk_mov_b32 v[28:29], v[26:27], v[24:25] op_sel:[1,0]
	v_mov_b32_e32 v27, v25
	v_pk_add_f32 v[34:35], v[28:29], v[26:27]
	global_load_dwordx4 v[24:27], v[36:37], off offset:-1024
	global_load_dwordx4 v[28:31], v[36:37], off
	v_pk_add_f32 v[34:35], v[34:35], v[34:35] op_sel:[0,1] op_sel_hi:[1,0]
	v_lshl_add_u64 v[36:37], v[36:37], 0, s[80:81]
	s_waitcnt vmcnt(0)
	v_mul_f32_e32 v40, v28, v28
	v_mul_f32_e32 v41, v29, v29
	v_mov_b32_e32 v33, v40
	v_mov_b32_e32 v35, v41
	v_pk_add_f32 v[32:33], v[32:33], v[34:35]
	v_mul_f32_e32 v34, v25, v25
	v_mul_f32_e32 v40, v27, v27
	v_mul_f32_e32 v42, v30, v30
	v_mul_f32_e32 v43, v31, v31
	v_pk_fma_f32 v[34:35], v[24:25], v[24:25], v[34:35] op_sel_hi:[1,1,0]
	v_pk_fma_f32 v[40:41], v[26:27], v[26:27], v[40:41] op_sel_hi:[1,1,0]
	v_mov_b32_e32 v35, v42
	v_mov_b32_e32 v41, v43
	v_pk_add_f32 v[34:35], v[34:35], v[40:41]
	s_nop 0
	v_pk_add_f32 v[32:33], v[32:33], v[34:35]
	s_nop 0
	v_add_f32_e32 v32, v32, v33
	ds_bpermute_b32 v33, v193, v32
	s_waitcnt lgkmcnt(0)
	v_add_f32_e32 v32, v32, v33
	ds_bpermute_b32 v33, v194, v32
	s_waitcnt lgkmcnt(0)
	v_add_f32_e32 v32, v32, v33
	ds_bpermute_b32 v33, v195, v32
	s_waitcnt lgkmcnt(0)
	v_add_f32_e32 v32, v32, v33
	ds_bpermute_b32 v33, v196, v32
	s_waitcnt lgkmcnt(0)
	v_add_f32_e32 v32, v32, v33
	ds_bpermute_b32 v33, v197, v32
	s_waitcnt lgkmcnt(0)
	v_add_f32_e32 v32, v32, v33
	ds_bpermute_b32 v33, v198, v32
	s_waitcnt lgkmcnt(0)
	v_add_f32_e32 v32, v32, v33
	v_fmamk_f32 v32, v32, 0x3a000000, v187
	v_cmp_gt_f32_e32 vcc, s97, v32
	v_mul_f32_e32 v33, 0x4b800000, v32
	s_nop 0
	v_cndmask_b32_e32 v32, v32, v33, vcc
	v_rsq_f32_e32 v32, v32
	s_nop 0
	v_mul_f32_e32 v33, 0x45800000, v32
	v_cndmask_b32_e32 v40, v32, v33, vcc
	global_load_dwordx4 v[32:35], v[132:133], off
	v_pk_mul_f32 v[12:13], v[12:13], v[40:41] op_sel_hi:[1,0]
	v_pk_mul_f32 v[14:15], v[14:15], v[40:41] op_sel_hi:[1,0]
	v_pk_mul_f32 v[8:9], v[8:9], v[40:41] op_sel_hi:[1,0]
	v_pk_mul_f32 v[10:11], v[10:11], v[40:41] op_sel_hi:[1,0]
	v_pk_mul_f32 v[4:5], v[4:5], v[40:41] op_sel_hi:[1,0]
	v_pk_mul_f32 v[6:7], v[6:7], v[40:41] op_sel_hi:[1,0]
	v_pk_mul_f32 v[0:1], v[0:1], v[40:41] op_sel_hi:[1,0]
	v_pk_mul_f32 v[2:3], v[2:3], v[40:41] op_sel_hi:[1,0]
	s_waitcnt vmcnt(0)
	v_pk_mul_f32 v[12:13], v[32:33], v[12:13]
	v_pk_mul_f32 v[14:15], v[34:35], v[14:15]
	v_cvt_pk_bf16_f32 v12, v12, v13
	v_cvt_pk_bf16_f32 v13, v14, v15
	global_store_dwordx2 v[38:39], v[12:13], off
	global_load_dwordx4 v[12:15], v[132:133], off offset:1024
	s_waitcnt vmcnt(0)
	v_pk_mul_f32 v[8:9], v[12:13], v[8:9]
	v_pk_mul_f32 v[10:11], v[14:15], v[10:11]
	v_cvt_pk_bf16_f32 v8, v8, v9
	v_cvt_pk_bf16_f32 v9, v10, v11
	global_store_dwordx2 v[38:39], v[8:9], off offset:512
	global_load_dwordx4 v[8:11], v[132:133], off offset:2048
	s_waitcnt vmcnt(0)
	v_pk_mul_f32 v[4:5], v[8:9], v[4:5]
	v_pk_mul_f32 v[6:7], v[10:11], v[6:7]
	v_cvt_pk_bf16_f32 v4, v4, v5
	v_cvt_pk_bf16_f32 v5, v6, v7
	global_store_dwordx2 v[38:39], v[4:5], off offset:1024
	global_load_dwordx4 v[4:7], v[132:133], off offset:3072
	s_waitcnt vmcnt(0)
	v_pk_mul_f32 v[0:1], v[4:5], v[0:1]
	v_pk_mul_f32 v[2:3], v[6:7], v[2:3]
	v_cvt_pk_bf16_f32 v0, v0, v1
	v_cvt_pk_bf16_f32 v1, v2, v3
	global_store_dwordx2 v[38:39], v[0:1], off offset:1536
	global_load_dwordx4 v[0:3], v[134:135], off
	v_pk_mul_f32 v[4:5], v[16:17], v[40:41] op_sel_hi:[1,0]
	s_waitcnt vmcnt(0)
	v_pk_mul_f32 v[0:1], v[0:1], v[4:5]
	v_pk_mul_f32 v[4:5], v[18:19], v[40:41] op_sel_hi:[1,0]
	v_cvt_pk_bf16_f32 v0, v0, v1
	v_pk_mul_f32 v[2:3], v[2:3], v[4:5]
	v_pk_mul_f32 v[4:5], v[20:21], v[40:41] op_sel_hi:[1,0]
	v_cvt_pk_bf16_f32 v1, v2, v3
	global_store_dwordx2 v[38:39], v[0:1], off offset:2048
	global_load_dwordx4 v[0:3], v[136:137], off
	s_waitcnt vmcnt(0)
	v_pk_mul_f32 v[0:1], v[4:5], v[0:1]
	v_pk_mul_f32 v[4:5], v[22:23], v[40:41] op_sel_hi:[1,0]
	v_cvt_pk_bf16_f32 v0, v0, v1
	v_pk_mul_f32 v[2:3], v[4:5], v[2:3]
	v_pk_mul_f32 v[4:5], v[24:25], v[40:41] op_sel_hi:[1,0]
	v_cvt_pk_bf16_f32 v1, v2, v3
	global_store_dwordx2 v[38:39], v[0:1], off offset:2560
	global_load_dwordx4 v[0:3], v[138:139], off
	s_waitcnt vmcnt(0)
	v_pk_mul_f32 v[0:1], v[4:5], v[0:1]
	v_pk_mul_f32 v[4:5], v[26:27], v[40:41] op_sel_hi:[1,0]
	v_cvt_pk_bf16_f32 v0, v0, v1
	v_pk_mul_f32 v[2:3], v[4:5], v[2:3]
	v_pk_mul_f32 v[4:5], v[28:29], v[40:41] op_sel_hi:[1,0]
	v_cvt_pk_bf16_f32 v1, v2, v3
	global_store_dwordx2 v[38:39], v[0:1], off offset:3072
	global_load_dwordx4 v[0:3], v[140:141], off
	s_waitcnt vmcnt(0)
	v_pk_mul_f32 v[0:1], v[4:5], v[0:1]
	v_pk_mul_f32 v[4:5], v[30:31], v[40:41] op_sel_hi:[1,0]
	v_cvt_pk_bf16_f32 v0, v0, v1
	v_pk_mul_f32 v[2:3], v[4:5], v[2:3]
	s_nop 0
	v_cvt_pk_bf16_f32 v1, v2, v3
	global_store_dwordx2 v[38:39], v[0:1], off offset:3584
	v_lshl_add_u64 v[38:39], v[38:39], 0, s[84:85]
	s_cbranch_scc1 .LBB0_1453
	s_mov_b64 s[2:3], 0
; DI void rms_rows4_to_bf16(const float* xb, size_t xstride, const float* g, bf16_t* ob, size_t ostride, int lane) {
;     f32x4 v[4][8]; float ss[4];
; #pragma unroll
;     for (int r = 0; r < 4; ++r)
; #pragma unroll
;         for (int j = 0; j < 8; ++j) v[r][j] = ((const f32x4*)(xb + r * xstride))[lane + 64 * j];
; #pragma unroll
;     for (int r = 0; r < 4; ++r) { float s = 0.f;
; #pragma unroll
;         for (int j = 0; j < 8; ++j) s += (v[r][j].x * v[r][j].x + v[r][j].y * v[r][j].y) + (v[r][j].z * v[r][j].z + v[r][j].w * v[r][j].w);
.LBB0_1455:
	s_and_b64 vcc, exec, s[2:3]
	s_cbranch_vccz .LBB0_1451
	s_ashr_i32 s1, s0, 31
	s_lshl_b64 s[2:3], s[0:1], 13
	s_add_u32 s2, s62, s2
	s_addc_u32 s3, s63, s3
	global_load_dwordx4 v[112:115], v149, s[2:3]
	global_load_dwordx4 v[96:99], v149, s[2:3] offset:1024
	global_load_dwordx4 v[80:83], v149, s[2:3] offset:2048
	global_load_dwordx4 v[64:67], v149, s[2:3] offset:3072
	global_load_dwordx4 v[60:63], v151, s[2:3]
	global_load_dwordx4 v[40:43], v153, s[2:3]
	global_load_dwordx4 v[24:27], v155, s[2:3]
	global_load_dwordx4 v[8:11], v158, s[2:3]
	s_lshl_b64 s[4:5], s[20:21], 2
	s_add_u32 s2, s2, s4
	s_addc_u32 s3, s3, s5
	global_load_dwordx4 v[116:119], v149, s[2:3]
	global_load_dwordx4 v[100:103], v149, s[2:3] offset:1024
	global_load_dwordx4 v[84:87], v149, s[2:3] offset:2048
	global_load_dwordx4 v[68:71], v149, s[2:3] offset:3072
	global_load_dwordx4 v[56:59], v151, s[2:3]
	global_load_dwordx4 v[44:47], v153, s[2:3]
	global_load_dwordx4 v[28:31], v155, s[2:3]
	global_load_dwordx4 v[12:15], v158, s[2:3]
	s_add_u32 s2, s2, s80
	s_addc_u32 s3, s3, s81
	global_load_dwordx4 v[120:123], v149, s[2:3]
	global_load_dwordx4 v[104:107], v149, s[2:3] offset:1024
	global_load_dwordx4 v[88:91], v149, s[2:3] offset:2048
	global_load_dwordx4 v[72:75], v149, s[2:3] offset:3072
	global_load_dwordx4 v[48:51], v151, s[2:3]
	global_load_dwordx4 v[36:39], v153, s[2:3]
	global_load_dwordx4 v[20:23], v155, s[2:3]
	global_load_dwordx4 v[4:7], v158, s[2:3]
	s_add_u32 s2, s2, s80
	s_addc_u32 s3, s3, s81
	global_load_dwordx4 v[124:127], v149, s[2:3]
	global_load_dwordx4 v[108:111], v149, s[2:3] offset:1024
	global_load_dwordx4 v[92:95], v149, s[2:3] offset:2048
	global_load_dwordx4 v[76:79], v149, s[2:3] offset:3072
	global_load_dwordx4 v[52:55], v151, s[2:3]
	global_load_dwordx4 v[32:35], v153, s[2:3]
	global_load_dwordx4 v[16:19], v155, s[2:3]
	global_load_dwordx4 v[0:3], v158, s[2:3]
	s_lshl_b64 s[2:3], s[0:1], 12
	s_waitcnt vmcnt(0)
	v_mov_b32_e32 v130, v113
	v_mov_b32_e32 v131, v97
	v_mov_b32_e32 v128, v112
	v_mov_b32_e32 v129, v96
	v_pk_mul_f32 v[130:131], v[130:131], v[130:131]
	v_mov_b32_e32 v156, v115
	v_mov_b32_e32 v157, v99
	v_pk_fma_f32 v[128:129], v[128:129], v[128:129], v[130:131]
	v_mov_b32_e32 v130, v114
	v_mov_b32_e32 v131, v98
	v_pk_mul_f32 v[156:157], v[156:157], v[156:157]
	v_mul_f32_e32 v148, v60, v60
	v_pk_fma_f32 v[130:131], v[130:131], v[130:131], v[156:157]
	v_pk_mul_f32 v[156:157], v[80:81], v[80:81]
	v_pk_add_f32 v[128:129], v[128:129], v[130:131]
	v_pk_mul_f32 v[130:131], v[82:83], v[82:83]
	v_mul_f32_e32 v150, v61, v61
	v_pk_mov_b32 v[166:167], v[156:157], v[130:131] op_sel:[1,0]
	v_mov_b32_e32 v157, v131
	v_pk_add_f32 v[130:131], v[166:167], v[156:157]
	v_pk_add_f32 v[128:129], v[128:129], v[128:129] op_sel:[0,1] op_sel_hi:[1,0]
	v_pk_add_f32 v[130:131], v[130:131], v[130:131] op_sel:[0,1] op_sel_hi:[1,0]
	v_mov_b32_e32 v129, v148
	v_mov_b32_e32 v131, v150
	v_pk_add_f32 v[128:129], v[128:129], v[130:131]
	v_mul_f32_e32 v130, v65, v65
	v_mul_f32_e32 v148, v67, v67
	v_mul_f32_e32 v152, v62, v62
	v_mul_f32_e32 v154, v63, v63
	v_pk_fma_f32 v[130:131], v[64:65], v[64:65], v[130:131] op_sel_hi:[1,1,0]
	v_pk_fma_f32 v[156:157], v[66:67], v[66:67], v[148:149] op_sel_hi:[1,1,0]
	v_mov_b32_e32 v131, v152
	v_mov_b32_e32 v157, v154
	v_pk_add_f32 v[130:131], v[130:131], v[156:157]
	v_pk_mul_f32 v[156:157], v[40:41], v[40:41]
	v_pk_add_f32 v[128:129], v[128:129], v[130:131]
	v_pk_mul_f32 v[130:131], v[42:43], v[42:43]
	v_mul_f32_e32 v148, v8, v8
	v_pk_mov_b32 v[166:167], v[156:157], v[130:131] op_sel:[1,0]
	v_mov_b32_e32 v157, v131
	v_pk_add_f32 v[130:131], v[166:167], v[156:157]
	v_mul_f32_e32 v150, v9, v9
	v_pk_add_f32 v[128:129], v[128:129], v[128:129] op_sel:[0,1] op_sel_hi:[1,0]
	v_pk_add_f32 v[130:131], v[130:131], v[130:131] op_sel:[0,1] op_sel_hi:[1,0]
	v_mov_b32_e32 v129, v148
	v_mov_b32_e32 v131, v150
	v_pk_add_f32 v[128:129], v[128:129], v[130:131]
	v_mul_f32_e32 v130, v25, v25
	v_mul_f32_e32 v148, v27, v27
	v_mul_f32_e32 v152, v10, v10
	v_mul_f32_e32 v154, v11, v11
	v_pk_fma_f32 v[130:131], v[24:25], v[24:25], v[130:131] op_sel_hi:[1,1,0]
	v_pk_fma_f32 v[156:157], v[26:27], v[26:27], v[148:149] op_sel_hi:[1,1,0]
	v_mov_b32_e32 v131, v152
	v_mov_b32_e32 v157, v154
	v_pk_add_f32 v[130:131], v[130:131], v[156:157]
	v_mov_b32_e32 v156, v117
	v_mov_b32_e32 v157, v101
	v_pk_add_f32 v[128:129], v[128:129], v[130:131]
	v_mov_b32_e32 v130, v116
	v_mov_b32_e32 v131, v100
	v_pk_mul_f32 v[156:157], v[156:157], v[156:157]
	v_mov_b32_e32 v166, v119
	v_mov_b32_e32 v167, v103
	v_pk_fma_f32 v[130:131], v[130:131], v[130:131], v[156:157]
	v_mov_b32_e32 v156, v118
	v_mov_b32_e32 v157, v102
	v_pk_mul_f32 v[166:167], v[166:167], v[166:167]
	v_mul_f32_e32 v148, v56, v56
	v_pk_fma_f32 v[156:157], v[156:157], v[156:157], v[166:167]
	v_pk_mul_f32 v[166:167], v[84:85], v[84:85]
	v_pk_add_f32 v[130:131], v[130:131], v[156:157]
	v_pk_mul_f32 v[156:157], v[86:87], v[86:87]
	v_mul_f32_e32 v150, v57, v57
	v_pk_mov_b32 v[168:169], v[166:167], v[156:157] op_sel:[1,0]
	v_mov_b32_e32 v167, v157
	v_pk_add_f32 v[156:157], v[168:169], v[166:167]
	v_pk_add_f32 v[130:131], v[130:131], v[130:131] op_sel:[0,1] op_sel_hi:[1,0]
	v_pk_add_f32 v[156:157], v[156:157], v[156:157] op_sel:[0,1] op_sel_hi:[1,0]
	v_mov_b32_e32 v131, v148
	v_mov_b32_e32 v157, v150
	v_mul_f32_e32 v148, v69, v69
	v_pk_add_f32 v[130:131], v[130:131], v[156:157]
	v_pk_fma_f32 v[156:157], v[68:69], v[68:69], v[148:149] op_sel_hi:[1,1,0]
	v_mul_f32_e32 v148, v71, v71
	v_mul_f32_e32 v152, v58, v58
	v_mul_f32_e32 v154, v59, v59
	v_pk_fma_f32 v[166:167], v[70:71], v[70:71], v[148:149] op_sel_hi:[1,1,0]
; DI void rms_rows4_to_bf16(const float* xb, size_t xstride, const float* g, bf16_t* ob, size_t ostride, int lane) {
;     ...
;     for (int r = 0; r < 4; ++r) { float s = 0.f;
; #pragma unroll
;         for (int j = 0; j < 8; ++j) s += (v[r][j].x * v[r][j].x + v[r][j].y * v[r][j].y) + (v[r][j].z * v[r][j].z + v[r][j].w * v[r][j].w);
;         ss[r] = rsqrtf(wave_sum(s) * (1.f / D_) + EPS_); }
	v_mov_b32_e32 v157, v152
	v_mov_b32_e32 v167, v154
	v_pk_add_f32 v[156:157], v[156:157], v[166:167]
	v_pk_mul_f32 v[166:167], v[44:45], v[44:45]
	v_pk_add_f32 v[130:131], v[130:131], v[156:157]
	v_pk_mul_f32 v[156:157], v[46:47], v[46:47]
	v_mul_f32_e32 v148, v12, v12
	v_pk_mov_b32 v[168:169], v[166:167], v[156:157] op_sel:[1,0]
	v_mov_b32_e32 v167, v157
	v_pk_add_f32 v[156:157], v[168:169], v[166:167]
	v_mul_f32_e32 v150, v13, v13
	v_pk_add_f32 v[130:131], v[130:131], v[130:131] op_sel:[0,1] op_sel_hi:[1,0]
	v_pk_add_f32 v[156:157], v[156:157], v[156:157] op_sel:[0,1] op_sel_hi:[1,0]
	v_mov_b32_e32 v131, v148
	v_mov_b32_e32 v157, v150
	v_mul_f32_e32 v148, v29, v29
	v_pk_add_f32 v[130:131], v[130:131], v[156:157]
	v_pk_fma_f32 v[156:157], v[28:29], v[28:29], v[148:149] op_sel_hi:[1,1,0]
	v_mul_f32_e32 v148, v31, v31
	v_mul_f32_e32 v152, v14, v14
	v_mul_f32_e32 v154, v15, v15
	v_pk_fma_f32 v[166:167], v[30:31], v[30:31], v[148:149] op_sel_hi:[1,1,0]
	v_mov_b32_e32 v157, v152
	v_mov_b32_e32 v167, v154
	v_pk_add_f32 v[156:157], v[156:157], v[166:167]
	v_mov_b32_e32 v166, v123
	v_pk_add_f32 v[130:131], v[130:131], v[156:157]
	v_mov_b32_e32 v157, v128
	v_mov_b32_e32 v156, v130
	v_mov_b32_e32 v128, v131
	v_pk_add_f32 v[128:129], v[156:157], v[128:129]
	ds_bpermute_b32 v131, v193, v129
	ds_bpermute_b32 v130, v193, v128
	v_mov_b32_e32 v156, v121
	v_mov_b32_e32 v157, v105
	v_pk_mul_f32 v[156:157], v[156:157], v[156:157]
	v_mov_b32_e32 v167, v107
	s_waitcnt lgkmcnt(0)
	v_pk_add_f32 v[128:129], v[128:129], v[130:131]
	ds_bpermute_b32 v131, v194, v129
	ds_bpermute_b32 v130, v194, v128
	v_pk_mul_f32 v[166:167], v[166:167], v[166:167]
	v_mul_f32_e32 v152, v48, v48
	v_mul_f32_e32 v154, v49, v49
	v_mul_f32_e32 v159, v50, v50
	s_waitcnt lgkmcnt(0)
	v_pk_add_f32 v[128:129], v[128:129], v[130:131]
	ds_bpermute_b32 v131, v195, v129
	ds_bpermute_b32 v130, v195, v128
	v_mul_f32_e32 v160, v51, v51
	s_waitcnt lgkmcnt(0)
	v_pk_add_f32 v[128:129], v[128:129], v[130:131]
	ds_bpermute_b32 v131, v196, v129
	ds_bpermute_b32 v130, v196, v128
	s_waitcnt lgkmcnt(0)
	v_pk_add_f32 v[128:129], v[128:129], v[130:131]
	ds_bpermute_b32 v131, v197, v129
	ds_bpermute_b32 v130, v197, v128
	s_waitcnt lgkmcnt(0)
	v_pk_add_f32 v[128:129], v[128:129], v[130:131]
	ds_bpermute_b32 v131, v198, v129
	ds_bpermute_b32 v130, v198, v128
	s_waitcnt lgkmcnt(0)
	v_pk_add_f32 v[130:131], v[128:129], v[130:131]
	v_mov_b64_e32 v[128:129], s[8:9]
	v_pk_fma_f32 v[130:131], v[130:131], s[6:7], v[128:129] op_sel_hi:[1,0,0]
	s_nop 0
	v_mul_f32_e32 v148, 0x4b800000, v131
	v_cmp_gt_f32_e64 s[38:39], s97, v131
	v_cmp_gt_f32_e32 vcc, s97, v130
	s_nop 0
	v_cndmask_b32_e64 v131, v131, v148, s[38:39]
	v_rsq_f32_e32 v131, v131
	s_nop 0
	v_mul_f32_e32 v148, 0x45800000, v131
	v_cndmask_b32_e64 v150, v131, v148, s[38:39]
	v_mul_f32_e32 v131, 0x4b800000, v130
	v_cndmask_b32_e32 v130, v130, v131, vcc
	v_rsq_f32_e32 v130, v130
	v_pk_mul_f32 v[112:113], v[112:113], v[150:151] op_sel_hi:[1,0]
	v_pk_mul_f32 v[114:115], v[114:115], v[150:151] op_sel_hi:[1,0]
	v_pk_mul_f32 v[96:97], v[96:97], v[150:151] op_sel_hi:[1,0]
	v_mul_f32_e32 v131, 0x45800000, v130
	v_cndmask_b32_e32 v148, v130, v131, vcc
	v_mov_b32_e32 v130, v120
	v_mov_b32_e32 v131, v104
	v_pk_fma_f32 v[130:131], v[130:131], v[130:131], v[156:157]
	v_mov_b32_e32 v156, v122
	v_mov_b32_e32 v157, v106
	v_pk_fma_f32 v[156:157], v[156:157], v[156:157], v[166:167]
	v_pk_mul_f32 v[166:167], v[88:89], v[88:89]
	v_pk_add_f32 v[130:131], v[130:131], v[156:157]
	v_pk_mul_f32 v[156:157], v[90:91], v[90:91]
	v_pk_add_f32 v[130:131], v[130:131], v[130:131] op_sel:[0,1] op_sel_hi:[1,0]
	v_pk_mov_b32 v[168:169], v[166:167], v[156:157] op_sel:[1,0]
	v_mov_b32_e32 v167, v157
	v_pk_add_f32 v[156:157], v[168:169], v[166:167]
	v_mov_b32_e32 v131, v152
	v_pk_add_f32 v[156:157], v[156:157], v[156:157] op_sel:[0,1] op_sel_hi:[1,0]
	v_mul_f32_e32 v152, v73, v73
	v_mov_b32_e32 v157, v154
	v_pk_add_f32 v[130:131], v[130:131], v[156:157]
	v_pk_fma_f32 v[156:157], v[72:73], v[72:73], v[152:153] op_sel_hi:[1,1,0]
	v_mul_f32_e32 v152, v75, v75
	v_pk_fma_f32 v[166:167], v[74:75], v[74:75], v[152:153] op_sel_hi:[1,1,0]
	v_mov_b32_e32 v157, v159
	v_mov_b32_e32 v167, v160
	v_pk_add_f32 v[156:157], v[156:157], v[166:167]
	v_pk_mul_f32 v[166:167], v[36:37], v[36:37]
	v_pk_add_f32 v[130:131], v[130:131], v[156:157]
	v_pk_mul_f32 v[156:157], v[38:39], v[38:39]
	v_mul_f32_e32 v152, v4, v4
	v_pk_mov_b32 v[168:169], v[166:167], v[156:157] op_sel:[1,0]
	v_mov_b32_e32 v167, v157
	v_pk_add_f32 v[156:157], v[168:169], v[166:167]
	v_mul_f32_e32 v154, v5, v5
	v_pk_add_f32 v[130:131], v[130:131], v[130:131] op_sel:[0,1] op_sel_hi:[1,0]
	v_pk_add_f32 v[156:157], v[156:157], v[156:157] op_sel:[0,1] op_sel_hi:[1,0]
	v_mov_b32_e32 v131, v152
	v_mov_b32_e32 v157, v154
	v_mul_f32_e32 v152, v21, v21
	v_pk_add_f32 v[130:131], v[130:131], v[156:157]
	v_pk_fma_f32 v[156:157], v[20:21], v[20:21], v[152:153] op_sel_hi:[1,1,0]
	v_mul_f32_e32 v152, v23, v23
	v_mul_f32_e32 v159, v6, v6
	v_mul_f32_e32 v160, v7, v7
	v_pk_fma_f32 v[166:167], v[22:23], v[22:23], v[152:153] op_sel_hi:[1,1,0]
	v_mov_b32_e32 v157, v159
	v_mov_b32_e32 v167, v160
	v_pk_add_f32 v[156:157], v[156:157], v[166:167]
	v_mov_b32_e32 v166, v125
	v_mov_b32_e32 v167, v109
	v_pk_add_f32 v[130:131], v[130:131], v[156:157]
	v_mov_b32_e32 v156, v124
	v_mov_b32_e32 v157, v108
	v_pk_mul_f32 v[166:167], v[166:167], v[166:167]
	v_mov_b32_e32 v168, v127
	v_mov_b32_e32 v169, v111
	v_pk_fma_f32 v[156:157], v[156:157], v[156:157], v[166:167]
	v_mov_b32_e32 v166, v126
	v_mov_b32_e32 v167, v110
	v_pk_mul_f32 v[168:169], v[168:169], v[168:169]
	v_mul_f32_e32 v152, v52, v52
; DI unsigned pk2(float lo, float hi) { f32x2 v = {lo, hi}; bf16x2_t b = __builtin_convertvector(v, bf16x2_t); return __builtin_bit_cast(unsigned, b); }
; DI void rms_rows4_to_bf16(const float* xb, size_t xstride, const float* g, bf16_t* ob, size_t ostride, int lane) {
;     ...
;     for (int r = 0; r < 4; ++r) { float s = 0.f;
; #pragma unroll
;         for (int j = 0; j < 8; ++j) s += (v[r][j].x * v[r][j].x + v[r][j].y * v[r][j].y) + (v[r][j].z * v[r][j].z + v[r][j].w * v[r][j].w);
;         ss[r] = rsqrtf(wave_sum(s) * (1.f / D_) + EPS_); }
;     const f32x4* gr = (const f32x4*)g + lane;
; #pragma unroll
;     for (int j = 0; j < 8; ++j) { const f32x4 gg = gr[64 * j];
; #pragma unroll
;         for (int r = 0; r < 4; ++r) { u32x2 w; w.x = pk2(v[r][j].x * ss[r] * gg.x, v[r][j].y * ss[r] * gg.y); w.y = pk2(v[r][j].z * ss[r] * gg.z, v[r][j].w * ss[r] * gg.w);
	v_pk_fma_f32 v[166:167], v[166:167], v[166:167], v[168:169]
	v_pk_mul_f32 v[168:169], v[92:93], v[92:93]
	v_pk_add_f32 v[156:157], v[156:157], v[166:167]
	v_pk_mul_f32 v[166:167], v[94:95], v[94:95]
	v_mul_f32_e32 v154, v53, v53
	v_pk_mov_b32 v[170:171], v[168:169], v[166:167] op_sel:[1,0]
	v_mov_b32_e32 v169, v167
	v_pk_add_f32 v[166:167], v[170:171], v[168:169]
	v_pk_add_f32 v[156:157], v[156:157], v[156:157] op_sel:[0,1] op_sel_hi:[1,0]
	v_pk_add_f32 v[166:167], v[166:167], v[166:167] op_sel:[0,1] op_sel_hi:[1,0]
	v_mov_b32_e32 v157, v152
	v_mov_b32_e32 v167, v154
	v_mul_f32_e32 v152, v77, v77
	v_pk_add_f32 v[156:157], v[156:157], v[166:167]
	v_pk_fma_f32 v[166:167], v[76:77], v[76:77], v[152:153] op_sel_hi:[1,1,0]
	v_mul_f32_e32 v152, v79, v79
	v_mul_f32_e32 v159, v54, v54
	v_mul_f32_e32 v160, v55, v55
	v_pk_fma_f32 v[168:169], v[78:79], v[78:79], v[152:153] op_sel_hi:[1,1,0]
	v_mov_b32_e32 v167, v159
	v_mov_b32_e32 v169, v160
	v_pk_add_f32 v[166:167], v[166:167], v[168:169]
	v_pk_mul_f32 v[168:169], v[32:33], v[32:33]
	v_pk_add_f32 v[156:157], v[156:157], v[166:167]
	v_pk_mul_f32 v[166:167], v[34:35], v[34:35]
	v_mul_f32_e32 v152, v0, v0
	v_pk_mov_b32 v[170:171], v[168:169], v[166:167] op_sel:[1,0]
	v_mov_b32_e32 v169, v167
	v_pk_add_f32 v[166:167], v[170:171], v[168:169]
	v_mul_f32_e32 v154, v1, v1
	v_pk_add_f32 v[156:157], v[156:157], v[156:157] op_sel:[0,1] op_sel_hi:[1,0]
	v_pk_add_f32 v[166:167], v[166:167], v[166:167] op_sel:[0,1] op_sel_hi:[1,0]
	v_mov_b32_e32 v157, v152
	v_mov_b32_e32 v167, v154
	v_mul_f32_e32 v152, v17, v17
	v_pk_add_f32 v[156:157], v[156:157], v[166:167]
	v_pk_fma_f32 v[166:167], v[16:17], v[16:17], v[152:153] op_sel_hi:[1,1,0]
	v_mul_f32_e32 v152, v19, v19
	v_mul_f32_e32 v159, v2, v2
	v_mul_f32_e32 v160, v3, v3
	v_pk_fma_f32 v[168:169], v[18:19], v[18:19], v[152:153] op_sel_hi:[1,1,0]
	v_mov_b32_e32 v167, v159
	v_mov_b32_e32 v169, v160
	v_pk_add_f32 v[166:167], v[166:167], v[168:169]
	v_pk_mul_f32 v[98:99], v[98:99], v[150:151] op_sel_hi:[1,0]
	v_pk_add_f32 v[156:157], v[156:157], v[166:167]
	v_mov_b32_e32 v167, v130
	v_mov_b32_e32 v166, v156
	v_mov_b32_e32 v130, v157
	v_pk_add_f32 v[130:131], v[166:167], v[130:131]
	ds_bpermute_b32 v157, v193, v131
	ds_bpermute_b32 v156, v193, v130
	v_pk_mul_f32 v[80:81], v[80:81], v[150:151] op_sel_hi:[1,0]
	v_pk_mul_f32 v[82:83], v[82:83], v[150:151] op_sel_hi:[1,0]
	v_pk_mul_f32 v[64:65], v[64:65], v[150:151] op_sel_hi:[1,0]
	v_pk_mul_f32 v[66:67], v[66:67], v[150:151] op_sel_hi:[1,0]
	s_waitcnt lgkmcnt(0)
	v_pk_add_f32 v[130:131], v[130:131], v[156:157]
	ds_bpermute_b32 v157, v194, v131
	ds_bpermute_b32 v156, v194, v130
	v_pk_mul_f32 v[56:57], v[56:57], v[148:149] op_sel_hi:[1,0]
	v_pk_mul_f32 v[58:59], v[58:59], v[148:149] op_sel_hi:[1,0]
	v_pk_mul_f32 v[60:61], v[60:61], v[150:151] op_sel_hi:[1,0]
	v_pk_mul_f32 v[62:63], v[62:63], v[150:151] op_sel_hi:[1,0]
	s_waitcnt lgkmcnt(0)
	v_pk_add_f32 v[130:131], v[130:131], v[156:157]
	ds_bpermute_b32 v157, v195, v131
	ds_bpermute_b32 v156, v195, v130
	v_pk_mul_f32 v[40:41], v[40:41], v[150:151] op_sel_hi:[1,0]
	v_pk_mul_f32 v[42:43], v[42:43], v[150:151] op_sel_hi:[1,0]
	v_pk_mul_f32 v[24:25], v[24:25], v[150:151] op_sel_hi:[1,0]
	v_pk_mul_f32 v[26:27], v[26:27], v[150:151] op_sel_hi:[1,0]
	s_waitcnt lgkmcnt(0)
	v_pk_add_f32 v[130:131], v[130:131], v[156:157]
	ds_bpermute_b32 v157, v196, v131
	ds_bpermute_b32 v156, v196, v130
	v_pk_mul_f32 v[8:9], v[8:9], v[150:151] op_sel_hi:[1,0]
	v_pk_mul_f32 v[10:11], v[10:11], v[150:151] op_sel_hi:[1,0]
	s_waitcnt lgkmcnt(0)
	v_pk_add_f32 v[130:131], v[130:131], v[156:157]
	ds_bpermute_b32 v157, v197, v131
	ds_bpermute_b32 v156, v197, v130
	s_waitcnt lgkmcnt(0)
	v_pk_add_f32 v[130:131], v[130:131], v[156:157]
	ds_bpermute_b32 v157, v198, v131
	ds_bpermute_b32 v156, v198, v130
	s_waitcnt lgkmcnt(0)
	v_pk_add_f32 v[130:131], v[130:131], v[156:157]
	s_nop 0
	v_pk_fma_f32 v[128:129], v[130:131], s[6:7], v[128:129] op_sel_hi:[1,0,0]
	v_lshl_add_u64 v[156:157], v[142:143], 0, s[2:3]
	v_mul_f32_e32 v130, 0x4b800000, v129
	v_cmp_gt_f32_e64 s[38:39], s97, v129
	v_cmp_gt_f32_e32 vcc, s97, v128
	v_readlane_b32 s2, v254, 22
	v_cndmask_b32_e64 v129, v129, v130, s[38:39]
	v_rsq_f32_e32 v129, v129
	v_readlane_b32 s3, v254, 23
	v_mul_f32_e32 v130, 0x45800000, v129
	v_cndmask_b32_e64 v154, v129, v130, s[38:39]
	v_mul_f32_e32 v129, 0x4b800000, v128
	v_cndmask_b32_e32 v128, v128, v129, vcc
	v_rsq_f32_e32 v128, v128
	v_pk_mul_f32 v[48:49], v[48:49], v[154:155] op_sel_hi:[1,0]
	v_pk_mul_f32 v[50:51], v[50:51], v[154:155] op_sel_hi:[1,0]
	v_pk_mul_f32 v[36:37], v[36:37], v[154:155] op_sel_hi:[1,0]
	v_mul_f32_e32 v129, 0x45800000, v128
	v_cndmask_b32_e32 v152, v128, v129, vcc
	global_load_dwordx4 v[128:131], v[132:133], off
	v_pk_mul_f32 v[38:39], v[38:39], v[154:155] op_sel_hi:[1,0]
	v_pk_mul_f32 v[32:33], v[32:33], v[152:153] op_sel_hi:[1,0]
	v_pk_mul_f32 v[34:35], v[34:35], v[152:153] op_sel_hi:[1,0]
	v_pk_mul_f32 v[20:21], v[20:21], v[154:155] op_sel_hi:[1,0]
	v_pk_mul_f32 v[22:23], v[22:23], v[154:155] op_sel_hi:[1,0]
	v_pk_mul_f32 v[16:17], v[16:17], v[152:153] op_sel_hi:[1,0]
	v_pk_mul_f32 v[18:19], v[18:19], v[152:153] op_sel_hi:[1,0]
	v_pk_mul_f32 v[4:5], v[4:5], v[154:155] op_sel_hi:[1,0]
	v_pk_mul_f32 v[6:7], v[6:7], v[154:155] op_sel_hi:[1,0]
	v_pk_mul_f32 v[0:1], v[0:1], v[152:153] op_sel_hi:[1,0]
	v_pk_mul_f32 v[2:3], v[2:3], v[152:153] op_sel_hi:[1,0]
	s_waitcnt vmcnt(0)
; DI unsigned pk2(float lo, float hi) { f32x2 v = {lo, hi}; bf16x2_t b = __builtin_convertvector(v, bf16x2_t); return __builtin_bit_cast(unsigned, b); }
; DI void rms_rows4_to_bf16(const float* xb, size_t xstride, const float* g, bf16_t* ob, size_t ostride, int lane) {
;     ...
;     for (int j = 0; j < 8; ++j) { const f32x4 gg = gr[64 * j];
; #pragma unroll
;         for (int r = 0; r < 4; ++r) { u32x2 w; w.x = pk2(v[r][j].x * ss[r] * gg.x, v[r][j].y * ss[r] * gg.y); w.y = pk2(v[r][j].z * ss[r] * gg.z, v[r][j].w * ss[r] * gg.w);
;             ((u32x2*)(ob + r * ostride))[lane + 64 * j] = w; } }
	v_pk_mul_f32 v[112:113], v[112:113], v[128:129]
	v_pk_mul_f32 v[114:115], v[114:115], v[130:131]
	v_cvt_pk_bf16_f32 v112, v112, v113
	v_cvt_pk_bf16_f32 v113, v114, v115
	global_store_dwordx2 v[156:157], v[112:113], off
	v_pk_mul_f32 v[112:113], v[116:117], v[148:149] op_sel_hi:[1,0]
	v_pk_mul_f32 v[114:115], v[118:119], v[148:149] op_sel_hi:[1,0]
	v_pk_mul_f32 v[112:113], v[112:113], v[128:129]
	v_pk_mul_f32 v[114:115], v[114:115], v[130:131]
	v_cvt_pk_bf16_f32 v112, v112, v113
	v_cvt_pk_bf16_f32 v113, v114, v115
	v_lshl_add_u64 v[114:115], s[20:21], 1, v[156:157]
	global_store_dwordx2 v[114:115], v[112:113], off
	v_pk_mul_f32 v[112:113], v[120:121], v[154:155] op_sel_hi:[1,0]
	v_pk_mul_f32 v[116:117], v[122:123], v[154:155] op_sel_hi:[1,0]
	v_pk_mul_f32 v[112:113], v[128:129], v[112:113]
	v_pk_mul_f32 v[116:117], v[130:131], v[116:117]
	v_cvt_pk_bf16_f32 v112, v112, v113
	v_cvt_pk_bf16_f32 v113, v116, v117
	v_lshl_add_u64 v[114:115], v[114:115], 0, s[84:85]
	global_store_dwordx2 v[114:115], v[112:113], off
	v_pk_mul_f32 v[112:113], v[124:125], v[152:153] op_sel_hi:[1,0]
	v_pk_mul_f32 v[116:117], v[126:127], v[152:153] op_sel_hi:[1,0]
	v_pk_mul_f32 v[112:113], v[128:129], v[112:113]
	v_pk_mul_f32 v[116:117], v[130:131], v[116:117]
	v_cvt_pk_bf16_f32 v112, v112, v113
	v_cvt_pk_bf16_f32 v113, v116, v117
	v_lshl_add_u64 v[116:117], v[114:115], 0, s[84:85]
	global_store_dwordx2 v[116:117], v[112:113], off
	global_load_dwordx4 v[112:115], v[132:133], off offset:1024
	s_waitcnt vmcnt(0)
	v_pk_mul_f32 v[96:97], v[96:97], v[112:113]
	v_pk_mul_f32 v[98:99], v[98:99], v[114:115]
	v_cvt_pk_bf16_f32 v96, v96, v97
	v_cvt_pk_bf16_f32 v97, v98, v99
	global_store_dwordx2 v[156:157], v[96:97], off offset:512
	v_pk_mul_f32 v[96:97], v[100:101], v[148:149] op_sel_hi:[1,0]
	v_pk_mul_f32 v[98:99], v[102:103], v[148:149] op_sel_hi:[1,0]
	v_pk_mul_f32 v[96:97], v[96:97], v[112:113]
	v_pk_mul_f32 v[98:99], v[98:99], v[114:115]
	v_cvt_pk_bf16_f32 v96, v96, v97
	v_cvt_pk_bf16_f32 v97, v98, v99
	v_lshl_add_u64 v[98:99], v[116:117], 0, s[2:3]
	global_store_dwordx2 v[98:99], v[96:97], off offset:512
	v_pk_mul_f32 v[96:97], v[104:105], v[154:155] op_sel_hi:[1,0]
	v_pk_mul_f32 v[100:101], v[106:107], v[154:155] op_sel_hi:[1,0]
	v_pk_mul_f32 v[96:97], v[96:97], v[112:113]
	v_pk_mul_f32 v[100:101], v[100:101], v[114:115]
	v_cvt_pk_bf16_f32 v96, v96, v97
	v_cvt_pk_bf16_f32 v97, v100, v101
	v_lshl_add_u64 v[98:99], v[98:99], 0, s[84:85]
	global_store_dwordx2 v[98:99], v[96:97], off offset:512
	v_pk_mul_f32 v[96:97], v[108:109], v[152:153] op_sel_hi:[1,0]
	v_pk_mul_f32 v[100:101], v[110:111], v[152:153] op_sel_hi:[1,0]
	v_pk_mul_f32 v[96:97], v[112:113], v[96:97]
	v_pk_mul_f32 v[100:101], v[114:115], v[100:101]
	v_cvt_pk_bf16_f32 v96, v96, v97
	v_cvt_pk_bf16_f32 v97, v100, v101
	v_lshl_add_u64 v[100:101], v[98:99], 0, s[84:85]
	global_store_dwordx2 v[100:101], v[96:97], off offset:512
	global_load_dwordx4 v[96:99], v[132:133], off offset:2048
	s_waitcnt vmcnt(0)
	v_pk_mul_f32 v[80:81], v[80:81], v[96:97]
	v_pk_mul_f32 v[82:83], v[82:83], v[98:99]
	v_cvt_pk_bf16_f32 v80, v80, v81
	v_cvt_pk_bf16_f32 v81, v82, v83
	global_store_dwordx2 v[156:157], v[80:81], off offset:1024
	v_pk_mul_f32 v[80:81], v[84:85], v[148:149] op_sel_hi:[1,0]
	v_pk_mul_f32 v[82:83], v[86:87], v[148:149] op_sel_hi:[1,0]
	v_pk_mul_f32 v[80:81], v[80:81], v[96:97]
	v_pk_mul_f32 v[82:83], v[82:83], v[98:99]
	v_cvt_pk_bf16_f32 v80, v80, v81
	v_cvt_pk_bf16_f32 v81, v82, v83
	v_lshl_add_u64 v[82:83], v[100:101], 0, s[2:3]
	global_store_dwordx2 v[82:83], v[80:81], off offset:1024
	v_pk_mul_f32 v[80:81], v[88:89], v[154:155] op_sel_hi:[1,0]
	v_pk_mul_f32 v[84:85], v[90:91], v[154:155] op_sel_hi:[1,0]
	v_pk_mul_f32 v[80:81], v[80:81], v[96:97]
	v_pk_mul_f32 v[84:85], v[84:85], v[98:99]
	v_cvt_pk_bf16_f32 v80, v80, v81
	v_cvt_pk_bf16_f32 v81, v84, v85
	v_lshl_add_u64 v[82:83], v[82:83], 0, s[84:85]
	global_store_dwordx2 v[82:83], v[80:81], off offset:1024
	v_pk_mul_f32 v[80:81], v[92:93], v[152:153] op_sel_hi:[1,0]
	v_pk_mul_f32 v[84:85], v[94:95], v[152:153] op_sel_hi:[1,0]
	v_pk_mul_f32 v[80:81], v[80:81], v[96:97]
	v_pk_mul_f32 v[84:85], v[84:85], v[98:99]
	v_cvt_pk_bf16_f32 v80, v80, v81
	v_cvt_pk_bf16_f32 v81, v84, v85
	v_lshl_add_u64 v[84:85], v[82:83], 0, s[84:85]
	global_store_dwordx2 v[84:85], v[80:81], off offset:1024
	global_load_dwordx4 v[80:83], v[132:133], off offset:3072
	s_waitcnt vmcnt(0)
	v_pk_mul_f32 v[64:65], v[64:65], v[80:81]
	v_pk_mul_f32 v[66:67], v[66:67], v[82:83]
	v_cvt_pk_bf16_f32 v64, v64, v65
	v_cvt_pk_bf16_f32 v65, v66, v67
	global_store_dwordx2 v[156:157], v[64:65], off offset:1536
	v_pk_mul_f32 v[64:65], v[68:69], v[148:149] op_sel_hi:[1,0]
	v_pk_mul_f32 v[66:67], v[70:71], v[148:149] op_sel_hi:[1,0]
	v_pk_mul_f32 v[64:65], v[64:65], v[80:81]
	v_pk_mul_f32 v[66:67], v[66:67], v[82:83]
	v_cvt_pk_bf16_f32 v64, v64, v65
	v_cvt_pk_bf16_f32 v65, v66, v67
	v_lshl_add_u64 v[66:67], v[84:85], 0, s[2:3]
	global_store_dwordx2 v[66:67], v[64:65], off offset:1536
	v_pk_mul_f32 v[64:65], v[72:73], v[154:155] op_sel_hi:[1,0]
	v_pk_mul_f32 v[68:69], v[74:75], v[154:155] op_sel_hi:[1,0]
	v_pk_mul_f32 v[64:65], v[64:65], v[80:81]
	v_pk_mul_f32 v[68:69], v[68:69], v[82:83]
	v_cvt_pk_bf16_f32 v64, v64, v65
	v_cvt_pk_bf16_f32 v65, v68, v69
	v_lshl_add_u64 v[66:67], v[66:67], 0, s[84:85]
	global_store_dwordx2 v[66:67], v[64:65], off offset:1536
	v_pk_mul_f32 v[64:65], v[76:77], v[152:153] op_sel_hi:[1,0]
	v_pk_mul_f32 v[68:69], v[78:79], v[152:153] op_sel_hi:[1,0]
	v_pk_mul_f32 v[64:65], v[64:65], v[80:81]
	v_pk_mul_f32 v[68:69], v[68:69], v[82:83]
	v_cvt_pk_bf16_f32 v64, v64, v65
	v_cvt_pk_bf16_f32 v65, v68, v69
	v_lshl_add_u64 v[68:69], v[66:67], 0, s[84:85]
	global_store_dwordx2 v[68:69], v[64:65], off offset:1536
	global_load_dwordx4 v[64:67], v[134:135], off
	s_waitcnt vmcnt(0)
; DI unsigned pk2(float lo, float hi) { f32x2 v = {lo, hi}; bf16x2_t b = __builtin_convertvector(v, bf16x2_t); return __builtin_bit_cast(unsigned, b); }
; DI void rms_rows4_to_bf16(const float* xb, size_t xstride, const float* g, bf16_t* ob, size_t ostride, int lane) {
;     ...
;     for (int j = 0; j < 8; ++j) { const f32x4 gg = gr[64 * j];
; #pragma unroll
;         for (int r = 0; r < 4; ++r) { u32x2 w; w.x = pk2(v[r][j].x * ss[r] * gg.x, v[r][j].y * ss[r] * gg.y); w.y = pk2(v[r][j].z * ss[r] * gg.z, v[r][j].w * ss[r] * gg.w);
;             ((u32x2*)(ob + r * ostride))[lane + 64 * j] = w; } }
	v_pk_mul_f32 v[56:57], v[56:57], v[64:65]
	v_pk_mul_f32 v[58:59], v[58:59], v[66:67]
	v_pk_mul_f32 v[60:61], v[60:61], v[64:65]
	v_pk_mul_f32 v[62:63], v[62:63], v[66:67]
	v_cvt_pk_bf16_f32 v56, v56, v57
	v_cvt_pk_bf16_f32 v57, v58, v59
	v_lshl_add_u64 v[58:59], v[68:69], 0, s[2:3]
	v_pk_mul_f32 v[48:49], v[48:49], v[64:65]
	v_pk_mul_f32 v[50:51], v[50:51], v[66:67]
	v_cvt_pk_bf16_f32 v60, v60, v61
	v_cvt_pk_bf16_f32 v61, v62, v63
	v_cvt_pk_bf16_f32 v48, v48, v49
	v_cvt_pk_bf16_f32 v49, v50, v51
	v_lshl_add_u64 v[50:51], v[58:59], 0, s[84:85]
	global_store_dwordx2 v[156:157], v[60:61], off offset:2048
	global_store_dwordx2 v[58:59], v[56:57], off offset:2048
	global_store_dwordx2 v[50:51], v[48:49], off offset:2048
	v_pk_mul_f32 v[48:49], v[52:53], v[152:153] op_sel_hi:[1,0]
	v_pk_mul_f32 v[52:53], v[54:55], v[152:153] op_sel_hi:[1,0]
	v_pk_mul_f32 v[48:49], v[48:49], v[64:65]
	v_pk_mul_f32 v[52:53], v[52:53], v[66:67]
	v_cvt_pk_bf16_f32 v48, v48, v49
	v_cvt_pk_bf16_f32 v49, v52, v53
	v_lshl_add_u64 v[52:53], v[50:51], 0, s[84:85]
	global_store_dwordx2 v[52:53], v[48:49], off offset:2048
	global_load_dwordx4 v[48:51], v[136:137], off
	s_waitcnt vmcnt(0)
	v_pk_mul_f32 v[40:41], v[40:41], v[48:49]
	v_pk_mul_f32 v[42:43], v[42:43], v[50:51]
	v_cvt_pk_bf16_f32 v40, v40, v41
	v_cvt_pk_bf16_f32 v41, v42, v43
	global_store_dwordx2 v[156:157], v[40:41], off offset:2560
	v_pk_mul_f32 v[40:41], v[44:45], v[148:149] op_sel_hi:[1,0]
	v_pk_mul_f32 v[42:43], v[46:47], v[148:149] op_sel_hi:[1,0]
	v_pk_mul_f32 v[40:41], v[40:41], v[48:49]
	v_pk_mul_f32 v[42:43], v[42:43], v[50:51]
	v_cvt_pk_bf16_f32 v40, v40, v41
	v_cvt_pk_bf16_f32 v41, v42, v43
	v_lshl_add_u64 v[42:43], v[52:53], 0, s[2:3]
	v_pk_mul_f32 v[36:37], v[36:37], v[48:49]
	v_pk_mul_f32 v[38:39], v[38:39], v[50:51]
	v_cvt_pk_bf16_f32 v36, v36, v37
	v_cvt_pk_bf16_f32 v37, v38, v39
	v_lshl_add_u64 v[38:39], v[42:43], 0, s[84:85]
	v_pk_mul_f32 v[32:33], v[32:33], v[48:49]
	v_pk_mul_f32 v[34:35], v[34:35], v[50:51]
	global_store_dwordx2 v[42:43], v[40:41], off offset:2560
	global_store_dwordx2 v[38:39], v[36:37], off offset:2560
	v_cvt_pk_bf16_f32 v32, v32, v33
	v_cvt_pk_bf16_f32 v33, v34, v35
	v_lshl_add_u64 v[36:37], v[38:39], 0, s[84:85]
	global_store_dwordx2 v[36:37], v[32:33], off offset:2560
	global_load_dwordx4 v[32:35], v[138:139], off
	s_waitcnt vmcnt(0)
	v_pk_mul_f32 v[24:25], v[24:25], v[32:33]
	v_pk_mul_f32 v[26:27], v[26:27], v[34:35]
	v_cvt_pk_bf16_f32 v24, v24, v25
	v_cvt_pk_bf16_f32 v25, v26, v27
	global_store_dwordx2 v[156:157], v[24:25], off offset:3072
	v_pk_mul_f32 v[24:25], v[28:29], v[148:149] op_sel_hi:[1,0]
	v_pk_mul_f32 v[26:27], v[30:31], v[148:149] op_sel_hi:[1,0]
	v_pk_mul_f32 v[24:25], v[24:25], v[32:33]
	v_pk_mul_f32 v[26:27], v[26:27], v[34:35]
	v_cvt_pk_bf16_f32 v24, v24, v25
	v_cvt_pk_bf16_f32 v25, v26, v27
	v_lshl_add_u64 v[26:27], v[36:37], 0, s[2:3]
	v_pk_mul_f32 v[20:21], v[20:21], v[32:33]
	v_pk_mul_f32 v[22:23], v[22:23], v[34:35]
	v_cvt_pk_bf16_f32 v20, v20, v21
	v_cvt_pk_bf16_f32 v21, v22, v23
	v_lshl_add_u64 v[22:23], v[26:27], 0, s[84:85]
	v_pk_mul_f32 v[16:17], v[16:17], v[32:33]
	v_pk_mul_f32 v[18:19], v[18:19], v[34:35]
	global_store_dwordx2 v[26:27], v[24:25], off offset:3072
	global_store_dwordx2 v[22:23], v[20:21], off offset:3072
	v_cvt_pk_bf16_f32 v16, v16, v17
	v_cvt_pk_bf16_f32 v17, v18, v19
	v_lshl_add_u64 v[20:21], v[22:23], 0, s[84:85]
	global_store_dwordx2 v[20:21], v[16:17], off offset:3072
	global_load_dwordx4 v[16:19], v[140:141], off
	s_waitcnt vmcnt(0)
	v_pk_mul_f32 v[8:9], v[8:9], v[16:17]
	v_pk_mul_f32 v[10:11], v[10:11], v[18:19]
	v_cvt_pk_bf16_f32 v8, v8, v9
	v_cvt_pk_bf16_f32 v9, v10, v11
	global_store_dwordx2 v[156:157], v[8:9], off offset:3584
	v_pk_mul_f32 v[8:9], v[12:13], v[148:149] op_sel_hi:[1,0]
	v_pk_mul_f32 v[10:11], v[14:15], v[148:149] op_sel_hi:[1,0]
	v_pk_mul_f32 v[8:9], v[8:9], v[16:17]
	v_pk_mul_f32 v[10:11], v[10:11], v[18:19]
	v_cvt_pk_bf16_f32 v8, v8, v9
	v_cvt_pk_bf16_f32 v9, v10, v11
	v_lshl_add_u64 v[10:11], v[20:21], 0, s[2:3]
	v_pk_mul_f32 v[4:5], v[4:5], v[16:17]
	v_pk_mul_f32 v[6:7], v[6:7], v[18:19]
	v_cvt_pk_bf16_f32 v4, v4, v5
	v_cvt_pk_bf16_f32 v5, v6, v7
	v_lshl_add_u64 v[6:7], v[10:11], 0, s[84:85]
	v_pk_mul_f32 v[0:1], v[0:1], v[16:17]
	v_pk_mul_f32 v[2:3], v[2:3], v[18:19]
	v_cvt_pk_bf16_f32 v0, v0, v1
	v_cvt_pk_bf16_f32 v1, v2, v3
	v_lshl_add_u64 v[2:3], v[6:7], 0, s[84:85]
	global_store_dwordx2 v[10:11], v[8:9], off offset:3584
	global_store_dwordx2 v[6:7], v[4:5], off offset:3584
	global_store_dwordx2 v[2:3], v[0:1], off offset:3584
	s_branch .LBB0_1451

; #define PG8_STAGE(bufoff, gbase, voff) do { _Pragma("unroll") for (int _i = 0; _i < 2; ++_i) \
;         __builtin_amdgcn_global_load_lds((const unsigned*)((const char*)(gbase) + (voff)[_i]), (LAS unsigned*)(lds + (bufoff) + ldsw + _i * 8192), 16, 0, 0); } while (0)
; #define PG8_LDA(dst, b, h) do { _Pragma("unroll") for (int m = 0; m < 4; ++m) _Pragma("unroll") for (int k = 0; k < 2; ++k) dst[m][k] = *(const LAS bf16x8*)(lds + PG8_SA(b, h) + aoff + m * 2048 + k * 1024); } while (0)
; #define PG8_LDB(dst, b, h) do { _Pragma("unroll") for (int n = 0; n < 2; ++n) _Pragma("unroll") for (int k = 0; k < 2; ++k) dst[n][k] = *(const LAS bf16x8*)(lds + PG8_SB(b, h) + boff + n * 2048 + k * 1024); } while (0)
; #define PG8_MMA(ai, bj, At, Bt) do { __builtin_amdgcn_s_setprio(1); _Pragma("unroll") for (int m = 0; m < 4; ++m) _Pragma("unroll") for (int n = 0; n < 2; ++n) _Pragma("unroll") for (int k = 0; k < 2; ++k) \
;         acc[ai][bj][m][n] = __builtin_amdgcn_mfma_f32_16x16x32_bf16(Bt[n][k], At[m][k], acc[ai][bj][m][n], 0, 0, 0); __builtin_amdgcn_s_setprio(0); } while (0)
; #define PG8_WAIT_V(n) asm volatile("s_waitcnt vmcnt(" #n ")" ::: "memory")
; #define PG8_WAIT_L(n) asm volatile("s_waitcnt lgkmcnt(" #n ")" ::: "memory")
; #define PG8_BAR __builtin_amdgcn_s_barrier()
; template <class Epi, class Sched>
; DI void gemm_phase(LAS unsigned char* lds, const Gemm g, const Sched& S, const Epi& E) {
;     ...
;         for (int t = 0; t < nt; t += 2) {
;             const bool last = (t == nt - 2);
;             const char* a1 = cA + (size_t)(t + 1) * kstep;
;             const char* a2 = last ? nA : cA + (size_t)(t + 2) * kstep; const char* b2 = last ? nB : cB + (size_t)(t + 2) * kstep;
;             const char* a3 = a2 + kstep; const char* b3 = b2 + kstep;
;             PG8_LDB(B0, 0, 0); PG8_SCHED; PG8_LDA(At, 0, 0); PG8_STAGE(PG8_SA(1, 1), a1 + hstep, voffA);
;             PG8_WAIT_L(8); PG8_BAR; PG8_WAIT_L(0); PG8_MMA(0, 0, At, B0); PG8_BAR; PG8_SCHED;
;             PG8_LDB(B1, 0, 1); PG8_STAGE(PG8_SB(0, 0), b2, voffB);
;             PG8_BAR; PG8_WAIT_L(0); PG8_MMA(0, 1, At, B1); PG8_BAR;
;             PG8_LDA(At, 0, 1); PG8_STAGE(PG8_SA(0, 0), a2, voffA);
;             PG8_BAR; PG8_WAIT_L(0); PG8_MMA(1, 0, At, B0); PG8_BAR; PG8_SCHED;
;             PG8_STAGE(PG8_SB(0, 1), b2 + hstep, voffB);
;             PG8_WAIT_V(6); PG8_BAR; PG8_MMA(1, 1, At, B1); PG8_BAR;
.LBB0_1520:
	s_add_u32 s2, s12, 0xfff80080
	s_addc_u32 s3, s13, -1
	s_add_i32 s47, 0, 0x10000
	v_add_u32_e32 v138, s47, v141
	ds_read_b128 v[144:147], v138
	ds_read_b128 v[148:151], v138 offset:1024
	ds_read_b128 v[152:155], v138 offset:2048
	ds_read_b128 v[156:159], v138 offset:3072
	s_cmp_eq_u32 s46, 28
	s_cselect_b32 s3, s7, s3
	s_cselect_b32 s2, s42, s2
	s_cselect_b32 s15, s5, s45
	s_cselect_b32 s14, s43, s44
	v_lshl_add_u64 v[138:139], s[12:13], 0, v[136:137]
	s_add_i32 m0, s29, 0xc000
	ds_read_b128 v[170:173], v143
	ds_read_b128 v[174:177], v143 offset:1024
	ds_read_b128 v[178:181], v143 offset:2048
	ds_read_b128 v[182:185], v143 offset:3072
	ds_read_b128 v[194:197], v143 offset:4096
	ds_read_b128 v[198:201], v143 offset:5120
	ds_read_b128 v[202:205], v143 offset:6144
	ds_read_b128 v[206:209], v143 offset:7168
	global_load_lds_dwordx4 v[138:139], off
	v_lshl_add_u64 v[138:139], s[12:13], 0, v[134:135]
	s_add_i32 m0, s29, 0xe000
	s_nop 0
	global_load_lds_dwordx4 v[138:139], off
	s_waitcnt lgkmcnt(8)
	s_barrier
	s_waitcnt lgkmcnt(0)
	s_setprio 1
	s_waitcnt lgkmcnt(0)
	v_mfma_f32_16x16x32_bf16 v[124:127], v[144:147], v[170:173], v[124:127]
	v_mfma_f32_16x16x32_bf16 v[120:123], v[152:155], v[170:173], v[120:123]
	v_mfma_f32_16x16x32_bf16 v[108:111], v[144:147], v[178:181], v[108:111]
	v_mfma_f32_16x16x32_bf16 v[104:107], v[152:155], v[178:181], v[104:107]
	v_mfma_f32_16x16x32_bf16 v[92:95], v[144:147], v[194:197], v[92:95]
	v_mfma_f32_16x16x32_bf16 v[88:91], v[152:155], v[194:197], v[88:91]
	v_mfma_f32_16x16x32_bf16 v[76:79], v[144:147], v[202:205], v[76:79]
	v_mfma_f32_16x16x32_bf16 v[72:75], v[152:155], v[202:205], v[72:75]
	v_mfma_f32_16x16x32_bf16 v[124:127], v[148:151], v[174:177], v[124:127]
	v_mfma_f32_16x16x32_bf16 v[120:123], v[156:159], v[174:177], v[120:123]
	v_mfma_f32_16x16x32_bf16 v[108:111], v[148:151], v[182:185], v[108:111]
	v_mfma_f32_16x16x32_bf16 v[104:107], v[156:159], v[182:185], v[104:107]
	v_mfma_f32_16x16x32_bf16 v[92:95], v[148:151], v[198:201], v[92:95]
	v_mfma_f32_16x16x32_bf16 v[88:91], v[156:159], v[198:201], v[88:91]
	v_mfma_f32_16x16x32_bf16 v[76:79], v[148:151], v[206:209], v[76:79]
	v_mfma_f32_16x16x32_bf16 v[72:75], v[156:159], v[206:209], v[72:75]
	s_setprio 0
	s_barrier
	s_add_i32 s50, 0, 0x14000
	v_add_u32_e32 v138, s50, v141
	s_add_i32 s47, s47, s23
	ds_read_b128 v[210:213], v138
	ds_read_b128 v[214:217], v138 offset:1024
	ds_read_b128 v[218:221], v138 offset:2048
	ds_read_b128 v[222:225], v138 offset:3072
	v_lshl_add_u64 v[138:139], s[14:15], 0, v[160:161]
	s_mov_b32 m0, s47
	v_lshl_add_u64 v[166:167], s[14:15], 0, v[128:129]
	global_load_lds_dwordx4 v[138:139], off
	s_add_i32 m0, s47, 0x2000
	s_nop 0
	global_load_lds_dwordx4 v[166:167], off
	s_barrier
	s_waitcnt lgkmcnt(0)
	s_setprio 1
	s_waitcnt lgkmcnt(0)
	v_mfma_f32_16x16x32_bf16 v[116:119], v[210:213], v[170:173], v[116:119]
	v_mfma_f32_16x16x32_bf16 v[112:115], v[218:221], v[170:173], v[112:115]
	v_mfma_f32_16x16x32_bf16 v[100:103], v[210:213], v[178:181], v[100:103]
	v_mfma_f32_16x16x32_bf16 v[96:99], v[218:221], v[178:181], v[96:99]
	v_mfma_f32_16x16x32_bf16 v[84:87], v[210:213], v[194:197], v[84:87]
	v_mfma_f32_16x16x32_bf16 v[80:83], v[218:221], v[194:197], v[80:83]
	v_mfma_f32_16x16x32_bf16 v[68:71], v[210:213], v[202:205], v[68:71]
	v_mfma_f32_16x16x32_bf16 v[64:67], v[218:221], v[202:205], v[64:67]
	v_mfma_f32_16x16x32_bf16 v[116:119], v[214:217], v[174:177], v[116:119]
	v_mfma_f32_16x16x32_bf16 v[112:115], v[222:225], v[174:177], v[112:115]
	v_mfma_f32_16x16x32_bf16 v[100:103], v[214:217], v[182:185], v[100:103]
	v_mfma_f32_16x16x32_bf16 v[96:99], v[222:225], v[182:185], v[96:99]
	v_mfma_f32_16x16x32_bf16 v[84:87], v[214:217], v[198:201], v[84:87]
	v_mfma_f32_16x16x32_bf16 v[80:83], v[222:225], v[198:201], v[80:83]
	v_mfma_f32_16x16x32_bf16 v[68:71], v[214:217], v[206:209], v[68:71]
	v_mfma_f32_16x16x32_bf16 v[64:67], v[222:225], v[206:209], v[64:67]
	s_setprio 0
	s_mov_b32 m0, s29
	v_lshl_add_u64 v[168:169], s[2:3], 0, v[132:133]
	s_barrier
	ds_read_b128 v[170:173], v143 offset:16384
	ds_read_b128 v[174:177], v143 offset:17408
	ds_read_b128 v[178:181], v143 offset:18432
	ds_read_b128 v[182:185], v143 offset:19456
	ds_read_b128 v[194:197], v143 offset:20480
	ds_read_b128 v[198:201], v143 offset:21504
	ds_read_b128 v[202:205], v143 offset:22528
	ds_read_b128 v[206:209], v143 offset:23552
	global_load_lds_dwordx4 v[168:169], off
	v_lshl_add_u64 v[190:191], s[2:3], 0, v[130:131]
	s_mov_b32 m0, s30
	s_nop 0
	global_load_lds_dwordx4 v[190:191], off
	s_barrier
	s_waitcnt lgkmcnt(0)
	s_setprio 1
	s_waitcnt lgkmcnt(0)
	v_mfma_f32_16x16x32_bf16 v[60:63], v[144:147], v[170:173], v[60:63]
	v_mfma_f32_16x16x32_bf16 v[56:59], v[152:155], v[170:173], v[56:59]
	v_mfma_f32_16x16x32_bf16 v[44:47], v[144:147], v[178:181], v[44:47]
	v_mfma_f32_16x16x32_bf16 v[40:43], v[152:155], v[178:181], v[40:43]
	v_mfma_f32_16x16x32_bf16 v[28:31], v[144:147], v[194:197], v[28:31]
	v_mfma_f32_16x16x32_bf16 v[24:27], v[152:155], v[194:197], v[24:27]
	v_mfma_f32_16x16x32_bf16 v[12:15], v[144:147], v[202:205], v[12:15]
	v_mfma_f32_16x16x32_bf16 v[8:11], v[152:155], v[202:205], v[8:11]
	v_mfma_f32_16x16x32_bf16 v[60:63], v[148:151], v[174:177], v[60:63]
	v_mfma_f32_16x16x32_bf16 v[56:59], v[156:159], v[174:177], v[56:59]
	v_mfma_f32_16x16x32_bf16 v[44:47], v[148:151], v[182:185], v[44:47]
	v_mfma_f32_16x16x32_bf16 v[40:43], v[156:159], v[182:185], v[40:43]
	v_mfma_f32_16x16x32_bf16 v[28:31], v[148:151], v[198:201], v[28:31]
	v_mfma_f32_16x16x32_bf16 v[24:27], v[156:159], v[198:201], v[24:27]
	v_mfma_f32_16x16x32_bf16 v[12:15], v[148:151], v[206:209], v[12:15]
	v_mfma_f32_16x16x32_bf16 v[8:11], v[156:159], v[206:209], v[8:11]
	s_setprio 0
	s_barrier
; #define PG8_STAGE(bufoff, gbase, voff) do { _Pragma("unroll") for (int _i = 0; _i < 2; ++_i) \
;         __builtin_amdgcn_global_load_lds((const unsigned*)((const char*)(gbase) + (voff)[_i]), (LAS unsigned*)(lds + (bufoff) + ldsw + _i * 8192), 16, 0, 0); } while (0)
; #define PG8_LDA(dst, b, h) do { _Pragma("unroll") for (int m = 0; m < 4; ++m) _Pragma("unroll") for (int k = 0; k < 2; ++k) dst[m][k] = *(const LAS bf16x8*)(lds + PG8_SA(b, h) + aoff + m * 2048 + k * 1024); } while (0)
; #define PG8_LDB(dst, b, h) do { _Pragma("unroll") for (int n = 0; n < 2; ++n) _Pragma("unroll") for (int k = 0; k < 2; ++k) dst[n][k] = *(const LAS bf16x8*)(lds + PG8_SB(b, h) + boff + n * 2048 + k * 1024); } while (0)
; #define PG8_MMA(ai, bj, At, Bt) do { __builtin_amdgcn_s_setprio(1); _Pragma("unroll") for (int m = 0; m < 4; ++m) _Pragma("unroll") for (int n = 0; n < 2; ++n) _Pragma("unroll") for (int k = 0; k < 2; ++k) \
;         acc[ai][bj][m][n] = __builtin_amdgcn_mfma_f32_16x16x32_bf16(Bt[n][k], At[m][k], acc[ai][bj][m][n], 0, 0, 0); __builtin_amdgcn_s_setprio(0); } while (0)
; #define PG8_WAIT_V(n) asm volatile("s_waitcnt vmcnt(" #n ")" ::: "memory")
; #define PG8_WAIT_L(n) asm volatile("s_waitcnt lgkmcnt(" #n ")" ::: "memory")
; #define PG8_BAR __builtin_amdgcn_s_barrier()
; #define PG8_SCHED __builtin_amdgcn_sched_barrier(0)
; #define PG8_STAGE(bufoff, gbase, RR, KK) do { _Pragma("unroll") for (int _i = 0; _i < 2; ++_i) \
;         __builtin_amdgcn_global_load_lds((const unsigned*)((const char*)(gbase) + (RR[_i] * (unsigned)(KK) + C2[_i])), (LAS unsigned*)(lds + (bufoff) + ldsw + _i * 8192), 16, 0, 0); } while (0)
; template <class Epi, class Sched>
; DI void gemm_phase(LAS unsigned char* lds, const Gemm g, const Sched& S, const Epi& E) {
;     ...
;             PG8_STAGE(PG8_SB(0, 1), b2 + hstep, voffB);
;             PG8_WAIT_V(6); PG8_BAR; PG8_MMA(1, 1, At, B1); PG8_BAR;
;             PG8_LDB(B0, 1, 0); PG8_SCHED; PG8_LDA(At, 1, 0); PG8_STAGE(PG8_SA(0, 1), a2 + hstep, voffA);
;             PG8_WAIT_L(8); PG8_BAR; PG8_WAIT_L(0); PG8_MMA(0, 0, At, B0); PG8_BAR; PG8_SCHED;
;             PG8_LDB(B1, 1, 1); PG8_STAGE(PG8_SB(1, 0), b3, voffB);
;             PG8_BAR; PG8_WAIT_L(0); PG8_MMA(0, 1, At, B1); PG8_BAR;
;             PG8_LDA(At, 1, 1); PG8_STAGE(PG8_SA(1, 0), a3, voffA);
;             PG8_BAR; PG8_WAIT_L(0); PG8_MMA(1, 0, At, B0); PG8_BAR; PG8_SCHED;
	s_add_u32 s48, s14, 0x80000
	s_addc_u32 s49, s15, 0
	s_add_i32 s47, s50, s23
	v_lshl_add_u64 v[144:145], s[48:49], 0, v[160:161]
	s_mov_b32 m0, s47
	s_nop 0
	global_load_lds_dwordx4 v[144:145], off
	v_lshl_add_u64 v[144:145], s[48:49], 0, v[128:129]
	s_add_i32 m0, s47, 0x2000
	s_nop 0
	global_load_lds_dwordx4 v[144:145], off
	s_waitcnt vmcnt(6)
	s_barrier
	s_setprio 1
	v_mfma_f32_16x16x32_bf16 v[52:55], v[210:213], v[170:173], v[52:55]
	v_mfma_f32_16x16x32_bf16 v[48:51], v[218:221], v[170:173], v[48:51]
	v_mfma_f32_16x16x32_bf16 v[36:39], v[210:213], v[178:181], v[36:39]
	v_mfma_f32_16x16x32_bf16 v[32:35], v[218:221], v[178:181], v[32:35]
	v_mfma_f32_16x16x32_bf16 v[20:23], v[210:213], v[194:197], v[20:23]
	v_mfma_f32_16x16x32_bf16 v[16:19], v[218:221], v[194:197], v[16:19]
	v_mfma_f32_16x16x32_bf16 v[4:7], v[210:213], v[202:205], v[4:7]
	v_mfma_f32_16x16x32_bf16 v[0:3], v[218:221], v[202:205], v[0:3]
	v_mfma_f32_16x16x32_bf16 v[52:55], v[214:217], v[174:177], v[52:55]
	v_mfma_f32_16x16x32_bf16 v[48:51], v[222:225], v[174:177], v[48:51]
	v_mfma_f32_16x16x32_bf16 v[36:39], v[214:217], v[182:185], v[36:39]
	v_mfma_f32_16x16x32_bf16 v[32:35], v[222:225], v[182:185], v[32:35]
	v_mfma_f32_16x16x32_bf16 v[20:23], v[214:217], v[198:201], v[20:23]
	v_mfma_f32_16x16x32_bf16 v[16:19], v[222:225], v[198:201], v[16:19]
	v_mfma_f32_16x16x32_bf16 v[4:7], v[214:217], v[206:209], v[4:7]
	v_mfma_f32_16x16x32_bf16 v[0:3], v[222:225], v[206:209], v[0:3]
	s_setprio 0
	s_add_i32 s47, 0, 0x18000
	v_add_u32_e32 v156, s47, v141
	s_barrier
	ds_read_b128 v[144:147], v156
	ds_read_b128 v[148:151], v156 offset:1024
	ds_read_b128 v[152:155], v156 offset:2048
	ds_read_b128 v[156:159], v156 offset:3072
	s_add_u32 s2, s2, 0x80000
	s_addc_u32 s3, s3, 0
	s_mov_b32 m0, s31
	v_lshl_add_u64 v[210:211], s[2:3], 0, v[132:133]
	ds_read_b128 v[170:173], v143 offset:32768
	ds_read_b128 v[174:177], v143 offset:33792
	ds_read_b128 v[178:181], v143 offset:34816
	ds_read_b128 v[182:185], v143 offset:35840
	ds_read_b128 v[194:197], v143 offset:36864
	ds_read_b128 v[198:201], v143 offset:37888
	ds_read_b128 v[202:205], v143 offset:38912
	ds_read_b128 v[206:209], v143 offset:39936
	global_load_lds_dwordx4 v[210:211], off
	v_lshl_add_u64 v[210:211], s[2:3], 0, v[130:131]
	s_mov_b32 m0, s34
	s_nop 0
	global_load_lds_dwordx4 v[210:211], off
	s_waitcnt lgkmcnt(8)
	s_barrier
	s_waitcnt lgkmcnt(0)
	s_setprio 1
	s_waitcnt lgkmcnt(0)
	v_mfma_f32_16x16x32_bf16 v[124:127], v[144:147], v[170:173], v[124:127]
	v_mfma_f32_16x16x32_bf16 v[120:123], v[152:155], v[170:173], v[120:123]
	v_mfma_f32_16x16x32_bf16 v[108:111], v[144:147], v[178:181], v[108:111]
	v_mfma_f32_16x16x32_bf16 v[104:107], v[152:155], v[178:181], v[104:107]
	v_mfma_f32_16x16x32_bf16 v[92:95], v[144:147], v[194:197], v[92:95]
	v_mfma_f32_16x16x32_bf16 v[88:91], v[152:155], v[194:197], v[88:91]
	v_mfma_f32_16x16x32_bf16 v[76:79], v[144:147], v[202:205], v[76:79]
	v_mfma_f32_16x16x32_bf16 v[72:75], v[152:155], v[202:205], v[72:75]
	v_mfma_f32_16x16x32_bf16 v[124:127], v[148:151], v[174:177], v[124:127]
	v_mfma_f32_16x16x32_bf16 v[120:123], v[156:159], v[174:177], v[120:123]
	v_mfma_f32_16x16x32_bf16 v[108:111], v[148:151], v[182:185], v[108:111]
	v_mfma_f32_16x16x32_bf16 v[104:107], v[156:159], v[182:185], v[104:107]
	v_mfma_f32_16x16x32_bf16 v[92:95], v[148:151], v[198:201], v[92:95]
	v_mfma_f32_16x16x32_bf16 v[88:91], v[156:159], v[198:201], v[88:91]
	v_mfma_f32_16x16x32_bf16 v[76:79], v[148:151], v[206:209], v[76:79]
	v_mfma_f32_16x16x32_bf16 v[72:75], v[156:159], v[206:209], v[72:75]
	s_setprio 0
	s_barrier
	s_add_i32 s48, 0, 0x1c000
	s_add_i32 s2, s47, s23
	v_add_u32_e32 v193, s48, v141
	v_lshl_add_u64 v[138:139], v[138:139], 0, s[78:79]
	s_mov_b32 m0, s2
	ds_read_b128 v[210:213], v193
	ds_read_b128 v[214:217], v193 offset:1024
	ds_read_b128 v[218:221], v193 offset:2048
	ds_read_b128 v[222:225], v193 offset:3072
	global_load_lds_dwordx4 v[138:139], off
	v_lshl_add_u64 v[138:139], v[166:167], 0, s[78:79]
	s_add_i32 m0, s2, 0x2000
	s_nop 0
	global_load_lds_dwordx4 v[138:139], off
	s_barrier
	s_waitcnt lgkmcnt(0)
	s_setprio 1
	s_waitcnt lgkmcnt(0)
	v_mfma_f32_16x16x32_bf16 v[116:119], v[210:213], v[170:173], v[116:119]
	v_mfma_f32_16x16x32_bf16 v[112:115], v[218:221], v[170:173], v[112:115]
	v_mfma_f32_16x16x32_bf16 v[100:103], v[210:213], v[178:181], v[100:103]
	v_mfma_f32_16x16x32_bf16 v[96:99], v[218:221], v[178:181], v[96:99]
	v_mfma_f32_16x16x32_bf16 v[84:87], v[210:213], v[194:197], v[84:87]
	v_mfma_f32_16x16x32_bf16 v[80:83], v[218:221], v[194:197], v[80:83]
	v_mfma_f32_16x16x32_bf16 v[68:71], v[210:213], v[202:205], v[68:71]
	v_mfma_f32_16x16x32_bf16 v[64:67], v[218:221], v[202:205], v[64:67]
	v_mfma_f32_16x16x32_bf16 v[116:119], v[214:217], v[174:177], v[116:119]
	v_mfma_f32_16x16x32_bf16 v[112:115], v[222:225], v[174:177], v[112:115]
	v_mfma_f32_16x16x32_bf16 v[100:103], v[214:217], v[182:185], v[100:103]
	v_mfma_f32_16x16x32_bf16 v[96:99], v[222:225], v[182:185], v[96:99]
	v_mfma_f32_16x16x32_bf16 v[84:87], v[214:217], v[198:201], v[84:87]
	v_mfma_f32_16x16x32_bf16 v[80:83], v[222:225], v[198:201], v[80:83]
	v_mfma_f32_16x16x32_bf16 v[68:71], v[214:217], v[206:209], v[68:71]
	v_mfma_f32_16x16x32_bf16 v[64:67], v[222:225], v[206:209], v[64:67]
	s_setprio 0
	s_mov_b32 m0, s35
	v_lshl_add_u64 v[138:139], v[168:169], 0, s[78:79]
	s_barrier
	ds_read_b128 v[170:173], v143 offset:49152
	ds_read_b128 v[174:177], v143 offset:50176
	ds_read_b128 v[178:181], v143 offset:51200
	ds_read_b128 v[182:185], v143 offset:52224
	ds_read_b128 v[194:197], v143 offset:53248
	ds_read_b128 v[198:201], v143 offset:54272
	ds_read_b128 v[202:205], v143 offset:55296
	ds_read_b128 v[206:209], v143 offset:56320
	global_load_lds_dwordx4 v[138:139], off
	v_lshl_add_u64 v[138:139], v[190:191], 0, s[78:79]
	s_mov_b32 m0, s36
	s_nop 0
	global_load_lds_dwordx4 v[138:139], off
	s_barrier
; DI unsigned pk2(float lo, float hi) { f32x2 v = {lo, hi}; bf16x2_t b = __builtin_convertvector(v, bf16x2_t); return __builtin_bit_cast(unsigned, b); }
; #define PG8_STAGE(bufoff, gbase, voff) do { _Pragma("unroll") for (int _i = 0; _i < 2; ++_i) \
;         __builtin_amdgcn_global_load_lds((const unsigned*)((const char*)(gbase) + (voff)[_i]), (LAS unsigned*)(lds + (bufoff) + ldsw + _i * 8192), 16, 0, 0); } while (0)
; #define PG8_LDA(dst, b, h) do { _Pragma("unroll") for (int m = 0; m < 4; ++m) _Pragma("unroll") for (int k = 0; k < 2; ++k) dst[m][k] = *(const LAS bf16x8*)(lds + PG8_SA(b, h) + aoff + m * 2048 + k * 1024); } while (0)
; #define PG8_MMA(ai, bj, At, Bt) do { __builtin_amdgcn_s_setprio(1); _Pragma("unroll") for (int m = 0; m < 4; ++m) _Pragma("unroll") for (int n = 0; n < 2; ++n) _Pragma("unroll") for (int k = 0; k < 2; ++k) \
;         acc[ai][bj][m][n] = __builtin_amdgcn_mfma_f32_16x16x32_bf16(Bt[n][k], At[m][k], acc[ai][bj][m][n], 0, 0, 0); __builtin_amdgcn_s_setprio(0); } while (0)
; #define PG8_BAR __builtin_amdgcn_s_barrier()
; template <class Epi, class Sched>
; DI void gemm_phase(LAS unsigned char* lds, const Gemm g, const Sched& S, const Epi& E) {
;     ...
;             PG8_BAR; PG8_WAIT_L(0); PG8_MMA(0, 1, At, B1); PG8_BAR;
;             PG8_LDA(At, 1, 1); PG8_STAGE(PG8_SA(1, 0), a3, voffA);
;             PG8_BAR; PG8_WAIT_L(0); PG8_MMA(1, 0, At, B0); PG8_BAR; PG8_SCHED;
;             PG8_STAGE(PG8_SB(1, 1), b3 + hstep, voffB);
;             PG8_WAIT_V(6); PG8_BAR; PG8_MMA(1, 1, At, B1); PG8_BAR;
;     DI void operator()(const AccT& acc, const Unit& u, int wr, int wc, int fr, int fq) const {
;         const int row0 = u.pm * BM + wr * 64 + fr, col0 = u.pn * BM + wc * 32 + 8 * fq;
; #pragma unroll
;         for (int ai = 0; ai < 2; ++ai)
; #pragma unroll
;             for (int m = 0; m < 4; ++m) { bf16_t* rowp = H + (size_t)(row0 + ai * HALF + m * 16) * FF_ + col0;
; #pragma unroll
;                 for (int bj = 0; bj < 2; ++bj) { f32x4 v0 = acc[ai][bj][m][0], v1 = acc[ai][bj][m][1];
; #pragma unroll
;                     for (int j = 0; j < 4; ++j) { const float a = fmaxf(v0[j], 0.f), b = fmaxf(v1[j], 0.f); v0[j] = a * a; v1[j] = b * b; }
;                     u32x4 w; w.x = pk2(v0[0], v0[1]); w.y = pk2(v0[2], v0[3]); w.z = pk2(v1[0], v1[1]); w.w = pk2(v1[2], v1[3]);
;                     *(u32x4*)(rowp + bj * HALF) = w; } }
	s_waitcnt lgkmcnt(0)
	s_setprio 1
	s_waitcnt lgkmcnt(0)
	v_mfma_f32_16x16x32_bf16 v[60:63], v[144:147], v[170:173], v[60:63]
	v_mfma_f32_16x16x32_bf16 v[56:59], v[152:155], v[170:173], v[56:59]
	v_mfma_f32_16x16x32_bf16 v[44:47], v[144:147], v[178:181], v[44:47]
	v_mfma_f32_16x16x32_bf16 v[40:43], v[152:155], v[178:181], v[40:43]
	v_mfma_f32_16x16x32_bf16 v[28:31], v[144:147], v[194:197], v[28:31]
	v_mfma_f32_16x16x32_bf16 v[24:27], v[152:155], v[194:197], v[24:27]
	v_mfma_f32_16x16x32_bf16 v[12:15], v[144:147], v[202:205], v[12:15]
	v_mfma_f32_16x16x32_bf16 v[8:11], v[152:155], v[202:205], v[8:11]
	v_mfma_f32_16x16x32_bf16 v[60:63], v[148:151], v[174:177], v[60:63]
	v_mfma_f32_16x16x32_bf16 v[56:59], v[156:159], v[174:177], v[56:59]
	v_mfma_f32_16x16x32_bf16 v[44:47], v[148:151], v[182:185], v[44:47]
	v_mfma_f32_16x16x32_bf16 v[40:43], v[156:159], v[182:185], v[40:43]
	v_mfma_f32_16x16x32_bf16 v[28:31], v[148:151], v[198:201], v[28:31]
	v_mfma_f32_16x16x32_bf16 v[24:27], v[156:159], v[198:201], v[24:27]
	v_mfma_f32_16x16x32_bf16 v[12:15], v[148:151], v[206:209], v[12:15]
	v_mfma_f32_16x16x32_bf16 v[8:11], v[156:159], v[206:209], v[8:11]
	s_setprio 0
	s_barrier
	s_add_u32 s2, s14, 0x80080
	s_addc_u32 s3, s15, 0
	s_add_i32 s14, s48, s23
	v_lshl_add_u64 v[138:139], s[2:3], 0, v[160:161]
	s_mov_b32 m0, s14
	s_nop 0
	global_load_lds_dwordx4 v[138:139], off
	v_lshl_add_u64 v[138:139], s[2:3], 0, v[128:129]
	s_add_i32 m0, s14, 0x2000
	s_nop 0
	global_load_lds_dwordx4 v[138:139], off
	s_waitcnt vmcnt(6)
	s_barrier
	s_setprio 1
	v_mfma_f32_16x16x32_bf16 v[52:55], v[210:213], v[170:173], v[52:55]
	v_mfma_f32_16x16x32_bf16 v[48:51], v[218:221], v[170:173], v[48:51]
	v_mfma_f32_16x16x32_bf16 v[36:39], v[210:213], v[178:181], v[36:39]
	v_mfma_f32_16x16x32_bf16 v[32:35], v[218:221], v[178:181], v[32:35]
	v_mfma_f32_16x16x32_bf16 v[20:23], v[210:213], v[194:197], v[20:23]
	v_mfma_f32_16x16x32_bf16 v[16:19], v[218:221], v[194:197], v[16:19]
	v_mfma_f32_16x16x32_bf16 v[4:7], v[210:213], v[202:205], v[4:7]
	v_mfma_f32_16x16x32_bf16 v[0:3], v[218:221], v[202:205], v[0:3]
	v_mfma_f32_16x16x32_bf16 v[52:55], v[214:217], v[174:177], v[52:55]
	v_mfma_f32_16x16x32_bf16 v[48:51], v[222:225], v[174:177], v[48:51]
	v_mfma_f32_16x16x32_bf16 v[36:39], v[214:217], v[182:185], v[36:39]
	v_mfma_f32_16x16x32_bf16 v[32:35], v[222:225], v[182:185], v[32:35]
	v_mfma_f32_16x16x32_bf16 v[20:23], v[214:217], v[198:201], v[20:23]
	v_mfma_f32_16x16x32_bf16 v[16:19], v[222:225], v[198:201], v[16:19]
	v_mfma_f32_16x16x32_bf16 v[4:7], v[214:217], v[206:209], v[4:7]
	v_mfma_f32_16x16x32_bf16 v[0:3], v[222:225], v[206:209], v[0:3]
	s_setprio 0
	s_add_i32 s46, s46, 2
	s_add_u32 s44, s44, 0x100
	s_addc_u32 s45, s45, 0
	s_add_u32 s12, s12, 0x100
	s_addc_u32 s13, s13, 0
	s_cmp_gt_u32 s46, 29
	s_barrier
	s_cbranch_scc0 .LBB0_1520
	v_lshl_add_u32 v144, s41, 8, v140
	v_lshl_or_b32 v138, s40, 8, v142
	v_ashrrev_i32_e32 v145, 31, v144
	v_ashrrev_i32_e32 v139, 31, v138
	v_lshlrev_b64 v[146:147], 14, v[144:145]
	v_max_f32_e32 v120, v120, v120
	v_max_f32_e32 v121, v121, v121
	v_lshl_add_u64 v[146:147], s[0:1], 0, v[146:147]
	v_lshlrev_b64 v[148:149], 1, v[138:139]
	v_max_f32_e32 v120, 0, v120
	v_max_f32_e32 v121, 0, v121
	v_lshl_add_u64 v[138:139], v[146:147], 0, v[148:149]
	v_pk_mul_f32 v[146:147], v[120:121], v[120:121]
	v_max_f32_e32 v121, v122, v122
	v_max_f32_e32 v124, v124, v124
	v_max_f32_e32 v125, v125, v125
	v_max_f32_e32 v120, v126, v126
	v_max_f32_e32 v122, 0, v121
	v_max_f32_e32 v121, v127, v127
	v_max_f32_e32 v123, v123, v123
	v_max_f32_e32 v124, 0, v124
	v_max_f32_e32 v125, 0, v125
	v_max_f32_e32 v120, 0, v120
	v_max_f32_e32 v121, 0, v121
	v_max_f32_e32 v123, 0, v123
	v_pk_mul_f32 v[124:125], v[124:125], v[124:125]
	v_pk_mul_f32 v[126:127], v[120:121], v[120:121]
	v_pk_mul_f32 v[150:151], v[122:123], v[122:123]
	v_max_f32_e32 v112, v112, v112
	v_max_f32_e32 v113, v113, v113
	v_cvt_pk_bf16_f32 v120, v124, v125
	v_cvt_pk_bf16_f32 v121, v126, v127
	v_cvt_pk_bf16_f32 v122, v146, v147
	v_cvt_pk_bf16_f32 v123, v150, v151
	v_max_f32_e32 v112, 0, v112
	v_max_f32_e32 v113, 0, v113
	global_store_dwordx4 v[138:139], v[120:123], off
	v_max_f32_e32 v116, v116, v116
	v_max_f32_e32 v117, v117, v117
	v_pk_mul_f32 v[120:121], v[112:113], v[112:113]
	v_max_f32_e32 v113, v114, v114
	v_max_f32_e32 v112, v118, v118
	v_max_f32_e32 v114, 0, v113
	v_max_f32_e32 v113, v119, v119
	v_max_f32_e32 v115, v115, v115
	v_max_f32_e32 v116, 0, v116
	v_max_f32_e32 v117, 0, v117
	v_max_f32_e32 v112, 0, v112
	v_max_f32_e32 v113, 0, v113
	v_max_f32_e32 v115, 0, v115
	v_pk_mul_f32 v[116:117], v[116:117], v[116:117]
	v_pk_mul_f32 v[118:119], v[112:113], v[112:113]
	v_pk_mul_f32 v[122:123], v[114:115], v[114:115]
	v_max_f32_e32 v104, v104, v104
	v_max_f32_e32 v105, v105, v105
	v_cvt_pk_bf16_f32 v112, v116, v117
	v_cvt_pk_bf16_f32 v113, v118, v119
	v_cvt_pk_bf16_f32 v114, v120, v121
	v_cvt_pk_bf16_f32 v115, v122, v123
	v_max_f32_e32 v104, 0, v104
	v_max_f32_e32 v105, 0, v105
	global_store_dwordx4 v[138:139], v[112:115], off offset:256
	v_max_f32_e32 v108, v108, v108
	v_max_f32_e32 v109, v109, v109
	v_or_b32_e32 v112, 16, v144
	v_pk_mul_f32 v[114:115], v[104:105], v[104:105]
	v_max_f32_e32 v105, v106, v106
	v_ashrrev_i32_e32 v113, 31, v112
	v_max_f32_e32 v104, v110, v110
	v_max_f32_e32 v106, 0, v105
	v_max_f32_e32 v105, v111, v111
	v_max_f32_e32 v107, v107, v107
	v_lshlrev_b64 v[112:113], 14, v[112:113]
	v_max_f32_e32 v108, 0, v108
	v_max_f32_e32 v109, 0, v109
	v_max_f32_e32 v104, 0, v104
	v_max_f32_e32 v105, 0, v105
	v_max_f32_e32 v107, 0, v107
	v_lshl_add_u64 v[112:113], s[0:1], 0, v[112:113]
; DI unsigned pk2(float lo, float hi) { f32x2 v = {lo, hi}; bf16x2_t b = __builtin_convertvector(v, bf16x2_t); return __builtin_bit_cast(unsigned, b); }
;     DI void operator()(const AccT& acc, const Unit& u, int wr, int wc, int fr, int fq) const {
;         const int row0 = u.pm * BM + wr * 64 + fr, col0 = u.pn * BM + wc * 32 + 8 * fq;
; #pragma unroll
;         for (int ai = 0; ai < 2; ++ai)
; #pragma unroll
;             for (int m = 0; m < 4; ++m) { bf16_t* rowp = H + (size_t)(row0 + ai * HALF + m * 16) * FF_ + col0;
; #pragma unroll
;                 for (int bj = 0; bj < 2; ++bj) { f32x4 v0 = acc[ai][bj][m][0], v1 = acc[ai][bj][m][1];
; #pragma unroll
;                     for (int j = 0; j < 4; ++j) { const float a = fmaxf(v0[j], 0.f), b = fmaxf(v1[j], 0.f); v0[j] = a * a; v1[j] = b * b; }
;                     u32x4 w; w.x = pk2(v0[0], v0[1]); w.y = pk2(v0[2], v0[3]); w.z = pk2(v1[0], v1[1]); w.w = pk2(v1[2], v1[3]);
;                     *(u32x4*)(rowp + bj * HALF) = w; } }
	v_pk_mul_f32 v[108:109], v[108:109], v[108:109]
	v_pk_mul_f32 v[110:111], v[104:105], v[104:105]
	v_pk_mul_f32 v[116:117], v[106:107], v[106:107]
	v_max_f32_e32 v96, v96, v96
	v_max_f32_e32 v97, v97, v97
	v_lshl_add_u64 v[112:113], v[112:113], 0, v[148:149]
	v_cvt_pk_bf16_f32 v104, v108, v109
	v_cvt_pk_bf16_f32 v105, v110, v111
	v_cvt_pk_bf16_f32 v106, v114, v115
	v_cvt_pk_bf16_f32 v107, v116, v117
	v_max_f32_e32 v96, 0, v96
	v_max_f32_e32 v97, 0, v97
	global_store_dwordx4 v[112:113], v[104:107], off
	v_max_f32_e32 v100, v100, v100
	v_max_f32_e32 v101, v101, v101
	v_pk_mul_f32 v[104:105], v[96:97], v[96:97]
	v_max_f32_e32 v97, v98, v98
	v_max_f32_e32 v96, v102, v102
	v_max_f32_e32 v98, 0, v97
	v_max_f32_e32 v97, v103, v103
	v_max_f32_e32 v99, v99, v99
	v_max_f32_e32 v100, 0, v100
	v_max_f32_e32 v101, 0, v101
	v_max_f32_e32 v96, 0, v96
	v_max_f32_e32 v97, 0, v97
	v_max_f32_e32 v99, 0, v99
	v_pk_mul_f32 v[100:101], v[100:101], v[100:101]
	v_pk_mul_f32 v[102:103], v[96:97], v[96:97]
	v_pk_mul_f32 v[106:107], v[98:99], v[98:99]
	v_max_f32_e32 v88, v88, v88
	v_max_f32_e32 v89, v89, v89
	v_cvt_pk_bf16_f32 v96, v100, v101
	v_cvt_pk_bf16_f32 v97, v102, v103
	v_cvt_pk_bf16_f32 v98, v104, v105
	v_cvt_pk_bf16_f32 v99, v106, v107
	v_max_f32_e32 v88, 0, v88
	v_max_f32_e32 v89, 0, v89
	global_store_dwordx4 v[112:113], v[96:99], off offset:256
	v_max_f32_e32 v92, v92, v92
	v_max_f32_e32 v93, v93, v93
	v_or_b32_e32 v96, 32, v144
	v_pk_mul_f32 v[98:99], v[88:89], v[88:89]
	v_max_f32_e32 v89, v90, v90
	v_ashrrev_i32_e32 v97, 31, v96
	v_max_f32_e32 v88, v94, v94
	v_max_f32_e32 v90, 0, v89
	v_max_f32_e32 v89, v95, v95
	v_max_f32_e32 v91, v91, v91
	v_lshlrev_b64 v[96:97], 14, v[96:97]
	v_max_f32_e32 v92, 0, v92
	v_max_f32_e32 v93, 0, v93
	v_max_f32_e32 v88, 0, v88
	v_max_f32_e32 v89, 0, v89
	v_max_f32_e32 v91, 0, v91
	v_lshl_add_u64 v[96:97], s[0:1], 0, v[96:97]
	v_pk_mul_f32 v[92:93], v[92:93], v[92:93]
	v_pk_mul_f32 v[94:95], v[88:89], v[88:89]
	v_pk_mul_f32 v[100:101], v[90:91], v[90:91]
	v_max_f32_e32 v80, v80, v80
	v_max_f32_e32 v81, v81, v81
	v_lshl_add_u64 v[96:97], v[96:97], 0, v[148:149]
	v_cvt_pk_bf16_f32 v88, v92, v93
	v_cvt_pk_bf16_f32 v89, v94, v95
	v_cvt_pk_bf16_f32 v90, v98, v99
	v_cvt_pk_bf16_f32 v91, v100, v101
	v_max_f32_e32 v80, 0, v80
	v_max_f32_e32 v81, 0, v81
	global_store_dwordx4 v[96:97], v[88:91], off
	v_max_f32_e32 v84, v84, v84
	v_max_f32_e32 v85, v85, v85
	v_pk_mul_f32 v[88:89], v[80:81], v[80:81]
	v_max_f32_e32 v81, v82, v82
	v_max_f32_e32 v80, v86, v86
	v_max_f32_e32 v82, 0, v81
	v_max_f32_e32 v81, v87, v87
	v_max_f32_e32 v83, v83, v83
	v_max_f32_e32 v84, 0, v84
	v_max_f32_e32 v85, 0, v85
	v_max_f32_e32 v80, 0, v80
	v_max_f32_e32 v81, 0, v81
	v_max_f32_e32 v83, 0, v83
	v_pk_mul_f32 v[84:85], v[84:85], v[84:85]
	v_pk_mul_f32 v[86:87], v[80:81], v[80:81]
	v_pk_mul_f32 v[90:91], v[82:83], v[82:83]
	v_max_f32_e32 v72, v72, v72
	v_max_f32_e32 v73, v73, v73
	v_cvt_pk_bf16_f32 v80, v84, v85
	v_cvt_pk_bf16_f32 v81, v86, v87
	v_cvt_pk_bf16_f32 v82, v88, v89
	v_cvt_pk_bf16_f32 v83, v90, v91
	v_max_f32_e32 v72, 0, v72
	v_max_f32_e32 v73, 0, v73
	global_store_dwordx4 v[96:97], v[80:83], off offset:256
	v_max_f32_e32 v76, v76, v76
	v_max_f32_e32 v77, v77, v77
	v_or_b32_e32 v80, 48, v144
	v_pk_mul_f32 v[82:83], v[72:73], v[72:73]
	v_max_f32_e32 v73, v74, v74
	v_ashrrev_i32_e32 v81, 31, v80
	v_max_f32_e32 v72, v78, v78
	v_max_f32_e32 v74, 0, v73
	v_max_f32_e32 v73, v79, v79
	v_max_f32_e32 v75, v75, v75
	v_lshlrev_b64 v[80:81], 14, v[80:81]
	v_max_f32_e32 v76, 0, v76
	v_max_f32_e32 v77, 0, v77
	v_max_f32_e32 v72, 0, v72
	v_max_f32_e32 v73, 0, v73
	v_max_f32_e32 v75, 0, v75
	v_lshl_add_u64 v[80:81], s[0:1], 0, v[80:81]
	v_pk_mul_f32 v[76:77], v[76:77], v[76:77]
	v_pk_mul_f32 v[78:79], v[72:73], v[72:73]
	v_pk_mul_f32 v[84:85], v[74:75], v[74:75]
	v_max_f32_e32 v64, v64, v64
	v_max_f32_e32 v65, v65, v65
	v_lshl_add_u64 v[80:81], v[80:81], 0, v[148:149]
	v_cvt_pk_bf16_f32 v72, v76, v77
	v_cvt_pk_bf16_f32 v73, v78, v79
	v_cvt_pk_bf16_f32 v74, v82, v83
	v_cvt_pk_bf16_f32 v75, v84, v85
	v_max_f32_e32 v64, 0, v64
	v_max_f32_e32 v65, 0, v65
	global_store_dwordx4 v[80:81], v[72:75], off
	v_max_f32_e32 v68, v68, v68
	v_max_f32_e32 v69, v69, v69
	v_pk_mul_f32 v[72:73], v[64:65], v[64:65]
	v_max_f32_e32 v65, v66, v66
	v_max_f32_e32 v64, v70, v70
	v_max_f32_e32 v66, 0, v65
	v_max_f32_e32 v65, v71, v71
	v_max_f32_e32 v67, v67, v67
	v_max_f32_e32 v68, 0, v68
	v_max_f32_e32 v69, 0, v69
	v_max_f32_e32 v64, 0, v64
	v_max_f32_e32 v65, 0, v65
	v_max_f32_e32 v67, 0, v67
	v_pk_mul_f32 v[68:69], v[68:69], v[68:69]
	v_pk_mul_f32 v[70:71], v[64:65], v[64:65]
	v_pk_mul_f32 v[74:75], v[66:67], v[66:67]
	v_max_f32_e32 v56, v56, v56
	v_max_f32_e32 v57, v57, v57
	v_cvt_pk_bf16_f32 v64, v68, v69
	v_cvt_pk_bf16_f32 v65, v70, v71
	v_cvt_pk_bf16_f32 v66, v72, v73
	v_cvt_pk_bf16_f32 v67, v74, v75
	v_max_f32_e32 v56, 0, v56
	v_max_f32_e32 v57, 0, v57
	global_store_dwordx4 v[80:81], v[64:67], off offset:256
	v_max_f32_e32 v60, v60, v60
	v_max_f32_e32 v61, v61, v61
	v_pk_mul_f32 v[66:67], v[56:57], v[56:57]
	v_max_f32_e32 v57, v58, v58
	s_mov_b64 s[2:3], 0x200000
	v_max_f32_e32 v60, 0, v60
	v_max_f32_e32 v61, 0, v61
	v_max_f32_e32 v56, v62, v62
	v_max_f32_e32 v58, 0, v57
	v_max_f32_e32 v57, v63, v63
	v_max_f32_e32 v59, v59, v59
	v_lshl_add_u64 v[64:65], v[138:139], 0, s[2:3]
	v_pk_mul_f32 v[60:61], v[60:61], v[60:61]
	v_max_f32_e32 v56, 0, v56
	v_max_f32_e32 v57, 0, v57
	v_max_f32_e32 v59, 0, v59
	s_mov_b32 s2, 0x200000
	v_pk_mul_f32 v[62:63], v[56:57], v[56:57]
	v_pk_mul_f32 v[68:69], v[58:59], v[58:59]
	v_cvt_pk_bf16_f32 v56, v60, v61
	v_add_co_u32_e32 v60, vcc, s2, v138
; DI unsigned pk2(float lo, float hi) { f32x2 v = {lo, hi}; bf16x2_t b = __builtin_convertvector(v, bf16x2_t); return __builtin_bit_cast(unsigned, b); }
; #define PG8_WAIT_V(n) asm volatile("s_waitcnt vmcnt(" #n ")" ::: "memory")
; #define PG8_BAR __builtin_amdgcn_s_barrier()
; #define PG8_WAIT_V(n) asm volatile("s_waitcnt vmcnt(" #n ")" ::: "memory")
; #define PG8_BAR __builtin_amdgcn_s_barrier()
; template <class Epi, class Sched>
; DI void gemm_phase(LAS unsigned char* lds, const Gemm g, const Sched& S, const Epi& E) {
;     ...
;         E(acc, cur, wr, wc, fr, fq);
;         if (!has_next) break;
; #pragma unroll
;         for (int a = 0; a < 2; ++a)
; #pragma unroll
;             for (int b = 0; b < 2; ++b)
; #pragma unroll
;                 for (int m = 0; m < 4; ++m)
; #pragma unroll
;                     for (int n = 0; n < 2; ++n) acc[a][b][m][n] = (f32x4){0.f, 0.f, 0.f, 0.f};
;         cur = nxt; cA = nA; cB = nB; ++ui;
;     }
;     PG8_WAIT_V(0);
;     if (wr == 0) PG8_BAR;
;     PG8_BAR;
;     DI void operator()(const AccT& acc, const Unit& u, int wr, int wc, int fr, int fq) const {
;         const int row0 = u.pm * BM + wr * 64 + fr, col0 = u.pn * BM + wc * 32 + 8 * fq;
; #pragma unroll
;         for (int ai = 0; ai < 2; ++ai)
; #pragma unroll
;             for (int m = 0; m < 4; ++m) { bf16_t* rowp = H + (size_t)(row0 + ai * HALF + m * 16) * FF_ + col0;
; #pragma unroll
;                 for (int bj = 0; bj < 2; ++bj) { f32x4 v0 = acc[ai][bj][m][0], v1 = acc[ai][bj][m][1];
; #pragma unroll
;                     for (int j = 0; j < 4; ++j) { const float a = fmaxf(v0[j], 0.f), b = fmaxf(v1[j], 0.f); v0[j] = a * a; v1[j] = b * b; }
;                     u32x4 w; w.x = pk2(v0[0], v0[1]); w.y = pk2(v0[2], v0[3]); w.z = pk2(v1[0], v1[1]); w.w = pk2(v1[2], v1[3]);
;                     *(u32x4*)(rowp + bj * HALF) = w; } }
	v_max_f32_e32 v48, v48, v48
	v_max_f32_e32 v49, v49, v49
	v_cvt_pk_bf16_f32 v57, v62, v63
	v_cvt_pk_bf16_f32 v58, v66, v67
	v_cvt_pk_bf16_f32 v59, v68, v69
	v_addc_co_u32_e32 v61, vcc, 0, v139, vcc
	v_max_f32_e32 v48, 0, v48
	v_max_f32_e32 v49, 0, v49
	global_store_dwordx4 v[60:61], v[56:59], off
	v_max_f32_e32 v52, v52, v52
	v_max_f32_e32 v53, v53, v53
	v_pk_mul_f32 v[56:57], v[48:49], v[48:49]
	v_max_f32_e32 v49, v50, v50
	v_max_f32_e32 v48, v54, v54
	v_max_f32_e32 v50, 0, v49
	v_max_f32_e32 v49, v55, v55
	v_max_f32_e32 v51, v51, v51
	v_max_f32_e32 v52, 0, v52
	v_max_f32_e32 v53, 0, v53
	v_max_f32_e32 v48, 0, v48
	v_max_f32_e32 v49, 0, v49
	v_max_f32_e32 v51, 0, v51
	v_pk_mul_f32 v[52:53], v[52:53], v[52:53]
	v_pk_mul_f32 v[54:55], v[48:49], v[48:49]
	v_pk_mul_f32 v[58:59], v[50:51], v[50:51]
	v_max_f32_e32 v40, v40, v40
	v_max_f32_e32 v41, v41, v41
	v_cvt_pk_bf16_f32 v48, v52, v53
	v_cvt_pk_bf16_f32 v49, v54, v55
	v_cvt_pk_bf16_f32 v50, v56, v57
	v_cvt_pk_bf16_f32 v51, v58, v59
	v_max_f32_e32 v40, 0, v40
	v_max_f32_e32 v41, 0, v41
	global_store_dwordx4 v[64:65], v[48:51], off offset:256
	v_max_f32_e32 v44, v44, v44
	v_max_f32_e32 v45, v45, v45
	v_pk_mul_f32 v[50:51], v[40:41], v[40:41]
	v_max_f32_e32 v41, v42, v42
	s_mov_b64 s[2:3], 0x240000
	v_max_f32_e32 v44, 0, v44
	v_max_f32_e32 v45, 0, v45
	v_max_f32_e32 v40, v46, v46
	v_max_f32_e32 v42, 0, v41
	v_max_f32_e32 v41, v47, v47
	v_max_f32_e32 v43, v43, v43
	v_lshl_add_u64 v[48:49], v[138:139], 0, s[2:3]
	v_pk_mul_f32 v[44:45], v[44:45], v[44:45]
	v_max_f32_e32 v40, 0, v40
	v_max_f32_e32 v41, 0, v41
	v_max_f32_e32 v43, 0, v43
	s_mov_b32 s2, 0x240000
	v_pk_mul_f32 v[46:47], v[40:41], v[40:41]
	v_pk_mul_f32 v[52:53], v[42:43], v[42:43]
	v_cvt_pk_bf16_f32 v40, v44, v45
	v_add_co_u32_e32 v44, vcc, s2, v138
	v_max_f32_e32 v32, v32, v32
	v_max_f32_e32 v33, v33, v33
	v_cvt_pk_bf16_f32 v41, v46, v47
	v_cvt_pk_bf16_f32 v42, v50, v51
	v_cvt_pk_bf16_f32 v43, v52, v53
	v_addc_co_u32_e32 v45, vcc, 0, v139, vcc
	v_max_f32_e32 v32, 0, v32
	v_max_f32_e32 v33, 0, v33
	global_store_dwordx4 v[44:45], v[40:43], off
	v_max_f32_e32 v36, v36, v36
	v_max_f32_e32 v37, v37, v37
	v_pk_mul_f32 v[40:41], v[32:33], v[32:33]
	v_max_f32_e32 v33, v34, v34
	v_max_f32_e32 v32, v38, v38
	v_max_f32_e32 v34, 0, v33
	v_max_f32_e32 v33, v39, v39
	v_max_f32_e32 v35, v35, v35
	v_max_f32_e32 v36, 0, v36
	v_max_f32_e32 v37, 0, v37
	v_max_f32_e32 v32, 0, v32
	v_max_f32_e32 v33, 0, v33
	v_max_f32_e32 v35, 0, v35
	v_pk_mul_f32 v[36:37], v[36:37], v[36:37]
	v_pk_mul_f32 v[38:39], v[32:33], v[32:33]
	v_pk_mul_f32 v[42:43], v[34:35], v[34:35]
	v_max_f32_e32 v24, v24, v24
	v_max_f32_e32 v25, v25, v25
	v_cvt_pk_bf16_f32 v32, v36, v37
	v_cvt_pk_bf16_f32 v33, v38, v39
	v_cvt_pk_bf16_f32 v34, v40, v41
	v_cvt_pk_bf16_f32 v35, v42, v43
	v_max_f32_e32 v24, 0, v24
	v_max_f32_e32 v25, 0, v25
	global_store_dwordx4 v[48:49], v[32:35], off offset:256
	v_max_f32_e32 v28, v28, v28
	v_max_f32_e32 v29, v29, v29
	v_pk_mul_f32 v[34:35], v[24:25], v[24:25]
	v_max_f32_e32 v25, v26, v26
	s_mov_b64 s[2:3], 0x280000
	v_max_f32_e32 v28, 0, v28
	v_max_f32_e32 v29, 0, v29
	v_max_f32_e32 v24, v30, v30
	v_max_f32_e32 v26, 0, v25
	v_max_f32_e32 v25, v31, v31
	v_max_f32_e32 v27, v27, v27
	v_lshl_add_u64 v[32:33], v[138:139], 0, s[2:3]
	v_pk_mul_f32 v[28:29], v[28:29], v[28:29]
	v_max_f32_e32 v24, 0, v24
	v_max_f32_e32 v25, 0, v25
	v_max_f32_e32 v27, 0, v27
	s_mov_b32 s2, 0x280000
	v_pk_mul_f32 v[30:31], v[24:25], v[24:25]
	v_pk_mul_f32 v[36:37], v[26:27], v[26:27]
	v_cvt_pk_bf16_f32 v24, v28, v29
	v_add_co_u32_e32 v28, vcc, s2, v138
	v_max_f32_e32 v16, v16, v16
	v_max_f32_e32 v17, v17, v17
	v_cvt_pk_bf16_f32 v25, v30, v31
	v_cvt_pk_bf16_f32 v26, v34, v35
	v_cvt_pk_bf16_f32 v27, v36, v37
	v_addc_co_u32_e32 v29, vcc, 0, v139, vcc
	v_max_f32_e32 v16, 0, v16
	v_max_f32_e32 v17, 0, v17
	global_store_dwordx4 v[28:29], v[24:27], off
	v_max_f32_e32 v20, v20, v20
	v_max_f32_e32 v21, v21, v21
	v_pk_mul_f32 v[24:25], v[16:17], v[16:17]
	v_max_f32_e32 v17, v18, v18
	v_max_f32_e32 v16, v22, v22
	v_max_f32_e32 v18, 0, v17
	v_max_f32_e32 v17, v23, v23
	v_max_f32_e32 v19, v19, v19
	v_max_f32_e32 v20, 0, v20
	v_max_f32_e32 v21, 0, v21
	v_max_f32_e32 v16, 0, v16
	v_max_f32_e32 v17, 0, v17
	v_max_f32_e32 v19, 0, v19
	v_pk_mul_f32 v[20:21], v[20:21], v[20:21]
	v_pk_mul_f32 v[22:23], v[16:17], v[16:17]
	v_pk_mul_f32 v[26:27], v[18:19], v[18:19]
	v_max_f32_e32 v8, v8, v8
	v_max_f32_e32 v9, v9, v9
	v_cvt_pk_bf16_f32 v16, v20, v21
	v_cvt_pk_bf16_f32 v17, v22, v23
	v_cvt_pk_bf16_f32 v18, v24, v25
	v_cvt_pk_bf16_f32 v19, v26, v27
	v_max_f32_e32 v8, 0, v8
	v_max_f32_e32 v9, 0, v9
	global_store_dwordx4 v[32:33], v[16:19], off offset:256
	v_max_f32_e32 v12, v12, v12
	v_max_f32_e32 v13, v13, v13
	v_pk_mul_f32 v[18:19], v[8:9], v[8:9]
	v_max_f32_e32 v9, v10, v10
	s_mov_b64 s[2:3], 0x2c0000
	v_max_f32_e32 v12, 0, v12
	v_max_f32_e32 v13, 0, v13
	v_max_f32_e32 v8, v14, v14
	v_max_f32_e32 v10, 0, v9
	v_max_f32_e32 v9, v15, v15
	v_max_f32_e32 v11, v11, v11
	v_lshl_add_u64 v[16:17], v[138:139], 0, s[2:3]
	v_pk_mul_f32 v[12:13], v[12:13], v[12:13]
	v_max_f32_e32 v8, 0, v8
	v_max_f32_e32 v9, 0, v9
	v_max_f32_e32 v11, 0, v11
	s_mov_b32 s2, 0x2c0000
	v_pk_mul_f32 v[14:15], v[8:9], v[8:9]
	v_pk_mul_f32 v[20:21], v[10:11], v[10:11]
	v_cvt_pk_bf16_f32 v8, v12, v13
	v_add_co_u32_e32 v12, vcc, s2, v138
	v_max_f32_e32 v0, v0, v0
	v_max_f32_e32 v1, v1, v1
	v_cvt_pk_bf16_f32 v9, v14, v15
	v_cvt_pk_bf16_f32 v10, v18, v19
	v_cvt_pk_bf16_f32 v11, v20, v21
	v_addc_co_u32_e32 v13, vcc, 0, v139, vcc
	v_max_f32_e32 v0, 0, v0
	v_max_f32_e32 v1, 0, v1
	global_store_dwordx4 v[12:13], v[8:11], off
	v_max_f32_e32 v4, v4, v4
	v_max_f32_e32 v5, v5, v5
	v_pk_mul_f32 v[8:9], v[0:1], v[0:1]
	v_max_f32_e32 v1, v2, v2
	v_max_f32_e32 v0, v6, v6
	v_max_f32_e32 v2, 0, v1
	v_max_f32_e32 v1, v7, v7
	v_max_f32_e32 v3, v3, v3
	v_max_f32_e32 v4, 0, v4
	v_max_f32_e32 v5, 0, v5
	v_max_f32_e32 v0, 0, v0
	v_max_f32_e32 v1, 0, v1
	v_max_f32_e32 v3, 0, v3
	v_pk_mul_f32 v[4:5], v[4:5], v[4:5]
	v_pk_mul_f32 v[6:7], v[0:1], v[0:1]
	v_pk_mul_f32 v[10:11], v[2:3], v[2:3]
	v_readlane_b32 s50, v255, 19
	v_cvt_pk_bf16_f32 v0, v4, v5
	v_cvt_pk_bf16_f32 v1, v6, v7
	v_cvt_pk_bf16_f32 v2, v8, v9
	v_cvt_pk_bf16_f32 v3, v10, v11
	s_and_b64 vcc, exec, s[38:39]
	s_mov_b32 s40, s4
	s_mov_b32 s41, s6
	s_mov_b64 s[12:13], s[10:11]
	s_mov_b64 s[14:15], s[8:9]
	v_readlane_b32 s51, v255, 20
	global_store_dwordx4 v[16:17], v[0:3], off offset:256
	s_cbranch_vccz .LBB0_1513
	s_waitcnt vmcnt(0)
	s_cmpk_gt_u32 s16, 0xff
	s_cbranch_scc1 .LBB0_1524
	s_barrier
